# v28 minus the redundant post-barrier lgkmcnt(0) wait only
# baseline (speedup 1.0000x reference)
.LBB0_379:
	v_add_u32_e32 v14, s56, v140
	v_add_u32_e32 v30, s57, v140
	ds_read_b128 v[2:5], v14
	ds_read_b128 v[6:9], v14 offset:1024
	ds_read_b128 v[10:13], v14 offset:2048
	ds_read_b128 v[14:17], v14 offset:3072
	ds_read_b128 v[18:21], v30
	ds_read_b128 v[22:25], v30 offset:1024
	ds_read_b128 v[26:29], v30 offset:2048
	ds_read_b128 v[30:33], v30 offset:3072
	v_add_u32_e32 v141, 0, v1
	ds_read_b128 v[34:37], v141
	ds_read_b128 v[38:41], v141 offset:1024
	ds_read_b128 v[42:45], v141 offset:2048
	ds_read_b128 v[46:49], v141 offset:3072
	ds_read_b128 v[50:53], v141 offset:4096
	ds_read_b128 v[54:57], v141 offset:5120
	ds_read_b128 v[58:61], v141 offset:6144
	ds_read_b128 v[62:65], v141 offset:7168
	s_waitcnt vmcnt(8)
	s_waitcnt lgkmcnt(0)
	s_barrier
	s_setprio 1
	v_mfma_f32_16x16x32_bf16 v[66:69], v[2:5], v[34:37], 0
	v_mfma_f32_16x16x32_bf16 v[66:69], v[6:9], v[38:41], v[66:69]
	v_mfma_f32_16x16x32_bf16 v[70:73], v[10:13], v[34:37], 0
	v_mfma_f32_16x16x32_bf16 v[70:73], v[14:17], v[38:41], v[70:73]
	v_mfma_f32_16x16x32_bf16 v[78:81], v[10:13], v[42:45], 0
	v_mfma_f32_16x16x32_bf16 v[78:81], v[14:17], v[46:49], v[78:81]
	v_mfma_f32_16x16x32_bf16 v[74:77], v[2:5], v[42:45], 0
	v_mfma_f32_16x16x32_bf16 v[74:77], v[6:9], v[46:49], v[74:77]
	v_mfma_f32_16x16x32_bf16 v[82:85], v[2:5], v[50:53], 0
	v_mfma_f32_16x16x32_bf16 v[82:85], v[6:9], v[54:57], v[82:85]
	v_mfma_f32_16x16x32_bf16 v[86:89], v[10:13], v[50:53], 0
	v_mfma_f32_16x16x32_bf16 v[86:89], v[14:17], v[54:57], v[86:89]
	v_mfma_f32_16x16x32_bf16 v[94:97], v[10:13], v[58:61], 0
	v_mfma_f32_16x16x32_bf16 v[94:97], v[14:17], v[62:65], v[94:97]
	v_mfma_f32_16x16x32_bf16 v[90:93], v[2:5], v[58:61], 0
	v_mfma_f32_16x16x32_bf16 v[90:93], v[6:9], v[62:65], v[90:93]
	s_setprio 0
	s_setprio 1
	v_mfma_f32_16x16x32_bf16 v[98:101], v[18:21], v[34:37], 0
	v_mfma_f32_16x16x32_bf16 v[34:37], v[26:29], v[34:37], 0
	v_mfma_f32_16x16x32_bf16 v[102:105], v[18:21], v[42:45], 0
	v_mfma_f32_16x16x32_bf16 v[42:45], v[26:29], v[42:45], 0
	v_mfma_f32_16x16x32_bf16 v[106:109], v[18:21], v[50:53], 0
	v_mfma_f32_16x16x32_bf16 v[50:53], v[26:29], v[50:53], 0
	v_mfma_f32_16x16x32_bf16 v[110:113], v[18:21], v[58:61], 0
	v_mfma_f32_16x16x32_bf16 v[58:61], v[26:29], v[58:61], 0
	v_mfma_f32_16x16x32_bf16 v[98:101], v[22:25], v[38:41], v[98:101]
	v_mfma_f32_16x16x32_bf16 v[38:41], v[30:33], v[38:41], v[34:37]
	v_mfma_f32_16x16x32_bf16 v[102:105], v[22:25], v[46:49], v[102:105]
	v_mfma_f32_16x16x32_bf16 v[46:49], v[30:33], v[46:49], v[42:45]
	v_mfma_f32_16x16x32_bf16 v[106:109], v[22:25], v[54:57], v[106:109]
	v_mfma_f32_16x16x32_bf16 v[54:57], v[30:33], v[54:57], v[50:53]
	s_setprio 2
	s_barrier
	v_mfma_f32_16x16x32_bf16 v[110:113], v[22:25], v[62:65], v[110:113]
	v_mfma_f32_16x16x32_bf16 v[62:65], v[30:33], v[62:65], v[58:61]
	s_setprio 0
	v_lshl_add_u64 v[136:137], s[38:39], 0, v[130:131]
	s_add_i32 s60, s56, s21
	v_mov_b32_e32 v135, v131
	v_lshl_add_u64 v[142:143], v[136:137], 0, s[10:11]
	s_mov_b32 m0, s60
	v_lshl_add_u64 v[244:245], s[38:39], 0, v[134:135]
	ds_read_b128 v[34:37], v141 offset:16384
	ds_read_b128 v[42:45], v141 offset:17408
	ds_read_b128 v[50:53], v141 offset:18432
	ds_read_b128 v[58:61], v141 offset:19456
	ds_read_b128 v[114:117], v141 offset:20480
	ds_read_b128 v[118:121], v141 offset:21504
	ds_read_b128 v[122:125], v141 offset:22528
	ds_read_b128 v[126:129], v141 offset:23552
	global_load_lds_dwordx4 v[142:143], off
	v_lshl_add_u64 v[142:143], v[244:245], 0, s[10:11]
	s_add_i32 m0, s60, 0x2000
	s_add_i32 s60, s57, s21
	global_load_lds_dwordx4 v[142:143], off
	s_mov_b32 m0, s60
	v_mov_b32_e32 v139, v131
	global_load_lds_dwordx4 v130, s[40:41]
	s_add_i32 m0, s60, 0x2000
	v_lshl_add_u64 v[246:247], s[36:37], 0, v[138:139]
	v_mov_b32_e32 v133, v131
	global_load_lds_dwordx4 v134, s[40:41]
	v_lshl_add_u64 v[142:143], v[246:247], 0, s[10:11]
	s_mov_b32 m0, s33
	v_lshl_add_u64 v[248:249], s[36:37], 0, v[132:133]
	global_load_lds_dwordx4 v[142:143], off
	v_lshl_add_u64 v[142:143], v[248:249], 0, s[10:11]
	s_mov_b32 m0, s46
	s_nop 0
	global_load_lds_dwordx4 v[142:143], off
	s_waitcnt vmcnt(8)
	s_waitcnt lgkmcnt(0)
	s_barrier
	s_setprio 1
	v_mfma_f32_16x16x32_bf16 v[142:145], v[2:5], v[34:37], 0
	v_mfma_f32_16x16x32_bf16 v[148:151], v[10:13], v[34:37], 0
	v_mfma_f32_16x16x32_bf16 v[152:155], v[2:5], v[50:53], 0
	v_mfma_f32_16x16x32_bf16 v[156:159], v[10:13], v[50:53], 0
	v_mfma_f32_16x16x32_bf16 v[160:163], v[2:5], v[114:117], 0
	v_mfma_f32_16x16x32_bf16 v[164:167], v[10:13], v[114:117], 0
	v_mfma_f32_16x16x32_bf16 v[2:5], v[2:5], v[122:125], 0
	v_mfma_f32_16x16x32_bf16 v[10:13], v[10:13], v[122:125], 0
	v_mfma_f32_16x16x32_bf16 v[142:145], v[6:9], v[42:45], v[142:145]
	v_mfma_f32_16x16x32_bf16 v[148:151], v[14:17], v[42:45], v[148:151]
	v_mfma_f32_16x16x32_bf16 v[152:155], v[6:9], v[58:61], v[152:155]
	v_mfma_f32_16x16x32_bf16 v[156:159], v[14:17], v[58:61], v[156:159]
	v_mfma_f32_16x16x32_bf16 v[160:163], v[6:9], v[118:121], v[160:163]
	v_mfma_f32_16x16x32_bf16 v[164:167], v[14:17], v[118:121], v[164:167]
	v_mfma_f32_16x16x32_bf16 v[168:171], v[6:9], v[126:129], v[2:5]
	v_mfma_f32_16x16x32_bf16 v[172:175], v[14:17], v[126:129], v[10:13]
	s_setprio 0
	s_setprio 1
	v_mfma_f32_16x16x32_bf16 v[2:5], v[18:21], v[34:37], 0
	v_mfma_f32_16x16x32_bf16 v[6:9], v[26:29], v[34:37], 0
	v_mfma_f32_16x16x32_bf16 v[10:13], v[18:21], v[50:53], 0
	v_mfma_f32_16x16x32_bf16 v[14:17], v[26:29], v[50:53], 0
	v_mfma_f32_16x16x32_bf16 v[34:37], v[18:21], v[114:117], 0
	v_mfma_f32_16x16x32_bf16 v[50:53], v[26:29], v[114:117], 0
	v_mfma_f32_16x16x32_bf16 v[18:21], v[18:21], v[122:125], 0
	v_mfma_f32_16x16x32_bf16 v[26:29], v[26:29], v[122:125], 0
	v_mfma_f32_16x16x32_bf16 v[114:117], v[22:25], v[42:45], v[2:5]
	v_mfma_f32_16x16x32_bf16 v[188:191], v[22:25], v[118:121], v[34:37]
	v_mfma_f32_16x16x32_bf16 v[118:121], v[30:33], v[118:121], v[50:53]
	v_mfma_f32_16x16x32_bf16 v[176:179], v[30:33], v[42:45], v[6:9]
	v_mfma_f32_16x16x32_bf16 v[180:183], v[22:25], v[58:61], v[10:13]
	v_mfma_f32_16x16x32_bf16 v[184:187], v[30:33], v[58:61], v[14:17]
	s_setprio 2
	s_barrier
	v_mfma_f32_16x16x32_bf16 v[192:195], v[22:25], v[126:129], v[18:21]
	v_mfma_f32_16x16x32_bf16 v[196:199], v[30:33], v[126:129], v[26:29]
	s_setprio 0
	s_add_i32 s60, 0, 0x18000
	v_add_u32_e32 v2, s60, v140
	s_add_i32 s61, 0, 0x1c000
	ds_read_b128 v[200:203], v2
	ds_read_b128 v[204:207], v2 offset:1024
	ds_read_b128 v[208:211], v2 offset:2048
	ds_read_b128 v[212:215], v2 offset:3072
	v_add_u32_e32 v2, s61, v140
	ds_read_b128 v[216:219], v2
	ds_read_b128 v[220:223], v2 offset:1024
	ds_read_b128 v[224:227], v2 offset:2048
	ds_read_b128 v[228:231], v2 offset:3072
	s_mov_b32 m0, s47
	ds_read_b128 v[42:45], v141 offset:32768
	ds_read_b128 v[50:53], v141 offset:33792
	ds_read_b128 v[58:61], v141 offset:34816
	ds_read_b128 v[122:125], v141 offset:35840
	ds_read_b128 v[126:129], v141 offset:36864
	ds_read_b128 v[232:235], v141 offset:37888
	ds_read_b128 v[236:239], v141 offset:38912
	ds_read_b128 v[240:243], v141 offset:39936
	global_load_lds_dwordx4 v138, s[42:43]
	s_mov_b32 m0, s48
	s_nop 0
	global_load_lds_dwordx4 v132, s[42:43]
	s_waitcnt vmcnt(8)
	s_waitcnt lgkmcnt(0)
	s_barrier
	s_setprio 1
	v_mfma_f32_16x16x32_bf16 v[2:5], v[200:203], v[42:45], v[66:69]
	v_mfma_f32_16x16x32_bf16 v[6:9], v[208:211], v[42:45], v[70:73]
	v_mfma_f32_16x16x32_bf16 v[10:13], v[200:203], v[58:61], v[74:77]
	v_mfma_f32_16x16x32_bf16 v[14:17], v[208:211], v[58:61], v[78:81]
	v_mfma_f32_16x16x32_bf16 v[18:21], v[200:203], v[126:129], v[82:85]
	v_mfma_f32_16x16x32_bf16 v[22:25], v[208:211], v[126:129], v[86:89]
	v_mfma_f32_16x16x32_bf16 v[26:29], v[200:203], v[236:239], v[90:93]
	v_mfma_f32_16x16x32_bf16 v[30:33], v[208:211], v[236:239], v[94:97]
	v_mfma_f32_16x16x32_bf16 v[2:5], v[204:207], v[50:53], v[2:5]
	v_mfma_f32_16x16x32_bf16 v[6:9], v[212:215], v[50:53], v[6:9]
	v_mfma_f32_16x16x32_bf16 v[10:13], v[204:207], v[122:125], v[10:13]
	v_mfma_f32_16x16x32_bf16 v[14:17], v[212:215], v[122:125], v[14:17]
	v_mfma_f32_16x16x32_bf16 v[18:21], v[204:207], v[232:235], v[18:21]
	v_mfma_f32_16x16x32_bf16 v[22:25], v[212:215], v[232:235], v[22:25]
	v_mfma_f32_16x16x32_bf16 v[26:29], v[204:207], v[240:243], v[26:29]
	v_mfma_f32_16x16x32_bf16 v[30:33], v[212:215], v[240:243], v[30:33]
	s_setprio 0
	s_setprio 1
	v_mfma_f32_16x16x32_bf16 v[34:37], v[216:219], v[42:45], v[98:101]
	v_mfma_f32_16x16x32_bf16 v[38:41], v[224:227], v[42:45], v[38:41]
	v_mfma_f32_16x16x32_bf16 v[34:37], v[220:223], v[50:53], v[34:37]
	v_mfma_f32_16x16x32_bf16 v[38:41], v[228:231], v[50:53], v[38:41]
	v_mfma_f32_16x16x32_bf16 v[42:45], v[216:219], v[58:61], v[102:105]
	v_mfma_f32_16x16x32_bf16 v[46:49], v[224:227], v[58:61], v[46:49]
	v_mfma_f32_16x16x32_bf16 v[50:53], v[216:219], v[126:129], v[106:109]
	v_mfma_f32_16x16x32_bf16 v[54:57], v[224:227], v[126:129], v[54:57]
	v_mfma_f32_16x16x32_bf16 v[58:61], v[216:219], v[236:239], v[110:113]
	v_mfma_f32_16x16x32_bf16 v[62:65], v[224:227], v[236:239], v[62:65]
	v_mfma_f32_16x16x32_bf16 v[42:45], v[220:223], v[122:125], v[42:45]
	v_mfma_f32_16x16x32_bf16 v[46:49], v[228:231], v[122:125], v[46:49]
	v_mfma_f32_16x16x32_bf16 v[50:53], v[220:223], v[232:235], v[50:53]
	v_mfma_f32_16x16x32_bf16 v[54:57], v[228:231], v[232:235], v[54:57]
	s_setprio 2
	s_barrier
	v_mfma_f32_16x16x32_bf16 v[58:61], v[220:223], v[240:243], v[58:61]
	v_mfma_f32_16x16x32_bf16 v[62:65], v[228:231], v[240:243], v[62:65]
	s_setprio 0
	s_add_i32 s60, s60, s21
	v_lshl_add_u64 v[66:67], v[136:137], 0, s[12:13]
	s_mov_b32 m0, s60
	ds_read_b128 v[94:97], v141 offset:49152
	ds_read_b128 v[98:101], v141 offset:50176
	ds_read_b128 v[102:105], v141 offset:51200
	ds_read_b128 v[106:109], v141 offset:52224
	ds_read_b128 v[110:113], v141 offset:53248
	ds_read_b128 v[232:235], v141 offset:54272
	ds_read_b128 v[236:239], v141 offset:55296
	ds_read_b128 v[240:243], v141 offset:56320
	global_load_lds_dwordx4 v[66:67], off
	v_lshl_add_u64 v[66:67], v[244:245], 0, s[12:13]
	s_add_i32 m0, s60, 0x2000
	s_add_i32 s60, s61, s21
	global_load_lds_dwordx4 v[66:67], off
	s_mov_b32 m0, s60
	v_lshl_add_u64 v[66:67], v[246:247], 0, s[12:13]
	global_load_lds_dwordx4 v130, s[44:45]
	s_add_i32 m0, s60, 0x2000
	s_nop 0
	global_load_lds_dwordx4 v134, s[44:45]
	s_mov_b32 m0, s52
	s_nop 0
	global_load_lds_dwordx4 v[66:67], off
	v_lshl_add_u64 v[66:67], v[248:249], 0, s[12:13]
	s_mov_b32 m0, s53
	s_nop 0
	global_load_lds_dwordx4 v[66:67], off
	s_waitcnt vmcnt(8)
	s_waitcnt lgkmcnt(0)
	s_barrier
	s_setprio 1
	v_mfma_f32_16x16x32_bf16 v[66:69], v[200:203], v[94:97], v[142:145]
	v_mfma_f32_16x16x32_bf16 v[122:125], v[204:207], v[98:101], v[66:69]
	v_mfma_f32_16x16x32_bf16 v[66:69], v[208:211], v[94:97], v[148:151]
	v_mfma_f32_16x16x32_bf16 v[126:129], v[212:215], v[98:101], v[66:69]
	v_mfma_f32_16x16x32_bf16 v[66:69], v[200:203], v[102:105], v[152:155]
	v_mfma_f32_16x16x32_bf16 v[70:73], v[208:211], v[102:105], v[156:159]
	v_mfma_f32_16x16x32_bf16 v[74:77], v[200:203], v[110:113], v[160:163]
	v_mfma_f32_16x16x32_bf16 v[78:81], v[208:211], v[110:113], v[164:167]
	v_mfma_f32_16x16x32_bf16 v[82:85], v[200:203], v[236:239], v[168:171]
	v_mfma_f32_16x16x32_bf16 v[86:89], v[208:211], v[236:239], v[172:175]
	v_mfma_f32_16x16x32_bf16 v[66:69], v[204:207], v[106:109], v[66:69]
	v_mfma_f32_16x16x32_bf16 v[70:73], v[212:215], v[106:109], v[70:73]
	v_mfma_f32_16x16x32_bf16 v[74:77], v[204:207], v[232:235], v[74:77]
	v_mfma_f32_16x16x32_bf16 v[78:81], v[212:215], v[232:235], v[78:81]
	v_mfma_f32_16x16x32_bf16 v[82:85], v[204:207], v[240:243], v[82:85]
	v_mfma_f32_16x16x32_bf16 v[86:89], v[212:215], v[240:243], v[86:89]
	s_setprio 0
	s_setprio 1
	v_mfma_f32_16x16x32_bf16 v[90:93], v[216:219], v[94:97], v[114:117]
	v_mfma_f32_16x16x32_bf16 v[94:97], v[224:227], v[94:97], v[176:179]
	v_mfma_f32_16x16x32_bf16 v[90:93], v[220:223], v[98:101], v[90:93]
	v_mfma_f32_16x16x32_bf16 v[94:97], v[228:231], v[98:101], v[94:97]
	v_mfma_f32_16x16x32_bf16 v[98:101], v[216:219], v[102:105], v[180:183]
	v_mfma_f32_16x16x32_bf16 v[102:105], v[224:227], v[102:105], v[184:187]
	v_mfma_f32_16x16x32_bf16 v[98:101], v[220:223], v[106:109], v[98:101]
	v_mfma_f32_16x16x32_bf16 v[102:105], v[228:231], v[106:109], v[102:105]
	v_mfma_f32_16x16x32_bf16 v[106:109], v[216:219], v[110:113], v[188:191]
	v_mfma_f32_16x16x32_bf16 v[110:113], v[224:227], v[110:113], v[118:121]
	v_mfma_f32_16x16x32_bf16 v[114:117], v[216:219], v[236:239], v[192:195]
	v_mfma_f32_16x16x32_bf16 v[118:121], v[224:227], v[236:239], v[196:199]
	v_mfma_f32_16x16x32_bf16 v[106:109], v[220:223], v[232:235], v[106:109]
	v_mfma_f32_16x16x32_bf16 v[110:113], v[228:231], v[232:235], v[110:113]
	s_setprio 2
	s_barrier
	v_mfma_f32_16x16x32_bf16 v[114:117], v[220:223], v[240:243], v[114:117]
	v_mfma_f32_16x16x32_bf16 v[118:121], v[228:231], v[240:243], v[118:121]
	s_setprio 0
	s_add_i32 s59, s59, 2
	s_cmp_ge_i32 s59, s15
	s_cbranch_scc0 .LBB0_379
	v_mov_b32_e32 v136, v130
	s_branch .LBB0_382

.LBB0_383:
	v_add_u32_e32 v133, s56, v140
	ds_read_b128 v[142:145], v133
	ds_read_b128 v[148:151], v133 offset:1024
	ds_read_b128 v[152:155], v133 offset:2048
	ds_read_b128 v[156:159], v133 offset:3072
	v_add_u32_e32 v133, s57, v140
	ds_read_b128 v[160:163], v133
	ds_read_b128 v[164:167], v133 offset:1024
	ds_read_b128 v[168:171], v133 offset:2048
	ds_read_b128 v[172:175], v133 offset:3072
	s_add_u32 s38, s36, 0xfff80080
	s_addc_u32 s39, s37, -1
	s_cmp_eq_u32 s43, 28
	s_cselect_b32 s41, s31, s39
	s_cselect_b32 s40, s30, s38
	s_cselect_b32 s39, s35, s42
	s_cselect_b32 s38, s34, s15
	s_mov_b32 m0, s54
	v_add_u32_e32 v141, 0, v1
	ds_read_b128 v[176:179], v141
	ds_read_b128 v[180:183], v141 offset:1024
	ds_read_b128 v[184:187], v141 offset:2048
	ds_read_b128 v[188:191], v141 offset:3072
	ds_read_b128 v[192:195], v141 offset:4096
	ds_read_b128 v[196:199], v141 offset:5120
	ds_read_b128 v[200:203], v141 offset:6144
	ds_read_b128 v[204:207], v141 offset:7168
	global_load_lds_dwordx4 v130, s[36:37]
	s_mov_b32 m0, s55
	v_mov_b32_e32 v133, v131
	global_load_lds_dwordx4 v132, s[36:37]
	s_waitcnt vmcnt(8)
	s_waitcnt lgkmcnt(0)
	s_barrier
	s_setprio 1
	v_mfma_f32_16x16x32_bf16 v[2:5], v[142:145], v[176:179], v[2:5]
	v_mfma_f32_16x16x32_bf16 v[2:5], v[148:151], v[180:183], v[2:5]
	v_mfma_f32_16x16x32_bf16 v[6:9], v[156:159], v[180:183], v[6:9]
	v_mfma_f32_16x16x32_bf16 v[6:9], v[152:155], v[176:179], v[6:9]
	v_mfma_f32_16x16x32_bf16 v[14:17], v[152:155], v[184:187], v[14:17]
	v_mfma_f32_16x16x32_bf16 v[14:17], v[156:159], v[188:191], v[14:17]
	v_mfma_f32_16x16x32_bf16 v[10:13], v[148:151], v[188:191], v[10:13]
	v_mfma_f32_16x16x32_bf16 v[10:13], v[142:145], v[184:187], v[10:13]
	v_mfma_f32_16x16x32_bf16 v[18:21], v[142:145], v[192:195], v[18:21]
	v_mfma_f32_16x16x32_bf16 v[18:21], v[148:151], v[196:199], v[18:21]
	v_mfma_f32_16x16x32_bf16 v[22:25], v[156:159], v[196:199], v[22:25]
	v_mfma_f32_16x16x32_bf16 v[22:25], v[152:155], v[192:195], v[22:25]
	v_mfma_f32_16x16x32_bf16 v[30:33], v[152:155], v[200:203], v[30:33]
	v_mfma_f32_16x16x32_bf16 v[30:33], v[156:159], v[204:207], v[30:33]
	v_mfma_f32_16x16x32_bf16 v[26:29], v[148:151], v[204:207], v[26:29]
	v_mfma_f32_16x16x32_bf16 v[26:29], v[142:145], v[200:203], v[26:29]
	s_setprio 0
	s_setprio 1
	v_mfma_f32_16x16x32_bf16 v[34:37], v[160:163], v[176:179], v[34:37]
	v_mfma_f32_16x16x32_bf16 v[34:37], v[164:167], v[180:183], v[34:37]
	v_mfma_f32_16x16x32_bf16 v[38:41], v[172:175], v[180:183], v[38:41]
	v_mfma_f32_16x16x32_bf16 v[38:41], v[168:171], v[176:179], v[38:41]
	v_mfma_f32_16x16x32_bf16 v[46:49], v[168:171], v[184:187], v[46:49]
	v_mfma_f32_16x16x32_bf16 v[46:49], v[172:175], v[188:191], v[46:49]
	v_mfma_f32_16x16x32_bf16 v[42:45], v[164:167], v[188:191], v[42:45]
	v_mfma_f32_16x16x32_bf16 v[42:45], v[160:163], v[184:187], v[42:45]
	v_mfma_f32_16x16x32_bf16 v[50:53], v[160:163], v[192:195], v[50:53]
	v_mfma_f32_16x16x32_bf16 v[50:53], v[164:167], v[196:199], v[50:53]
	v_mfma_f32_16x16x32_bf16 v[54:57], v[172:175], v[196:199], v[54:57]
	v_mfma_f32_16x16x32_bf16 v[54:57], v[168:171], v[192:195], v[54:57]
	v_mfma_f32_16x16x32_bf16 v[62:65], v[168:171], v[200:203], v[62:65]
	v_mfma_f32_16x16x32_bf16 v[62:65], v[172:175], v[204:207], v[62:65]
	s_setprio 2
	s_barrier
	v_mfma_f32_16x16x32_bf16 v[58:61], v[164:167], v[204:207], v[58:61]
	v_mfma_f32_16x16x32_bf16 v[58:61], v[160:163], v[200:203], v[58:61]
	s_setprio 0
	s_add_i32 s44, s56, s21
	s_mov_b32 m0, s44
	ds_read_b128 v[176:179], v141 offset:16384
	ds_read_b128 v[180:183], v141 offset:17408
	ds_read_b128 v[184:187], v141 offset:18432
	ds_read_b128 v[188:191], v141 offset:19456
	ds_read_b128 v[192:195], v141 offset:20480
	ds_read_b128 v[196:199], v141 offset:21504
	ds_read_b128 v[200:203], v141 offset:22528
	ds_read_b128 v[204:207], v141 offset:23552
	global_load_lds_dwordx4 v136, s[38:39]
	s_add_i32 m0, s44, 0x2000
	s_add_u32 s44, s38, 0x80000
	s_addc_u32 s45, s39, 0
	s_add_i32 s59, s57, s21
	global_load_lds_dwordx4 v134, s[38:39]
	s_mov_b32 m0, s59
	v_mov_b32_e32 v137, v131
	global_load_lds_dwordx4 v136, s[44:45]
	s_add_i32 m0, s59, 0x2000
	v_mov_b32_e32 v135, v131
	global_load_lds_dwordx4 v134, s[44:45]
	s_mov_b32 m0, s33
	v_lshl_add_u64 v[138:139], s[38:39], 0, v[136:137]
	global_load_lds_dwordx4 v130, s[40:41]
	s_mov_b32 m0, s46
	v_lshl_add_u64 v[208:209], s[38:39], 0, v[134:135]
	global_load_lds_dwordx4 v132, s[40:41]
	s_waitcnt vmcnt(8)
	s_waitcnt lgkmcnt(0)
	v_lshl_add_u64 v[210:211], s[40:41], 0, v[130:131]
	v_lshl_add_u64 v[212:213], s[40:41], 0, v[132:133]
	s_barrier
	s_setprio 1
	v_mfma_f32_16x16x32_bf16 v[122:125], v[142:145], v[176:179], v[122:125]
	v_mfma_f32_16x16x32_bf16 v[122:125], v[148:151], v[180:183], v[122:125]
	v_mfma_f32_16x16x32_bf16 v[126:129], v[156:159], v[180:183], v[126:129]
	v_mfma_f32_16x16x32_bf16 v[126:129], v[152:155], v[176:179], v[126:129]
	v_mfma_f32_16x16x32_bf16 v[70:73], v[152:155], v[184:187], v[70:73]
	v_mfma_f32_16x16x32_bf16 v[70:73], v[156:159], v[188:191], v[70:73]
	v_mfma_f32_16x16x32_bf16 v[66:69], v[148:151], v[188:191], v[66:69]
	v_mfma_f32_16x16x32_bf16 v[66:69], v[142:145], v[184:187], v[66:69]
	v_mfma_f32_16x16x32_bf16 v[74:77], v[142:145], v[192:195], v[74:77]
	v_mfma_f32_16x16x32_bf16 v[74:77], v[148:151], v[196:199], v[74:77]
	v_mfma_f32_16x16x32_bf16 v[78:81], v[156:159], v[196:199], v[78:81]
	v_mfma_f32_16x16x32_bf16 v[78:81], v[152:155], v[192:195], v[78:81]
	v_mfma_f32_16x16x32_bf16 v[86:89], v[152:155], v[200:203], v[86:89]
	v_mfma_f32_16x16x32_bf16 v[86:89], v[156:159], v[204:207], v[86:89]
	v_mfma_f32_16x16x32_bf16 v[82:85], v[148:151], v[204:207], v[82:85]
	v_mfma_f32_16x16x32_bf16 v[82:85], v[142:145], v[200:203], v[82:85]
	s_setprio 0
	s_setprio 1
	v_mfma_f32_16x16x32_bf16 v[90:93], v[160:163], v[176:179], v[90:93]
	v_mfma_f32_16x16x32_bf16 v[90:93], v[164:167], v[180:183], v[90:93]
	v_mfma_f32_16x16x32_bf16 v[94:97], v[172:175], v[180:183], v[94:97]
	v_mfma_f32_16x16x32_bf16 v[94:97], v[168:171], v[176:179], v[94:97]
	v_mfma_f32_16x16x32_bf16 v[102:105], v[168:171], v[184:187], v[102:105]
	v_mfma_f32_16x16x32_bf16 v[102:105], v[172:175], v[188:191], v[102:105]
	v_mfma_f32_16x16x32_bf16 v[98:101], v[164:167], v[188:191], v[98:101]
	v_mfma_f32_16x16x32_bf16 v[98:101], v[160:163], v[184:187], v[98:101]
	v_mfma_f32_16x16x32_bf16 v[106:109], v[160:163], v[192:195], v[106:109]
	v_mfma_f32_16x16x32_bf16 v[106:109], v[164:167], v[196:199], v[106:109]
	v_mfma_f32_16x16x32_bf16 v[110:113], v[172:175], v[196:199], v[110:113]
	v_mfma_f32_16x16x32_bf16 v[110:113], v[168:171], v[192:195], v[110:113]
	v_mfma_f32_16x16x32_bf16 v[118:121], v[168:171], v[200:203], v[118:121]
	v_mfma_f32_16x16x32_bf16 v[118:121], v[172:175], v[204:207], v[118:121]
	s_setprio 2
	s_barrier
	v_mfma_f32_16x16x32_bf16 v[114:117], v[164:167], v[204:207], v[114:117]
	v_mfma_f32_16x16x32_bf16 v[114:117], v[160:163], v[200:203], v[114:117]
	s_setprio 0
	s_add_i32 s44, 0, 0x18000
	v_add_u32_e32 v135, s44, v140
	s_add_i32 s45, 0, 0x1c000
	ds_read_b128 v[142:145], v135
	ds_read_b128 v[148:151], v135 offset:1024
	ds_read_b128 v[152:155], v135 offset:2048
	ds_read_b128 v[156:159], v135 offset:3072
	v_add_u32_e32 v135, s45, v140
	ds_read_b128 v[160:163], v135
	ds_read_b128 v[164:167], v135 offset:1024
	ds_read_b128 v[168:171], v135 offset:2048
	ds_read_b128 v[172:175], v135 offset:3072
	s_add_u32 s40, s40, 0x80000
	s_addc_u32 s41, s41, 0
	s_mov_b32 m0, s47
	ds_read_b128 v[176:179], v141 offset:32768
	ds_read_b128 v[180:183], v141 offset:33792
	ds_read_b128 v[184:187], v141 offset:34816
	ds_read_b128 v[188:191], v141 offset:35840
	ds_read_b128 v[192:195], v141 offset:36864
	ds_read_b128 v[196:199], v141 offset:37888
	ds_read_b128 v[200:203], v141 offset:38912
	ds_read_b128 v[204:207], v141 offset:39936
	global_load_lds_dwordx4 v130, s[40:41]
	s_mov_b32 m0, s48
	s_nop 0
	global_load_lds_dwordx4 v132, s[40:41]
	s_waitcnt vmcnt(8)
	s_waitcnt lgkmcnt(0)
	s_barrier
	s_setprio 1
	v_mfma_f32_16x16x32_bf16 v[2:5], v[142:145], v[176:179], v[2:5]
	v_mfma_f32_16x16x32_bf16 v[2:5], v[148:151], v[180:183], v[2:5]
	v_mfma_f32_16x16x32_bf16 v[6:9], v[156:159], v[180:183], v[6:9]
	v_mfma_f32_16x16x32_bf16 v[6:9], v[152:155], v[176:179], v[6:9]
	v_mfma_f32_16x16x32_bf16 v[14:17], v[152:155], v[184:187], v[14:17]
	v_mfma_f32_16x16x32_bf16 v[14:17], v[156:159], v[188:191], v[14:17]
	v_mfma_f32_16x16x32_bf16 v[10:13], v[148:151], v[188:191], v[10:13]
	v_mfma_f32_16x16x32_bf16 v[10:13], v[142:145], v[184:187], v[10:13]
	v_mfma_f32_16x16x32_bf16 v[18:21], v[142:145], v[192:195], v[18:21]
	v_mfma_f32_16x16x32_bf16 v[18:21], v[148:151], v[196:199], v[18:21]
	v_mfma_f32_16x16x32_bf16 v[22:25], v[156:159], v[196:199], v[22:25]
	v_mfma_f32_16x16x32_bf16 v[22:25], v[152:155], v[192:195], v[22:25]
	v_mfma_f32_16x16x32_bf16 v[30:33], v[152:155], v[200:203], v[30:33]
	v_mfma_f32_16x16x32_bf16 v[30:33], v[156:159], v[204:207], v[30:33]
	v_mfma_f32_16x16x32_bf16 v[26:29], v[148:151], v[204:207], v[26:29]
	v_mfma_f32_16x16x32_bf16 v[26:29], v[142:145], v[200:203], v[26:29]
	s_setprio 0
	s_setprio 1
	v_mfma_f32_16x16x32_bf16 v[34:37], v[160:163], v[176:179], v[34:37]
	v_mfma_f32_16x16x32_bf16 v[34:37], v[164:167], v[180:183], v[34:37]
	v_mfma_f32_16x16x32_bf16 v[38:41], v[172:175], v[180:183], v[38:41]
	v_mfma_f32_16x16x32_bf16 v[38:41], v[168:171], v[176:179], v[38:41]
	v_mfma_f32_16x16x32_bf16 v[46:49], v[168:171], v[184:187], v[46:49]
	v_mfma_f32_16x16x32_bf16 v[46:49], v[172:175], v[188:191], v[46:49]
	v_mfma_f32_16x16x32_bf16 v[42:45], v[164:167], v[188:191], v[42:45]
	v_mfma_f32_16x16x32_bf16 v[42:45], v[160:163], v[184:187], v[42:45]
	v_mfma_f32_16x16x32_bf16 v[50:53], v[160:163], v[192:195], v[50:53]
	v_mfma_f32_16x16x32_bf16 v[50:53], v[164:167], v[196:199], v[50:53]
	v_mfma_f32_16x16x32_bf16 v[54:57], v[172:175], v[196:199], v[54:57]
	v_mfma_f32_16x16x32_bf16 v[54:57], v[168:171], v[192:195], v[54:57]
	v_mfma_f32_16x16x32_bf16 v[62:65], v[168:171], v[200:203], v[62:65]
	v_mfma_f32_16x16x32_bf16 v[62:65], v[172:175], v[204:207], v[62:65]
	s_setprio 2
	s_barrier
	v_mfma_f32_16x16x32_bf16 v[58:61], v[164:167], v[204:207], v[58:61]
	v_mfma_f32_16x16x32_bf16 v[58:61], v[160:163], v[200:203], v[58:61]
	s_setprio 0
	s_add_i32 s40, s44, s21
	v_lshl_add_u64 v[138:139], v[138:139], 0, s[6:7]
	s_mov_b32 m0, s40
	ds_read_b128 v[176:179], v141 offset:49152
	ds_read_b128 v[180:183], v141 offset:50176
	ds_read_b128 v[184:187], v141 offset:51200
	ds_read_b128 v[188:191], v141 offset:52224
	ds_read_b128 v[192:195], v141 offset:53248
	ds_read_b128 v[196:199], v141 offset:54272
	ds_read_b128 v[200:203], v141 offset:55296
	ds_read_b128 v[204:207], v141 offset:56320
	global_load_lds_dwordx4 v[138:139], off
	s_add_i32 m0, s40, 0x2000
	s_add_u32 s38, s38, 0x80080
	v_lshl_add_u64 v[138:139], v[208:209], 0, s[6:7]
	s_addc_u32 s39, s39, 0
	s_add_i32 s40, s45, s21
	global_load_lds_dwordx4 v[138:139], off
	s_mov_b32 m0, s40
	v_lshl_add_u64 v[138:139], v[210:211], 0, s[6:7]
	global_load_lds_dwordx4 v136, s[38:39]
	s_add_i32 m0, s40, 0x2000
	s_nop 0
	global_load_lds_dwordx4 v134, s[38:39]
	s_mov_b32 m0, s52
	s_nop 0
	global_load_lds_dwordx4 v[138:139], off
	v_lshl_add_u64 v[138:139], v[212:213], 0, s[6:7]
	s_mov_b32 m0, s53
	s_nop 0
	global_load_lds_dwordx4 v[138:139], off
	s_waitcnt vmcnt(8)
	s_waitcnt lgkmcnt(0)
	s_barrier
	s_setprio 1
	v_mfma_f32_16x16x32_bf16 v[122:125], v[142:145], v[176:179], v[122:125]
	v_mfma_f32_16x16x32_bf16 v[122:125], v[148:151], v[180:183], v[122:125]
	v_mfma_f32_16x16x32_bf16 v[126:129], v[156:159], v[180:183], v[126:129]
	v_mfma_f32_16x16x32_bf16 v[126:129], v[152:155], v[176:179], v[126:129]
	v_mfma_f32_16x16x32_bf16 v[70:73], v[152:155], v[184:187], v[70:73]
	v_mfma_f32_16x16x32_bf16 v[70:73], v[156:159], v[188:191], v[70:73]
	v_mfma_f32_16x16x32_bf16 v[66:69], v[148:151], v[188:191], v[66:69]
	v_mfma_f32_16x16x32_bf16 v[66:69], v[142:145], v[184:187], v[66:69]
	v_mfma_f32_16x16x32_bf16 v[74:77], v[142:145], v[192:195], v[74:77]
	v_mfma_f32_16x16x32_bf16 v[74:77], v[148:151], v[196:199], v[74:77]
	v_mfma_f32_16x16x32_bf16 v[78:81], v[156:159], v[196:199], v[78:81]
	v_mfma_f32_16x16x32_bf16 v[78:81], v[152:155], v[192:195], v[78:81]
	v_mfma_f32_16x16x32_bf16 v[86:89], v[152:155], v[200:203], v[86:89]
	v_mfma_f32_16x16x32_bf16 v[86:89], v[156:159], v[204:207], v[86:89]
	v_mfma_f32_16x16x32_bf16 v[82:85], v[148:151], v[204:207], v[82:85]
	v_mfma_f32_16x16x32_bf16 v[82:85], v[142:145], v[200:203], v[82:85]
	s_setprio 0
	s_setprio 1
	v_mfma_f32_16x16x32_bf16 v[90:93], v[160:163], v[176:179], v[90:93]
	v_mfma_f32_16x16x32_bf16 v[90:93], v[164:167], v[180:183], v[90:93]
	v_mfma_f32_16x16x32_bf16 v[94:97], v[172:175], v[180:183], v[94:97]
	v_mfma_f32_16x16x32_bf16 v[94:97], v[168:171], v[176:179], v[94:97]
	v_mfma_f32_16x16x32_bf16 v[102:105], v[168:171], v[184:187], v[102:105]
	v_mfma_f32_16x16x32_bf16 v[102:105], v[172:175], v[188:191], v[102:105]
	v_mfma_f32_16x16x32_bf16 v[98:101], v[164:167], v[188:191], v[98:101]
	v_mfma_f32_16x16x32_bf16 v[98:101], v[160:163], v[184:187], v[98:101]
	v_mfma_f32_16x16x32_bf16 v[106:109], v[160:163], v[192:195], v[106:109]
	v_mfma_f32_16x16x32_bf16 v[106:109], v[164:167], v[196:199], v[106:109]
	v_mfma_f32_16x16x32_bf16 v[110:113], v[172:175], v[196:199], v[110:113]
	v_mfma_f32_16x16x32_bf16 v[110:113], v[168:171], v[192:195], v[110:113]
	v_mfma_f32_16x16x32_bf16 v[118:121], v[168:171], v[200:203], v[118:121]
	v_mfma_f32_16x16x32_bf16 v[118:121], v[172:175], v[204:207], v[118:121]
	s_setprio 2
	s_barrier
	v_mfma_f32_16x16x32_bf16 v[114:117], v[164:167], v[204:207], v[114:117]
	v_mfma_f32_16x16x32_bf16 v[114:117], v[160:163], v[200:203], v[114:117]
	s_setprio 0
	s_add_i32 s43, s43, 2
	s_add_u32 s36, s36, 0x100
	s_addc_u32 s37, s37, 0
	s_add_u32 s15, s15, 0x100
	s_addc_u32 s42, s42, 0
	s_cmp_gt_u32 s43, 29
	s_cbranch_scc0 .LBB0_383
	s_and_b64 vcc, exec, s[8:9]
	s_cbranch_vccz .LBB0_386
	s_barrier

.LBB0_462:
	v_add_u32_e32 v14, s54, v140
	v_add_u32_e32 v30, s55, v140
	ds_read_b128 v[2:5], v14
	ds_read_b128 v[6:9], v14 offset:1024
	ds_read_b128 v[10:13], v14 offset:2048
	ds_read_b128 v[14:17], v14 offset:3072
	ds_read_b128 v[18:21], v30
	ds_read_b128 v[22:25], v30 offset:1024
	ds_read_b128 v[26:29], v30 offset:2048
	ds_read_b128 v[30:33], v30 offset:3072
	v_add_u32_e32 v141, 0, v1
	ds_read_b128 v[34:37], v141
	ds_read_b128 v[38:41], v141 offset:1024
	ds_read_b128 v[42:45], v141 offset:2048
	ds_read_b128 v[46:49], v141 offset:3072
	ds_read_b128 v[50:53], v141 offset:4096
	ds_read_b128 v[54:57], v141 offset:5120
	ds_read_b128 v[58:61], v141 offset:6144
	ds_read_b128 v[62:65], v141 offset:7168
	s_waitcnt vmcnt(8)
	s_waitcnt lgkmcnt(0)
	s_barrier
	s_setprio 1
	v_mfma_f32_16x16x32_bf16 v[66:69], v[2:5], v[34:37], 0
	v_mfma_f32_16x16x32_bf16 v[66:69], v[6:9], v[38:41], v[66:69]
	v_mfma_f32_16x16x32_bf16 v[70:73], v[10:13], v[34:37], 0
	v_mfma_f32_16x16x32_bf16 v[70:73], v[14:17], v[38:41], v[70:73]
	v_mfma_f32_16x16x32_bf16 v[78:81], v[10:13], v[42:45], 0
	v_mfma_f32_16x16x32_bf16 v[78:81], v[14:17], v[46:49], v[78:81]
	v_mfma_f32_16x16x32_bf16 v[74:77], v[2:5], v[42:45], 0
	v_mfma_f32_16x16x32_bf16 v[74:77], v[6:9], v[46:49], v[74:77]
	v_mfma_f32_16x16x32_bf16 v[82:85], v[2:5], v[50:53], 0
	v_mfma_f32_16x16x32_bf16 v[82:85], v[6:9], v[54:57], v[82:85]
	v_mfma_f32_16x16x32_bf16 v[86:89], v[10:13], v[50:53], 0
	v_mfma_f32_16x16x32_bf16 v[86:89], v[14:17], v[54:57], v[86:89]
	v_mfma_f32_16x16x32_bf16 v[94:97], v[10:13], v[58:61], 0
	v_mfma_f32_16x16x32_bf16 v[94:97], v[14:17], v[62:65], v[94:97]
	v_mfma_f32_16x16x32_bf16 v[90:93], v[2:5], v[58:61], 0
	v_mfma_f32_16x16x32_bf16 v[90:93], v[6:9], v[62:65], v[90:93]
	s_setprio 0
	s_setprio 1
	v_mfma_f32_16x16x32_bf16 v[98:101], v[18:21], v[34:37], 0
	v_mfma_f32_16x16x32_bf16 v[34:37], v[26:29], v[34:37], 0
	v_mfma_f32_16x16x32_bf16 v[102:105], v[18:21], v[42:45], 0
	v_mfma_f32_16x16x32_bf16 v[42:45], v[26:29], v[42:45], 0
	v_mfma_f32_16x16x32_bf16 v[106:109], v[18:21], v[50:53], 0
	v_mfma_f32_16x16x32_bf16 v[50:53], v[26:29], v[50:53], 0
	v_mfma_f32_16x16x32_bf16 v[110:113], v[18:21], v[58:61], 0
	v_mfma_f32_16x16x32_bf16 v[58:61], v[26:29], v[58:61], 0
	v_mfma_f32_16x16x32_bf16 v[98:101], v[22:25], v[38:41], v[98:101]
	v_mfma_f32_16x16x32_bf16 v[38:41], v[30:33], v[38:41], v[34:37]
	v_mfma_f32_16x16x32_bf16 v[102:105], v[22:25], v[46:49], v[102:105]
	v_mfma_f32_16x16x32_bf16 v[46:49], v[30:33], v[46:49], v[42:45]
	v_mfma_f32_16x16x32_bf16 v[106:109], v[22:25], v[54:57], v[106:109]
	v_mfma_f32_16x16x32_bf16 v[54:57], v[30:33], v[54:57], v[50:53]
	s_setprio 2
	s_barrier
	v_mfma_f32_16x16x32_bf16 v[110:113], v[22:25], v[62:65], v[110:113]
	v_mfma_f32_16x16x32_bf16 v[62:65], v[30:33], v[62:65], v[58:61]
	s_setprio 0
	v_lshl_add_u64 v[136:137], s[36:37], 0, v[130:131]
	s_add_i32 s62, s54, s21
	v_mov_b32_e32 v135, v131
	v_lshl_add_u64 v[142:143], v[136:137], 0, s[12:13]
	s_mov_b32 m0, s62
	v_lshl_add_u64 v[244:245], s[36:37], 0, v[134:135]
	ds_read_b128 v[34:37], v141 offset:16384
	ds_read_b128 v[42:45], v141 offset:17408
	ds_read_b128 v[50:53], v141 offset:18432
	ds_read_b128 v[58:61], v141 offset:19456
	ds_read_b128 v[114:117], v141 offset:20480
	ds_read_b128 v[118:121], v141 offset:21504
	ds_read_b128 v[122:125], v141 offset:22528
	ds_read_b128 v[126:129], v141 offset:23552
	global_load_lds_dwordx4 v[142:143], off
	v_lshl_add_u64 v[142:143], v[244:245], 0, s[12:13]
	s_add_i32 m0, s62, 0x2000
	s_add_i32 s62, s55, s21
	global_load_lds_dwordx4 v[142:143], off
	s_mov_b32 m0, s62
	v_mov_b32_e32 v139, v131
	global_load_lds_dwordx4 v130, s[38:39]
	s_add_i32 m0, s62, 0x2000
	v_lshl_add_u64 v[246:247], s[34:35], 0, v[138:139]
	v_mov_b32_e32 v133, v131
	global_load_lds_dwordx4 v134, s[38:39]
	v_lshl_add_u64 v[142:143], v[246:247], 0, s[12:13]
	s_mov_b32 m0, s33
	v_lshl_add_u64 v[248:249], s[34:35], 0, v[132:133]
	global_load_lds_dwordx4 v[142:143], off
	v_lshl_add_u64 v[142:143], v[248:249], 0, s[12:13]
	s_mov_b32 m0, s44
	s_nop 0
	global_load_lds_dwordx4 v[142:143], off
	s_waitcnt vmcnt(8)
	s_waitcnt lgkmcnt(0)
	s_barrier
	s_setprio 1
	v_mfma_f32_16x16x32_bf16 v[142:145], v[2:5], v[34:37], 0
	v_mfma_f32_16x16x32_bf16 v[148:151], v[10:13], v[34:37], 0
	v_mfma_f32_16x16x32_bf16 v[152:155], v[2:5], v[50:53], 0
	v_mfma_f32_16x16x32_bf16 v[156:159], v[10:13], v[50:53], 0
	v_mfma_f32_16x16x32_bf16 v[160:163], v[2:5], v[114:117], 0
	v_mfma_f32_16x16x32_bf16 v[164:167], v[10:13], v[114:117], 0
	v_mfma_f32_16x16x32_bf16 v[2:5], v[2:5], v[122:125], 0
	v_mfma_f32_16x16x32_bf16 v[10:13], v[10:13], v[122:125], 0
	v_mfma_f32_16x16x32_bf16 v[142:145], v[6:9], v[42:45], v[142:145]
	v_mfma_f32_16x16x32_bf16 v[148:151], v[14:17], v[42:45], v[148:151]
	v_mfma_f32_16x16x32_bf16 v[152:155], v[6:9], v[58:61], v[152:155]
	v_mfma_f32_16x16x32_bf16 v[156:159], v[14:17], v[58:61], v[156:159]
	v_mfma_f32_16x16x32_bf16 v[160:163], v[6:9], v[118:121], v[160:163]
	v_mfma_f32_16x16x32_bf16 v[164:167], v[14:17], v[118:121], v[164:167]
	v_mfma_f32_16x16x32_bf16 v[168:171], v[6:9], v[126:129], v[2:5]
	v_mfma_f32_16x16x32_bf16 v[172:175], v[14:17], v[126:129], v[10:13]
	s_setprio 0
	s_setprio 1
	v_mfma_f32_16x16x32_bf16 v[2:5], v[18:21], v[34:37], 0
	v_mfma_f32_16x16x32_bf16 v[6:9], v[26:29], v[34:37], 0
	v_mfma_f32_16x16x32_bf16 v[10:13], v[18:21], v[50:53], 0
	v_mfma_f32_16x16x32_bf16 v[14:17], v[26:29], v[50:53], 0
	v_mfma_f32_16x16x32_bf16 v[34:37], v[18:21], v[114:117], 0
	v_mfma_f32_16x16x32_bf16 v[50:53], v[26:29], v[114:117], 0
	v_mfma_f32_16x16x32_bf16 v[18:21], v[18:21], v[122:125], 0
	v_mfma_f32_16x16x32_bf16 v[26:29], v[26:29], v[122:125], 0
	v_mfma_f32_16x16x32_bf16 v[114:117], v[22:25], v[42:45], v[2:5]
	v_mfma_f32_16x16x32_bf16 v[122:125], v[30:33], v[42:45], v[6:9]
	v_mfma_f32_16x16x32_bf16 v[184:187], v[22:25], v[118:121], v[34:37]
	v_mfma_f32_16x16x32_bf16 v[118:121], v[30:33], v[118:121], v[50:53]
	v_mfma_f32_16x16x32_bf16 v[188:191], v[22:25], v[126:129], v[18:21]
	v_mfma_f32_16x16x32_bf16 v[126:129], v[30:33], v[126:129], v[26:29]
	s_setprio 2
	s_barrier
	v_mfma_f32_16x16x32_bf16 v[176:179], v[22:25], v[58:61], v[10:13]
	v_mfma_f32_16x16x32_bf16 v[180:183], v[30:33], v[58:61], v[14:17]
	s_setprio 0
	s_add_i32 s62, 0, 0x18000
	v_add_u32_e32 v2, s62, v140
	s_add_i32 s63, 0, 0x1c000
	ds_read_b128 v[192:195], v2
	ds_read_b128 v[196:199], v2 offset:1024
	ds_read_b128 v[200:203], v2 offset:2048
	ds_read_b128 v[204:207], v2 offset:3072
	v_add_u32_e32 v2, s63, v140
	ds_read_b128 v[208:211], v2
	ds_read_b128 v[212:215], v2 offset:1024
	ds_read_b128 v[216:219], v2 offset:2048
	ds_read_b128 v[220:223], v2 offset:3072
	s_mov_b32 m0, s45
	ds_read_b128 v[42:45], v141 offset:32768
	ds_read_b128 v[50:53], v141 offset:33792
	ds_read_b128 v[58:61], v141 offset:34816
	ds_read_b128 v[224:227], v141 offset:35840
	ds_read_b128 v[228:231], v141 offset:36864
	ds_read_b128 v[232:235], v141 offset:37888
	ds_read_b128 v[236:239], v141 offset:38912
	ds_read_b128 v[240:243], v141 offset:39936
	global_load_lds_dwordx4 v138, s[40:41]
	s_mov_b32 m0, s46
	s_nop 0
	global_load_lds_dwordx4 v132, s[40:41]
	s_waitcnt vmcnt(8)
	s_waitcnt lgkmcnt(0)
	s_barrier
	s_setprio 1
	v_mfma_f32_16x16x32_bf16 v[2:5], v[192:195], v[42:45], v[66:69]
	v_mfma_f32_16x16x32_bf16 v[6:9], v[200:203], v[42:45], v[70:73]
	v_mfma_f32_16x16x32_bf16 v[10:13], v[192:195], v[58:61], v[74:77]
	v_mfma_f32_16x16x32_bf16 v[14:17], v[200:203], v[58:61], v[78:81]
	v_mfma_f32_16x16x32_bf16 v[18:21], v[192:195], v[228:231], v[82:85]
	v_mfma_f32_16x16x32_bf16 v[22:25], v[200:203], v[228:231], v[86:89]
	v_mfma_f32_16x16x32_bf16 v[26:29], v[192:195], v[236:239], v[90:93]
	v_mfma_f32_16x16x32_bf16 v[30:33], v[200:203], v[236:239], v[94:97]
	v_mfma_f32_16x16x32_bf16 v[2:5], v[196:199], v[50:53], v[2:5]
	v_mfma_f32_16x16x32_bf16 v[6:9], v[204:207], v[50:53], v[6:9]
	v_mfma_f32_16x16x32_bf16 v[10:13], v[196:199], v[224:227], v[10:13]
	v_mfma_f32_16x16x32_bf16 v[14:17], v[204:207], v[224:227], v[14:17]
	v_mfma_f32_16x16x32_bf16 v[18:21], v[196:199], v[232:235], v[18:21]
	v_mfma_f32_16x16x32_bf16 v[22:25], v[204:207], v[232:235], v[22:25]
	v_mfma_f32_16x16x32_bf16 v[26:29], v[196:199], v[240:243], v[26:29]
	v_mfma_f32_16x16x32_bf16 v[30:33], v[204:207], v[240:243], v[30:33]
	s_setprio 0
	s_setprio 1
	v_mfma_f32_16x16x32_bf16 v[34:37], v[208:211], v[42:45], v[98:101]
	v_mfma_f32_16x16x32_bf16 v[38:41], v[216:219], v[42:45], v[38:41]
	v_mfma_f32_16x16x32_bf16 v[34:37], v[212:215], v[50:53], v[34:37]
	v_mfma_f32_16x16x32_bf16 v[38:41], v[220:223], v[50:53], v[38:41]
	v_mfma_f32_16x16x32_bf16 v[42:45], v[208:211], v[58:61], v[102:105]
	v_mfma_f32_16x16x32_bf16 v[46:49], v[216:219], v[58:61], v[46:49]
	v_mfma_f32_16x16x32_bf16 v[50:53], v[208:211], v[228:231], v[106:109]
	v_mfma_f32_16x16x32_bf16 v[54:57], v[216:219], v[228:231], v[54:57]
	v_mfma_f32_16x16x32_bf16 v[58:61], v[208:211], v[236:239], v[110:113]
	v_mfma_f32_16x16x32_bf16 v[62:65], v[216:219], v[236:239], v[62:65]
	v_mfma_f32_16x16x32_bf16 v[42:45], v[212:215], v[224:227], v[42:45]
	v_mfma_f32_16x16x32_bf16 v[46:49], v[220:223], v[224:227], v[46:49]
	v_mfma_f32_16x16x32_bf16 v[50:53], v[212:215], v[232:235], v[50:53]
	v_mfma_f32_16x16x32_bf16 v[54:57], v[220:223], v[232:235], v[54:57]
	s_setprio 2
	s_barrier
	v_mfma_f32_16x16x32_bf16 v[58:61], v[212:215], v[240:243], v[58:61]
	v_mfma_f32_16x16x32_bf16 v[62:65], v[220:223], v[240:243], v[62:65]
	s_setprio 0
	s_add_i32 s62, s62, s21
	v_lshl_add_u64 v[66:67], v[136:137], 0, s[14:15]
	s_mov_b32 m0, s62
	ds_read_b128 v[102:105], v141 offset:49152
	ds_read_b128 v[106:109], v141 offset:50176
	ds_read_b128 v[110:113], v141 offset:51200
	ds_read_b128 v[224:227], v141 offset:52224
	ds_read_b128 v[228:231], v141 offset:53248
	ds_read_b128 v[232:235], v141 offset:54272
	ds_read_b128 v[236:239], v141 offset:55296
	ds_read_b128 v[240:243], v141 offset:56320
	global_load_lds_dwordx4 v[66:67], off
	v_lshl_add_u64 v[66:67], v[244:245], 0, s[14:15]
	s_add_i32 m0, s62, 0x2000
	s_add_i32 s62, s63, s21
	global_load_lds_dwordx4 v[66:67], off
	s_mov_b32 m0, s62
	v_lshl_add_u64 v[66:67], v[246:247], 0, s[14:15]
	global_load_lds_dwordx4 v130, s[42:43]
	s_add_i32 m0, s62, 0x2000
	s_nop 0
	global_load_lds_dwordx4 v134, s[42:43]
	s_mov_b32 m0, s50
	s_nop 0
	global_load_lds_dwordx4 v[66:67], off
	v_lshl_add_u64 v[66:67], v[248:249], 0, s[14:15]
	s_mov_b32 m0, s51
	s_nop 0
	global_load_lds_dwordx4 v[66:67], off
	s_waitcnt vmcnt(8)
	s_waitcnt lgkmcnt(0)
	s_barrier
	s_setprio 1
	v_mfma_f32_16x16x32_bf16 v[66:69], v[192:195], v[102:105], v[142:145]
	v_mfma_f32_16x16x32_bf16 v[70:73], v[200:203], v[102:105], v[148:151]
	v_mfma_f32_16x16x32_bf16 v[74:77], v[192:195], v[110:113], v[152:155]
	v_mfma_f32_16x16x32_bf16 v[78:81], v[200:203], v[110:113], v[156:159]
	v_mfma_f32_16x16x32_bf16 v[82:85], v[192:195], v[228:231], v[160:163]
	v_mfma_f32_16x16x32_bf16 v[86:89], v[200:203], v[228:231], v[164:167]
	v_mfma_f32_16x16x32_bf16 v[90:93], v[192:195], v[236:239], v[168:171]
	v_mfma_f32_16x16x32_bf16 v[94:97], v[200:203], v[236:239], v[172:175]
	v_mfma_f32_16x16x32_bf16 v[66:69], v[196:199], v[106:109], v[66:69]
	v_mfma_f32_16x16x32_bf16 v[70:73], v[204:207], v[106:109], v[70:73]
	v_mfma_f32_16x16x32_bf16 v[74:77], v[196:199], v[224:227], v[74:77]
	v_mfma_f32_16x16x32_bf16 v[78:81], v[204:207], v[224:227], v[78:81]
	v_mfma_f32_16x16x32_bf16 v[82:85], v[196:199], v[232:235], v[82:85]
	v_mfma_f32_16x16x32_bf16 v[86:89], v[204:207], v[232:235], v[86:89]
	v_mfma_f32_16x16x32_bf16 v[90:93], v[196:199], v[240:243], v[90:93]
	v_mfma_f32_16x16x32_bf16 v[94:97], v[204:207], v[240:243], v[94:97]
	s_setprio 0
	s_setprio 1
	v_mfma_f32_16x16x32_bf16 v[98:101], v[208:211], v[102:105], v[114:117]
	v_mfma_f32_16x16x32_bf16 v[102:105], v[216:219], v[102:105], v[122:125]
	v_mfma_f32_16x16x32_bf16 v[98:101], v[212:215], v[106:109], v[98:101]
	v_mfma_f32_16x16x32_bf16 v[102:105], v[220:223], v[106:109], v[102:105]
	v_mfma_f32_16x16x32_bf16 v[106:109], v[208:211], v[110:113], v[176:179]
	v_mfma_f32_16x16x32_bf16 v[110:113], v[216:219], v[110:113], v[180:183]
	v_mfma_f32_16x16x32_bf16 v[114:117], v[208:211], v[228:231], v[184:187]
	v_mfma_f32_16x16x32_bf16 v[118:121], v[216:219], v[228:231], v[118:121]
	v_mfma_f32_16x16x32_bf16 v[122:125], v[208:211], v[236:239], v[188:191]
	v_mfma_f32_16x16x32_bf16 v[126:129], v[216:219], v[236:239], v[126:129]
	v_mfma_f32_16x16x32_bf16 v[106:109], v[212:215], v[224:227], v[106:109]
	v_mfma_f32_16x16x32_bf16 v[110:113], v[220:223], v[224:227], v[110:113]
	v_mfma_f32_16x16x32_bf16 v[114:117], v[212:215], v[232:235], v[114:117]
	v_mfma_f32_16x16x32_bf16 v[118:121], v[220:223], v[232:235], v[118:121]
	s_setprio 2
	s_barrier
	v_mfma_f32_16x16x32_bf16 v[122:125], v[212:215], v[240:243], v[122:125]
	v_mfma_f32_16x16x32_bf16 v[126:129], v[220:223], v[240:243], v[126:129]
	s_setprio 0
	s_add_i32 s61, s61, 2
	s_cmp_ge_i32 s61, s60
	s_cbranch_scc0 .LBB0_462
	v_mov_b32_e32 v136, v130
	s_branch .LBB0_465

.LBB0_466:
	v_add_u32_e32 v133, s54, v140
	ds_read_b128 v[142:145], v133
	ds_read_b128 v[148:151], v133 offset:1024
	ds_read_b128 v[152:155], v133 offset:2048
	ds_read_b128 v[156:159], v133 offset:3072
	v_add_u32_e32 v133, s55, v140
	ds_read_b128 v[160:163], v133
	ds_read_b128 v[164:167], v133 offset:1024
	ds_read_b128 v[168:171], v133 offset:2048
	ds_read_b128 v[172:175], v133 offset:3072
	s_add_u32 s36, s34, 0xffc00080
	s_addc_u32 s37, s35, -1
	s_cmp_eq_u32 s42, 4
	s_cselect_b32 s39, s29, s37
	s_cselect_b32 s38, s28, s36
	s_cselect_b32 s37, s31, s41
	s_cselect_b32 s36, s30, s40
	s_mov_b32 m0, s52
	v_add_u32_e32 v141, 0, v1
	ds_read_b128 v[176:179], v141
	ds_read_b128 v[180:183], v141 offset:1024
	ds_read_b128 v[184:187], v141 offset:2048
	ds_read_b128 v[188:191], v141 offset:3072
	ds_read_b128 v[192:195], v141 offset:4096
	ds_read_b128 v[196:199], v141 offset:5120
	ds_read_b128 v[200:203], v141 offset:6144
	ds_read_b128 v[204:207], v141 offset:7168
	global_load_lds_dwordx4 v130, s[34:35]
	s_mov_b32 m0, s53
	v_mov_b32_e32 v133, v131
	global_load_lds_dwordx4 v132, s[34:35]
	s_waitcnt vmcnt(8)
	s_waitcnt lgkmcnt(0)
	s_barrier
	s_setprio 1
	v_mfma_f32_16x16x32_bf16 v[2:5], v[142:145], v[176:179], v[2:5]
	v_mfma_f32_16x16x32_bf16 v[2:5], v[148:151], v[180:183], v[2:5]
	v_mfma_f32_16x16x32_bf16 v[6:9], v[156:159], v[180:183], v[6:9]
	v_mfma_f32_16x16x32_bf16 v[6:9], v[152:155], v[176:179], v[6:9]
	v_mfma_f32_16x16x32_bf16 v[14:17], v[152:155], v[184:187], v[14:17]
	v_mfma_f32_16x16x32_bf16 v[14:17], v[156:159], v[188:191], v[14:17]
	v_mfma_f32_16x16x32_bf16 v[10:13], v[148:151], v[188:191], v[10:13]
	v_mfma_f32_16x16x32_bf16 v[10:13], v[142:145], v[184:187], v[10:13]
	v_mfma_f32_16x16x32_bf16 v[18:21], v[142:145], v[192:195], v[18:21]
	v_mfma_f32_16x16x32_bf16 v[18:21], v[148:151], v[196:199], v[18:21]
	v_mfma_f32_16x16x32_bf16 v[22:25], v[156:159], v[196:199], v[22:25]
	v_mfma_f32_16x16x32_bf16 v[22:25], v[152:155], v[192:195], v[22:25]
	v_mfma_f32_16x16x32_bf16 v[30:33], v[152:155], v[200:203], v[30:33]
	v_mfma_f32_16x16x32_bf16 v[30:33], v[156:159], v[204:207], v[30:33]
	v_mfma_f32_16x16x32_bf16 v[26:29], v[148:151], v[204:207], v[26:29]
	v_mfma_f32_16x16x32_bf16 v[26:29], v[142:145], v[200:203], v[26:29]
	s_setprio 0
	s_setprio 1
	v_mfma_f32_16x16x32_bf16 v[34:37], v[160:163], v[176:179], v[34:37]
	v_mfma_f32_16x16x32_bf16 v[34:37], v[164:167], v[180:183], v[34:37]
	v_mfma_f32_16x16x32_bf16 v[38:41], v[172:175], v[180:183], v[38:41]
	v_mfma_f32_16x16x32_bf16 v[38:41], v[168:171], v[176:179], v[38:41]
	v_mfma_f32_16x16x32_bf16 v[46:49], v[168:171], v[184:187], v[46:49]
	v_mfma_f32_16x16x32_bf16 v[46:49], v[172:175], v[188:191], v[46:49]
	v_mfma_f32_16x16x32_bf16 v[42:45], v[164:167], v[188:191], v[42:45]
	v_mfma_f32_16x16x32_bf16 v[42:45], v[160:163], v[184:187], v[42:45]
	v_mfma_f32_16x16x32_bf16 v[50:53], v[160:163], v[192:195], v[50:53]
	v_mfma_f32_16x16x32_bf16 v[50:53], v[164:167], v[196:199], v[50:53]
	v_mfma_f32_16x16x32_bf16 v[54:57], v[172:175], v[196:199], v[54:57]
	v_mfma_f32_16x16x32_bf16 v[54:57], v[168:171], v[192:195], v[54:57]
	v_mfma_f32_16x16x32_bf16 v[62:65], v[168:171], v[200:203], v[62:65]
	v_mfma_f32_16x16x32_bf16 v[62:65], v[172:175], v[204:207], v[62:65]
	s_setprio 2
	s_barrier
	v_mfma_f32_16x16x32_bf16 v[58:61], v[164:167], v[204:207], v[58:61]
	v_mfma_f32_16x16x32_bf16 v[58:61], v[160:163], v[200:203], v[58:61]
	s_setprio 0
	s_add_i32 s43, s54, s21
	s_mov_b32 m0, s43
	ds_read_b128 v[176:179], v141 offset:16384
	ds_read_b128 v[180:183], v141 offset:17408
	ds_read_b128 v[184:187], v141 offset:18432
	ds_read_b128 v[188:191], v141 offset:19456
	ds_read_b128 v[192:195], v141 offset:20480
	ds_read_b128 v[196:199], v141 offset:21504
	ds_read_b128 v[200:203], v141 offset:22528
	ds_read_b128 v[204:207], v141 offset:23552
	global_load_lds_dwordx4 v136, s[36:37]
	s_add_i32 m0, s43, 0x2000
	s_add_u32 s60, s36, 0x80000
	s_addc_u32 s61, s37, 0
	s_add_i32 s43, s55, s21
	global_load_lds_dwordx4 v134, s[36:37]
	s_mov_b32 m0, s43
	v_mov_b32_e32 v137, v131
	global_load_lds_dwordx4 v136, s[60:61]
	s_add_i32 m0, s43, 0x2000
	v_mov_b32_e32 v135, v131
	global_load_lds_dwordx4 v134, s[60:61]
	s_mov_b32 m0, s33
	v_lshl_add_u64 v[138:139], s[36:37], 0, v[136:137]
	global_load_lds_dwordx4 v130, s[38:39]
	s_mov_b32 m0, s44
	v_lshl_add_u64 v[208:209], s[36:37], 0, v[134:135]
	global_load_lds_dwordx4 v132, s[38:39]
	s_waitcnt vmcnt(8)
	s_waitcnt lgkmcnt(0)
	v_lshl_add_u64 v[210:211], s[38:39], 0, v[130:131]
	v_lshl_add_u64 v[212:213], s[38:39], 0, v[132:133]
	s_barrier
	s_setprio 1
	v_mfma_f32_16x16x32_bf16 v[66:69], v[142:145], v[176:179], v[66:69]
	v_mfma_f32_16x16x32_bf16 v[66:69], v[148:151], v[180:183], v[66:69]
	v_mfma_f32_16x16x32_bf16 v[70:73], v[156:159], v[180:183], v[70:73]
	v_mfma_f32_16x16x32_bf16 v[70:73], v[152:155], v[176:179], v[70:73]
	v_mfma_f32_16x16x32_bf16 v[78:81], v[152:155], v[184:187], v[78:81]
	v_mfma_f32_16x16x32_bf16 v[78:81], v[156:159], v[188:191], v[78:81]
	v_mfma_f32_16x16x32_bf16 v[74:77], v[148:151], v[188:191], v[74:77]
	v_mfma_f32_16x16x32_bf16 v[74:77], v[142:145], v[184:187], v[74:77]
	v_mfma_f32_16x16x32_bf16 v[82:85], v[142:145], v[192:195], v[82:85]
	v_mfma_f32_16x16x32_bf16 v[82:85], v[148:151], v[196:199], v[82:85]
	v_mfma_f32_16x16x32_bf16 v[86:89], v[156:159], v[196:199], v[86:89]
	v_mfma_f32_16x16x32_bf16 v[86:89], v[152:155], v[192:195], v[86:89]
	v_mfma_f32_16x16x32_bf16 v[94:97], v[152:155], v[200:203], v[94:97]
	v_mfma_f32_16x16x32_bf16 v[94:97], v[156:159], v[204:207], v[94:97]
	v_mfma_f32_16x16x32_bf16 v[90:93], v[148:151], v[204:207], v[90:93]
	v_mfma_f32_16x16x32_bf16 v[90:93], v[142:145], v[200:203], v[90:93]
	s_setprio 0
	s_setprio 1
	v_mfma_f32_16x16x32_bf16 v[98:101], v[160:163], v[176:179], v[98:101]
	v_mfma_f32_16x16x32_bf16 v[98:101], v[164:167], v[180:183], v[98:101]
	v_mfma_f32_16x16x32_bf16 v[102:105], v[172:175], v[180:183], v[102:105]
	v_mfma_f32_16x16x32_bf16 v[102:105], v[168:171], v[176:179], v[102:105]
	v_mfma_f32_16x16x32_bf16 v[110:113], v[168:171], v[184:187], v[110:113]
	v_mfma_f32_16x16x32_bf16 v[110:113], v[172:175], v[188:191], v[110:113]
	v_mfma_f32_16x16x32_bf16 v[106:109], v[164:167], v[188:191], v[106:109]
	v_mfma_f32_16x16x32_bf16 v[106:109], v[160:163], v[184:187], v[106:109]
	v_mfma_f32_16x16x32_bf16 v[114:117], v[160:163], v[192:195], v[114:117]
	v_mfma_f32_16x16x32_bf16 v[114:117], v[164:167], v[196:199], v[114:117]
	v_mfma_f32_16x16x32_bf16 v[118:121], v[172:175], v[196:199], v[118:121]
	v_mfma_f32_16x16x32_bf16 v[118:121], v[168:171], v[192:195], v[118:121]
	v_mfma_f32_16x16x32_bf16 v[126:129], v[168:171], v[200:203], v[126:129]
	v_mfma_f32_16x16x32_bf16 v[126:129], v[172:175], v[204:207], v[126:129]
	s_setprio 2
	s_barrier
	v_mfma_f32_16x16x32_bf16 v[122:125], v[164:167], v[204:207], v[122:125]
	v_mfma_f32_16x16x32_bf16 v[122:125], v[160:163], v[200:203], v[122:125]
	s_setprio 0
	s_add_i32 s43, 0, 0x18000
	v_add_u32_e32 v135, s43, v140
	s_add_i32 s60, 0, 0x1c000
	ds_read_b128 v[142:145], v135
	ds_read_b128 v[148:151], v135 offset:1024
	ds_read_b128 v[152:155], v135 offset:2048
	ds_read_b128 v[156:159], v135 offset:3072
	v_add_u32_e32 v135, s60, v140
	ds_read_b128 v[160:163], v135
	ds_read_b128 v[164:167], v135 offset:1024
	ds_read_b128 v[168:171], v135 offset:2048
	ds_read_b128 v[172:175], v135 offset:3072
	s_add_u32 s38, s38, 0x400000
	s_addc_u32 s39, s39, 0
	s_mov_b32 m0, s45
	ds_read_b128 v[176:179], v141 offset:32768
	ds_read_b128 v[180:183], v141 offset:33792
	ds_read_b128 v[184:187], v141 offset:34816
	ds_read_b128 v[188:191], v141 offset:35840
	ds_read_b128 v[192:195], v141 offset:36864
	ds_read_b128 v[196:199], v141 offset:37888
	ds_read_b128 v[200:203], v141 offset:38912
	ds_read_b128 v[204:207], v141 offset:39936
	global_load_lds_dwordx4 v130, s[38:39]
	s_mov_b32 m0, s46
	s_nop 0
	global_load_lds_dwordx4 v132, s[38:39]
	s_waitcnt vmcnt(8)
	s_waitcnt lgkmcnt(0)
	s_barrier
	s_setprio 1
	v_mfma_f32_16x16x32_bf16 v[2:5], v[142:145], v[176:179], v[2:5]
	v_mfma_f32_16x16x32_bf16 v[2:5], v[148:151], v[180:183], v[2:5]
	v_mfma_f32_16x16x32_bf16 v[6:9], v[156:159], v[180:183], v[6:9]
	v_mfma_f32_16x16x32_bf16 v[6:9], v[152:155], v[176:179], v[6:9]
	v_mfma_f32_16x16x32_bf16 v[14:17], v[152:155], v[184:187], v[14:17]
	v_mfma_f32_16x16x32_bf16 v[14:17], v[156:159], v[188:191], v[14:17]
	v_mfma_f32_16x16x32_bf16 v[10:13], v[148:151], v[188:191], v[10:13]
	v_mfma_f32_16x16x32_bf16 v[10:13], v[142:145], v[184:187], v[10:13]
	v_mfma_f32_16x16x32_bf16 v[18:21], v[142:145], v[192:195], v[18:21]
	v_mfma_f32_16x16x32_bf16 v[18:21], v[148:151], v[196:199], v[18:21]
	v_mfma_f32_16x16x32_bf16 v[22:25], v[156:159], v[196:199], v[22:25]
	v_mfma_f32_16x16x32_bf16 v[22:25], v[152:155], v[192:195], v[22:25]
	v_mfma_f32_16x16x32_bf16 v[30:33], v[152:155], v[200:203], v[30:33]
	v_mfma_f32_16x16x32_bf16 v[30:33], v[156:159], v[204:207], v[30:33]
	v_mfma_f32_16x16x32_bf16 v[26:29], v[148:151], v[204:207], v[26:29]
	v_mfma_f32_16x16x32_bf16 v[26:29], v[142:145], v[200:203], v[26:29]
	s_setprio 0
	s_setprio 1
	v_mfma_f32_16x16x32_bf16 v[34:37], v[160:163], v[176:179], v[34:37]
	v_mfma_f32_16x16x32_bf16 v[34:37], v[164:167], v[180:183], v[34:37]
	v_mfma_f32_16x16x32_bf16 v[38:41], v[172:175], v[180:183], v[38:41]
	v_mfma_f32_16x16x32_bf16 v[38:41], v[168:171], v[176:179], v[38:41]
	v_mfma_f32_16x16x32_bf16 v[46:49], v[168:171], v[184:187], v[46:49]
	v_mfma_f32_16x16x32_bf16 v[46:49], v[172:175], v[188:191], v[46:49]
	v_mfma_f32_16x16x32_bf16 v[42:45], v[164:167], v[188:191], v[42:45]
	v_mfma_f32_16x16x32_bf16 v[42:45], v[160:163], v[184:187], v[42:45]
	v_mfma_f32_16x16x32_bf16 v[50:53], v[160:163], v[192:195], v[50:53]
	v_mfma_f32_16x16x32_bf16 v[50:53], v[164:167], v[196:199], v[50:53]
	v_mfma_f32_16x16x32_bf16 v[54:57], v[172:175], v[196:199], v[54:57]
	v_mfma_f32_16x16x32_bf16 v[54:57], v[168:171], v[192:195], v[54:57]
	v_mfma_f32_16x16x32_bf16 v[62:65], v[168:171], v[200:203], v[62:65]
	v_mfma_f32_16x16x32_bf16 v[62:65], v[172:175], v[204:207], v[62:65]
	s_setprio 2
	s_barrier
	v_mfma_f32_16x16x32_bf16 v[58:61], v[164:167], v[204:207], v[58:61]
	v_mfma_f32_16x16x32_bf16 v[58:61], v[160:163], v[200:203], v[58:61]
	s_setprio 0
	s_add_i32 s38, s43, s21
	v_lshl_add_u64 v[138:139], v[138:139], 0, s[8:9]
	s_mov_b32 m0, s38
	ds_read_b128 v[176:179], v141 offset:49152
	ds_read_b128 v[180:183], v141 offset:50176
	ds_read_b128 v[184:187], v141 offset:51200
	ds_read_b128 v[188:191], v141 offset:52224
	ds_read_b128 v[192:195], v141 offset:53248
	ds_read_b128 v[196:199], v141 offset:54272
	ds_read_b128 v[200:203], v141 offset:55296
	ds_read_b128 v[204:207], v141 offset:56320
	global_load_lds_dwordx4 v[138:139], off
	s_add_i32 m0, s38, 0x2000
	s_add_u32 s36, s36, 0x80080
	v_lshl_add_u64 v[138:139], v[208:209], 0, s[8:9]
	s_addc_u32 s37, s37, 0
	s_add_i32 s38, s60, s21
	global_load_lds_dwordx4 v[138:139], off
	s_mov_b32 m0, s38
	v_lshl_add_u64 v[138:139], v[210:211], 0, s[8:9]
	global_load_lds_dwordx4 v136, s[36:37]
	s_add_i32 m0, s38, 0x2000
	s_nop 0
	global_load_lds_dwordx4 v134, s[36:37]
	s_mov_b32 m0, s50
	s_nop 0
	global_load_lds_dwordx4 v[138:139], off
	v_lshl_add_u64 v[138:139], v[212:213], 0, s[8:9]
	s_mov_b32 m0, s51
	s_nop 0
	global_load_lds_dwordx4 v[138:139], off
	s_waitcnt vmcnt(8)
	s_waitcnt lgkmcnt(0)
	s_barrier
	s_setprio 1
	v_mfma_f32_16x16x32_bf16 v[66:69], v[142:145], v[176:179], v[66:69]
	v_mfma_f32_16x16x32_bf16 v[66:69], v[148:151], v[180:183], v[66:69]
	v_mfma_f32_16x16x32_bf16 v[70:73], v[156:159], v[180:183], v[70:73]
	v_mfma_f32_16x16x32_bf16 v[70:73], v[152:155], v[176:179], v[70:73]
	v_mfma_f32_16x16x32_bf16 v[78:81], v[152:155], v[184:187], v[78:81]
	v_mfma_f32_16x16x32_bf16 v[78:81], v[156:159], v[188:191], v[78:81]
	v_mfma_f32_16x16x32_bf16 v[74:77], v[148:151], v[188:191], v[74:77]
	v_mfma_f32_16x16x32_bf16 v[74:77], v[142:145], v[184:187], v[74:77]
	v_mfma_f32_16x16x32_bf16 v[82:85], v[142:145], v[192:195], v[82:85]
	v_mfma_f32_16x16x32_bf16 v[82:85], v[148:151], v[196:199], v[82:85]
	v_mfma_f32_16x16x32_bf16 v[86:89], v[156:159], v[196:199], v[86:89]
	v_mfma_f32_16x16x32_bf16 v[86:89], v[152:155], v[192:195], v[86:89]
	v_mfma_f32_16x16x32_bf16 v[94:97], v[152:155], v[200:203], v[94:97]
	v_mfma_f32_16x16x32_bf16 v[94:97], v[156:159], v[204:207], v[94:97]
	v_mfma_f32_16x16x32_bf16 v[90:93], v[148:151], v[204:207], v[90:93]
	v_mfma_f32_16x16x32_bf16 v[90:93], v[142:145], v[200:203], v[90:93]
	s_setprio 0
	s_setprio 1
	v_mfma_f32_16x16x32_bf16 v[98:101], v[160:163], v[176:179], v[98:101]
	v_mfma_f32_16x16x32_bf16 v[98:101], v[164:167], v[180:183], v[98:101]
	v_mfma_f32_16x16x32_bf16 v[102:105], v[172:175], v[180:183], v[102:105]
	v_mfma_f32_16x16x32_bf16 v[102:105], v[168:171], v[176:179], v[102:105]
	v_mfma_f32_16x16x32_bf16 v[110:113], v[168:171], v[184:187], v[110:113]
	v_mfma_f32_16x16x32_bf16 v[110:113], v[172:175], v[188:191], v[110:113]
	v_mfma_f32_16x16x32_bf16 v[106:109], v[164:167], v[188:191], v[106:109]
	v_mfma_f32_16x16x32_bf16 v[106:109], v[160:163], v[184:187], v[106:109]
	v_mfma_f32_16x16x32_bf16 v[114:117], v[160:163], v[192:195], v[114:117]
	v_mfma_f32_16x16x32_bf16 v[114:117], v[164:167], v[196:199], v[114:117]
	v_mfma_f32_16x16x32_bf16 v[118:121], v[172:175], v[196:199], v[118:121]
	v_mfma_f32_16x16x32_bf16 v[118:121], v[168:171], v[192:195], v[118:121]
	v_mfma_f32_16x16x32_bf16 v[126:129], v[168:171], v[200:203], v[126:129]
	v_mfma_f32_16x16x32_bf16 v[126:129], v[172:175], v[204:207], v[126:129]
	s_setprio 2
	s_barrier
	v_mfma_f32_16x16x32_bf16 v[122:125], v[164:167], v[204:207], v[122:125]
	v_mfma_f32_16x16x32_bf16 v[122:125], v[160:163], v[200:203], v[122:125]
	s_setprio 0
	s_add_i32 s42, s42, 2
	s_add_u32 s34, s34, 0x100
	s_addc_u32 s35, s35, 0
	s_add_u32 s40, s40, 0x100
	s_addc_u32 s41, s41, 0
	s_cmp_gt_u32 s42, 5
	s_cbranch_scc0 .LBB0_466
	s_and_b64 vcc, exec, s[10:11]
	s_cbranch_vccz .LBB0_469
	s_barrier

.LBB0_495:
	v_add_u32_e32 v14, s58, v140
	v_add_u32_e32 v30, s59, v140
	ds_read_b128 v[2:5], v14
	ds_read_b128 v[6:9], v14 offset:1024
	ds_read_b128 v[10:13], v14 offset:2048
	ds_read_b128 v[14:17], v14 offset:3072
	ds_read_b128 v[18:21], v30
	ds_read_b128 v[22:25], v30 offset:1024
	ds_read_b128 v[26:29], v30 offset:2048
	ds_read_b128 v[30:33], v30 offset:3072
	v_add_u32_e32 v141, 0, v1
	ds_read_b128 v[34:37], v141
	ds_read_b128 v[38:41], v141 offset:1024
	ds_read_b128 v[42:45], v141 offset:2048
	ds_read_b128 v[46:49], v141 offset:3072
	ds_read_b128 v[50:53], v141 offset:4096
	ds_read_b128 v[54:57], v141 offset:5120
	ds_read_b128 v[58:61], v141 offset:6144
	ds_read_b128 v[62:65], v141 offset:7168
	s_waitcnt vmcnt(8)
	s_waitcnt lgkmcnt(0)
	s_barrier
	s_setprio 1
	v_mfma_f32_16x16x32_bf16 v[66:69], v[2:5], v[34:37], 0
	v_mfma_f32_16x16x32_bf16 v[66:69], v[6:9], v[38:41], v[66:69]
	v_mfma_f32_16x16x32_bf16 v[70:73], v[10:13], v[34:37], 0
	v_mfma_f32_16x16x32_bf16 v[70:73], v[14:17], v[38:41], v[70:73]
	v_mfma_f32_16x16x32_bf16 v[78:81], v[10:13], v[42:45], 0
	v_mfma_f32_16x16x32_bf16 v[78:81], v[14:17], v[46:49], v[78:81]
	v_mfma_f32_16x16x32_bf16 v[74:77], v[2:5], v[42:45], 0
	v_mfma_f32_16x16x32_bf16 v[74:77], v[6:9], v[46:49], v[74:77]
	v_mfma_f32_16x16x32_bf16 v[82:85], v[2:5], v[50:53], 0
	v_mfma_f32_16x16x32_bf16 v[82:85], v[6:9], v[54:57], v[82:85]
	v_mfma_f32_16x16x32_bf16 v[86:89], v[10:13], v[50:53], 0
	v_mfma_f32_16x16x32_bf16 v[86:89], v[14:17], v[54:57], v[86:89]
	v_mfma_f32_16x16x32_bf16 v[94:97], v[10:13], v[58:61], 0
	v_mfma_f32_16x16x32_bf16 v[94:97], v[14:17], v[62:65], v[94:97]
	v_mfma_f32_16x16x32_bf16 v[90:93], v[2:5], v[58:61], 0
	v_mfma_f32_16x16x32_bf16 v[90:93], v[6:9], v[62:65], v[90:93]
	s_setprio 0
	s_setprio 1
	v_mfma_f32_16x16x32_bf16 v[98:101], v[18:21], v[34:37], 0
	v_mfma_f32_16x16x32_bf16 v[34:37], v[26:29], v[34:37], 0
	v_mfma_f32_16x16x32_bf16 v[102:105], v[18:21], v[42:45], 0
	v_mfma_f32_16x16x32_bf16 v[42:45], v[26:29], v[42:45], 0
	v_mfma_f32_16x16x32_bf16 v[106:109], v[18:21], v[50:53], 0
	v_mfma_f32_16x16x32_bf16 v[50:53], v[26:29], v[50:53], 0
	v_mfma_f32_16x16x32_bf16 v[110:113], v[18:21], v[58:61], 0
	v_mfma_f32_16x16x32_bf16 v[58:61], v[26:29], v[58:61], 0
	v_mfma_f32_16x16x32_bf16 v[98:101], v[22:25], v[38:41], v[98:101]
	v_mfma_f32_16x16x32_bf16 v[38:41], v[30:33], v[38:41], v[34:37]
	v_mfma_f32_16x16x32_bf16 v[102:105], v[22:25], v[46:49], v[102:105]
	v_mfma_f32_16x16x32_bf16 v[46:49], v[30:33], v[46:49], v[42:45]
	v_mfma_f32_16x16x32_bf16 v[106:109], v[22:25], v[54:57], v[106:109]
	v_mfma_f32_16x16x32_bf16 v[54:57], v[30:33], v[54:57], v[50:53]
	s_setprio 2
	s_barrier
	v_mfma_f32_16x16x32_bf16 v[110:113], v[22:25], v[62:65], v[110:113]
	v_mfma_f32_16x16x32_bf16 v[62:65], v[30:33], v[62:65], v[58:61]
	s_setprio 0
	v_lshl_add_u64 v[136:137], s[38:39], 0, v[130:131]
	s_add_i32 s62, s58, s46
	v_mov_b32_e32 v135, v131
	v_lshl_add_u64 v[142:143], v[136:137], 0, s[10:11]
	s_mov_b32 m0, s62
	v_lshl_add_u64 v[244:245], s[38:39], 0, v[134:135]
	ds_read_b128 v[34:37], v141 offset:16384
	ds_read_b128 v[42:45], v141 offset:17408
	ds_read_b128 v[50:53], v141 offset:18432
	ds_read_b128 v[58:61], v141 offset:19456
	ds_read_b128 v[114:117], v141 offset:20480
	ds_read_b128 v[118:121], v141 offset:21504
	ds_read_b128 v[122:125], v141 offset:22528
	ds_read_b128 v[126:129], v141 offset:23552
	global_load_lds_dwordx4 v[142:143], off
	v_lshl_add_u64 v[142:143], v[244:245], 0, s[10:11]
	s_add_i32 m0, s62, 0x2000
	s_add_i32 s62, s59, s46
	global_load_lds_dwordx4 v[142:143], off
	s_mov_b32 m0, s62
	v_mov_b32_e32 v139, v131
	global_load_lds_dwordx4 v130, s[40:41]
	s_add_i32 m0, s62, 0x2000
	v_lshl_add_u64 v[246:247], s[36:37], 0, v[138:139]
	v_mov_b32_e32 v133, v131
	global_load_lds_dwordx4 v134, s[40:41]
	v_lshl_add_u64 v[142:143], v[246:247], 0, s[10:11]
	s_mov_b32 m0, s47
	v_lshl_add_u64 v[248:249], s[36:37], 0, v[132:133]
	global_load_lds_dwordx4 v[142:143], off
	v_lshl_add_u64 v[142:143], v[248:249], 0, s[10:11]
	s_mov_b32 m0, s48
	s_nop 0
	global_load_lds_dwordx4 v[142:143], off
	s_waitcnt vmcnt(8)
	s_waitcnt lgkmcnt(0)
	s_barrier
	s_setprio 1
	v_mfma_f32_16x16x32_bf16 v[142:145], v[2:5], v[34:37], 0
	v_mfma_f32_16x16x32_bf16 v[148:151], v[10:13], v[34:37], 0
	v_mfma_f32_16x16x32_bf16 v[152:155], v[2:5], v[50:53], 0
	v_mfma_f32_16x16x32_bf16 v[156:159], v[10:13], v[50:53], 0
	v_mfma_f32_16x16x32_bf16 v[160:163], v[2:5], v[114:117], 0
	v_mfma_f32_16x16x32_bf16 v[164:167], v[10:13], v[114:117], 0
	v_mfma_f32_16x16x32_bf16 v[2:5], v[2:5], v[122:125], 0
	v_mfma_f32_16x16x32_bf16 v[10:13], v[10:13], v[122:125], 0
	v_mfma_f32_16x16x32_bf16 v[142:145], v[6:9], v[42:45], v[142:145]
	v_mfma_f32_16x16x32_bf16 v[148:151], v[14:17], v[42:45], v[148:151]
	v_mfma_f32_16x16x32_bf16 v[152:155], v[6:9], v[58:61], v[152:155]
	v_mfma_f32_16x16x32_bf16 v[156:159], v[14:17], v[58:61], v[156:159]
	v_mfma_f32_16x16x32_bf16 v[160:163], v[6:9], v[118:121], v[160:163]
	v_mfma_f32_16x16x32_bf16 v[164:167], v[14:17], v[118:121], v[164:167]
	v_mfma_f32_16x16x32_bf16 v[168:171], v[6:9], v[126:129], v[2:5]
	v_mfma_f32_16x16x32_bf16 v[172:175], v[14:17], v[126:129], v[10:13]
	s_setprio 0
	s_setprio 1
	v_mfma_f32_16x16x32_bf16 v[2:5], v[18:21], v[34:37], 0
	v_mfma_f32_16x16x32_bf16 v[6:9], v[26:29], v[34:37], 0
	v_mfma_f32_16x16x32_bf16 v[10:13], v[18:21], v[50:53], 0
	v_mfma_f32_16x16x32_bf16 v[14:17], v[26:29], v[50:53], 0
	v_mfma_f32_16x16x32_bf16 v[34:37], v[18:21], v[114:117], 0
	v_mfma_f32_16x16x32_bf16 v[50:53], v[26:29], v[114:117], 0
	v_mfma_f32_16x16x32_bf16 v[18:21], v[18:21], v[122:125], 0
	v_mfma_f32_16x16x32_bf16 v[26:29], v[26:29], v[122:125], 0
	v_mfma_f32_16x16x32_bf16 v[114:117], v[22:25], v[42:45], v[2:5]
	v_mfma_f32_16x16x32_bf16 v[122:125], v[30:33], v[42:45], v[6:9]
	v_mfma_f32_16x16x32_bf16 v[184:187], v[22:25], v[118:121], v[34:37]
	v_mfma_f32_16x16x32_bf16 v[118:121], v[30:33], v[118:121], v[50:53]
	v_mfma_f32_16x16x32_bf16 v[188:191], v[22:25], v[126:129], v[18:21]
	v_mfma_f32_16x16x32_bf16 v[126:129], v[30:33], v[126:129], v[26:29]
	s_setprio 2
	s_barrier
	v_mfma_f32_16x16x32_bf16 v[176:179], v[22:25], v[58:61], v[10:13]
	v_mfma_f32_16x16x32_bf16 v[180:183], v[30:33], v[58:61], v[14:17]
	s_setprio 0
	s_add_i32 s62, 0, 0x18000
	v_add_u32_e32 v2, s62, v140
	s_add_i32 s63, 0, 0x1c000
	ds_read_b128 v[192:195], v2
	ds_read_b128 v[196:199], v2 offset:1024
	ds_read_b128 v[200:203], v2 offset:2048
	ds_read_b128 v[204:207], v2 offset:3072
	v_add_u32_e32 v2, s63, v140
	ds_read_b128 v[208:211], v2
	ds_read_b128 v[212:215], v2 offset:1024
	ds_read_b128 v[216:219], v2 offset:2048
	ds_read_b128 v[220:223], v2 offset:3072
	s_mov_b32 m0, s49
	ds_read_b128 v[42:45], v141 offset:32768
	ds_read_b128 v[50:53], v141 offset:33792
	ds_read_b128 v[58:61], v141 offset:34816
	ds_read_b128 v[224:227], v141 offset:35840
	ds_read_b128 v[228:231], v141 offset:36864
	ds_read_b128 v[232:235], v141 offset:37888
	ds_read_b128 v[236:239], v141 offset:38912
	ds_read_b128 v[240:243], v141 offset:39936
	global_load_lds_dwordx4 v138, s[42:43]
	s_mov_b32 m0, s50
	s_nop 0
	global_load_lds_dwordx4 v132, s[42:43]
	s_waitcnt vmcnt(8)
	s_waitcnt lgkmcnt(0)
	s_barrier
	s_setprio 1
	v_mfma_f32_16x16x32_bf16 v[2:5], v[192:195], v[42:45], v[66:69]
	v_mfma_f32_16x16x32_bf16 v[6:9], v[200:203], v[42:45], v[70:73]
	v_mfma_f32_16x16x32_bf16 v[10:13], v[192:195], v[58:61], v[74:77]
	v_mfma_f32_16x16x32_bf16 v[14:17], v[200:203], v[58:61], v[78:81]
	v_mfma_f32_16x16x32_bf16 v[18:21], v[192:195], v[228:231], v[82:85]
	v_mfma_f32_16x16x32_bf16 v[22:25], v[200:203], v[228:231], v[86:89]
	v_mfma_f32_16x16x32_bf16 v[26:29], v[192:195], v[236:239], v[90:93]
	v_mfma_f32_16x16x32_bf16 v[30:33], v[200:203], v[236:239], v[94:97]
	v_mfma_f32_16x16x32_bf16 v[2:5], v[196:199], v[50:53], v[2:5]
	v_mfma_f32_16x16x32_bf16 v[6:9], v[204:207], v[50:53], v[6:9]
	v_mfma_f32_16x16x32_bf16 v[10:13], v[196:199], v[224:227], v[10:13]
	v_mfma_f32_16x16x32_bf16 v[14:17], v[204:207], v[224:227], v[14:17]
	v_mfma_f32_16x16x32_bf16 v[18:21], v[196:199], v[232:235], v[18:21]
	v_mfma_f32_16x16x32_bf16 v[22:25], v[204:207], v[232:235], v[22:25]
	v_mfma_f32_16x16x32_bf16 v[26:29], v[196:199], v[240:243], v[26:29]
	v_mfma_f32_16x16x32_bf16 v[30:33], v[204:207], v[240:243], v[30:33]
	s_setprio 0
	s_setprio 1
	v_mfma_f32_16x16x32_bf16 v[34:37], v[208:211], v[42:45], v[98:101]
	v_mfma_f32_16x16x32_bf16 v[38:41], v[216:219], v[42:45], v[38:41]
	v_mfma_f32_16x16x32_bf16 v[34:37], v[212:215], v[50:53], v[34:37]
	v_mfma_f32_16x16x32_bf16 v[38:41], v[220:223], v[50:53], v[38:41]
	v_mfma_f32_16x16x32_bf16 v[42:45], v[208:211], v[58:61], v[102:105]
	v_mfma_f32_16x16x32_bf16 v[46:49], v[216:219], v[58:61], v[46:49]
	v_mfma_f32_16x16x32_bf16 v[50:53], v[208:211], v[228:231], v[106:109]
	v_mfma_f32_16x16x32_bf16 v[54:57], v[216:219], v[228:231], v[54:57]
	v_mfma_f32_16x16x32_bf16 v[58:61], v[208:211], v[236:239], v[110:113]
	v_mfma_f32_16x16x32_bf16 v[62:65], v[216:219], v[236:239], v[62:65]
	v_mfma_f32_16x16x32_bf16 v[42:45], v[212:215], v[224:227], v[42:45]
	v_mfma_f32_16x16x32_bf16 v[46:49], v[220:223], v[224:227], v[46:49]
	v_mfma_f32_16x16x32_bf16 v[50:53], v[212:215], v[232:235], v[50:53]
	v_mfma_f32_16x16x32_bf16 v[54:57], v[220:223], v[232:235], v[54:57]
	s_setprio 2
	s_barrier
	v_mfma_f32_16x16x32_bf16 v[58:61], v[212:215], v[240:243], v[58:61]
	v_mfma_f32_16x16x32_bf16 v[62:65], v[220:223], v[240:243], v[62:65]
	s_setprio 0
	s_add_i32 s62, s62, s46
	v_lshl_add_u64 v[66:67], v[136:137], 0, s[12:13]
	s_mov_b32 m0, s62
	ds_read_b128 v[102:105], v141 offset:49152
	ds_read_b128 v[106:109], v141 offset:50176
	ds_read_b128 v[110:113], v141 offset:51200
	ds_read_b128 v[224:227], v141 offset:52224
	ds_read_b128 v[228:231], v141 offset:53248
	ds_read_b128 v[232:235], v141 offset:54272
	ds_read_b128 v[236:239], v141 offset:55296
	ds_read_b128 v[240:243], v141 offset:56320
	global_load_lds_dwordx4 v[66:67], off
	v_lshl_add_u64 v[66:67], v[244:245], 0, s[12:13]
	s_add_i32 m0, s62, 0x2000
	s_add_i32 s62, s63, s46
	global_load_lds_dwordx4 v[66:67], off
	s_mov_b32 m0, s62
	v_lshl_add_u64 v[66:67], v[246:247], 0, s[12:13]
	global_load_lds_dwordx4 v130, s[44:45]
	s_add_i32 m0, s62, 0x2000
	s_nop 0
	global_load_lds_dwordx4 v134, s[44:45]
	s_mov_b32 m0, s54
	s_nop 0
	global_load_lds_dwordx4 v[66:67], off
	v_lshl_add_u64 v[66:67], v[248:249], 0, s[12:13]
	s_mov_b32 m0, s55
	s_nop 0
	global_load_lds_dwordx4 v[66:67], off
	s_waitcnt vmcnt(8)
	s_waitcnt lgkmcnt(0)
	s_barrier
	s_setprio 1
	v_mfma_f32_16x16x32_bf16 v[66:69], v[192:195], v[102:105], v[142:145]
	v_mfma_f32_16x16x32_bf16 v[70:73], v[200:203], v[102:105], v[148:151]
	v_mfma_f32_16x16x32_bf16 v[74:77], v[192:195], v[110:113], v[152:155]
	v_mfma_f32_16x16x32_bf16 v[78:81], v[200:203], v[110:113], v[156:159]
	v_mfma_f32_16x16x32_bf16 v[82:85], v[192:195], v[228:231], v[160:163]
	v_mfma_f32_16x16x32_bf16 v[86:89], v[200:203], v[228:231], v[164:167]
	v_mfma_f32_16x16x32_bf16 v[90:93], v[192:195], v[236:239], v[168:171]
	v_mfma_f32_16x16x32_bf16 v[94:97], v[200:203], v[236:239], v[172:175]
	v_mfma_f32_16x16x32_bf16 v[66:69], v[196:199], v[106:109], v[66:69]
	v_mfma_f32_16x16x32_bf16 v[70:73], v[204:207], v[106:109], v[70:73]
	v_mfma_f32_16x16x32_bf16 v[74:77], v[196:199], v[224:227], v[74:77]
	v_mfma_f32_16x16x32_bf16 v[78:81], v[204:207], v[224:227], v[78:81]
	v_mfma_f32_16x16x32_bf16 v[82:85], v[196:199], v[232:235], v[82:85]
	v_mfma_f32_16x16x32_bf16 v[86:89], v[204:207], v[232:235], v[86:89]
	v_mfma_f32_16x16x32_bf16 v[90:93], v[196:199], v[240:243], v[90:93]
	v_mfma_f32_16x16x32_bf16 v[94:97], v[204:207], v[240:243], v[94:97]
	s_setprio 0
	s_setprio 1
	v_mfma_f32_16x16x32_bf16 v[98:101], v[208:211], v[102:105], v[114:117]
	v_mfma_f32_16x16x32_bf16 v[102:105], v[216:219], v[102:105], v[122:125]
	v_mfma_f32_16x16x32_bf16 v[98:101], v[212:215], v[106:109], v[98:101]
	v_mfma_f32_16x16x32_bf16 v[102:105], v[220:223], v[106:109], v[102:105]
	v_mfma_f32_16x16x32_bf16 v[106:109], v[208:211], v[110:113], v[176:179]
	v_mfma_f32_16x16x32_bf16 v[110:113], v[216:219], v[110:113], v[180:183]
	v_mfma_f32_16x16x32_bf16 v[114:117], v[208:211], v[228:231], v[184:187]
	v_mfma_f32_16x16x32_bf16 v[118:121], v[216:219], v[228:231], v[118:121]
	v_mfma_f32_16x16x32_bf16 v[122:125], v[208:211], v[236:239], v[188:191]
	v_mfma_f32_16x16x32_bf16 v[126:129], v[216:219], v[236:239], v[126:129]
	v_mfma_f32_16x16x32_bf16 v[106:109], v[212:215], v[224:227], v[106:109]
	v_mfma_f32_16x16x32_bf16 v[110:113], v[220:223], v[224:227], v[110:113]
	v_mfma_f32_16x16x32_bf16 v[114:117], v[212:215], v[232:235], v[114:117]
	v_mfma_f32_16x16x32_bf16 v[118:121], v[220:223], v[232:235], v[118:121]
	s_setprio 2
	s_barrier
	v_mfma_f32_16x16x32_bf16 v[122:125], v[212:215], v[240:243], v[122:125]
	v_mfma_f32_16x16x32_bf16 v[126:129], v[220:223], v[240:243], v[126:129]
	s_setprio 0
	s_add_i32 s27, s27, 2
	s_cmp_ge_i32 s27, s15
	s_cbranch_scc0 .LBB0_495
	v_mov_b32_e32 v136, v130
	s_branch .LBB0_498

.LBB0_499:
	v_add_u32_e32 v133, s58, v140
	ds_read_b128 v[142:145], v133
	ds_read_b128 v[148:151], v133 offset:1024
	ds_read_b128 v[152:155], v133 offset:2048
	ds_read_b128 v[156:159], v133 offset:3072
	v_add_u32_e32 v133, s59, v140
	ds_read_b128 v[160:163], v133
	ds_read_b128 v[164:167], v133 offset:1024
	ds_read_b128 v[168:171], v133 offset:2048
	ds_read_b128 v[172:175], v133 offset:3072
	s_add_u32 s38, s36, 0xfff80080
	s_addc_u32 s39, s37, -1
	s_cmp_eq_u32 s42, 4
	s_cselect_b32 s41, s31, s39
	s_cselect_b32 s40, s30, s38
	s_cselect_b32 s39, s35, s27
	s_cselect_b32 s38, s34, s15
	s_mov_b32 m0, s56
	v_add_u32_e32 v141, 0, v1
	ds_read_b128 v[176:179], v141
	ds_read_b128 v[180:183], v141 offset:1024
	ds_read_b128 v[184:187], v141 offset:2048
	ds_read_b128 v[188:191], v141 offset:3072
	ds_read_b128 v[192:195], v141 offset:4096
	ds_read_b128 v[196:199], v141 offset:5120
	ds_read_b128 v[200:203], v141 offset:6144
	ds_read_b128 v[204:207], v141 offset:7168
	global_load_lds_dwordx4 v130, s[36:37]
	s_mov_b32 m0, s57
	v_mov_b32_e32 v133, v131
	global_load_lds_dwordx4 v132, s[36:37]
	s_waitcnt vmcnt(8)
	s_waitcnt lgkmcnt(0)
	s_barrier
	s_setprio 1
	v_mfma_f32_16x16x32_bf16 v[2:5], v[142:145], v[176:179], v[2:5]
	v_mfma_f32_16x16x32_bf16 v[2:5], v[148:151], v[180:183], v[2:5]
	v_mfma_f32_16x16x32_bf16 v[6:9], v[156:159], v[180:183], v[6:9]
	v_mfma_f32_16x16x32_bf16 v[6:9], v[152:155], v[176:179], v[6:9]
	v_mfma_f32_16x16x32_bf16 v[14:17], v[152:155], v[184:187], v[14:17]
	v_mfma_f32_16x16x32_bf16 v[14:17], v[156:159], v[188:191], v[14:17]
	v_mfma_f32_16x16x32_bf16 v[10:13], v[148:151], v[188:191], v[10:13]
	v_mfma_f32_16x16x32_bf16 v[10:13], v[142:145], v[184:187], v[10:13]
	v_mfma_f32_16x16x32_bf16 v[18:21], v[142:145], v[192:195], v[18:21]
	v_mfma_f32_16x16x32_bf16 v[18:21], v[148:151], v[196:199], v[18:21]
	v_mfma_f32_16x16x32_bf16 v[22:25], v[156:159], v[196:199], v[22:25]
	v_mfma_f32_16x16x32_bf16 v[22:25], v[152:155], v[192:195], v[22:25]
	v_mfma_f32_16x16x32_bf16 v[30:33], v[152:155], v[200:203], v[30:33]
	v_mfma_f32_16x16x32_bf16 v[30:33], v[156:159], v[204:207], v[30:33]
	v_mfma_f32_16x16x32_bf16 v[26:29], v[148:151], v[204:207], v[26:29]
	v_mfma_f32_16x16x32_bf16 v[26:29], v[142:145], v[200:203], v[26:29]
	s_setprio 0
	s_setprio 1
	v_mfma_f32_16x16x32_bf16 v[34:37], v[160:163], v[176:179], v[34:37]
	v_mfma_f32_16x16x32_bf16 v[34:37], v[164:167], v[180:183], v[34:37]
	v_mfma_f32_16x16x32_bf16 v[38:41], v[172:175], v[180:183], v[38:41]
	v_mfma_f32_16x16x32_bf16 v[38:41], v[168:171], v[176:179], v[38:41]
	v_mfma_f32_16x16x32_bf16 v[46:49], v[168:171], v[184:187], v[46:49]
	v_mfma_f32_16x16x32_bf16 v[46:49], v[172:175], v[188:191], v[46:49]
	v_mfma_f32_16x16x32_bf16 v[42:45], v[164:167], v[188:191], v[42:45]
	v_mfma_f32_16x16x32_bf16 v[42:45], v[160:163], v[184:187], v[42:45]
	v_mfma_f32_16x16x32_bf16 v[50:53], v[160:163], v[192:195], v[50:53]
	v_mfma_f32_16x16x32_bf16 v[50:53], v[164:167], v[196:199], v[50:53]
	v_mfma_f32_16x16x32_bf16 v[54:57], v[172:175], v[196:199], v[54:57]
	v_mfma_f32_16x16x32_bf16 v[54:57], v[168:171], v[192:195], v[54:57]
	v_mfma_f32_16x16x32_bf16 v[62:65], v[168:171], v[200:203], v[62:65]
	v_mfma_f32_16x16x32_bf16 v[62:65], v[172:175], v[204:207], v[62:65]
	s_setprio 2
	s_barrier
	v_mfma_f32_16x16x32_bf16 v[58:61], v[164:167], v[204:207], v[58:61]
	v_mfma_f32_16x16x32_bf16 v[58:61], v[160:163], v[200:203], v[58:61]
	s_setprio 0
	s_add_i32 s43, s58, s46
	s_mov_b32 m0, s43
	ds_read_b128 v[176:179], v141 offset:16384
	ds_read_b128 v[180:183], v141 offset:17408
	ds_read_b128 v[184:187], v141 offset:18432
	ds_read_b128 v[188:191], v141 offset:19456
	ds_read_b128 v[192:195], v141 offset:20480
	ds_read_b128 v[196:199], v141 offset:21504
	ds_read_b128 v[200:203], v141 offset:22528
	ds_read_b128 v[204:207], v141 offset:23552
	global_load_lds_dwordx4 v136, s[38:39]
	s_add_i32 m0, s43, 0x2000
	s_add_u32 s44, s38, 0x400000
	s_addc_u32 s45, s39, 0
	s_add_i32 s43, s59, s46
	global_load_lds_dwordx4 v134, s[38:39]
	s_mov_b32 m0, s43
	v_mov_b32_e32 v137, v131
	global_load_lds_dwordx4 v136, s[44:45]
	s_add_i32 m0, s43, 0x2000
	v_mov_b32_e32 v135, v131
	global_load_lds_dwordx4 v134, s[44:45]
	s_mov_b32 m0, s47
	v_lshl_add_u64 v[138:139], s[38:39], 0, v[136:137]
	global_load_lds_dwordx4 v130, s[40:41]
	s_mov_b32 m0, s48
	v_lshl_add_u64 v[208:209], s[38:39], 0, v[134:135]
	global_load_lds_dwordx4 v132, s[40:41]
	s_waitcnt vmcnt(8)
	s_waitcnt lgkmcnt(0)
	v_lshl_add_u64 v[210:211], s[40:41], 0, v[130:131]
	v_lshl_add_u64 v[212:213], s[40:41], 0, v[132:133]
	s_barrier
	s_setprio 1
	v_mfma_f32_16x16x32_bf16 v[66:69], v[142:145], v[176:179], v[66:69]
	v_mfma_f32_16x16x32_bf16 v[66:69], v[148:151], v[180:183], v[66:69]
	v_mfma_f32_16x16x32_bf16 v[70:73], v[156:159], v[180:183], v[70:73]
	v_mfma_f32_16x16x32_bf16 v[70:73], v[152:155], v[176:179], v[70:73]
	v_mfma_f32_16x16x32_bf16 v[78:81], v[152:155], v[184:187], v[78:81]
	v_mfma_f32_16x16x32_bf16 v[78:81], v[156:159], v[188:191], v[78:81]
	v_mfma_f32_16x16x32_bf16 v[74:77], v[148:151], v[188:191], v[74:77]
	v_mfma_f32_16x16x32_bf16 v[74:77], v[142:145], v[184:187], v[74:77]
	v_mfma_f32_16x16x32_bf16 v[82:85], v[142:145], v[192:195], v[82:85]
	v_mfma_f32_16x16x32_bf16 v[82:85], v[148:151], v[196:199], v[82:85]
	v_mfma_f32_16x16x32_bf16 v[86:89], v[156:159], v[196:199], v[86:89]
	v_mfma_f32_16x16x32_bf16 v[86:89], v[152:155], v[192:195], v[86:89]
	v_mfma_f32_16x16x32_bf16 v[94:97], v[152:155], v[200:203], v[94:97]
	v_mfma_f32_16x16x32_bf16 v[94:97], v[156:159], v[204:207], v[94:97]
	v_mfma_f32_16x16x32_bf16 v[90:93], v[148:151], v[204:207], v[90:93]
	v_mfma_f32_16x16x32_bf16 v[90:93], v[142:145], v[200:203], v[90:93]
	s_setprio 0
	s_setprio 1
	v_mfma_f32_16x16x32_bf16 v[98:101], v[160:163], v[176:179], v[98:101]
	v_mfma_f32_16x16x32_bf16 v[98:101], v[164:167], v[180:183], v[98:101]
	v_mfma_f32_16x16x32_bf16 v[102:105], v[172:175], v[180:183], v[102:105]
	v_mfma_f32_16x16x32_bf16 v[102:105], v[168:171], v[176:179], v[102:105]
	v_mfma_f32_16x16x32_bf16 v[110:113], v[168:171], v[184:187], v[110:113]
	v_mfma_f32_16x16x32_bf16 v[110:113], v[172:175], v[188:191], v[110:113]
	v_mfma_f32_16x16x32_bf16 v[106:109], v[164:167], v[188:191], v[106:109]
	v_mfma_f32_16x16x32_bf16 v[106:109], v[160:163], v[184:187], v[106:109]
	v_mfma_f32_16x16x32_bf16 v[114:117], v[160:163], v[192:195], v[114:117]
	v_mfma_f32_16x16x32_bf16 v[114:117], v[164:167], v[196:199], v[114:117]
	v_mfma_f32_16x16x32_bf16 v[118:121], v[172:175], v[196:199], v[118:121]
	v_mfma_f32_16x16x32_bf16 v[118:121], v[168:171], v[192:195], v[118:121]
	v_mfma_f32_16x16x32_bf16 v[126:129], v[168:171], v[200:203], v[126:129]
	v_mfma_f32_16x16x32_bf16 v[126:129], v[172:175], v[204:207], v[126:129]
	s_setprio 2
	s_barrier
	v_mfma_f32_16x16x32_bf16 v[122:125], v[164:167], v[204:207], v[122:125]
	v_mfma_f32_16x16x32_bf16 v[122:125], v[160:163], v[200:203], v[122:125]
	s_setprio 0
	s_add_i32 s43, 0, 0x18000
	v_add_u32_e32 v135, s43, v140
	s_add_i32 s44, 0, 0x1c000
	ds_read_b128 v[142:145], v135
	ds_read_b128 v[148:151], v135 offset:1024
	ds_read_b128 v[152:155], v135 offset:2048
	ds_read_b128 v[156:159], v135 offset:3072
	v_add_u32_e32 v135, s44, v140
	ds_read_b128 v[160:163], v135
	ds_read_b128 v[164:167], v135 offset:1024
	ds_read_b128 v[168:171], v135 offset:2048
	ds_read_b128 v[172:175], v135 offset:3072
	s_add_u32 s40, s40, 0x80000
	s_addc_u32 s41, s41, 0
	s_mov_b32 m0, s49
	ds_read_b128 v[176:179], v141 offset:32768
	ds_read_b128 v[180:183], v141 offset:33792
	ds_read_b128 v[184:187], v141 offset:34816
	ds_read_b128 v[188:191], v141 offset:35840
	ds_read_b128 v[192:195], v141 offset:36864
	ds_read_b128 v[196:199], v141 offset:37888
	ds_read_b128 v[200:203], v141 offset:38912
	ds_read_b128 v[204:207], v141 offset:39936
	global_load_lds_dwordx4 v130, s[40:41]
	s_mov_b32 m0, s50
	s_nop 0
	global_load_lds_dwordx4 v132, s[40:41]
	s_waitcnt vmcnt(8)
	s_waitcnt lgkmcnt(0)
	s_barrier
	s_setprio 1
	v_mfma_f32_16x16x32_bf16 v[2:5], v[142:145], v[176:179], v[2:5]
	v_mfma_f32_16x16x32_bf16 v[2:5], v[148:151], v[180:183], v[2:5]
	v_mfma_f32_16x16x32_bf16 v[6:9], v[156:159], v[180:183], v[6:9]
	v_mfma_f32_16x16x32_bf16 v[6:9], v[152:155], v[176:179], v[6:9]
	v_mfma_f32_16x16x32_bf16 v[14:17], v[152:155], v[184:187], v[14:17]
	v_mfma_f32_16x16x32_bf16 v[14:17], v[156:159], v[188:191], v[14:17]
	v_mfma_f32_16x16x32_bf16 v[10:13], v[148:151], v[188:191], v[10:13]
	v_mfma_f32_16x16x32_bf16 v[10:13], v[142:145], v[184:187], v[10:13]
	v_mfma_f32_16x16x32_bf16 v[18:21], v[142:145], v[192:195], v[18:21]
	v_mfma_f32_16x16x32_bf16 v[18:21], v[148:151], v[196:199], v[18:21]
	v_mfma_f32_16x16x32_bf16 v[22:25], v[156:159], v[196:199], v[22:25]
	v_mfma_f32_16x16x32_bf16 v[22:25], v[152:155], v[192:195], v[22:25]
	v_mfma_f32_16x16x32_bf16 v[30:33], v[152:155], v[200:203], v[30:33]
	v_mfma_f32_16x16x32_bf16 v[30:33], v[156:159], v[204:207], v[30:33]
	v_mfma_f32_16x16x32_bf16 v[26:29], v[148:151], v[204:207], v[26:29]
	v_mfma_f32_16x16x32_bf16 v[26:29], v[142:145], v[200:203], v[26:29]
	s_setprio 0
	s_setprio 1
	v_mfma_f32_16x16x32_bf16 v[34:37], v[160:163], v[176:179], v[34:37]
	v_mfma_f32_16x16x32_bf16 v[34:37], v[164:167], v[180:183], v[34:37]
	v_mfma_f32_16x16x32_bf16 v[38:41], v[172:175], v[180:183], v[38:41]
	v_mfma_f32_16x16x32_bf16 v[38:41], v[168:171], v[176:179], v[38:41]
	v_mfma_f32_16x16x32_bf16 v[46:49], v[168:171], v[184:187], v[46:49]
	v_mfma_f32_16x16x32_bf16 v[46:49], v[172:175], v[188:191], v[46:49]
	v_mfma_f32_16x16x32_bf16 v[42:45], v[164:167], v[188:191], v[42:45]
	v_mfma_f32_16x16x32_bf16 v[42:45], v[160:163], v[184:187], v[42:45]
	v_mfma_f32_16x16x32_bf16 v[50:53], v[160:163], v[192:195], v[50:53]
	v_mfma_f32_16x16x32_bf16 v[50:53], v[164:167], v[196:199], v[50:53]
	v_mfma_f32_16x16x32_bf16 v[54:57], v[172:175], v[196:199], v[54:57]
	v_mfma_f32_16x16x32_bf16 v[54:57], v[168:171], v[192:195], v[54:57]
	v_mfma_f32_16x16x32_bf16 v[62:65], v[168:171], v[200:203], v[62:65]
	v_mfma_f32_16x16x32_bf16 v[62:65], v[172:175], v[204:207], v[62:65]
	s_setprio 2
	s_barrier
	v_mfma_f32_16x16x32_bf16 v[58:61], v[164:167], v[204:207], v[58:61]
	v_mfma_f32_16x16x32_bf16 v[58:61], v[160:163], v[200:203], v[58:61]
	s_setprio 0
	s_add_i32 s40, s43, s46
	v_lshl_add_u64 v[138:139], v[138:139], 0, s[6:7]
	s_mov_b32 m0, s40
	ds_read_b128 v[176:179], v141 offset:49152
	ds_read_b128 v[180:183], v141 offset:50176
	ds_read_b128 v[184:187], v141 offset:51200
	ds_read_b128 v[188:191], v141 offset:52224
	ds_read_b128 v[192:195], v141 offset:53248
	ds_read_b128 v[196:199], v141 offset:54272
	ds_read_b128 v[200:203], v141 offset:55296
	ds_read_b128 v[204:207], v141 offset:56320
	global_load_lds_dwordx4 v[138:139], off
	s_add_i32 m0, s40, 0x2000
	s_add_u32 s38, s38, 0x400080
	v_lshl_add_u64 v[138:139], v[208:209], 0, s[6:7]
	s_addc_u32 s39, s39, 0
	s_add_i32 s40, s44, s46
	global_load_lds_dwordx4 v[138:139], off
	s_mov_b32 m0, s40
	v_lshl_add_u64 v[138:139], v[210:211], 0, s[6:7]
	global_load_lds_dwordx4 v136, s[38:39]
	s_add_i32 m0, s40, 0x2000
	s_nop 0
	global_load_lds_dwordx4 v134, s[38:39]
	s_mov_b32 m0, s54
	s_nop 0
	global_load_lds_dwordx4 v[138:139], off
	v_lshl_add_u64 v[138:139], v[212:213], 0, s[6:7]
	s_mov_b32 m0, s55
	s_nop 0
	global_load_lds_dwordx4 v[138:139], off
	s_waitcnt vmcnt(8)
	s_waitcnt lgkmcnt(0)
	s_barrier
	s_setprio 1
	v_mfma_f32_16x16x32_bf16 v[66:69], v[142:145], v[176:179], v[66:69]
	v_mfma_f32_16x16x32_bf16 v[66:69], v[148:151], v[180:183], v[66:69]
	v_mfma_f32_16x16x32_bf16 v[70:73], v[156:159], v[180:183], v[70:73]
	v_mfma_f32_16x16x32_bf16 v[70:73], v[152:155], v[176:179], v[70:73]
	v_mfma_f32_16x16x32_bf16 v[78:81], v[152:155], v[184:187], v[78:81]
	v_mfma_f32_16x16x32_bf16 v[78:81], v[156:159], v[188:191], v[78:81]
	v_mfma_f32_16x16x32_bf16 v[74:77], v[148:151], v[188:191], v[74:77]
	v_mfma_f32_16x16x32_bf16 v[74:77], v[142:145], v[184:187], v[74:77]
	v_mfma_f32_16x16x32_bf16 v[82:85], v[142:145], v[192:195], v[82:85]
	v_mfma_f32_16x16x32_bf16 v[82:85], v[148:151], v[196:199], v[82:85]
	v_mfma_f32_16x16x32_bf16 v[86:89], v[156:159], v[196:199], v[86:89]
	v_mfma_f32_16x16x32_bf16 v[86:89], v[152:155], v[192:195], v[86:89]
	v_mfma_f32_16x16x32_bf16 v[94:97], v[152:155], v[200:203], v[94:97]
	v_mfma_f32_16x16x32_bf16 v[94:97], v[156:159], v[204:207], v[94:97]
	v_mfma_f32_16x16x32_bf16 v[90:93], v[148:151], v[204:207], v[90:93]
	v_mfma_f32_16x16x32_bf16 v[90:93], v[142:145], v[200:203], v[90:93]
	s_setprio 0
	s_setprio 1
	v_mfma_f32_16x16x32_bf16 v[98:101], v[160:163], v[176:179], v[98:101]
	v_mfma_f32_16x16x32_bf16 v[98:101], v[164:167], v[180:183], v[98:101]
	v_mfma_f32_16x16x32_bf16 v[102:105], v[172:175], v[180:183], v[102:105]
	v_mfma_f32_16x16x32_bf16 v[102:105], v[168:171], v[176:179], v[102:105]
	v_mfma_f32_16x16x32_bf16 v[110:113], v[168:171], v[184:187], v[110:113]
	v_mfma_f32_16x16x32_bf16 v[110:113], v[172:175], v[188:191], v[110:113]
	v_mfma_f32_16x16x32_bf16 v[106:109], v[164:167], v[188:191], v[106:109]
	v_mfma_f32_16x16x32_bf16 v[106:109], v[160:163], v[184:187], v[106:109]
	v_mfma_f32_16x16x32_bf16 v[114:117], v[160:163], v[192:195], v[114:117]
	v_mfma_f32_16x16x32_bf16 v[114:117], v[164:167], v[196:199], v[114:117]
	v_mfma_f32_16x16x32_bf16 v[118:121], v[172:175], v[196:199], v[118:121]
	v_mfma_f32_16x16x32_bf16 v[118:121], v[168:171], v[192:195], v[118:121]
	v_mfma_f32_16x16x32_bf16 v[126:129], v[168:171], v[200:203], v[126:129]
	v_mfma_f32_16x16x32_bf16 v[126:129], v[172:175], v[204:207], v[126:129]
	s_setprio 2
	s_barrier
	v_mfma_f32_16x16x32_bf16 v[122:125], v[164:167], v[204:207], v[122:125]
	v_mfma_f32_16x16x32_bf16 v[122:125], v[160:163], v[200:203], v[122:125]
	s_setprio 0
	s_add_i32 s42, s42, 2
	s_add_u32 s36, s36, 0x100
	s_addc_u32 s37, s37, 0
	s_add_u32 s15, s15, 0x100
	s_addc_u32 s27, s27, 0
	s_cmp_gt_u32 s42, 5
	s_cbranch_scc0 .LBB0_499
	s_and_b64 vcc, exec, s[8:9]
	s_cbranch_vccz .LBB0_502
	s_barrier

.LBB0_528:
	s_add_i32 s53, 0, 0x10000
	s_add_i32 s72, 0, 0x14000
	v_add_u32_e32 v16, s53, v147
	v_add_u32_e32 v32, s72, v147
	ds_read_b128 v[4:7], v16
	ds_read_b128 v[8:11], v16 offset:1024
	ds_read_b128 v[12:15], v16 offset:2048
	ds_read_b128 v[16:19], v16 offset:3072
	ds_read_b128 v[20:23], v32
	ds_read_b128 v[24:27], v32 offset:1024
	ds_read_b128 v[28:31], v32 offset:2048
	ds_read_b128 v[32:35], v32 offset:3072
	v_add_u32_e32 v231, 0, v146
	ds_read_b128 v[36:39], v231
	ds_read_b128 v[40:43], v231 offset:1024
	ds_read_b128 v[44:47], v231 offset:2048
	ds_read_b128 v[48:51], v231 offset:3072
	ds_read_b128 v[52:55], v231 offset:4096
	ds_read_b128 v[56:59], v231 offset:5120
	ds_read_b128 v[60:63], v231 offset:6144
	ds_read_b128 v[64:67], v231 offset:7168
	s_waitcnt vmcnt(8)
	s_waitcnt lgkmcnt(0)
	s_barrier
	s_setprio 1
	v_mfma_f32_16x16x32_f16 v[68:71], v[4:7], v[36:39], 0
	v_mfma_f32_16x16x32_f16 v[68:71], v[8:11], v[40:43], v[68:71]
	v_mfma_f32_16x16x32_f16 v[72:75], v[12:15], v[36:39], 0
	v_mfma_f32_16x16x32_f16 v[72:75], v[16:19], v[40:43], v[72:75]
	v_mfma_f32_16x16x32_f16 v[80:83], v[12:15], v[44:47], 0
	v_mfma_f32_16x16x32_f16 v[80:83], v[16:19], v[48:51], v[80:83]
	v_mfma_f32_16x16x32_f16 v[76:79], v[4:7], v[44:47], 0
	v_mfma_f32_16x16x32_f16 v[76:79], v[8:11], v[48:51], v[76:79]
	v_mfma_f32_16x16x32_f16 v[84:87], v[4:7], v[52:55], 0
	v_mfma_f32_16x16x32_f16 v[84:87], v[8:11], v[56:59], v[84:87]
	v_mfma_f32_16x16x32_f16 v[88:91], v[12:15], v[52:55], 0
	v_mfma_f32_16x16x32_f16 v[88:91], v[16:19], v[56:59], v[88:91]
	v_mfma_f32_16x16x32_f16 v[96:99], v[12:15], v[60:63], 0
	v_mfma_f32_16x16x32_f16 v[96:99], v[16:19], v[64:67], v[96:99]
	v_mfma_f32_16x16x32_f16 v[92:95], v[4:7], v[60:63], 0
	v_mfma_f32_16x16x32_f16 v[92:95], v[8:11], v[64:67], v[92:95]
	s_setprio 0
	s_setprio 1
	v_mfma_f32_16x16x32_f16 v[100:103], v[20:23], v[36:39], 0
	v_mfma_f32_16x16x32_f16 v[36:39], v[28:31], v[36:39], 0
	v_mfma_f32_16x16x32_f16 v[104:107], v[20:23], v[44:47], 0
	v_mfma_f32_16x16x32_f16 v[44:47], v[28:31], v[44:47], 0
	v_mfma_f32_16x16x32_f16 v[108:111], v[20:23], v[52:55], 0
	v_mfma_f32_16x16x32_f16 v[52:55], v[28:31], v[52:55], 0
	v_mfma_f32_16x16x32_f16 v[112:115], v[20:23], v[60:63], 0
	v_mfma_f32_16x16x32_f16 v[60:63], v[28:31], v[60:63], 0
	v_mfma_f32_16x16x32_f16 v[100:103], v[24:27], v[40:43], v[100:103]
	v_mfma_f32_16x16x32_f16 v[40:43], v[32:35], v[40:43], v[36:39]
	v_mfma_f32_16x16x32_f16 v[104:107], v[24:27], v[48:51], v[104:107]
	v_mfma_f32_16x16x32_f16 v[48:51], v[32:35], v[48:51], v[44:47]
	v_mfma_f32_16x16x32_f16 v[108:111], v[24:27], v[56:59], v[108:111]
	v_mfma_f32_16x16x32_f16 v[56:59], v[32:35], v[56:59], v[52:55]
	s_setprio 2
	s_barrier
	v_mfma_f32_16x16x32_f16 v[112:115], v[24:27], v[64:67], v[112:115]
	v_mfma_f32_16x16x32_f16 v[64:67], v[32:35], v[64:67], v[60:63]
	s_setprio 0
	v_lshl_add_u64 v[136:137], s[6:7], 0, v[2:3]
	s_add_i32 s53, s53, s38
	v_mov_b32_e32 v135, v3
	v_lshl_add_u64 v[140:141], v[136:137], 0, s[74:75]
	s_mov_b32 m0, s53
	v_lshl_add_u64 v[144:145], s[6:7], 0, v[134:135]
	ds_read_b128 v[36:39], v231 offset:16384
	ds_read_b128 v[44:47], v231 offset:17408
	ds_read_b128 v[52:55], v231 offset:18432
	ds_read_b128 v[60:63], v231 offset:19456
	ds_read_b128 v[116:119], v231 offset:20480
	ds_read_b128 v[120:123], v231 offset:21504
	ds_read_b128 v[124:127], v231 offset:22528
	ds_read_b128 v[128:131], v231 offset:23552
	global_load_lds_dwordx4 v[140:141], off
	v_lshl_add_u64 v[140:141], v[144:145], 0, s[74:75]
	s_add_i32 m0, s53, 0x2000
	s_add_i32 s53, s72, s38
	global_load_lds_dwordx4 v[140:141], off
	s_mov_b32 m0, s53
	v_mov_b32_e32 v139, v3
	global_load_lds_dwordx4 v2, s[16:17]
	s_add_i32 m0, s53, 0x2000
	v_lshl_add_u64 v[248:249], s[8:9], 0, v[138:139]
	v_mov_b32_e32 v133, v3
	global_load_lds_dwordx4 v134, s[16:17]
	v_lshl_add_u64 v[140:141], v[248:249], 0, s[74:75]
	s_mov_b32 m0, s58
	v_lshl_add_u64 v[250:251], s[8:9], 0, v[132:133]
	global_load_lds_dwordx4 v[140:141], off
	v_lshl_add_u64 v[140:141], v[250:251], 0, s[74:75]
	s_mov_b32 m0, s59
	s_nop 0
	global_load_lds_dwordx4 v[140:141], off
	s_waitcnt vmcnt(8)
	s_waitcnt lgkmcnt(0)
	s_barrier
	s_setprio 1
	v_mfma_f32_16x16x32_f16 v[140:143], v[4:7], v[36:39], 0
	v_mfma_f32_16x16x32_f16 v[148:151], v[12:15], v[36:39], 0
	v_mfma_f32_16x16x32_f16 v[152:155], v[4:7], v[52:55], 0
	v_mfma_f32_16x16x32_f16 v[156:159], v[12:15], v[52:55], 0
	v_mfma_f32_16x16x32_f16 v[160:163], v[4:7], v[116:119], 0
	v_mfma_f32_16x16x32_f16 v[164:167], v[12:15], v[116:119], 0
	v_mfma_f32_16x16x32_f16 v[4:7], v[4:7], v[124:127], 0
	v_mfma_f32_16x16x32_f16 v[12:15], v[12:15], v[124:127], 0
	v_mfma_f32_16x16x32_f16 v[140:143], v[8:11], v[44:47], v[140:143]
	v_mfma_f32_16x16x32_f16 v[148:151], v[16:19], v[44:47], v[148:151]
	v_mfma_f32_16x16x32_f16 v[152:155], v[8:11], v[60:63], v[152:155]
	v_mfma_f32_16x16x32_f16 v[156:159], v[16:19], v[60:63], v[156:159]
	v_mfma_f32_16x16x32_f16 v[160:163], v[8:11], v[120:123], v[160:163]
	v_mfma_f32_16x16x32_f16 v[164:167], v[16:19], v[120:123], v[164:167]
	v_mfma_f32_16x16x32_f16 v[168:171], v[8:11], v[128:131], v[4:7]
	v_mfma_f32_16x16x32_f16 v[172:175], v[16:19], v[128:131], v[12:15]
	s_setprio 0
	s_setprio 1
	v_mfma_f32_16x16x32_f16 v[4:7], v[20:23], v[36:39], 0
	v_mfma_f32_16x16x32_f16 v[8:11], v[28:31], v[36:39], 0
	v_mfma_f32_16x16x32_f16 v[12:15], v[20:23], v[52:55], 0
	v_mfma_f32_16x16x32_f16 v[16:19], v[28:31], v[52:55], 0
	v_mfma_f32_16x16x32_f16 v[36:39], v[20:23], v[116:119], 0
	v_mfma_f32_16x16x32_f16 v[52:55], v[28:31], v[116:119], 0
	v_mfma_f32_16x16x32_f16 v[20:23], v[20:23], v[124:127], 0
	v_mfma_f32_16x16x32_f16 v[28:31], v[28:31], v[124:127], 0
	v_mfma_f32_16x16x32_f16 v[116:119], v[24:27], v[44:47], v[4:7]
	v_mfma_f32_16x16x32_f16 v[124:127], v[32:35], v[44:47], v[8:11]
	v_mfma_f32_16x16x32_f16 v[184:187], v[24:27], v[120:123], v[36:39]
	v_mfma_f32_16x16x32_f16 v[120:123], v[32:35], v[120:123], v[52:55]
	v_mfma_f32_16x16x32_f16 v[188:191], v[24:27], v[128:131], v[20:23]
	v_mfma_f32_16x16x32_f16 v[128:131], v[32:35], v[128:131], v[28:31]
	s_setprio 2
	s_barrier
	v_mfma_f32_16x16x32_f16 v[176:179], v[24:27], v[60:63], v[12:15]
	v_mfma_f32_16x16x32_f16 v[180:183], v[32:35], v[60:63], v[16:19]
	s_setprio 0
	s_add_i32 s53, 0, 0x18000
	v_add_u32_e32 v4, s53, v147
	s_add_i32 s72, 0, 0x1c000
	ds_read_b128 v[192:195], v4
	ds_read_b128 v[196:199], v4 offset:1024
	ds_read_b128 v[200:203], v4 offset:2048
	ds_read_b128 v[204:207], v4 offset:3072
	v_add_u32_e32 v4, s72, v147
	ds_read_b128 v[208:211], v4
	ds_read_b128 v[212:215], v4 offset:1024
	ds_read_b128 v[216:219], v4 offset:2048
	ds_read_b128 v[220:223], v4 offset:3072
	s_mov_b32 m0, s60
	ds_read_b128 v[44:47], v231 offset:32768
	ds_read_b128 v[52:55], v231 offset:33792
	ds_read_b128 v[60:63], v231 offset:34816
	ds_read_b128 v[224:227], v231 offset:35840
	ds_read_b128 v[232:235], v231 offset:36864
	ds_read_b128 v[236:239], v231 offset:37888
	ds_read_b128 v[240:243], v231 offset:38912
	ds_read_b128 v[244:247], v231 offset:39936
	global_load_lds_dwordx4 v138, s[26:27]
	s_mov_b32 m0, s61
	s_nop 0
	global_load_lds_dwordx4 v132, s[26:27]
	s_waitcnt vmcnt(8)
	s_waitcnt lgkmcnt(0)
	s_barrier
	s_setprio 1
	v_mfma_f32_16x16x32_f16 v[4:7], v[192:195], v[44:47], v[68:71]
	v_mfma_f32_16x16x32_f16 v[8:11], v[200:203], v[44:47], v[72:75]
	v_mfma_f32_16x16x32_f16 v[12:15], v[192:195], v[60:63], v[76:79]
	v_mfma_f32_16x16x32_f16 v[16:19], v[200:203], v[60:63], v[80:83]
	v_mfma_f32_16x16x32_f16 v[20:23], v[192:195], v[232:235], v[84:87]
	v_mfma_f32_16x16x32_f16 v[24:27], v[200:203], v[232:235], v[88:91]
	v_mfma_f32_16x16x32_f16 v[28:31], v[192:195], v[240:243], v[92:95]
	v_mfma_f32_16x16x32_f16 v[32:35], v[200:203], v[240:243], v[96:99]
	v_mfma_f32_16x16x32_f16 v[4:7], v[196:199], v[52:55], v[4:7]
	v_mfma_f32_16x16x32_f16 v[8:11], v[204:207], v[52:55], v[8:11]
	v_mfma_f32_16x16x32_f16 v[12:15], v[196:199], v[224:227], v[12:15]
	v_mfma_f32_16x16x32_f16 v[16:19], v[204:207], v[224:227], v[16:19]
	v_mfma_f32_16x16x32_f16 v[20:23], v[196:199], v[236:239], v[20:23]
	v_mfma_f32_16x16x32_f16 v[24:27], v[204:207], v[236:239], v[24:27]
	v_mfma_f32_16x16x32_f16 v[28:31], v[196:199], v[244:247], v[28:31]
	v_mfma_f32_16x16x32_f16 v[32:35], v[204:207], v[244:247], v[32:35]
	s_setprio 0
	s_setprio 1
	v_mfma_f32_16x16x32_f16 v[36:39], v[208:211], v[44:47], v[100:103]
	v_mfma_f32_16x16x32_f16 v[40:43], v[216:219], v[44:47], v[40:43]
	v_mfma_f32_16x16x32_f16 v[36:39], v[212:215], v[52:55], v[36:39]
	v_mfma_f32_16x16x32_f16 v[40:43], v[220:223], v[52:55], v[40:43]
	v_mfma_f32_16x16x32_f16 v[44:47], v[208:211], v[60:63], v[104:107]
	v_mfma_f32_16x16x32_f16 v[48:51], v[216:219], v[60:63], v[48:51]
	v_mfma_f32_16x16x32_f16 v[52:55], v[208:211], v[232:235], v[108:111]
	v_mfma_f32_16x16x32_f16 v[56:59], v[216:219], v[232:235], v[56:59]
	v_mfma_f32_16x16x32_f16 v[60:63], v[208:211], v[240:243], v[112:115]
	v_mfma_f32_16x16x32_f16 v[64:67], v[216:219], v[240:243], v[64:67]
	v_mfma_f32_16x16x32_f16 v[44:47], v[212:215], v[224:227], v[44:47]
	v_mfma_f32_16x16x32_f16 v[48:51], v[220:223], v[224:227], v[48:51]
	v_mfma_f32_16x16x32_f16 v[52:55], v[212:215], v[236:239], v[52:55]
	v_mfma_f32_16x16x32_f16 v[56:59], v[220:223], v[236:239], v[56:59]
	s_setprio 2
	s_barrier
	v_mfma_f32_16x16x32_f16 v[60:63], v[212:215], v[244:247], v[60:63]
	v_mfma_f32_16x16x32_f16 v[64:67], v[220:223], v[244:247], v[64:67]
	s_setprio 0
	s_add_i32 s53, s53, s38
	v_lshl_add_u64 v[68:69], v[136:137], 0, s[24:25]
	s_mov_b32 m0, s53
	ds_read_b128 v[104:107], v231 offset:49152
	ds_read_b128 v[108:111], v231 offset:50176
	ds_read_b128 v[112:115], v231 offset:51200
	ds_read_b128 v[224:227], v231 offset:52224
	ds_read_b128 v[232:235], v231 offset:53248
	ds_read_b128 v[236:239], v231 offset:54272
	ds_read_b128 v[240:243], v231 offset:55296
	ds_read_b128 v[244:247], v231 offset:56320
	global_load_lds_dwordx4 v[68:69], off
	v_lshl_add_u64 v[68:69], v[144:145], 0, s[24:25]
	s_add_i32 m0, s53, 0x2000
	s_add_i32 s53, s72, s38
	global_load_lds_dwordx4 v[68:69], off
	s_mov_b32 m0, s53
	v_lshl_add_u64 v[68:69], v[248:249], 0, s[24:25]
	global_load_lds_dwordx4 v2, s[28:29]
	s_add_i32 m0, s53, 0x2000
	s_nop 0
	global_load_lds_dwordx4 v134, s[28:29]
	s_mov_b32 m0, s64
	s_nop 0
	global_load_lds_dwordx4 v[68:69], off
	v_lshl_add_u64 v[68:69], v[250:251], 0, s[24:25]
	s_mov_b32 m0, s65
	s_nop 0
	global_load_lds_dwordx4 v[68:69], off
	s_waitcnt vmcnt(8)
	s_waitcnt lgkmcnt(0)
	s_barrier
	s_setprio 1
	v_mfma_f32_16x16x32_f16 v[68:71], v[192:195], v[104:107], v[140:143]
	v_mfma_f32_16x16x32_f16 v[72:75], v[200:203], v[104:107], v[148:151]
	v_mfma_f32_16x16x32_f16 v[76:79], v[192:195], v[112:115], v[152:155]
	v_mfma_f32_16x16x32_f16 v[80:83], v[200:203], v[112:115], v[156:159]
	v_mfma_f32_16x16x32_f16 v[84:87], v[192:195], v[232:235], v[160:163]
	v_mfma_f32_16x16x32_f16 v[88:91], v[200:203], v[232:235], v[164:167]
	v_mfma_f32_16x16x32_f16 v[92:95], v[192:195], v[240:243], v[168:171]
	v_mfma_f32_16x16x32_f16 v[96:99], v[200:203], v[240:243], v[172:175]
	v_mfma_f32_16x16x32_f16 v[68:71], v[196:199], v[108:111], v[68:71]
	v_mfma_f32_16x16x32_f16 v[72:75], v[204:207], v[108:111], v[72:75]
	v_mfma_f32_16x16x32_f16 v[76:79], v[196:199], v[224:227], v[76:79]
	v_mfma_f32_16x16x32_f16 v[80:83], v[204:207], v[224:227], v[80:83]
	v_mfma_f32_16x16x32_f16 v[84:87], v[196:199], v[236:239], v[84:87]
	v_mfma_f32_16x16x32_f16 v[88:91], v[204:207], v[236:239], v[88:91]
	v_mfma_f32_16x16x32_f16 v[92:95], v[196:199], v[244:247], v[92:95]
	v_mfma_f32_16x16x32_f16 v[96:99], v[204:207], v[244:247], v[96:99]
	s_setprio 0
	s_setprio 1
	v_mfma_f32_16x16x32_f16 v[100:103], v[208:211], v[104:107], v[116:119]
	v_mfma_f32_16x16x32_f16 v[104:107], v[216:219], v[104:107], v[124:127]
	v_mfma_f32_16x16x32_f16 v[100:103], v[212:215], v[108:111], v[100:103]
	v_mfma_f32_16x16x32_f16 v[104:107], v[220:223], v[108:111], v[104:107]
	v_mfma_f32_16x16x32_f16 v[108:111], v[208:211], v[112:115], v[176:179]
	v_mfma_f32_16x16x32_f16 v[112:115], v[216:219], v[112:115], v[180:183]
	v_mfma_f32_16x16x32_f16 v[116:119], v[208:211], v[232:235], v[184:187]
	v_mfma_f32_16x16x32_f16 v[120:123], v[216:219], v[232:235], v[120:123]
	v_mfma_f32_16x16x32_f16 v[124:127], v[208:211], v[240:243], v[188:191]
	v_mfma_f32_16x16x32_f16 v[128:131], v[216:219], v[240:243], v[128:131]
	v_mfma_f32_16x16x32_f16 v[108:111], v[212:215], v[224:227], v[108:111]
	v_mfma_f32_16x16x32_f16 v[112:115], v[220:223], v[224:227], v[112:115]
	v_mfma_f32_16x16x32_f16 v[116:119], v[212:215], v[236:239], v[116:119]
	v_mfma_f32_16x16x32_f16 v[120:123], v[220:223], v[236:239], v[120:123]
	s_setprio 2
	s_barrier
	v_mfma_f32_16x16x32_f16 v[124:127], v[212:215], v[244:247], v[124:127]
	v_mfma_f32_16x16x32_f16 v[128:131], v[220:223], v[244:247], v[128:131]
	s_setprio 0
	s_add_i32 s41, s41, 2
	s_cmp_ge_i32 s41, s40
	s_cbranch_scc0 .LBB0_528
	v_mov_b32_e32 v136, v2
	s_branch .LBB0_531

.LBB0_532:
	s_add_u32 s6, s8, 0xfff80080
	s_addc_u32 s7, s9, -1
	s_add_i32 s29, 0, 0x10000
	s_cmp_eq_u32 s28, 28
	s_cselect_b32 s17, s13, s7
	s_cselect_b32 s16, s12, s6
	v_add_u32_e32 v133, s29, v147
	s_cselect_b32 s7, s15, s27
	s_cselect_b32 s6, s14, s26
	s_add_i32 s53, 0, 0x14000
	ds_read_b128 v[138:141], v133
	ds_read_b128 v[142:145], v133 offset:1024
	ds_read_b128 v[148:151], v133 offset:2048
	ds_read_b128 v[152:155], v133 offset:3072
	v_add_u32_e32 v133, s53, v147
	ds_read_b128 v[156:159], v133
	ds_read_b128 v[160:163], v133 offset:1024
	ds_read_b128 v[164:167], v133 offset:2048
	ds_read_b128 v[168:171], v133 offset:3072
	s_mov_b32 m0, s66
	v_add_u32_e32 v212, 0, v146
	ds_read_b128 v[172:175], v212
	ds_read_b128 v[176:179], v212 offset:1024
	ds_read_b128 v[180:183], v212 offset:2048
	ds_read_b128 v[184:187], v212 offset:3072
	ds_read_b128 v[188:191], v212 offset:4096
	ds_read_b128 v[192:195], v212 offset:5120
	ds_read_b128 v[196:199], v212 offset:6144
	ds_read_b128 v[200:203], v212 offset:7168
	global_load_lds_dwordx4 v2, s[8:9]
	s_mov_b32 m0, s67
	v_mov_b32_e32 v133, v3
	global_load_lds_dwordx4 v132, s[8:9]
	s_waitcnt vmcnt(8)
	s_waitcnt lgkmcnt(0)
	s_barrier
	s_setprio 1
	v_mfma_f32_16x16x32_f16 v[4:7], v[138:141], v[172:175], v[4:7]
	v_mfma_f32_16x16x32_f16 v[4:7], v[142:145], v[176:179], v[4:7]
	v_mfma_f32_16x16x32_f16 v[8:11], v[152:155], v[176:179], v[8:11]
	v_mfma_f32_16x16x32_f16 v[8:11], v[148:151], v[172:175], v[8:11]
	v_mfma_f32_16x16x32_f16 v[16:19], v[148:151], v[180:183], v[16:19]
	v_mfma_f32_16x16x32_f16 v[16:19], v[152:155], v[184:187], v[16:19]
	v_mfma_f32_16x16x32_f16 v[12:15], v[142:145], v[184:187], v[12:15]
	v_mfma_f32_16x16x32_f16 v[12:15], v[138:141], v[180:183], v[12:15]
	v_mfma_f32_16x16x32_f16 v[20:23], v[138:141], v[188:191], v[20:23]
	v_mfma_f32_16x16x32_f16 v[20:23], v[142:145], v[192:195], v[20:23]
	v_mfma_f32_16x16x32_f16 v[24:27], v[152:155], v[192:195], v[24:27]
	v_mfma_f32_16x16x32_f16 v[24:27], v[148:151], v[188:191], v[24:27]
	v_mfma_f32_16x16x32_f16 v[32:35], v[148:151], v[196:199], v[32:35]
	v_mfma_f32_16x16x32_f16 v[32:35], v[152:155], v[200:203], v[32:35]
	v_mfma_f32_16x16x32_f16 v[28:31], v[142:145], v[200:203], v[28:31]
	v_mfma_f32_16x16x32_f16 v[28:31], v[138:141], v[196:199], v[28:31]
	s_setprio 0
	s_setprio 1
	v_mfma_f32_16x16x32_f16 v[36:39], v[156:159], v[172:175], v[36:39]
	v_mfma_f32_16x16x32_f16 v[36:39], v[160:163], v[176:179], v[36:39]
	v_mfma_f32_16x16x32_f16 v[40:43], v[168:171], v[176:179], v[40:43]
	v_mfma_f32_16x16x32_f16 v[40:43], v[164:167], v[172:175], v[40:43]
	v_mfma_f32_16x16x32_f16 v[48:51], v[164:167], v[180:183], v[48:51]
	v_mfma_f32_16x16x32_f16 v[48:51], v[168:171], v[184:187], v[48:51]
	v_mfma_f32_16x16x32_f16 v[44:47], v[160:163], v[184:187], v[44:47]
	v_mfma_f32_16x16x32_f16 v[44:47], v[156:159], v[180:183], v[44:47]
	v_mfma_f32_16x16x32_f16 v[52:55], v[156:159], v[188:191], v[52:55]
	v_mfma_f32_16x16x32_f16 v[52:55], v[160:163], v[192:195], v[52:55]
	v_mfma_f32_16x16x32_f16 v[56:59], v[168:171], v[192:195], v[56:59]
	v_mfma_f32_16x16x32_f16 v[56:59], v[164:167], v[188:191], v[56:59]
	v_mfma_f32_16x16x32_f16 v[64:67], v[164:167], v[196:199], v[64:67]
	v_mfma_f32_16x16x32_f16 v[64:67], v[168:171], v[200:203], v[64:67]
	s_setprio 2
	s_barrier
	v_mfma_f32_16x16x32_f16 v[60:63], v[160:163], v[200:203], v[60:63]
	v_mfma_f32_16x16x32_f16 v[60:63], v[156:159], v[196:199], v[60:63]
	s_setprio 0
	s_add_i32 s29, s29, s38
	s_mov_b32 m0, s29
	ds_read_b128 v[172:175], v212 offset:16384
	ds_read_b128 v[176:179], v212 offset:17408
	ds_read_b128 v[180:183], v212 offset:18432
	ds_read_b128 v[184:187], v212 offset:19456
	ds_read_b128 v[188:191], v212 offset:20480
	ds_read_b128 v[192:195], v212 offset:21504
	ds_read_b128 v[196:199], v212 offset:22528
	ds_read_b128 v[200:203], v212 offset:23552
	global_load_lds_dwordx4 v136, s[6:7]
	s_add_i32 m0, s29, 0x2000
	s_add_u32 s40, s6, 0x80000
	s_addc_u32 s41, s7, 0
	s_add_i32 s29, s53, s38
	global_load_lds_dwordx4 v134, s[6:7]
	s_mov_b32 m0, s29
	v_mov_b32_e32 v137, v3
	global_load_lds_dwordx4 v136, s[40:41]
	s_add_i32 m0, s29, 0x2000
	v_mov_b32_e32 v135, v3
	global_load_lds_dwordx4 v134, s[40:41]
	s_mov_b32 m0, s58
	v_lshl_add_u64 v[204:205], s[6:7], 0, v[136:137]
	global_load_lds_dwordx4 v2, s[16:17]
	s_mov_b32 m0, s59
	v_lshl_add_u64 v[206:207], s[6:7], 0, v[134:135]
	global_load_lds_dwordx4 v132, s[16:17]
	s_waitcnt vmcnt(8)
	s_waitcnt lgkmcnt(0)
	v_lshl_add_u64 v[208:209], s[16:17], 0, v[2:3]
	v_lshl_add_u64 v[210:211], s[16:17], 0, v[132:133]
	s_barrier
	s_setprio 1
	v_mfma_f32_16x16x32_f16 v[68:71], v[138:141], v[172:175], v[68:71]
	v_mfma_f32_16x16x32_f16 v[68:71], v[142:145], v[176:179], v[68:71]
	v_mfma_f32_16x16x32_f16 v[72:75], v[152:155], v[176:179], v[72:75]
	v_mfma_f32_16x16x32_f16 v[72:75], v[148:151], v[172:175], v[72:75]
	v_mfma_f32_16x16x32_f16 v[80:83], v[148:151], v[180:183], v[80:83]
	v_mfma_f32_16x16x32_f16 v[80:83], v[152:155], v[184:187], v[80:83]
	v_mfma_f32_16x16x32_f16 v[76:79], v[142:145], v[184:187], v[76:79]
	v_mfma_f32_16x16x32_f16 v[76:79], v[138:141], v[180:183], v[76:79]
	v_mfma_f32_16x16x32_f16 v[84:87], v[138:141], v[188:191], v[84:87]
	v_mfma_f32_16x16x32_f16 v[84:87], v[142:145], v[192:195], v[84:87]
	v_mfma_f32_16x16x32_f16 v[88:91], v[152:155], v[192:195], v[88:91]
	v_mfma_f32_16x16x32_f16 v[88:91], v[148:151], v[188:191], v[88:91]
	v_mfma_f32_16x16x32_f16 v[96:99], v[148:151], v[196:199], v[96:99]
	v_mfma_f32_16x16x32_f16 v[96:99], v[152:155], v[200:203], v[96:99]
	v_mfma_f32_16x16x32_f16 v[92:95], v[142:145], v[200:203], v[92:95]
	v_mfma_f32_16x16x32_f16 v[92:95], v[138:141], v[196:199], v[92:95]
	s_setprio 0
	s_setprio 1
	v_mfma_f32_16x16x32_f16 v[100:103], v[156:159], v[172:175], v[100:103]
	v_mfma_f32_16x16x32_f16 v[100:103], v[160:163], v[176:179], v[100:103]
	v_mfma_f32_16x16x32_f16 v[104:107], v[168:171], v[176:179], v[104:107]
	v_mfma_f32_16x16x32_f16 v[104:107], v[164:167], v[172:175], v[104:107]
	v_mfma_f32_16x16x32_f16 v[112:115], v[164:167], v[180:183], v[112:115]
	v_mfma_f32_16x16x32_f16 v[112:115], v[168:171], v[184:187], v[112:115]
	v_mfma_f32_16x16x32_f16 v[108:111], v[160:163], v[184:187], v[108:111]
	v_mfma_f32_16x16x32_f16 v[108:111], v[156:159], v[180:183], v[108:111]
	v_mfma_f32_16x16x32_f16 v[116:119], v[156:159], v[188:191], v[116:119]
	v_mfma_f32_16x16x32_f16 v[116:119], v[160:163], v[192:195], v[116:119]
	v_mfma_f32_16x16x32_f16 v[120:123], v[168:171], v[192:195], v[120:123]
	v_mfma_f32_16x16x32_f16 v[120:123], v[164:167], v[188:191], v[120:123]
	v_mfma_f32_16x16x32_f16 v[128:131], v[164:167], v[196:199], v[128:131]
	v_mfma_f32_16x16x32_f16 v[128:131], v[168:171], v[200:203], v[128:131]
	s_setprio 2
	s_barrier
	v_mfma_f32_16x16x32_f16 v[124:127], v[160:163], v[200:203], v[124:127]
	v_mfma_f32_16x16x32_f16 v[124:127], v[156:159], v[196:199], v[124:127]
	s_setprio 0
	s_add_i32 s29, 0, 0x18000
	v_add_u32_e32 v135, s29, v147
	s_add_i32 s40, 0, 0x1c000
	ds_read_b128 v[138:141], v135
	ds_read_b128 v[142:145], v135 offset:1024
	ds_read_b128 v[148:151], v135 offset:2048
	ds_read_b128 v[152:155], v135 offset:3072
	v_add_u32_e32 v135, s40, v147
	ds_read_b128 v[156:159], v135
	ds_read_b128 v[160:163], v135 offset:1024
	ds_read_b128 v[164:167], v135 offset:2048
	ds_read_b128 v[168:171], v135 offset:3072
	s_add_u32 s16, s16, 0x80000
	s_addc_u32 s17, s17, 0
	s_mov_b32 m0, s60
	ds_read_b128 v[172:175], v212 offset:32768
	ds_read_b128 v[176:179], v212 offset:33792
	ds_read_b128 v[180:183], v212 offset:34816
	ds_read_b128 v[184:187], v212 offset:35840
	ds_read_b128 v[188:191], v212 offset:36864
	ds_read_b128 v[192:195], v212 offset:37888
	ds_read_b128 v[196:199], v212 offset:38912
	ds_read_b128 v[200:203], v212 offset:39936
	global_load_lds_dwordx4 v2, s[16:17]
	s_mov_b32 m0, s61
	s_nop 0
	global_load_lds_dwordx4 v132, s[16:17]
	s_waitcnt vmcnt(8)
	s_waitcnt lgkmcnt(0)
	s_barrier
	s_setprio 1
	v_mfma_f32_16x16x32_f16 v[4:7], v[138:141], v[172:175], v[4:7]
	v_mfma_f32_16x16x32_f16 v[4:7], v[142:145], v[176:179], v[4:7]
	v_mfma_f32_16x16x32_f16 v[8:11], v[152:155], v[176:179], v[8:11]
	v_mfma_f32_16x16x32_f16 v[8:11], v[148:151], v[172:175], v[8:11]
	v_mfma_f32_16x16x32_f16 v[16:19], v[148:151], v[180:183], v[16:19]
	v_mfma_f32_16x16x32_f16 v[16:19], v[152:155], v[184:187], v[16:19]
	v_mfma_f32_16x16x32_f16 v[12:15], v[142:145], v[184:187], v[12:15]
	v_mfma_f32_16x16x32_f16 v[12:15], v[138:141], v[180:183], v[12:15]
	v_mfma_f32_16x16x32_f16 v[20:23], v[138:141], v[188:191], v[20:23]
	v_mfma_f32_16x16x32_f16 v[20:23], v[142:145], v[192:195], v[20:23]
	v_mfma_f32_16x16x32_f16 v[24:27], v[152:155], v[192:195], v[24:27]
	v_mfma_f32_16x16x32_f16 v[24:27], v[148:151], v[188:191], v[24:27]
	v_mfma_f32_16x16x32_f16 v[32:35], v[148:151], v[196:199], v[32:35]
	v_mfma_f32_16x16x32_f16 v[32:35], v[152:155], v[200:203], v[32:35]
	v_mfma_f32_16x16x32_f16 v[28:31], v[142:145], v[200:203], v[28:31]
	v_mfma_f32_16x16x32_f16 v[28:31], v[138:141], v[196:199], v[28:31]
	s_setprio 0
	s_setprio 1
	v_mfma_f32_16x16x32_f16 v[36:39], v[156:159], v[172:175], v[36:39]
	v_mfma_f32_16x16x32_f16 v[36:39], v[160:163], v[176:179], v[36:39]
	v_mfma_f32_16x16x32_f16 v[40:43], v[168:171], v[176:179], v[40:43]
	v_mfma_f32_16x16x32_f16 v[40:43], v[164:167], v[172:175], v[40:43]
	v_mfma_f32_16x16x32_f16 v[48:51], v[164:167], v[180:183], v[48:51]
	v_mfma_f32_16x16x32_f16 v[48:51], v[168:171], v[184:187], v[48:51]
	v_mfma_f32_16x16x32_f16 v[44:47], v[160:163], v[184:187], v[44:47]
	v_mfma_f32_16x16x32_f16 v[44:47], v[156:159], v[180:183], v[44:47]
	v_mfma_f32_16x16x32_f16 v[52:55], v[156:159], v[188:191], v[52:55]
	v_mfma_f32_16x16x32_f16 v[52:55], v[160:163], v[192:195], v[52:55]
	v_mfma_f32_16x16x32_f16 v[56:59], v[168:171], v[192:195], v[56:59]
	v_mfma_f32_16x16x32_f16 v[56:59], v[164:167], v[188:191], v[56:59]
	v_mfma_f32_16x16x32_f16 v[64:67], v[164:167], v[196:199], v[64:67]
	v_mfma_f32_16x16x32_f16 v[64:67], v[168:171], v[200:203], v[64:67]
	s_setprio 2
	s_barrier
	v_mfma_f32_16x16x32_f16 v[60:63], v[160:163], v[200:203], v[60:63]
	v_mfma_f32_16x16x32_f16 v[60:63], v[156:159], v[196:199], v[60:63]
	s_setprio 0
	s_add_i32 s16, s29, s38
	v_lshl_add_u64 v[204:205], v[204:205], 0, s[86:87]
	s_mov_b32 m0, s16
	ds_read_b128 v[172:175], v212 offset:49152
	ds_read_b128 v[176:179], v212 offset:50176
	ds_read_b128 v[180:183], v212 offset:51200
	ds_read_b128 v[184:187], v212 offset:52224
	ds_read_b128 v[188:191], v212 offset:53248
	ds_read_b128 v[192:195], v212 offset:54272
	ds_read_b128 v[196:199], v212 offset:55296
	ds_read_b128 v[200:203], v212 offset:56320
	global_load_lds_dwordx4 v[204:205], off
	s_add_i32 m0, s16, 0x2000
	s_add_u32 s6, s6, 0x80080
	v_lshl_add_u64 v[204:205], v[206:207], 0, s[86:87]
	s_addc_u32 s7, s7, 0
	s_add_i32 s16, s40, s38
	global_load_lds_dwordx4 v[204:205], off
	s_mov_b32 m0, s16
	v_lshl_add_u64 v[204:205], v[208:209], 0, s[86:87]
	global_load_lds_dwordx4 v136, s[6:7]
	s_add_i32 m0, s16, 0x2000
	s_nop 0
	global_load_lds_dwordx4 v134, s[6:7]
	s_mov_b32 m0, s64
	s_nop 0
	global_load_lds_dwordx4 v[204:205], off
	v_lshl_add_u64 v[204:205], v[210:211], 0, s[86:87]
	s_mov_b32 m0, s65
	s_nop 0
	global_load_lds_dwordx4 v[204:205], off
	s_waitcnt vmcnt(8)
	s_waitcnt lgkmcnt(0)
	s_barrier
	s_setprio 1
	v_mfma_f32_16x16x32_f16 v[68:71], v[138:141], v[172:175], v[68:71]
	v_mfma_f32_16x16x32_f16 v[68:71], v[142:145], v[176:179], v[68:71]
	v_mfma_f32_16x16x32_f16 v[72:75], v[152:155], v[176:179], v[72:75]
	v_mfma_f32_16x16x32_f16 v[72:75], v[148:151], v[172:175], v[72:75]
	v_mfma_f32_16x16x32_f16 v[80:83], v[148:151], v[180:183], v[80:83]
	v_mfma_f32_16x16x32_f16 v[80:83], v[152:155], v[184:187], v[80:83]
	v_mfma_f32_16x16x32_f16 v[76:79], v[142:145], v[184:187], v[76:79]
	v_mfma_f32_16x16x32_f16 v[76:79], v[138:141], v[180:183], v[76:79]
	v_mfma_f32_16x16x32_f16 v[84:87], v[138:141], v[188:191], v[84:87]
	v_mfma_f32_16x16x32_f16 v[84:87], v[142:145], v[192:195], v[84:87]
	v_mfma_f32_16x16x32_f16 v[88:91], v[152:155], v[192:195], v[88:91]
	v_mfma_f32_16x16x32_f16 v[88:91], v[148:151], v[188:191], v[88:91]
	v_mfma_f32_16x16x32_f16 v[96:99], v[148:151], v[196:199], v[96:99]
	v_mfma_f32_16x16x32_f16 v[96:99], v[152:155], v[200:203], v[96:99]
	v_mfma_f32_16x16x32_f16 v[92:95], v[142:145], v[200:203], v[92:95]
	v_mfma_f32_16x16x32_f16 v[92:95], v[138:141], v[196:199], v[92:95]
	s_setprio 0
	s_setprio 1
	v_mfma_f32_16x16x32_f16 v[100:103], v[156:159], v[172:175], v[100:103]
	v_mfma_f32_16x16x32_f16 v[100:103], v[160:163], v[176:179], v[100:103]
	v_mfma_f32_16x16x32_f16 v[104:107], v[168:171], v[176:179], v[104:107]
	v_mfma_f32_16x16x32_f16 v[104:107], v[164:167], v[172:175], v[104:107]
	v_mfma_f32_16x16x32_f16 v[112:115], v[164:167], v[180:183], v[112:115]
	v_mfma_f32_16x16x32_f16 v[112:115], v[168:171], v[184:187], v[112:115]
	v_mfma_f32_16x16x32_f16 v[108:111], v[160:163], v[184:187], v[108:111]
	v_mfma_f32_16x16x32_f16 v[108:111], v[156:159], v[180:183], v[108:111]
	v_mfma_f32_16x16x32_f16 v[116:119], v[156:159], v[188:191], v[116:119]
	v_mfma_f32_16x16x32_f16 v[116:119], v[160:163], v[192:195], v[116:119]
	v_mfma_f32_16x16x32_f16 v[120:123], v[168:171], v[192:195], v[120:123]
	v_mfma_f32_16x16x32_f16 v[120:123], v[164:167], v[188:191], v[120:123]
	v_mfma_f32_16x16x32_f16 v[128:131], v[164:167], v[196:199], v[128:131]
	v_mfma_f32_16x16x32_f16 v[128:131], v[168:171], v[200:203], v[128:131]
	s_setprio 2
	s_barrier
	v_mfma_f32_16x16x32_f16 v[124:127], v[160:163], v[200:203], v[124:127]
	v_mfma_f32_16x16x32_f16 v[124:127], v[156:159], v[196:199], v[124:127]
	s_setprio 0
	s_add_i32 s28, s28, 2
	s_add_u32 s8, s8, 0x100
	s_addc_u32 s9, s9, 0
	s_add_u32 s26, s26, 0x100
	s_addc_u32 s27, s27, 0
	s_cmp_gt_u32 s28, 29
	s_cbranch_scc0 .LBB0_532
	s_and_b64 vcc, exec, s[50:51]
	s_cbranch_vccz .LBB0_535
	s_barrier

.LBB0_641:
	s_add_i32 s43, 0, 0x10000
	s_add_i32 s71, 0, 0x14000
	v_add_u32_e32 v16, s43, v232
	v_add_u32_e32 v32, s71, v232
	ds_read_b128 v[4:7], v16
	ds_read_b128 v[8:11], v16 offset:1024
	ds_read_b128 v[12:15], v16 offset:2048
	ds_read_b128 v[16:19], v16 offset:3072
	ds_read_b128 v[20:23], v32
	ds_read_b128 v[24:27], v32 offset:1024
	ds_read_b128 v[28:31], v32 offset:2048
	ds_read_b128 v[32:35], v32 offset:3072
	v_add_u32_e32 v233, 0, v231
	ds_read_b128 v[36:39], v233
	ds_read_b128 v[40:43], v233 offset:1024
	ds_read_b128 v[44:47], v233 offset:2048
	ds_read_b128 v[48:51], v233 offset:3072
	ds_read_b128 v[52:55], v233 offset:4096
	ds_read_b128 v[56:59], v233 offset:5120
	ds_read_b128 v[60:63], v233 offset:6144
	ds_read_b128 v[64:67], v233 offset:7168
	s_waitcnt vmcnt(8)
	s_waitcnt lgkmcnt(0)
	s_barrier
	s_setprio 1
	v_mfma_f32_16x16x32_bf16 v[68:71], v[4:7], v[36:39], 0
	v_mfma_f32_16x16x32_bf16 v[68:71], v[8:11], v[40:43], v[68:71]
	v_mfma_f32_16x16x32_bf16 v[72:75], v[12:15], v[36:39], 0
	v_mfma_f32_16x16x32_bf16 v[72:75], v[16:19], v[40:43], v[72:75]
	v_mfma_f32_16x16x32_bf16 v[80:83], v[12:15], v[44:47], 0
	v_mfma_f32_16x16x32_bf16 v[80:83], v[16:19], v[48:51], v[80:83]
	v_mfma_f32_16x16x32_bf16 v[76:79], v[4:7], v[44:47], 0
	v_mfma_f32_16x16x32_bf16 v[76:79], v[8:11], v[48:51], v[76:79]
	v_mfma_f32_16x16x32_bf16 v[84:87], v[4:7], v[52:55], 0
	v_mfma_f32_16x16x32_bf16 v[84:87], v[8:11], v[56:59], v[84:87]
	v_mfma_f32_16x16x32_bf16 v[88:91], v[12:15], v[52:55], 0
	v_mfma_f32_16x16x32_bf16 v[88:91], v[16:19], v[56:59], v[88:91]
	v_mfma_f32_16x16x32_bf16 v[96:99], v[12:15], v[60:63], 0
	v_mfma_f32_16x16x32_bf16 v[96:99], v[16:19], v[64:67], v[96:99]
	v_mfma_f32_16x16x32_bf16 v[92:95], v[4:7], v[60:63], 0
	v_mfma_f32_16x16x32_bf16 v[92:95], v[8:11], v[64:67], v[92:95]
	s_setprio 0
	s_setprio 1
	v_mfma_f32_16x16x32_bf16 v[100:103], v[20:23], v[36:39], 0
	v_mfma_f32_16x16x32_bf16 v[36:39], v[28:31], v[36:39], 0
	v_mfma_f32_16x16x32_bf16 v[104:107], v[20:23], v[44:47], 0
	v_mfma_f32_16x16x32_bf16 v[44:47], v[28:31], v[44:47], 0
	v_mfma_f32_16x16x32_bf16 v[108:111], v[20:23], v[52:55], 0
	v_mfma_f32_16x16x32_bf16 v[52:55], v[28:31], v[52:55], 0
	v_mfma_f32_16x16x32_bf16 v[112:115], v[20:23], v[60:63], 0
	v_mfma_f32_16x16x32_bf16 v[60:63], v[28:31], v[60:63], 0
	v_mfma_f32_16x16x32_bf16 v[100:103], v[24:27], v[40:43], v[100:103]
	v_mfma_f32_16x16x32_bf16 v[40:43], v[32:35], v[40:43], v[36:39]
	v_mfma_f32_16x16x32_bf16 v[104:107], v[24:27], v[48:51], v[104:107]
	v_mfma_f32_16x16x32_bf16 v[48:51], v[32:35], v[48:51], v[44:47]
	v_mfma_f32_16x16x32_bf16 v[108:111], v[24:27], v[56:59], v[108:111]
	v_mfma_f32_16x16x32_bf16 v[56:59], v[32:35], v[56:59], v[52:55]
	s_setprio 2
	s_barrier
	v_mfma_f32_16x16x32_bf16 v[112:115], v[24:27], v[64:67], v[112:115]
	v_mfma_f32_16x16x32_bf16 v[64:67], v[32:35], v[64:67], v[60:63]
	s_setprio 0
	v_lshl_add_u64 v[186:187], s[8:9], 0, v[2:3]
	s_add_i32 s43, s43, s54
	v_mov_b32_e32 v191, v3
	v_lshl_add_u64 v[134:135], v[186:187], 0, s[80:81]
	s_mov_b32 m0, s43
	v_lshl_add_u64 v[246:247], s[8:9], 0, v[190:191]
	ds_read_b128 v[36:39], v233 offset:16384
	ds_read_b128 v[44:47], v233 offset:17408
	ds_read_b128 v[52:55], v233 offset:18432
	ds_read_b128 v[60:63], v233 offset:19456
	ds_read_b128 v[116:119], v233 offset:20480
	ds_read_b128 v[120:123], v233 offset:21504
	ds_read_b128 v[124:127], v233 offset:22528
	ds_read_b128 v[128:131], v233 offset:23552
	global_load_lds_dwordx4 v[134:135], off
	v_lshl_add_u64 v[134:135], v[246:247], 0, s[80:81]
	s_add_i32 m0, s43, 0x2000
	s_add_i32 s43, s71, s54
	global_load_lds_dwordx4 v[134:135], off
	s_mov_b32 m0, s43
	v_mov_b32_e32 v133, v3
	global_load_lds_dwordx4 v2, s[16:17]
	s_add_i32 m0, s43, 0x2000
	v_lshl_add_u64 v[248:249], s[6:7], 0, v[132:133]
	v_mov_b32_e32 v189, v3
	global_load_lds_dwordx4 v190, s[16:17]
	v_lshl_add_u64 v[134:135], v[248:249], 0, s[80:81]
	s_mov_b32 m0, s55
	v_lshl_add_u64 v[250:251], s[6:7], 0, v[188:189]
	global_load_lds_dwordx4 v[134:135], off
	v_lshl_add_u64 v[134:135], v[250:251], 0, s[80:81]
	s_mov_b32 m0, s56
	s_nop 0
	global_load_lds_dwordx4 v[134:135], off
	s_waitcnt vmcnt(8)
	s_waitcnt lgkmcnt(0)
	s_barrier
	s_setprio 1
	v_mfma_f32_16x16x32_bf16 v[134:137], v[4:7], v[36:39], 0
	v_mfma_f32_16x16x32_bf16 v[138:141], v[12:15], v[36:39], 0
	v_mfma_f32_16x16x32_bf16 v[142:145], v[4:7], v[52:55], 0
	v_mfma_f32_16x16x32_bf16 v[146:149], v[12:15], v[52:55], 0
	v_mfma_f32_16x16x32_bf16 v[150:153], v[4:7], v[116:119], 0
	v_mfma_f32_16x16x32_bf16 v[154:157], v[12:15], v[116:119], 0
	v_mfma_f32_16x16x32_bf16 v[4:7], v[4:7], v[124:127], 0
	v_mfma_f32_16x16x32_bf16 v[12:15], v[12:15], v[124:127], 0
	v_mfma_f32_16x16x32_bf16 v[134:137], v[8:11], v[44:47], v[134:137]
	v_mfma_f32_16x16x32_bf16 v[138:141], v[16:19], v[44:47], v[138:141]
	v_mfma_f32_16x16x32_bf16 v[142:145], v[8:11], v[60:63], v[142:145]
	v_mfma_f32_16x16x32_bf16 v[146:149], v[16:19], v[60:63], v[146:149]
	v_mfma_f32_16x16x32_bf16 v[150:153], v[8:11], v[120:123], v[150:153]
	v_mfma_f32_16x16x32_bf16 v[154:157], v[16:19], v[120:123], v[154:157]
	v_mfma_f32_16x16x32_bf16 v[158:161], v[8:11], v[128:131], v[4:7]
	v_mfma_f32_16x16x32_bf16 v[162:165], v[16:19], v[128:131], v[12:15]
	s_setprio 0
	s_setprio 1
	v_mfma_f32_16x16x32_bf16 v[4:7], v[20:23], v[36:39], 0
	v_mfma_f32_16x16x32_bf16 v[8:11], v[28:31], v[36:39], 0
	v_mfma_f32_16x16x32_bf16 v[12:15], v[20:23], v[52:55], 0
	v_mfma_f32_16x16x32_bf16 v[16:19], v[28:31], v[52:55], 0
	v_mfma_f32_16x16x32_bf16 v[36:39], v[20:23], v[116:119], 0
	v_mfma_f32_16x16x32_bf16 v[52:55], v[28:31], v[116:119], 0
	v_mfma_f32_16x16x32_bf16 v[20:23], v[20:23], v[124:127], 0
	v_mfma_f32_16x16x32_bf16 v[28:31], v[28:31], v[124:127], 0
	v_mfma_f32_16x16x32_bf16 v[116:119], v[24:27], v[44:47], v[4:7]
	v_mfma_f32_16x16x32_bf16 v[124:127], v[32:35], v[44:47], v[8:11]
	v_mfma_f32_16x16x32_bf16 v[174:177], v[24:27], v[120:123], v[36:39]
	v_mfma_f32_16x16x32_bf16 v[120:123], v[32:35], v[120:123], v[52:55]
	v_mfma_f32_16x16x32_bf16 v[178:181], v[24:27], v[128:131], v[20:23]
	v_mfma_f32_16x16x32_bf16 v[128:131], v[32:35], v[128:131], v[28:31]
	s_setprio 2
	s_barrier
	v_mfma_f32_16x16x32_bf16 v[166:169], v[24:27], v[60:63], v[12:15]
	v_mfma_f32_16x16x32_bf16 v[170:173], v[32:35], v[60:63], v[16:19]
	s_setprio 0
	s_add_i32 s43, 0, 0x18000
	v_add_u32_e32 v4, s43, v232
	s_add_i32 s71, 0, 0x1c000
	ds_read_b128 v[182:185], v4
	ds_read_b128 v[192:195], v4 offset:1024
	ds_read_b128 v[196:199], v4 offset:2048
	ds_read_b128 v[200:203], v4 offset:3072
	v_add_u32_e32 v4, s71, v232
	ds_read_b128 v[204:207], v4
	ds_read_b128 v[208:211], v4 offset:1024
	ds_read_b128 v[212:215], v4 offset:2048
	ds_read_b128 v[216:219], v4 offset:3072
	s_mov_b32 m0, s57
	ds_read_b128 v[44:47], v233 offset:32768
	ds_read_b128 v[52:55], v233 offset:33792
	ds_read_b128 v[60:63], v233 offset:34816
	ds_read_b128 v[220:223], v233 offset:35840
	ds_read_b128 v[224:227], v233 offset:36864
	ds_read_b128 v[234:237], v233 offset:37888
	ds_read_b128 v[238:241], v233 offset:38912
	ds_read_b128 v[242:245], v233 offset:39936
	global_load_lds_dwordx4 v132, s[26:27]
	s_mov_b32 m0, s58
	s_nop 0
	global_load_lds_dwordx4 v188, s[26:27]
	s_waitcnt vmcnt(8)
	s_waitcnt lgkmcnt(0)
	s_barrier
	s_setprio 1
	v_mfma_f32_16x16x32_bf16 v[4:7], v[182:185], v[44:47], v[68:71]
	v_mfma_f32_16x16x32_bf16 v[8:11], v[196:199], v[44:47], v[72:75]
	v_mfma_f32_16x16x32_bf16 v[12:15], v[182:185], v[60:63], v[76:79]
	v_mfma_f32_16x16x32_bf16 v[16:19], v[196:199], v[60:63], v[80:83]
	v_mfma_f32_16x16x32_bf16 v[20:23], v[182:185], v[224:227], v[84:87]
	v_mfma_f32_16x16x32_bf16 v[24:27], v[196:199], v[224:227], v[88:91]
	v_mfma_f32_16x16x32_bf16 v[28:31], v[182:185], v[238:241], v[92:95]
	v_mfma_f32_16x16x32_bf16 v[32:35], v[196:199], v[238:241], v[96:99]
	v_mfma_f32_16x16x32_bf16 v[4:7], v[192:195], v[52:55], v[4:7]
	v_mfma_f32_16x16x32_bf16 v[8:11], v[200:203], v[52:55], v[8:11]
	v_mfma_f32_16x16x32_bf16 v[12:15], v[192:195], v[220:223], v[12:15]
	v_mfma_f32_16x16x32_bf16 v[16:19], v[200:203], v[220:223], v[16:19]
	v_mfma_f32_16x16x32_bf16 v[20:23], v[192:195], v[234:237], v[20:23]
	v_mfma_f32_16x16x32_bf16 v[24:27], v[200:203], v[234:237], v[24:27]
	v_mfma_f32_16x16x32_bf16 v[28:31], v[192:195], v[242:245], v[28:31]
	v_mfma_f32_16x16x32_bf16 v[32:35], v[200:203], v[242:245], v[32:35]
	s_setprio 0
	s_setprio 1
	v_mfma_f32_16x16x32_bf16 v[36:39], v[204:207], v[44:47], v[100:103]
	v_mfma_f32_16x16x32_bf16 v[40:43], v[212:215], v[44:47], v[40:43]
	v_mfma_f32_16x16x32_bf16 v[36:39], v[208:211], v[52:55], v[36:39]
	v_mfma_f32_16x16x32_bf16 v[40:43], v[216:219], v[52:55], v[40:43]
	v_mfma_f32_16x16x32_bf16 v[44:47], v[204:207], v[60:63], v[104:107]
	v_mfma_f32_16x16x32_bf16 v[48:51], v[212:215], v[60:63], v[48:51]
	v_mfma_f32_16x16x32_bf16 v[52:55], v[204:207], v[224:227], v[108:111]
	v_mfma_f32_16x16x32_bf16 v[56:59], v[212:215], v[224:227], v[56:59]
	v_mfma_f32_16x16x32_bf16 v[60:63], v[204:207], v[238:241], v[112:115]
	v_mfma_f32_16x16x32_bf16 v[64:67], v[212:215], v[238:241], v[64:67]
	v_mfma_f32_16x16x32_bf16 v[44:47], v[208:211], v[220:223], v[44:47]
	v_mfma_f32_16x16x32_bf16 v[48:51], v[216:219], v[220:223], v[48:51]
	v_mfma_f32_16x16x32_bf16 v[52:55], v[208:211], v[234:237], v[52:55]
	v_mfma_f32_16x16x32_bf16 v[56:59], v[216:219], v[234:237], v[56:59]
	s_setprio 2
	s_barrier
	v_mfma_f32_16x16x32_bf16 v[60:63], v[208:211], v[242:245], v[60:63]
	v_mfma_f32_16x16x32_bf16 v[64:67], v[216:219], v[242:245], v[64:67]
	s_setprio 0
	s_add_i32 s43, s43, s54
	v_lshl_add_u64 v[68:69], v[186:187], 0, s[0:1]
	s_mov_b32 m0, s43
	ds_read_b128 v[104:107], v233 offset:49152
	ds_read_b128 v[108:111], v233 offset:50176
	ds_read_b128 v[112:115], v233 offset:51200
	ds_read_b128 v[220:223], v233 offset:52224
	ds_read_b128 v[224:227], v233 offset:53248
	ds_read_b128 v[234:237], v233 offset:54272
	ds_read_b128 v[238:241], v233 offset:55296
	ds_read_b128 v[242:245], v233 offset:56320
	global_load_lds_dwordx4 v[68:69], off
	v_lshl_add_u64 v[68:69], v[246:247], 0, s[0:1]
	s_add_i32 m0, s43, 0x2000
	s_add_i32 s43, s71, s54
	global_load_lds_dwordx4 v[68:69], off
	s_mov_b32 m0, s43
	v_lshl_add_u64 v[68:69], v[248:249], 0, s[0:1]
	global_load_lds_dwordx4 v2, s[28:29]
	s_add_i32 m0, s43, 0x2000
	s_nop 0
	global_load_lds_dwordx4 v190, s[28:29]
	s_mov_b32 m0, s62
	s_nop 0
	global_load_lds_dwordx4 v[68:69], off
	v_lshl_add_u64 v[68:69], v[250:251], 0, s[0:1]
	s_mov_b32 m0, s63
	s_nop 0
	global_load_lds_dwordx4 v[68:69], off
	s_waitcnt vmcnt(8)
	s_waitcnt lgkmcnt(0)
	s_barrier
	s_setprio 1
	v_mfma_f32_16x16x32_bf16 v[68:71], v[182:185], v[104:107], v[134:137]
	v_mfma_f32_16x16x32_bf16 v[72:75], v[196:199], v[104:107], v[138:141]
	v_mfma_f32_16x16x32_bf16 v[76:79], v[182:185], v[112:115], v[142:145]
	v_mfma_f32_16x16x32_bf16 v[80:83], v[196:199], v[112:115], v[146:149]
	v_mfma_f32_16x16x32_bf16 v[84:87], v[182:185], v[224:227], v[150:153]
	v_mfma_f32_16x16x32_bf16 v[88:91], v[196:199], v[224:227], v[154:157]
	v_mfma_f32_16x16x32_bf16 v[92:95], v[182:185], v[238:241], v[158:161]
	v_mfma_f32_16x16x32_bf16 v[96:99], v[196:199], v[238:241], v[162:165]
	v_mfma_f32_16x16x32_bf16 v[68:71], v[192:195], v[108:111], v[68:71]
	v_mfma_f32_16x16x32_bf16 v[72:75], v[200:203], v[108:111], v[72:75]
	v_mfma_f32_16x16x32_bf16 v[76:79], v[192:195], v[220:223], v[76:79]
	v_mfma_f32_16x16x32_bf16 v[80:83], v[200:203], v[220:223], v[80:83]
	v_mfma_f32_16x16x32_bf16 v[84:87], v[192:195], v[234:237], v[84:87]
	v_mfma_f32_16x16x32_bf16 v[88:91], v[200:203], v[234:237], v[88:91]
	v_mfma_f32_16x16x32_bf16 v[92:95], v[192:195], v[242:245], v[92:95]
	v_mfma_f32_16x16x32_bf16 v[96:99], v[200:203], v[242:245], v[96:99]
	s_setprio 0
	s_setprio 1
	v_mfma_f32_16x16x32_bf16 v[100:103], v[204:207], v[104:107], v[116:119]
	v_mfma_f32_16x16x32_bf16 v[104:107], v[212:215], v[104:107], v[124:127]
	v_mfma_f32_16x16x32_bf16 v[100:103], v[208:211], v[108:111], v[100:103]
	v_mfma_f32_16x16x32_bf16 v[104:107], v[216:219], v[108:111], v[104:107]
	v_mfma_f32_16x16x32_bf16 v[108:111], v[204:207], v[112:115], v[166:169]
	v_mfma_f32_16x16x32_bf16 v[112:115], v[212:215], v[112:115], v[170:173]
	v_mfma_f32_16x16x32_bf16 v[116:119], v[204:207], v[224:227], v[174:177]
	v_mfma_f32_16x16x32_bf16 v[120:123], v[212:215], v[224:227], v[120:123]
	v_mfma_f32_16x16x32_bf16 v[124:127], v[204:207], v[238:241], v[178:181]
	v_mfma_f32_16x16x32_bf16 v[128:131], v[212:215], v[238:241], v[128:131]
	v_mfma_f32_16x16x32_bf16 v[108:111], v[208:211], v[220:223], v[108:111]
	v_mfma_f32_16x16x32_bf16 v[112:115], v[216:219], v[220:223], v[112:115]
	v_mfma_f32_16x16x32_bf16 v[116:119], v[208:211], v[234:237], v[116:119]
	v_mfma_f32_16x16x32_bf16 v[120:123], v[216:219], v[234:237], v[120:123]
	s_setprio 2
	s_barrier
	v_mfma_f32_16x16x32_bf16 v[124:127], v[208:211], v[242:245], v[124:127]
	v_mfma_f32_16x16x32_bf16 v[128:131], v[216:219], v[242:245], v[128:131]
	s_setprio 0
	s_add_i32 s42, s42, 2
	s_cmp_ge_i32 s42, s38
	s_cbranch_scc0 .LBB0_641
	v_mov_b32_e32 v192, v2
	s_branch .LBB0_644

.LBB0_649:
	s_or_b32 s38, s28, 1
	s_lshl_b64 s[42:43], s[38:39], 7
	s_sub_u32 s38, 0, s42
	s_subb_u32 s42, 0, s43
	s_add_u32 s38, s6, s38
	s_addc_u32 s43, s7, s42
	s_add_i32 s71, 0, 0x10000
	s_add_i32 s72, 0, 0x14000
	v_add_u32_e32 v144, s71, v232
	v_add_u32_e32 v160, s72, v232
	s_waitcnt lgkmcnt(0)
	ds_read_b128 v[132:135], v144
	ds_read_b128 v[136:139], v144 offset:1024
	ds_read_b128 v[140:143], v144 offset:2048
	ds_read_b128 v[144:147], v144 offset:3072
	ds_read_b128 v[148:151], v160
	ds_read_b128 v[152:155], v160 offset:1024
	ds_read_b128 v[156:159], v160 offset:2048
	ds_read_b128 v[160:163], v160 offset:3072
	s_add_u32 s42, s38, 0x160000
	s_mov_b32 m0, s64
	v_add_u32_e32 v210, 0, v231
	s_addc_u32 s43, s43, 0
	ds_read_b128 v[164:167], v210
	ds_read_b128 v[168:171], v210 offset:1024
	ds_read_b128 v[172:175], v210 offset:2048
	ds_read_b128 v[176:179], v210 offset:3072
	ds_read_b128 v[180:183], v210 offset:4096
	ds_read_b128 v[184:187], v210 offset:5120
	ds_read_b128 v[194:197], v210 offset:6144
	ds_read_b128 v[198:201], v210 offset:7168
	global_load_lds_dwordx4 v2, s[42:43]
	s_mov_b32 m0, s65
	v_mov_b32_e32 v189, v3
	global_load_lds_dwordx4 v188, s[42:43]
	s_waitcnt vmcnt(8)
	s_waitcnt lgkmcnt(0)
	s_barrier
	s_setprio 1
	v_mfma_f32_16x16x32_bf16 v[4:7], v[132:135], v[164:167], v[4:7]
	v_mfma_f32_16x16x32_bf16 v[4:7], v[136:139], v[168:171], v[4:7]
	v_mfma_f32_16x16x32_bf16 v[8:11], v[144:147], v[168:171], v[8:11]
	v_mfma_f32_16x16x32_bf16 v[8:11], v[140:143], v[164:167], v[8:11]
	v_mfma_f32_16x16x32_bf16 v[16:19], v[140:143], v[172:175], v[16:19]
	v_mfma_f32_16x16x32_bf16 v[16:19], v[144:147], v[176:179], v[16:19]
	v_mfma_f32_16x16x32_bf16 v[12:15], v[136:139], v[176:179], v[12:15]
	v_mfma_f32_16x16x32_bf16 v[12:15], v[132:135], v[172:175], v[12:15]
	v_mfma_f32_16x16x32_bf16 v[20:23], v[132:135], v[180:183], v[20:23]
	v_mfma_f32_16x16x32_bf16 v[20:23], v[136:139], v[184:187], v[20:23]
	v_mfma_f32_16x16x32_bf16 v[24:27], v[144:147], v[184:187], v[24:27]
	v_mfma_f32_16x16x32_bf16 v[24:27], v[140:143], v[180:183], v[24:27]
	v_mfma_f32_16x16x32_bf16 v[32:35], v[140:143], v[194:197], v[32:35]
	v_mfma_f32_16x16x32_bf16 v[32:35], v[144:147], v[198:201], v[32:35]
	v_mfma_f32_16x16x32_bf16 v[28:31], v[136:139], v[198:201], v[28:31]
	v_mfma_f32_16x16x32_bf16 v[28:31], v[132:135], v[194:197], v[28:31]
	s_setprio 0
	s_setprio 1
	v_mfma_f32_16x16x32_bf16 v[36:39], v[148:151], v[164:167], v[36:39]
	v_mfma_f32_16x16x32_bf16 v[36:39], v[152:155], v[168:171], v[36:39]
	v_mfma_f32_16x16x32_bf16 v[40:43], v[160:163], v[168:171], v[40:43]
	v_mfma_f32_16x16x32_bf16 v[40:43], v[156:159], v[164:167], v[40:43]
	v_mfma_f32_16x16x32_bf16 v[48:51], v[156:159], v[172:175], v[48:51]
	v_mfma_f32_16x16x32_bf16 v[48:51], v[160:163], v[176:179], v[48:51]
	v_mfma_f32_16x16x32_bf16 v[44:47], v[152:155], v[176:179], v[44:47]
	v_mfma_f32_16x16x32_bf16 v[44:47], v[148:151], v[172:175], v[44:47]
	v_mfma_f32_16x16x32_bf16 v[52:55], v[148:151], v[180:183], v[52:55]
	v_mfma_f32_16x16x32_bf16 v[52:55], v[152:155], v[184:187], v[52:55]
	v_mfma_f32_16x16x32_bf16 v[56:59], v[160:163], v[184:187], v[56:59]
	v_mfma_f32_16x16x32_bf16 v[56:59], v[156:159], v[180:183], v[56:59]
	v_mfma_f32_16x16x32_bf16 v[64:67], v[156:159], v[194:197], v[64:67]
	v_mfma_f32_16x16x32_bf16 v[64:67], v[160:163], v[198:201], v[64:67]
	s_setprio 2
	s_barrier
	v_mfma_f32_16x16x32_bf16 v[60:63], v[152:155], v[198:201], v[60:63]
	v_mfma_f32_16x16x32_bf16 v[60:63], v[148:151], v[194:197], v[60:63]
	s_setprio 0
	s_add_i32 s38, s71, s54
	s_mov_b32 m0, s38
	ds_read_b128 v[164:167], v210 offset:16384
	ds_read_b128 v[168:171], v210 offset:17408
	ds_read_b128 v[172:175], v210 offset:18432
	ds_read_b128 v[176:179], v210 offset:19456
	ds_read_b128 v[180:183], v210 offset:20480
	ds_read_b128 v[184:187], v210 offset:21504
	ds_read_b128 v[194:197], v210 offset:22528
	ds_read_b128 v[198:201], v210 offset:23552
	global_load_lds_dwordx4 v192, s[16:17]
	s_add_i32 m0, s38, 0x2000
	s_add_u32 s42, s16, 0x160000
	s_addc_u32 s43, s17, 0
	s_add_i32 s38, s72, s54
	global_load_lds_dwordx4 v190, s[16:17]
	s_mov_b32 m0, s38
	v_mov_b32_e32 v193, v3
	global_load_lds_dwordx4 v192, s[42:43]
	s_add_i32 m0, s38, 0x2000
	v_mov_b32_e32 v191, v3
	global_load_lds_dwordx4 v190, s[42:43]
	s_mov_b32 m0, s55
	v_lshl_add_u64 v[202:203], s[16:17], 0, v[192:193]
	global_load_lds_dwordx4 v2, s[26:27]
	s_mov_b32 m0, s56
	v_lshl_add_u64 v[204:205], s[16:17], 0, v[190:191]
	global_load_lds_dwordx4 v188, s[26:27]
	s_waitcnt vmcnt(8)
	s_waitcnt lgkmcnt(0)
	v_lshl_add_u64 v[206:207], s[26:27], 0, v[2:3]
	v_lshl_add_u64 v[208:209], s[26:27], 0, v[188:189]
	s_barrier
	s_setprio 1
	v_mfma_f32_16x16x32_bf16 v[68:71], v[132:135], v[164:167], v[68:71]
	v_mfma_f32_16x16x32_bf16 v[68:71], v[136:139], v[168:171], v[68:71]
	v_mfma_f32_16x16x32_bf16 v[72:75], v[144:147], v[168:171], v[72:75]
	v_mfma_f32_16x16x32_bf16 v[72:75], v[140:143], v[164:167], v[72:75]
	v_mfma_f32_16x16x32_bf16 v[80:83], v[140:143], v[172:175], v[80:83]
	v_mfma_f32_16x16x32_bf16 v[80:83], v[144:147], v[176:179], v[80:83]
	v_mfma_f32_16x16x32_bf16 v[76:79], v[136:139], v[176:179], v[76:79]
	v_mfma_f32_16x16x32_bf16 v[76:79], v[132:135], v[172:175], v[76:79]
	v_mfma_f32_16x16x32_bf16 v[84:87], v[132:135], v[180:183], v[84:87]
	v_mfma_f32_16x16x32_bf16 v[84:87], v[136:139], v[184:187], v[84:87]
	v_mfma_f32_16x16x32_bf16 v[88:91], v[144:147], v[184:187], v[88:91]
	v_mfma_f32_16x16x32_bf16 v[88:91], v[140:143], v[180:183], v[88:91]
	v_mfma_f32_16x16x32_bf16 v[96:99], v[140:143], v[194:197], v[96:99]
	v_mfma_f32_16x16x32_bf16 v[96:99], v[144:147], v[198:201], v[96:99]
	v_mfma_f32_16x16x32_bf16 v[92:95], v[136:139], v[198:201], v[92:95]
	v_mfma_f32_16x16x32_bf16 v[92:95], v[132:135], v[194:197], v[92:95]
	s_setprio 0
	s_setprio 1
	v_mfma_f32_16x16x32_bf16 v[100:103], v[148:151], v[164:167], v[100:103]
	v_mfma_f32_16x16x32_bf16 v[100:103], v[152:155], v[168:171], v[100:103]
	v_mfma_f32_16x16x32_bf16 v[104:107], v[160:163], v[168:171], v[104:107]
	v_mfma_f32_16x16x32_bf16 v[104:107], v[156:159], v[164:167], v[104:107]
	v_mfma_f32_16x16x32_bf16 v[112:115], v[156:159], v[172:175], v[112:115]
	v_mfma_f32_16x16x32_bf16 v[112:115], v[160:163], v[176:179], v[112:115]
	v_mfma_f32_16x16x32_bf16 v[108:111], v[152:155], v[176:179], v[108:111]
	v_mfma_f32_16x16x32_bf16 v[108:111], v[148:151], v[172:175], v[108:111]
	v_mfma_f32_16x16x32_bf16 v[116:119], v[148:151], v[180:183], v[116:119]
	v_mfma_f32_16x16x32_bf16 v[116:119], v[152:155], v[184:187], v[116:119]
	v_mfma_f32_16x16x32_bf16 v[120:123], v[160:163], v[184:187], v[120:123]
	v_mfma_f32_16x16x32_bf16 v[120:123], v[156:159], v[180:183], v[120:123]
	v_mfma_f32_16x16x32_bf16 v[128:131], v[156:159], v[194:197], v[128:131]
	v_mfma_f32_16x16x32_bf16 v[128:131], v[160:163], v[198:201], v[128:131]
	s_setprio 2
	s_barrier
	v_mfma_f32_16x16x32_bf16 v[124:127], v[152:155], v[198:201], v[124:127]
	v_mfma_f32_16x16x32_bf16 v[124:127], v[148:151], v[194:197], v[124:127]
	s_setprio 0
	s_add_i32 s38, 0, 0x18000
	s_add_i32 s42, 0, 0x1c000
	v_add_u32_e32 v144, s38, v232
	v_add_u32_e32 v160, s42, v232
	ds_read_b128 v[132:135], v144
	ds_read_b128 v[136:139], v144 offset:1024
	ds_read_b128 v[140:143], v144 offset:2048
	ds_read_b128 v[144:147], v144 offset:3072
	ds_read_b128 v[148:151], v160
	ds_read_b128 v[152:155], v160 offset:1024
	ds_read_b128 v[156:159], v160 offset:2048
	ds_read_b128 v[160:163], v160 offset:3072
	s_add_u32 s26, s26, 0x160000
	s_addc_u32 s27, s27, 0
	s_mov_b32 m0, s57
	ds_read_b128 v[164:167], v210 offset:32768
	ds_read_b128 v[168:171], v210 offset:33792
	ds_read_b128 v[172:175], v210 offset:34816
	ds_read_b128 v[176:179], v210 offset:35840
	ds_read_b128 v[180:183], v210 offset:36864
	ds_read_b128 v[184:187], v210 offset:37888
	ds_read_b128 v[194:197], v210 offset:38912
	ds_read_b128 v[198:201], v210 offset:39936
	global_load_lds_dwordx4 v2, s[26:27]
	s_mov_b32 m0, s58
	s_nop 0
	global_load_lds_dwordx4 v188, s[26:27]
	s_waitcnt vmcnt(8)
	s_waitcnt lgkmcnt(0)
	s_barrier
	s_setprio 1
	v_mfma_f32_16x16x32_bf16 v[4:7], v[132:135], v[164:167], v[4:7]
	v_mfma_f32_16x16x32_bf16 v[4:7], v[136:139], v[168:171], v[4:7]
	v_mfma_f32_16x16x32_bf16 v[8:11], v[144:147], v[168:171], v[8:11]
	v_mfma_f32_16x16x32_bf16 v[8:11], v[140:143], v[164:167], v[8:11]
	v_mfma_f32_16x16x32_bf16 v[16:19], v[140:143], v[172:175], v[16:19]
	v_mfma_f32_16x16x32_bf16 v[16:19], v[144:147], v[176:179], v[16:19]
	v_mfma_f32_16x16x32_bf16 v[12:15], v[136:139], v[176:179], v[12:15]
	v_mfma_f32_16x16x32_bf16 v[12:15], v[132:135], v[172:175], v[12:15]
	v_mfma_f32_16x16x32_bf16 v[20:23], v[132:135], v[180:183], v[20:23]
	v_mfma_f32_16x16x32_bf16 v[20:23], v[136:139], v[184:187], v[20:23]
	v_mfma_f32_16x16x32_bf16 v[24:27], v[144:147], v[184:187], v[24:27]
	v_mfma_f32_16x16x32_bf16 v[24:27], v[140:143], v[180:183], v[24:27]
	v_mfma_f32_16x16x32_bf16 v[32:35], v[140:143], v[194:197], v[32:35]
	v_mfma_f32_16x16x32_bf16 v[32:35], v[144:147], v[198:201], v[32:35]
	v_mfma_f32_16x16x32_bf16 v[28:31], v[136:139], v[198:201], v[28:31]
	v_mfma_f32_16x16x32_bf16 v[28:31], v[132:135], v[194:197], v[28:31]
	s_setprio 0
	s_setprio 1
	v_mfma_f32_16x16x32_bf16 v[36:39], v[148:151], v[164:167], v[36:39]
	v_mfma_f32_16x16x32_bf16 v[36:39], v[152:155], v[168:171], v[36:39]
	v_mfma_f32_16x16x32_bf16 v[40:43], v[160:163], v[168:171], v[40:43]
	v_mfma_f32_16x16x32_bf16 v[40:43], v[156:159], v[164:167], v[40:43]
	v_mfma_f32_16x16x32_bf16 v[48:51], v[156:159], v[172:175], v[48:51]
	v_mfma_f32_16x16x32_bf16 v[48:51], v[160:163], v[176:179], v[48:51]
	v_mfma_f32_16x16x32_bf16 v[44:47], v[152:155], v[176:179], v[44:47]
	v_mfma_f32_16x16x32_bf16 v[44:47], v[148:151], v[172:175], v[44:47]
	v_mfma_f32_16x16x32_bf16 v[52:55], v[148:151], v[180:183], v[52:55]
	v_mfma_f32_16x16x32_bf16 v[52:55], v[152:155], v[184:187], v[52:55]
	v_mfma_f32_16x16x32_bf16 v[56:59], v[160:163], v[184:187], v[56:59]
	v_mfma_f32_16x16x32_bf16 v[56:59], v[156:159], v[180:183], v[56:59]
	v_mfma_f32_16x16x32_bf16 v[64:67], v[156:159], v[194:197], v[64:67]
	v_mfma_f32_16x16x32_bf16 v[64:67], v[160:163], v[198:201], v[64:67]
	s_setprio 2
	s_barrier
	v_mfma_f32_16x16x32_bf16 v[60:63], v[152:155], v[198:201], v[60:63]
	v_mfma_f32_16x16x32_bf16 v[60:63], v[148:151], v[194:197], v[60:63]
	s_setprio 0
	s_add_i32 s26, s38, s54
	v_lshl_add_u64 v[202:203], v[202:203], 0, s[4:5]
	s_mov_b32 m0, s26
	ds_read_b128 v[164:167], v210 offset:49152
	ds_read_b128 v[168:171], v210 offset:50176
	ds_read_b128 v[172:175], v210 offset:51200
	ds_read_b128 v[176:179], v210 offset:52224
	ds_read_b128 v[180:183], v210 offset:53248
	ds_read_b128 v[184:187], v210 offset:54272
	ds_read_b128 v[194:197], v210 offset:55296
	ds_read_b128 v[198:201], v210 offset:56320
	global_load_lds_dwordx4 v[202:203], off
	s_add_i32 m0, s26, 0x2000
	s_add_u32 s16, s16, 0x15ff80
	v_lshl_add_u64 v[202:203], v[204:205], 0, s[4:5]
	s_addc_u32 s17, s17, 0
	s_add_i32 s26, s42, s54
	global_load_lds_dwordx4 v[202:203], off
	s_mov_b32 m0, s26
	v_lshl_add_u64 v[202:203], v[206:207], 0, s[4:5]
	global_load_lds_dwordx4 v192, s[16:17]
	s_add_i32 m0, s26, 0x2000
	s_nop 0
	global_load_lds_dwordx4 v190, s[16:17]
	s_mov_b32 m0, s62
	s_nop 0
	global_load_lds_dwordx4 v[202:203], off
	v_lshl_add_u64 v[202:203], v[208:209], 0, s[4:5]
	s_mov_b32 m0, s63
	s_nop 0
	global_load_lds_dwordx4 v[202:203], off
	s_waitcnt vmcnt(8)
	s_waitcnt lgkmcnt(0)
	s_barrier
	s_setprio 1
	v_mfma_f32_16x16x32_bf16 v[68:71], v[132:135], v[164:167], v[68:71]
	v_mfma_f32_16x16x32_bf16 v[68:71], v[136:139], v[168:171], v[68:71]
	v_mfma_f32_16x16x32_bf16 v[72:75], v[144:147], v[168:171], v[72:75]
	v_mfma_f32_16x16x32_bf16 v[72:75], v[140:143], v[164:167], v[72:75]
	v_mfma_f32_16x16x32_bf16 v[80:83], v[140:143], v[172:175], v[80:83]
	v_mfma_f32_16x16x32_bf16 v[80:83], v[144:147], v[176:179], v[80:83]
	v_mfma_f32_16x16x32_bf16 v[76:79], v[136:139], v[176:179], v[76:79]
	v_mfma_f32_16x16x32_bf16 v[76:79], v[132:135], v[172:175], v[76:79]
	v_mfma_f32_16x16x32_bf16 v[84:87], v[132:135], v[180:183], v[84:87]
	v_mfma_f32_16x16x32_bf16 v[84:87], v[136:139], v[184:187], v[84:87]
	v_mfma_f32_16x16x32_bf16 v[88:91], v[144:147], v[184:187], v[88:91]
	v_mfma_f32_16x16x32_bf16 v[88:91], v[140:143], v[180:183], v[88:91]
	v_mfma_f32_16x16x32_bf16 v[96:99], v[140:143], v[194:197], v[96:99]
	v_mfma_f32_16x16x32_bf16 v[96:99], v[144:147], v[198:201], v[96:99]
	v_mfma_f32_16x16x32_bf16 v[92:95], v[136:139], v[198:201], v[92:95]
	v_mfma_f32_16x16x32_bf16 v[92:95], v[132:135], v[194:197], v[92:95]
	s_setprio 0
	s_setprio 1
	v_mfma_f32_16x16x32_bf16 v[100:103], v[148:151], v[164:167], v[100:103]
	v_mfma_f32_16x16x32_bf16 v[100:103], v[152:155], v[168:171], v[100:103]
	v_mfma_f32_16x16x32_bf16 v[104:107], v[160:163], v[168:171], v[104:107]
	v_mfma_f32_16x16x32_bf16 v[104:107], v[156:159], v[164:167], v[104:107]
	v_mfma_f32_16x16x32_bf16 v[112:115], v[156:159], v[172:175], v[112:115]
	v_mfma_f32_16x16x32_bf16 v[112:115], v[160:163], v[176:179], v[112:115]
	v_mfma_f32_16x16x32_bf16 v[108:111], v[152:155], v[176:179], v[108:111]
	v_mfma_f32_16x16x32_bf16 v[108:111], v[148:151], v[172:175], v[108:111]
	v_mfma_f32_16x16x32_bf16 v[116:119], v[148:151], v[180:183], v[116:119]
	v_mfma_f32_16x16x32_bf16 v[116:119], v[152:155], v[184:187], v[116:119]
	v_mfma_f32_16x16x32_bf16 v[120:123], v[160:163], v[184:187], v[120:123]
	v_mfma_f32_16x16x32_bf16 v[120:123], v[156:159], v[180:183], v[120:123]
	v_mfma_f32_16x16x32_bf16 v[128:131], v[156:159], v[194:197], v[128:131]
	v_mfma_f32_16x16x32_bf16 v[128:131], v[160:163], v[198:201], v[128:131]
	s_setprio 2
	s_barrier
	v_mfma_f32_16x16x32_bf16 v[124:127], v[152:155], v[198:201], v[124:127]
	v_mfma_f32_16x16x32_bf16 v[124:127], v[148:151], v[194:197], v[124:127]
	s_setprio 0
	s_cmpk_gt_u32 s28, 0x55
	s_cbranch_scc1 .LBB0_651
	s_mov_b32 s28, s29
	s_branch .LBB0_645

.LBB0_749:
	s_add_i32 s47, 0, 0x10000
	s_add_i32 s49, 0, 0x14000
	v_add_u32_e32 v16, s47, v147
	v_add_u32_e32 v32, s49, v147
	ds_read_b128 v[4:7], v16
	ds_read_b128 v[8:11], v16 offset:1024
	ds_read_b128 v[12:15], v16 offset:2048
	ds_read_b128 v[16:19], v16 offset:3072
	ds_read_b128 v[20:23], v32
	ds_read_b128 v[24:27], v32 offset:1024
	ds_read_b128 v[28:31], v32 offset:2048
	ds_read_b128 v[32:35], v32 offset:3072
	v_add_u32_e32 v231, 0, v146
	ds_read_b128 v[36:39], v231
	ds_read_b128 v[40:43], v231 offset:1024
	ds_read_b128 v[44:47], v231 offset:2048
	ds_read_b128 v[48:51], v231 offset:3072
	ds_read_b128 v[52:55], v231 offset:4096
	ds_read_b128 v[56:59], v231 offset:5120
	ds_read_b128 v[60:63], v231 offset:6144
	ds_read_b128 v[64:67], v231 offset:7168
	s_waitcnt vmcnt(8)
	s_waitcnt lgkmcnt(0)
	s_barrier
	s_setprio 1
	v_mfma_f32_16x16x32_f16 v[68:71], v[4:7], v[36:39], 0
	v_mfma_f32_16x16x32_f16 v[68:71], v[8:11], v[40:43], v[68:71]
	v_mfma_f32_16x16x32_f16 v[72:75], v[12:15], v[36:39], 0
	v_mfma_f32_16x16x32_f16 v[72:75], v[16:19], v[40:43], v[72:75]
	v_mfma_f32_16x16x32_f16 v[80:83], v[12:15], v[44:47], 0
	v_mfma_f32_16x16x32_f16 v[80:83], v[16:19], v[48:51], v[80:83]
	v_mfma_f32_16x16x32_f16 v[76:79], v[4:7], v[44:47], 0
	v_mfma_f32_16x16x32_f16 v[76:79], v[8:11], v[48:51], v[76:79]
	v_mfma_f32_16x16x32_f16 v[84:87], v[4:7], v[52:55], 0
	v_mfma_f32_16x16x32_f16 v[84:87], v[8:11], v[56:59], v[84:87]
	v_mfma_f32_16x16x32_f16 v[88:91], v[12:15], v[52:55], 0
	v_mfma_f32_16x16x32_f16 v[88:91], v[16:19], v[56:59], v[88:91]
	v_mfma_f32_16x16x32_f16 v[96:99], v[12:15], v[60:63], 0
	v_mfma_f32_16x16x32_f16 v[96:99], v[16:19], v[64:67], v[96:99]
	v_mfma_f32_16x16x32_f16 v[92:95], v[4:7], v[60:63], 0
	v_mfma_f32_16x16x32_f16 v[92:95], v[8:11], v[64:67], v[92:95]
	s_setprio 0
	s_setprio 1
	v_mfma_f32_16x16x32_f16 v[100:103], v[20:23], v[36:39], 0
	v_mfma_f32_16x16x32_f16 v[36:39], v[28:31], v[36:39], 0
	v_mfma_f32_16x16x32_f16 v[104:107], v[20:23], v[44:47], 0
	v_mfma_f32_16x16x32_f16 v[44:47], v[28:31], v[44:47], 0
	v_mfma_f32_16x16x32_f16 v[108:111], v[20:23], v[52:55], 0
	v_mfma_f32_16x16x32_f16 v[52:55], v[28:31], v[52:55], 0
	v_mfma_f32_16x16x32_f16 v[112:115], v[20:23], v[60:63], 0
	v_mfma_f32_16x16x32_f16 v[60:63], v[28:31], v[60:63], 0
	v_mfma_f32_16x16x32_f16 v[100:103], v[24:27], v[40:43], v[100:103]
	v_mfma_f32_16x16x32_f16 v[40:43], v[32:35], v[40:43], v[36:39]
	v_mfma_f32_16x16x32_f16 v[104:107], v[24:27], v[48:51], v[104:107]
	v_mfma_f32_16x16x32_f16 v[48:51], v[32:35], v[48:51], v[44:47]
	v_mfma_f32_16x16x32_f16 v[108:111], v[24:27], v[56:59], v[108:111]
	v_mfma_f32_16x16x32_f16 v[56:59], v[32:35], v[56:59], v[52:55]
	s_setprio 2
	s_barrier
	v_mfma_f32_16x16x32_f16 v[112:115], v[24:27], v[64:67], v[112:115]
	v_mfma_f32_16x16x32_f16 v[64:67], v[32:35], v[64:67], v[60:63]
	s_setprio 0
	v_lshl_add_u64 v[136:137], s[6:7], 0, v[2:3]
	s_add_i32 s47, s47, s62
	v_mov_b32_e32 v135, v3
	v_lshl_add_u64 v[140:141], v[136:137], 0, s[74:75]
	s_mov_b32 m0, s47
	v_lshl_add_u64 v[144:145], s[6:7], 0, v[134:135]
	ds_read_b128 v[36:39], v231 offset:16384
	ds_read_b128 v[44:47], v231 offset:17408
	ds_read_b128 v[52:55], v231 offset:18432
	ds_read_b128 v[60:63], v231 offset:19456
	ds_read_b128 v[116:119], v231 offset:20480
	ds_read_b128 v[120:123], v231 offset:21504
	ds_read_b128 v[124:127], v231 offset:22528
	ds_read_b128 v[128:131], v231 offset:23552
	global_load_lds_dwordx4 v[140:141], off
	v_lshl_add_u64 v[140:141], v[144:145], 0, s[74:75]
	s_add_i32 m0, s47, 0x2000
	s_add_i32 s47, s49, s62
	global_load_lds_dwordx4 v[140:141], off
	s_mov_b32 m0, s47
	v_mov_b32_e32 v139, v3
	global_load_lds_dwordx4 v2, s[16:17]
	s_add_i32 m0, s47, 0x2000
	v_lshl_add_u64 v[248:249], s[8:9], 0, v[138:139]
	v_mov_b32_e32 v133, v3
	global_load_lds_dwordx4 v134, s[16:17]
	v_lshl_add_u64 v[140:141], v[248:249], 0, s[74:75]
	s_mov_b32 m0, s63
	v_lshl_add_u64 v[250:251], s[8:9], 0, v[132:133]
	global_load_lds_dwordx4 v[140:141], off
	v_lshl_add_u64 v[140:141], v[250:251], 0, s[74:75]
	s_mov_b32 m0, s64
	s_nop 0
	global_load_lds_dwordx4 v[140:141], off
	s_waitcnt vmcnt(8)
	s_waitcnt lgkmcnt(0)
	s_barrier
	s_setprio 1
	v_mfma_f32_16x16x32_f16 v[140:143], v[4:7], v[36:39], 0
	v_mfma_f32_16x16x32_f16 v[148:151], v[12:15], v[36:39], 0
	v_mfma_f32_16x16x32_f16 v[152:155], v[4:7], v[52:55], 0
	v_mfma_f32_16x16x32_f16 v[156:159], v[12:15], v[52:55], 0
	v_mfma_f32_16x16x32_f16 v[160:163], v[4:7], v[116:119], 0
	v_mfma_f32_16x16x32_f16 v[164:167], v[12:15], v[116:119], 0
	v_mfma_f32_16x16x32_f16 v[4:7], v[4:7], v[124:127], 0
	v_mfma_f32_16x16x32_f16 v[12:15], v[12:15], v[124:127], 0
	v_mfma_f32_16x16x32_f16 v[140:143], v[8:11], v[44:47], v[140:143]
	v_mfma_f32_16x16x32_f16 v[148:151], v[16:19], v[44:47], v[148:151]
	v_mfma_f32_16x16x32_f16 v[152:155], v[8:11], v[60:63], v[152:155]
	v_mfma_f32_16x16x32_f16 v[156:159], v[16:19], v[60:63], v[156:159]
	v_mfma_f32_16x16x32_f16 v[160:163], v[8:11], v[120:123], v[160:163]
	v_mfma_f32_16x16x32_f16 v[164:167], v[16:19], v[120:123], v[164:167]
	v_mfma_f32_16x16x32_f16 v[168:171], v[8:11], v[128:131], v[4:7]
	v_mfma_f32_16x16x32_f16 v[172:175], v[16:19], v[128:131], v[12:15]
	s_setprio 0
	s_setprio 1
	v_mfma_f32_16x16x32_f16 v[4:7], v[20:23], v[36:39], 0
	v_mfma_f32_16x16x32_f16 v[8:11], v[28:31], v[36:39], 0
	v_mfma_f32_16x16x32_f16 v[12:15], v[20:23], v[52:55], 0
	v_mfma_f32_16x16x32_f16 v[16:19], v[28:31], v[52:55], 0
	v_mfma_f32_16x16x32_f16 v[36:39], v[20:23], v[116:119], 0
	v_mfma_f32_16x16x32_f16 v[52:55], v[28:31], v[116:119], 0
	v_mfma_f32_16x16x32_f16 v[20:23], v[20:23], v[124:127], 0
	v_mfma_f32_16x16x32_f16 v[28:31], v[28:31], v[124:127], 0
	v_mfma_f32_16x16x32_f16 v[116:119], v[24:27], v[44:47], v[4:7]
	v_mfma_f32_16x16x32_f16 v[124:127], v[32:35], v[44:47], v[8:11]
	v_mfma_f32_16x16x32_f16 v[184:187], v[24:27], v[120:123], v[36:39]
	v_mfma_f32_16x16x32_f16 v[120:123], v[32:35], v[120:123], v[52:55]
	v_mfma_f32_16x16x32_f16 v[188:191], v[24:27], v[128:131], v[20:23]
	v_mfma_f32_16x16x32_f16 v[128:131], v[32:35], v[128:131], v[28:31]
	s_setprio 2
	s_barrier
	v_mfma_f32_16x16x32_f16 v[176:179], v[24:27], v[60:63], v[12:15]
	v_mfma_f32_16x16x32_f16 v[180:183], v[32:35], v[60:63], v[16:19]
	s_setprio 0
	s_add_i32 s47, 0, 0x18000
	v_add_u32_e32 v4, s47, v147
	s_add_i32 s49, 0, 0x1c000
	ds_read_b128 v[192:195], v4
	ds_read_b128 v[196:199], v4 offset:1024
	ds_read_b128 v[200:203], v4 offset:2048
	ds_read_b128 v[204:207], v4 offset:3072
	v_add_u32_e32 v4, s49, v147
	ds_read_b128 v[208:211], v4
	ds_read_b128 v[212:215], v4 offset:1024
	ds_read_b128 v[216:219], v4 offset:2048
	ds_read_b128 v[220:223], v4 offset:3072
	s_mov_b32 m0, s65
	ds_read_b128 v[44:47], v231 offset:32768
	ds_read_b128 v[52:55], v231 offset:33792
	ds_read_b128 v[60:63], v231 offset:34816
	ds_read_b128 v[224:227], v231 offset:35840
	ds_read_b128 v[232:235], v231 offset:36864
	ds_read_b128 v[236:239], v231 offset:37888
	ds_read_b128 v[240:243], v231 offset:38912
	ds_read_b128 v[244:247], v231 offset:39936
	global_load_lds_dwordx4 v138, s[26:27]
	s_mov_b32 m0, s66
	s_nop 0
	global_load_lds_dwordx4 v132, s[26:27]
	s_waitcnt vmcnt(8)
	s_waitcnt lgkmcnt(0)
	s_barrier
	s_setprio 1
	v_mfma_f32_16x16x32_f16 v[4:7], v[192:195], v[44:47], v[68:71]
	v_mfma_f32_16x16x32_f16 v[8:11], v[200:203], v[44:47], v[72:75]
	v_mfma_f32_16x16x32_f16 v[12:15], v[192:195], v[60:63], v[76:79]
	v_mfma_f32_16x16x32_f16 v[16:19], v[200:203], v[60:63], v[80:83]
	v_mfma_f32_16x16x32_f16 v[20:23], v[192:195], v[232:235], v[84:87]
	v_mfma_f32_16x16x32_f16 v[24:27], v[200:203], v[232:235], v[88:91]
	v_mfma_f32_16x16x32_f16 v[28:31], v[192:195], v[240:243], v[92:95]
	v_mfma_f32_16x16x32_f16 v[32:35], v[200:203], v[240:243], v[96:99]
	v_mfma_f32_16x16x32_f16 v[4:7], v[196:199], v[52:55], v[4:7]
	v_mfma_f32_16x16x32_f16 v[8:11], v[204:207], v[52:55], v[8:11]
	v_mfma_f32_16x16x32_f16 v[12:15], v[196:199], v[224:227], v[12:15]
	v_mfma_f32_16x16x32_f16 v[16:19], v[204:207], v[224:227], v[16:19]
	v_mfma_f32_16x16x32_f16 v[20:23], v[196:199], v[236:239], v[20:23]
	v_mfma_f32_16x16x32_f16 v[24:27], v[204:207], v[236:239], v[24:27]
	v_mfma_f32_16x16x32_f16 v[28:31], v[196:199], v[244:247], v[28:31]
	v_mfma_f32_16x16x32_f16 v[32:35], v[204:207], v[244:247], v[32:35]
	s_setprio 0
	s_setprio 1
	v_mfma_f32_16x16x32_f16 v[36:39], v[208:211], v[44:47], v[100:103]
	v_mfma_f32_16x16x32_f16 v[40:43], v[216:219], v[44:47], v[40:43]
	v_mfma_f32_16x16x32_f16 v[36:39], v[212:215], v[52:55], v[36:39]
	v_mfma_f32_16x16x32_f16 v[40:43], v[220:223], v[52:55], v[40:43]
	v_mfma_f32_16x16x32_f16 v[44:47], v[208:211], v[60:63], v[104:107]
	v_mfma_f32_16x16x32_f16 v[48:51], v[216:219], v[60:63], v[48:51]
	v_mfma_f32_16x16x32_f16 v[52:55], v[208:211], v[232:235], v[108:111]
	v_mfma_f32_16x16x32_f16 v[56:59], v[216:219], v[232:235], v[56:59]
	v_mfma_f32_16x16x32_f16 v[60:63], v[208:211], v[240:243], v[112:115]
	v_mfma_f32_16x16x32_f16 v[64:67], v[216:219], v[240:243], v[64:67]
	v_mfma_f32_16x16x32_f16 v[44:47], v[212:215], v[224:227], v[44:47]
	v_mfma_f32_16x16x32_f16 v[48:51], v[220:223], v[224:227], v[48:51]
	v_mfma_f32_16x16x32_f16 v[52:55], v[212:215], v[236:239], v[52:55]
	v_mfma_f32_16x16x32_f16 v[56:59], v[220:223], v[236:239], v[56:59]
	s_setprio 2
	s_barrier
	v_mfma_f32_16x16x32_f16 v[60:63], v[212:215], v[244:247], v[60:63]
	v_mfma_f32_16x16x32_f16 v[64:67], v[220:223], v[244:247], v[64:67]
	s_setprio 0
	s_add_i32 s47, s47, s62
	v_lshl_add_u64 v[68:69], v[136:137], 0, s[24:25]
	s_mov_b32 m0, s47
	ds_read_b128 v[104:107], v231 offset:49152
	ds_read_b128 v[108:111], v231 offset:50176
	ds_read_b128 v[112:115], v231 offset:51200
	ds_read_b128 v[224:227], v231 offset:52224
	ds_read_b128 v[232:235], v231 offset:53248
	ds_read_b128 v[236:239], v231 offset:54272
	ds_read_b128 v[240:243], v231 offset:55296
	ds_read_b128 v[244:247], v231 offset:56320
	global_load_lds_dwordx4 v[68:69], off
	v_lshl_add_u64 v[68:69], v[144:145], 0, s[24:25]
	s_add_i32 m0, s47, 0x2000
	s_add_i32 s47, s49, s62
	global_load_lds_dwordx4 v[68:69], off
	s_mov_b32 m0, s47
	v_lshl_add_u64 v[68:69], v[248:249], 0, s[24:25]
	global_load_lds_dwordx4 v2, s[28:29]
	s_add_i32 m0, s47, 0x2000
	s_nop 0
	global_load_lds_dwordx4 v134, s[28:29]
	s_mov_b32 m0, s69
	s_nop 0
	global_load_lds_dwordx4 v[68:69], off
	v_lshl_add_u64 v[68:69], v[250:251], 0, s[24:25]
	s_mov_b32 m0, s70
	s_nop 0
	global_load_lds_dwordx4 v[68:69], off
	s_waitcnt vmcnt(8)
	s_waitcnt lgkmcnt(0)
	s_barrier
	s_setprio 1
	v_mfma_f32_16x16x32_f16 v[68:71], v[192:195], v[104:107], v[140:143]
	v_mfma_f32_16x16x32_f16 v[72:75], v[200:203], v[104:107], v[148:151]
	v_mfma_f32_16x16x32_f16 v[76:79], v[192:195], v[112:115], v[152:155]
	v_mfma_f32_16x16x32_f16 v[80:83], v[200:203], v[112:115], v[156:159]
	v_mfma_f32_16x16x32_f16 v[84:87], v[192:195], v[232:235], v[160:163]
	v_mfma_f32_16x16x32_f16 v[88:91], v[200:203], v[232:235], v[164:167]
	v_mfma_f32_16x16x32_f16 v[92:95], v[192:195], v[240:243], v[168:171]
	v_mfma_f32_16x16x32_f16 v[96:99], v[200:203], v[240:243], v[172:175]
	v_mfma_f32_16x16x32_f16 v[68:71], v[196:199], v[108:111], v[68:71]
	v_mfma_f32_16x16x32_f16 v[72:75], v[204:207], v[108:111], v[72:75]
	v_mfma_f32_16x16x32_f16 v[76:79], v[196:199], v[224:227], v[76:79]
	v_mfma_f32_16x16x32_f16 v[80:83], v[204:207], v[224:227], v[80:83]
	v_mfma_f32_16x16x32_f16 v[84:87], v[196:199], v[236:239], v[84:87]
	v_mfma_f32_16x16x32_f16 v[88:91], v[204:207], v[236:239], v[88:91]
	v_mfma_f32_16x16x32_f16 v[92:95], v[196:199], v[244:247], v[92:95]
	v_mfma_f32_16x16x32_f16 v[96:99], v[204:207], v[244:247], v[96:99]
	s_setprio 0
	s_setprio 1
	v_mfma_f32_16x16x32_f16 v[100:103], v[208:211], v[104:107], v[116:119]
	v_mfma_f32_16x16x32_f16 v[104:107], v[216:219], v[104:107], v[124:127]
	v_mfma_f32_16x16x32_f16 v[100:103], v[212:215], v[108:111], v[100:103]
	v_mfma_f32_16x16x32_f16 v[104:107], v[220:223], v[108:111], v[104:107]
	v_mfma_f32_16x16x32_f16 v[108:111], v[208:211], v[112:115], v[176:179]
	v_mfma_f32_16x16x32_f16 v[112:115], v[216:219], v[112:115], v[180:183]
	v_mfma_f32_16x16x32_f16 v[116:119], v[208:211], v[232:235], v[184:187]
	v_mfma_f32_16x16x32_f16 v[120:123], v[216:219], v[232:235], v[120:123]
	v_mfma_f32_16x16x32_f16 v[124:127], v[208:211], v[240:243], v[188:191]
	v_mfma_f32_16x16x32_f16 v[128:131], v[216:219], v[240:243], v[128:131]
	v_mfma_f32_16x16x32_f16 v[108:111], v[212:215], v[224:227], v[108:111]
	v_mfma_f32_16x16x32_f16 v[112:115], v[220:223], v[224:227], v[112:115]
	v_mfma_f32_16x16x32_f16 v[116:119], v[212:215], v[236:239], v[116:119]
	v_mfma_f32_16x16x32_f16 v[120:123], v[220:223], v[236:239], v[120:123]
	s_setprio 2
	s_barrier
	v_mfma_f32_16x16x32_f16 v[124:127], v[212:215], v[244:247], v[124:127]
	v_mfma_f32_16x16x32_f16 v[128:131], v[220:223], v[244:247], v[128:131]
	s_setprio 0
	s_add_i32 s45, s45, 2
	s_cmp_ge_i32 s45, s44
	s_cbranch_scc0 .LBB0_749
	v_mov_b32_e32 v136, v2
	s_branch .LBB0_752

.LBB0_753:
	s_add_u32 s6, s8, 0xfff80080
	s_addc_u32 s7, s9, -1
	s_add_i32 s29, 0, 0x10000
	s_cmp_eq_u32 s28, 28
	s_cselect_b32 s17, s13, s7
	s_cselect_b32 s16, s12, s6
	v_add_u32_e32 v133, s29, v147
	s_cselect_b32 s7, s15, s27
	s_cselect_b32 s6, s14, s26
	s_add_i32 s47, 0, 0x14000
	ds_read_b128 v[138:141], v133
	ds_read_b128 v[142:145], v133 offset:1024
	ds_read_b128 v[148:151], v133 offset:2048
	ds_read_b128 v[152:155], v133 offset:3072
	v_add_u32_e32 v133, s47, v147
	ds_read_b128 v[156:159], v133
	ds_read_b128 v[160:163], v133 offset:1024
	ds_read_b128 v[164:167], v133 offset:2048
	ds_read_b128 v[168:171], v133 offset:3072
	s_mov_b32 m0, s71
	v_add_u32_e32 v212, 0, v146
	ds_read_b128 v[172:175], v212
	ds_read_b128 v[176:179], v212 offset:1024
	ds_read_b128 v[180:183], v212 offset:2048
	ds_read_b128 v[184:187], v212 offset:3072
	ds_read_b128 v[188:191], v212 offset:4096
	ds_read_b128 v[192:195], v212 offset:5120
	ds_read_b128 v[196:199], v212 offset:6144
	ds_read_b128 v[200:203], v212 offset:7168
	global_load_lds_dwordx4 v2, s[8:9]
	s_mov_b32 m0, s72
	v_mov_b32_e32 v133, v3
	global_load_lds_dwordx4 v132, s[8:9]
	s_waitcnt vmcnt(8)
	s_waitcnt lgkmcnt(0)
	s_barrier
	s_setprio 1
	v_mfma_f32_16x16x32_f16 v[4:7], v[138:141], v[172:175], v[4:7]
	v_mfma_f32_16x16x32_f16 v[4:7], v[142:145], v[176:179], v[4:7]
	v_mfma_f32_16x16x32_f16 v[8:11], v[152:155], v[176:179], v[8:11]
	v_mfma_f32_16x16x32_f16 v[8:11], v[148:151], v[172:175], v[8:11]
	v_mfma_f32_16x16x32_f16 v[16:19], v[148:151], v[180:183], v[16:19]
	v_mfma_f32_16x16x32_f16 v[16:19], v[152:155], v[184:187], v[16:19]
	v_mfma_f32_16x16x32_f16 v[12:15], v[142:145], v[184:187], v[12:15]
	v_mfma_f32_16x16x32_f16 v[12:15], v[138:141], v[180:183], v[12:15]
	v_mfma_f32_16x16x32_f16 v[20:23], v[138:141], v[188:191], v[20:23]
	v_mfma_f32_16x16x32_f16 v[20:23], v[142:145], v[192:195], v[20:23]
	v_mfma_f32_16x16x32_f16 v[24:27], v[152:155], v[192:195], v[24:27]
	v_mfma_f32_16x16x32_f16 v[24:27], v[148:151], v[188:191], v[24:27]
	v_mfma_f32_16x16x32_f16 v[32:35], v[148:151], v[196:199], v[32:35]
	v_mfma_f32_16x16x32_f16 v[32:35], v[152:155], v[200:203], v[32:35]
	v_mfma_f32_16x16x32_f16 v[28:31], v[142:145], v[200:203], v[28:31]
	v_mfma_f32_16x16x32_f16 v[28:31], v[138:141], v[196:199], v[28:31]
	s_setprio 0
	s_setprio 1
	v_mfma_f32_16x16x32_f16 v[36:39], v[156:159], v[172:175], v[36:39]
	v_mfma_f32_16x16x32_f16 v[36:39], v[160:163], v[176:179], v[36:39]
	v_mfma_f32_16x16x32_f16 v[40:43], v[168:171], v[176:179], v[40:43]
	v_mfma_f32_16x16x32_f16 v[40:43], v[164:167], v[172:175], v[40:43]
	v_mfma_f32_16x16x32_f16 v[48:51], v[164:167], v[180:183], v[48:51]
	v_mfma_f32_16x16x32_f16 v[48:51], v[168:171], v[184:187], v[48:51]
	v_mfma_f32_16x16x32_f16 v[44:47], v[160:163], v[184:187], v[44:47]
	v_mfma_f32_16x16x32_f16 v[44:47], v[156:159], v[180:183], v[44:47]
	v_mfma_f32_16x16x32_f16 v[52:55], v[156:159], v[188:191], v[52:55]
	v_mfma_f32_16x16x32_f16 v[52:55], v[160:163], v[192:195], v[52:55]
	v_mfma_f32_16x16x32_f16 v[56:59], v[168:171], v[192:195], v[56:59]
	v_mfma_f32_16x16x32_f16 v[56:59], v[164:167], v[188:191], v[56:59]
	v_mfma_f32_16x16x32_f16 v[64:67], v[164:167], v[196:199], v[64:67]
	v_mfma_f32_16x16x32_f16 v[64:67], v[168:171], v[200:203], v[64:67]
	s_setprio 2
	s_barrier
	v_mfma_f32_16x16x32_f16 v[60:63], v[160:163], v[200:203], v[60:63]
	v_mfma_f32_16x16x32_f16 v[60:63], v[156:159], v[196:199], v[60:63]
	s_setprio 0
	s_add_i32 s29, s29, s62
	s_mov_b32 m0, s29
	ds_read_b128 v[172:175], v212 offset:16384
	ds_read_b128 v[176:179], v212 offset:17408
	ds_read_b128 v[180:183], v212 offset:18432
	ds_read_b128 v[184:187], v212 offset:19456
	ds_read_b128 v[188:191], v212 offset:20480
	ds_read_b128 v[192:195], v212 offset:21504
	ds_read_b128 v[196:199], v212 offset:22528
	ds_read_b128 v[200:203], v212 offset:23552
	global_load_lds_dwordx4 v136, s[6:7]
	s_add_i32 m0, s29, 0x2000
	s_add_u32 s44, s6, 0x80000
	s_addc_u32 s45, s7, 0
	s_add_i32 s29, s47, s62
	global_load_lds_dwordx4 v134, s[6:7]
	s_mov_b32 m0, s29
	v_mov_b32_e32 v137, v3
	global_load_lds_dwordx4 v136, s[44:45]
	s_add_i32 m0, s29, 0x2000
	v_mov_b32_e32 v135, v3
	global_load_lds_dwordx4 v134, s[44:45]
	s_mov_b32 m0, s63
	v_lshl_add_u64 v[204:205], s[6:7], 0, v[136:137]
	global_load_lds_dwordx4 v2, s[16:17]
	s_mov_b32 m0, s64
	v_lshl_add_u64 v[206:207], s[6:7], 0, v[134:135]
	global_load_lds_dwordx4 v132, s[16:17]
	s_waitcnt vmcnt(8)
	s_waitcnt lgkmcnt(0)
	v_lshl_add_u64 v[208:209], s[16:17], 0, v[2:3]
	v_lshl_add_u64 v[210:211], s[16:17], 0, v[132:133]
	s_barrier
	s_setprio 1
	v_mfma_f32_16x16x32_f16 v[68:71], v[138:141], v[172:175], v[68:71]
	v_mfma_f32_16x16x32_f16 v[68:71], v[142:145], v[176:179], v[68:71]
	v_mfma_f32_16x16x32_f16 v[72:75], v[152:155], v[176:179], v[72:75]
	v_mfma_f32_16x16x32_f16 v[72:75], v[148:151], v[172:175], v[72:75]
	v_mfma_f32_16x16x32_f16 v[80:83], v[148:151], v[180:183], v[80:83]
	v_mfma_f32_16x16x32_f16 v[80:83], v[152:155], v[184:187], v[80:83]
	v_mfma_f32_16x16x32_f16 v[76:79], v[142:145], v[184:187], v[76:79]
	v_mfma_f32_16x16x32_f16 v[76:79], v[138:141], v[180:183], v[76:79]
	v_mfma_f32_16x16x32_f16 v[84:87], v[138:141], v[188:191], v[84:87]
	v_mfma_f32_16x16x32_f16 v[84:87], v[142:145], v[192:195], v[84:87]
	v_mfma_f32_16x16x32_f16 v[88:91], v[152:155], v[192:195], v[88:91]
	v_mfma_f32_16x16x32_f16 v[88:91], v[148:151], v[188:191], v[88:91]
	v_mfma_f32_16x16x32_f16 v[96:99], v[148:151], v[196:199], v[96:99]
	v_mfma_f32_16x16x32_f16 v[96:99], v[152:155], v[200:203], v[96:99]
	v_mfma_f32_16x16x32_f16 v[92:95], v[142:145], v[200:203], v[92:95]
	v_mfma_f32_16x16x32_f16 v[92:95], v[138:141], v[196:199], v[92:95]
	s_setprio 0
	s_setprio 1
	v_mfma_f32_16x16x32_f16 v[100:103], v[156:159], v[172:175], v[100:103]
	v_mfma_f32_16x16x32_f16 v[100:103], v[160:163], v[176:179], v[100:103]
	v_mfma_f32_16x16x32_f16 v[104:107], v[168:171], v[176:179], v[104:107]
	v_mfma_f32_16x16x32_f16 v[104:107], v[164:167], v[172:175], v[104:107]
	v_mfma_f32_16x16x32_f16 v[112:115], v[164:167], v[180:183], v[112:115]
	v_mfma_f32_16x16x32_f16 v[112:115], v[168:171], v[184:187], v[112:115]
	v_mfma_f32_16x16x32_f16 v[108:111], v[160:163], v[184:187], v[108:111]
	v_mfma_f32_16x16x32_f16 v[108:111], v[156:159], v[180:183], v[108:111]
	v_mfma_f32_16x16x32_f16 v[116:119], v[156:159], v[188:191], v[116:119]
	v_mfma_f32_16x16x32_f16 v[116:119], v[160:163], v[192:195], v[116:119]
	v_mfma_f32_16x16x32_f16 v[120:123], v[168:171], v[192:195], v[120:123]
	v_mfma_f32_16x16x32_f16 v[120:123], v[164:167], v[188:191], v[120:123]
	v_mfma_f32_16x16x32_f16 v[128:131], v[164:167], v[196:199], v[128:131]
	v_mfma_f32_16x16x32_f16 v[128:131], v[168:171], v[200:203], v[128:131]
	s_setprio 2
	s_barrier
	v_mfma_f32_16x16x32_f16 v[124:127], v[160:163], v[200:203], v[124:127]
	v_mfma_f32_16x16x32_f16 v[124:127], v[156:159], v[196:199], v[124:127]
	s_setprio 0
	s_add_i32 s29, 0, 0x18000
	v_add_u32_e32 v135, s29, v147
	s_add_i32 s44, 0, 0x1c000
	ds_read_b128 v[138:141], v135
	ds_read_b128 v[142:145], v135 offset:1024
	ds_read_b128 v[148:151], v135 offset:2048
	ds_read_b128 v[152:155], v135 offset:3072
	v_add_u32_e32 v135, s44, v147
	ds_read_b128 v[156:159], v135
	ds_read_b128 v[160:163], v135 offset:1024
	ds_read_b128 v[164:167], v135 offset:2048
	ds_read_b128 v[168:171], v135 offset:3072
	s_add_u32 s16, s16, 0x80000
	s_addc_u32 s17, s17, 0
	s_mov_b32 m0, s65
	ds_read_b128 v[172:175], v212 offset:32768
	ds_read_b128 v[176:179], v212 offset:33792
	ds_read_b128 v[180:183], v212 offset:34816
	ds_read_b128 v[184:187], v212 offset:35840
	ds_read_b128 v[188:191], v212 offset:36864
	ds_read_b128 v[192:195], v212 offset:37888
	ds_read_b128 v[196:199], v212 offset:38912
	ds_read_b128 v[200:203], v212 offset:39936
	global_load_lds_dwordx4 v2, s[16:17]
	s_mov_b32 m0, s66
	s_nop 0
	global_load_lds_dwordx4 v132, s[16:17]
	s_waitcnt vmcnt(8)
	s_waitcnt lgkmcnt(0)
	s_barrier
	s_setprio 1
	v_mfma_f32_16x16x32_f16 v[4:7], v[138:141], v[172:175], v[4:7]
	v_mfma_f32_16x16x32_f16 v[4:7], v[142:145], v[176:179], v[4:7]
	v_mfma_f32_16x16x32_f16 v[8:11], v[152:155], v[176:179], v[8:11]
	v_mfma_f32_16x16x32_f16 v[8:11], v[148:151], v[172:175], v[8:11]
	v_mfma_f32_16x16x32_f16 v[16:19], v[148:151], v[180:183], v[16:19]
	v_mfma_f32_16x16x32_f16 v[16:19], v[152:155], v[184:187], v[16:19]
	v_mfma_f32_16x16x32_f16 v[12:15], v[142:145], v[184:187], v[12:15]
	v_mfma_f32_16x16x32_f16 v[12:15], v[138:141], v[180:183], v[12:15]
	v_mfma_f32_16x16x32_f16 v[20:23], v[138:141], v[188:191], v[20:23]
	v_mfma_f32_16x16x32_f16 v[20:23], v[142:145], v[192:195], v[20:23]
	v_mfma_f32_16x16x32_f16 v[24:27], v[152:155], v[192:195], v[24:27]
	v_mfma_f32_16x16x32_f16 v[24:27], v[148:151], v[188:191], v[24:27]
	v_mfma_f32_16x16x32_f16 v[32:35], v[148:151], v[196:199], v[32:35]
	v_mfma_f32_16x16x32_f16 v[32:35], v[152:155], v[200:203], v[32:35]
	v_mfma_f32_16x16x32_f16 v[28:31], v[142:145], v[200:203], v[28:31]
	v_mfma_f32_16x16x32_f16 v[28:31], v[138:141], v[196:199], v[28:31]
	s_setprio 0
	s_setprio 1
	v_mfma_f32_16x16x32_f16 v[36:39], v[156:159], v[172:175], v[36:39]
	v_mfma_f32_16x16x32_f16 v[36:39], v[160:163], v[176:179], v[36:39]
	v_mfma_f32_16x16x32_f16 v[40:43], v[168:171], v[176:179], v[40:43]
	v_mfma_f32_16x16x32_f16 v[40:43], v[164:167], v[172:175], v[40:43]
	v_mfma_f32_16x16x32_f16 v[48:51], v[164:167], v[180:183], v[48:51]
	v_mfma_f32_16x16x32_f16 v[48:51], v[168:171], v[184:187], v[48:51]
	v_mfma_f32_16x16x32_f16 v[44:47], v[160:163], v[184:187], v[44:47]
	v_mfma_f32_16x16x32_f16 v[44:47], v[156:159], v[180:183], v[44:47]
	v_mfma_f32_16x16x32_f16 v[52:55], v[156:159], v[188:191], v[52:55]
	v_mfma_f32_16x16x32_f16 v[52:55], v[160:163], v[192:195], v[52:55]
	v_mfma_f32_16x16x32_f16 v[56:59], v[168:171], v[192:195], v[56:59]
	v_mfma_f32_16x16x32_f16 v[56:59], v[164:167], v[188:191], v[56:59]
	v_mfma_f32_16x16x32_f16 v[64:67], v[164:167], v[196:199], v[64:67]
	v_mfma_f32_16x16x32_f16 v[64:67], v[168:171], v[200:203], v[64:67]
	s_setprio 2
	s_barrier
	v_mfma_f32_16x16x32_f16 v[60:63], v[160:163], v[200:203], v[60:63]
	v_mfma_f32_16x16x32_f16 v[60:63], v[156:159], v[196:199], v[60:63]
	s_setprio 0
	s_add_i32 s16, s29, s62
	v_lshl_add_u64 v[204:205], v[204:205], 0, s[86:87]
	s_mov_b32 m0, s16
	ds_read_b128 v[172:175], v212 offset:49152
	ds_read_b128 v[176:179], v212 offset:50176
	ds_read_b128 v[180:183], v212 offset:51200
	ds_read_b128 v[184:187], v212 offset:52224
	ds_read_b128 v[188:191], v212 offset:53248
	ds_read_b128 v[192:195], v212 offset:54272
	ds_read_b128 v[196:199], v212 offset:55296
	ds_read_b128 v[200:203], v212 offset:56320
	global_load_lds_dwordx4 v[204:205], off
	s_add_i32 m0, s16, 0x2000
	s_add_u32 s6, s6, 0x80080
	v_lshl_add_u64 v[204:205], v[206:207], 0, s[86:87]
	s_addc_u32 s7, s7, 0
	s_add_i32 s16, s44, s62
	global_load_lds_dwordx4 v[204:205], off
	s_mov_b32 m0, s16
	v_lshl_add_u64 v[204:205], v[208:209], 0, s[86:87]
	global_load_lds_dwordx4 v136, s[6:7]
	s_add_i32 m0, s16, 0x2000
	s_nop 0
	global_load_lds_dwordx4 v134, s[6:7]
	s_mov_b32 m0, s69
	s_nop 0
	global_load_lds_dwordx4 v[204:205], off
	v_lshl_add_u64 v[204:205], v[210:211], 0, s[86:87]
	s_mov_b32 m0, s70
	s_nop 0
	global_load_lds_dwordx4 v[204:205], off
	s_waitcnt vmcnt(8)
	s_waitcnt lgkmcnt(0)
	s_barrier
	s_setprio 1
	v_mfma_f32_16x16x32_f16 v[68:71], v[138:141], v[172:175], v[68:71]
	v_mfma_f32_16x16x32_f16 v[68:71], v[142:145], v[176:179], v[68:71]
	v_mfma_f32_16x16x32_f16 v[72:75], v[152:155], v[176:179], v[72:75]
	v_mfma_f32_16x16x32_f16 v[72:75], v[148:151], v[172:175], v[72:75]
	v_mfma_f32_16x16x32_f16 v[80:83], v[148:151], v[180:183], v[80:83]
	v_mfma_f32_16x16x32_f16 v[80:83], v[152:155], v[184:187], v[80:83]
	v_mfma_f32_16x16x32_f16 v[76:79], v[142:145], v[184:187], v[76:79]
	v_mfma_f32_16x16x32_f16 v[76:79], v[138:141], v[180:183], v[76:79]
	v_mfma_f32_16x16x32_f16 v[84:87], v[138:141], v[188:191], v[84:87]
	v_mfma_f32_16x16x32_f16 v[84:87], v[142:145], v[192:195], v[84:87]
	v_mfma_f32_16x16x32_f16 v[88:91], v[152:155], v[192:195], v[88:91]
	v_mfma_f32_16x16x32_f16 v[88:91], v[148:151], v[188:191], v[88:91]
	v_mfma_f32_16x16x32_f16 v[96:99], v[148:151], v[196:199], v[96:99]
	v_mfma_f32_16x16x32_f16 v[96:99], v[152:155], v[200:203], v[96:99]
	v_mfma_f32_16x16x32_f16 v[92:95], v[142:145], v[200:203], v[92:95]
	v_mfma_f32_16x16x32_f16 v[92:95], v[138:141], v[196:199], v[92:95]
	s_setprio 0
	s_setprio 1
	v_mfma_f32_16x16x32_f16 v[100:103], v[156:159], v[172:175], v[100:103]
	v_mfma_f32_16x16x32_f16 v[100:103], v[160:163], v[176:179], v[100:103]
	v_mfma_f32_16x16x32_f16 v[104:107], v[168:171], v[176:179], v[104:107]
	v_mfma_f32_16x16x32_f16 v[104:107], v[164:167], v[172:175], v[104:107]
	v_mfma_f32_16x16x32_f16 v[112:115], v[164:167], v[180:183], v[112:115]
	v_mfma_f32_16x16x32_f16 v[112:115], v[168:171], v[184:187], v[112:115]
	v_mfma_f32_16x16x32_f16 v[108:111], v[160:163], v[184:187], v[108:111]
	v_mfma_f32_16x16x32_f16 v[108:111], v[156:159], v[180:183], v[108:111]
	v_mfma_f32_16x16x32_f16 v[116:119], v[156:159], v[188:191], v[116:119]
	v_mfma_f32_16x16x32_f16 v[116:119], v[160:163], v[192:195], v[116:119]
	v_mfma_f32_16x16x32_f16 v[120:123], v[168:171], v[192:195], v[120:123]
	v_mfma_f32_16x16x32_f16 v[120:123], v[164:167], v[188:191], v[120:123]
	v_mfma_f32_16x16x32_f16 v[128:131], v[164:167], v[196:199], v[128:131]
	v_mfma_f32_16x16x32_f16 v[128:131], v[168:171], v[200:203], v[128:131]
	s_setprio 2
	s_barrier
	v_mfma_f32_16x16x32_f16 v[124:127], v[160:163], v[200:203], v[124:127]
	v_mfma_f32_16x16x32_f16 v[124:127], v[156:159], v[196:199], v[124:127]
	s_setprio 0
	s_add_i32 s28, s28, 2
	s_add_u32 s8, s8, 0x100
	s_addc_u32 s9, s9, 0
	s_add_u32 s26, s26, 0x100
	s_addc_u32 s27, s27, 0
	s_cmp_gt_u32 s28, 29
	s_cbranch_scc0 .LBB0_753
	s_and_b64 vcc, exec, s[52:53]
	s_cbranch_vccz .LBB0_756
	s_barrier

.LBB0_1175:
	s_add_i32 s61, 0, 0x10000
	s_add_i32 s79, 0, 0x14000
	v_add_u32_e32 v16, s61, v209
	v_add_u32_e32 v32, s79, v209
	ds_read_b128 v[4:7], v16
	ds_read_b128 v[8:11], v16 offset:1024
	ds_read_b128 v[12:15], v16 offset:2048
	ds_read_b128 v[16:19], v16 offset:3072
	ds_read_b128 v[20:23], v32
	ds_read_b128 v[24:27], v32 offset:1024
	ds_read_b128 v[28:31], v32 offset:2048
	ds_read_b128 v[32:35], v32 offset:3072
	v_add_u32_e32 v231, 0, v208
	ds_read_b128 v[36:39], v231
	ds_read_b128 v[40:43], v231 offset:1024
	ds_read_b128 v[44:47], v231 offset:2048
	ds_read_b128 v[48:51], v231 offset:3072
	ds_read_b128 v[52:55], v231 offset:4096
	ds_read_b128 v[56:59], v231 offset:5120
	ds_read_b128 v[60:63], v231 offset:6144
	ds_read_b128 v[64:67], v231 offset:7168
	s_waitcnt vmcnt(8)
	s_waitcnt lgkmcnt(0)
	s_barrier
	s_setprio 1
	v_mfma_f32_16x16x32_bf16 v[68:71], v[4:7], v[36:39], 0
	v_mfma_f32_16x16x32_bf16 v[68:71], v[8:11], v[40:43], v[68:71]
	v_mfma_f32_16x16x32_bf16 v[72:75], v[12:15], v[36:39], 0
	v_mfma_f32_16x16x32_bf16 v[72:75], v[16:19], v[40:43], v[72:75]
	v_mfma_f32_16x16x32_bf16 v[80:83], v[12:15], v[44:47], 0
	v_mfma_f32_16x16x32_bf16 v[80:83], v[16:19], v[48:51], v[80:83]
	v_mfma_f32_16x16x32_bf16 v[76:79], v[4:7], v[44:47], 0
	v_mfma_f32_16x16x32_bf16 v[76:79], v[8:11], v[48:51], v[76:79]
	v_mfma_f32_16x16x32_bf16 v[84:87], v[4:7], v[52:55], 0
	v_mfma_f32_16x16x32_bf16 v[84:87], v[8:11], v[56:59], v[84:87]
	v_mfma_f32_16x16x32_bf16 v[88:91], v[12:15], v[52:55], 0
	v_mfma_f32_16x16x32_bf16 v[88:91], v[16:19], v[56:59], v[88:91]
	v_mfma_f32_16x16x32_bf16 v[96:99], v[12:15], v[60:63], 0
	v_mfma_f32_16x16x32_bf16 v[96:99], v[16:19], v[64:67], v[96:99]
	v_mfma_f32_16x16x32_bf16 v[92:95], v[4:7], v[60:63], 0
	v_mfma_f32_16x16x32_bf16 v[92:95], v[8:11], v[64:67], v[92:95]
	s_setprio 0
	s_setprio 1
	v_mfma_f32_16x16x32_bf16 v[100:103], v[20:23], v[36:39], 0
	v_mfma_f32_16x16x32_bf16 v[36:39], v[28:31], v[36:39], 0
	v_mfma_f32_16x16x32_bf16 v[104:107], v[20:23], v[44:47], 0
	v_mfma_f32_16x16x32_bf16 v[44:47], v[28:31], v[44:47], 0
	v_mfma_f32_16x16x32_bf16 v[108:111], v[20:23], v[52:55], 0
	v_mfma_f32_16x16x32_bf16 v[52:55], v[28:31], v[52:55], 0
	v_mfma_f32_16x16x32_bf16 v[112:115], v[20:23], v[60:63], 0
	v_mfma_f32_16x16x32_bf16 v[60:63], v[28:31], v[60:63], 0
	v_mfma_f32_16x16x32_bf16 v[100:103], v[24:27], v[40:43], v[100:103]
	v_mfma_f32_16x16x32_bf16 v[40:43], v[32:35], v[40:43], v[36:39]
	v_mfma_f32_16x16x32_bf16 v[104:107], v[24:27], v[48:51], v[104:107]
	v_mfma_f32_16x16x32_bf16 v[48:51], v[32:35], v[48:51], v[44:47]
	v_mfma_f32_16x16x32_bf16 v[108:111], v[24:27], v[56:59], v[108:111]
	v_mfma_f32_16x16x32_bf16 v[56:59], v[32:35], v[56:59], v[52:55]
	s_setprio 2
	s_barrier
	v_mfma_f32_16x16x32_bf16 v[112:115], v[24:27], v[64:67], v[112:115]
	v_mfma_f32_16x16x32_bf16 v[64:67], v[32:35], v[64:67], v[60:63]
	s_setprio 0
	v_lshl_add_u64 v[186:187], s[12:13], 0, v[2:3]
	s_add_i32 s61, s61, s36
	v_mov_b32_e32 v191, v3
	v_lshl_add_u64 v[134:135], v[186:187], 0, s[74:75]
	s_mov_b32 m0, s61
	v_lshl_add_u64 v[226:227], s[12:13], 0, v[190:191]
	ds_read_b128 v[36:39], v231 offset:16384
	ds_read_b128 v[44:47], v231 offset:17408
	ds_read_b128 v[52:55], v231 offset:18432
	ds_read_b128 v[60:63], v231 offset:19456
	ds_read_b128 v[116:119], v231 offset:20480
	ds_read_b128 v[120:123], v231 offset:21504
	ds_read_b128 v[124:127], v231 offset:22528
	ds_read_b128 v[128:131], v231 offset:23552
	global_load_lds_dwordx4 v[134:135], off
	v_lshl_add_u64 v[134:135], v[226:227], 0, s[74:75]
	s_add_i32 m0, s61, 0x2000
	s_add_i32 s61, s79, s36
	global_load_lds_dwordx4 v[134:135], off
	s_mov_b32 m0, s61
	v_mov_b32_e32 v133, v3
	global_load_lds_dwordx4 v2, s[16:17]
	s_add_i32 m0, s61, 0x2000
	v_lshl_add_u64 v[248:249], s[6:7], 0, v[132:133]
	v_mov_b32_e32 v189, v3
	global_load_lds_dwordx4 v190, s[16:17]
	v_lshl_add_u64 v[134:135], v[248:249], 0, s[74:75]
	s_mov_b32 m0, s37
	v_lshl_add_u64 v[250:251], s[6:7], 0, v[188:189]
	global_load_lds_dwordx4 v[134:135], off
	v_lshl_add_u64 v[134:135], v[250:251], 0, s[74:75]
	s_mov_b32 m0, s66
	s_nop 0
	global_load_lds_dwordx4 v[134:135], off
	s_waitcnt vmcnt(8)
	s_waitcnt lgkmcnt(0)
	s_barrier
	s_setprio 1
	v_mfma_f32_16x16x32_bf16 v[134:137], v[4:7], v[36:39], 0
	v_mfma_f32_16x16x32_bf16 v[138:141], v[12:15], v[36:39], 0
	v_mfma_f32_16x16x32_bf16 v[142:145], v[4:7], v[52:55], 0
	v_mfma_f32_16x16x32_bf16 v[146:149], v[12:15], v[52:55], 0
	v_mfma_f32_16x16x32_bf16 v[150:153], v[4:7], v[116:119], 0
	v_mfma_f32_16x16x32_bf16 v[154:157], v[12:15], v[116:119], 0
	v_mfma_f32_16x16x32_bf16 v[4:7], v[4:7], v[124:127], 0
	v_mfma_f32_16x16x32_bf16 v[12:15], v[12:15], v[124:127], 0
	v_mfma_f32_16x16x32_bf16 v[134:137], v[8:11], v[44:47], v[134:137]
	v_mfma_f32_16x16x32_bf16 v[138:141], v[16:19], v[44:47], v[138:141]
	v_mfma_f32_16x16x32_bf16 v[142:145], v[8:11], v[60:63], v[142:145]
	v_mfma_f32_16x16x32_bf16 v[146:149], v[16:19], v[60:63], v[146:149]
	v_mfma_f32_16x16x32_bf16 v[150:153], v[8:11], v[120:123], v[150:153]
	v_mfma_f32_16x16x32_bf16 v[154:157], v[16:19], v[120:123], v[154:157]
	v_mfma_f32_16x16x32_bf16 v[158:161], v[8:11], v[128:131], v[4:7]
	v_mfma_f32_16x16x32_bf16 v[162:165], v[16:19], v[128:131], v[12:15]
	s_setprio 0
	s_setprio 1
	v_mfma_f32_16x16x32_bf16 v[4:7], v[20:23], v[36:39], 0
	v_mfma_f32_16x16x32_bf16 v[8:11], v[28:31], v[36:39], 0
	v_mfma_f32_16x16x32_bf16 v[12:15], v[20:23], v[52:55], 0
	v_mfma_f32_16x16x32_bf16 v[16:19], v[28:31], v[52:55], 0
	v_mfma_f32_16x16x32_bf16 v[36:39], v[20:23], v[116:119], 0
	v_mfma_f32_16x16x32_bf16 v[52:55], v[28:31], v[116:119], 0
	v_mfma_f32_16x16x32_bf16 v[20:23], v[20:23], v[124:127], 0
	v_mfma_f32_16x16x32_bf16 v[28:31], v[28:31], v[124:127], 0
	v_mfma_f32_16x16x32_bf16 v[116:119], v[24:27], v[44:47], v[4:7]
	v_mfma_f32_16x16x32_bf16 v[124:127], v[32:35], v[44:47], v[8:11]
	v_mfma_f32_16x16x32_bf16 v[174:177], v[24:27], v[120:123], v[36:39]
	v_mfma_f32_16x16x32_bf16 v[120:123], v[32:35], v[120:123], v[52:55]
	v_mfma_f32_16x16x32_bf16 v[178:181], v[24:27], v[128:131], v[20:23]
	v_mfma_f32_16x16x32_bf16 v[128:131], v[32:35], v[128:131], v[28:31]
	s_setprio 2
	s_barrier
	v_mfma_f32_16x16x32_bf16 v[166:169], v[24:27], v[60:63], v[12:15]
	v_mfma_f32_16x16x32_bf16 v[170:173], v[32:35], v[60:63], v[16:19]
	s_setprio 0
	s_add_i32 s61, 0, 0x18000
	v_add_u32_e32 v4, s61, v209
	s_add_i32 s79, 0, 0x1c000
	ds_read_b128 v[182:185], v4
	ds_read_b128 v[192:195], v4 offset:1024
	ds_read_b128 v[196:199], v4 offset:2048
	ds_read_b128 v[200:203], v4 offset:3072
	v_add_u32_e32 v4, s79, v209
	ds_read_b128 v[204:207], v4
	ds_read_b128 v[210:213], v4 offset:1024
	ds_read_b128 v[214:217], v4 offset:2048
	ds_read_b128 v[218:221], v4 offset:3072
	s_mov_b32 m0, s67
	ds_read_b128 v[44:47], v231 offset:32768
	ds_read_b128 v[52:55], v231 offset:33792
	ds_read_b128 v[60:63], v231 offset:34816
	ds_read_b128 v[222:225], v231 offset:35840
	ds_read_b128 v[232:235], v231 offset:36864
	ds_read_b128 v[236:239], v231 offset:37888
	ds_read_b128 v[240:243], v231 offset:38912
	ds_read_b128 v[244:247], v231 offset:39936
	global_load_lds_dwordx4 v132, s[26:27]
	s_mov_b32 m0, s68
	s_nop 0
	global_load_lds_dwordx4 v188, s[26:27]
	s_waitcnt vmcnt(8)
	s_waitcnt lgkmcnt(0)
	s_barrier
	s_setprio 1
	v_mfma_f32_16x16x32_bf16 v[4:7], v[182:185], v[44:47], v[68:71]
	v_mfma_f32_16x16x32_bf16 v[8:11], v[196:199], v[44:47], v[72:75]
	v_mfma_f32_16x16x32_bf16 v[12:15], v[182:185], v[60:63], v[76:79]
	v_mfma_f32_16x16x32_bf16 v[16:19], v[196:199], v[60:63], v[80:83]
	v_mfma_f32_16x16x32_bf16 v[20:23], v[182:185], v[232:235], v[84:87]
	v_mfma_f32_16x16x32_bf16 v[24:27], v[196:199], v[232:235], v[88:91]
	v_mfma_f32_16x16x32_bf16 v[28:31], v[182:185], v[240:243], v[92:95]
	v_mfma_f32_16x16x32_bf16 v[32:35], v[196:199], v[240:243], v[96:99]
	v_mfma_f32_16x16x32_bf16 v[4:7], v[192:195], v[52:55], v[4:7]
	v_mfma_f32_16x16x32_bf16 v[8:11], v[200:203], v[52:55], v[8:11]
	v_mfma_f32_16x16x32_bf16 v[12:15], v[192:195], v[222:225], v[12:15]
	v_mfma_f32_16x16x32_bf16 v[16:19], v[200:203], v[222:225], v[16:19]
	v_mfma_f32_16x16x32_bf16 v[20:23], v[192:195], v[236:239], v[20:23]
	v_mfma_f32_16x16x32_bf16 v[24:27], v[200:203], v[236:239], v[24:27]
	v_mfma_f32_16x16x32_bf16 v[28:31], v[192:195], v[244:247], v[28:31]
	v_mfma_f32_16x16x32_bf16 v[32:35], v[200:203], v[244:247], v[32:35]
	s_setprio 0
	s_setprio 1
	v_mfma_f32_16x16x32_bf16 v[36:39], v[204:207], v[44:47], v[100:103]
	v_mfma_f32_16x16x32_bf16 v[40:43], v[214:217], v[44:47], v[40:43]
	v_mfma_f32_16x16x32_bf16 v[36:39], v[210:213], v[52:55], v[36:39]
	v_mfma_f32_16x16x32_bf16 v[40:43], v[218:221], v[52:55], v[40:43]
	v_mfma_f32_16x16x32_bf16 v[44:47], v[204:207], v[60:63], v[104:107]
	v_mfma_f32_16x16x32_bf16 v[48:51], v[214:217], v[60:63], v[48:51]
	v_mfma_f32_16x16x32_bf16 v[52:55], v[204:207], v[232:235], v[108:111]
	v_mfma_f32_16x16x32_bf16 v[56:59], v[214:217], v[232:235], v[56:59]
	v_mfma_f32_16x16x32_bf16 v[60:63], v[204:207], v[240:243], v[112:115]
	v_mfma_f32_16x16x32_bf16 v[64:67], v[214:217], v[240:243], v[64:67]
	v_mfma_f32_16x16x32_bf16 v[44:47], v[210:213], v[222:225], v[44:47]
	v_mfma_f32_16x16x32_bf16 v[48:51], v[218:221], v[222:225], v[48:51]
	v_mfma_f32_16x16x32_bf16 v[52:55], v[210:213], v[236:239], v[52:55]
	v_mfma_f32_16x16x32_bf16 v[56:59], v[218:221], v[236:239], v[56:59]
	s_setprio 2
	s_barrier
	v_mfma_f32_16x16x32_bf16 v[60:63], v[210:213], v[244:247], v[60:63]
	v_mfma_f32_16x16x32_bf16 v[64:67], v[218:221], v[244:247], v[64:67]
	s_setprio 0
	s_add_i32 s61, s61, s36
	v_lshl_add_u64 v[68:69], v[186:187], 0, s[24:25]
	s_mov_b32 m0, s61
	ds_read_b128 v[104:107], v231 offset:49152
	ds_read_b128 v[108:111], v231 offset:50176
	ds_read_b128 v[112:115], v231 offset:51200
	ds_read_b128 v[222:225], v231 offset:52224
	ds_read_b128 v[232:235], v231 offset:53248
	ds_read_b128 v[236:239], v231 offset:54272
	ds_read_b128 v[240:243], v231 offset:55296
	ds_read_b128 v[244:247], v231 offset:56320
	global_load_lds_dwordx4 v[68:69], off
	v_lshl_add_u64 v[68:69], v[226:227], 0, s[24:25]
	s_add_i32 m0, s61, 0x2000
	s_add_i32 s61, s79, s36
	global_load_lds_dwordx4 v[68:69], off
	s_mov_b32 m0, s61
	v_lshl_add_u64 v[68:69], v[248:249], 0, s[24:25]
	global_load_lds_dwordx4 v2, s[28:29]
	s_add_i32 m0, s61, 0x2000
	s_nop 0
	global_load_lds_dwordx4 v190, s[28:29]
	s_mov_b32 m0, s71
	s_nop 0
	global_load_lds_dwordx4 v[68:69], off
	v_lshl_add_u64 v[68:69], v[250:251], 0, s[24:25]
	s_mov_b32 m0, s72
	s_nop 0
	global_load_lds_dwordx4 v[68:69], off
	s_waitcnt vmcnt(8)
	s_waitcnt lgkmcnt(0)
	s_barrier
	s_setprio 1
	v_mfma_f32_16x16x32_bf16 v[68:71], v[182:185], v[104:107], v[134:137]
	v_mfma_f32_16x16x32_bf16 v[72:75], v[196:199], v[104:107], v[138:141]
	v_mfma_f32_16x16x32_bf16 v[76:79], v[182:185], v[112:115], v[142:145]
	v_mfma_f32_16x16x32_bf16 v[80:83], v[196:199], v[112:115], v[146:149]
	v_mfma_f32_16x16x32_bf16 v[84:87], v[182:185], v[232:235], v[150:153]
	v_mfma_f32_16x16x32_bf16 v[88:91], v[196:199], v[232:235], v[154:157]
	v_mfma_f32_16x16x32_bf16 v[92:95], v[182:185], v[240:243], v[158:161]
	v_mfma_f32_16x16x32_bf16 v[96:99], v[196:199], v[240:243], v[162:165]
	v_mfma_f32_16x16x32_bf16 v[68:71], v[192:195], v[108:111], v[68:71]
	v_mfma_f32_16x16x32_bf16 v[72:75], v[200:203], v[108:111], v[72:75]
	v_mfma_f32_16x16x32_bf16 v[76:79], v[192:195], v[222:225], v[76:79]
	v_mfma_f32_16x16x32_bf16 v[80:83], v[200:203], v[222:225], v[80:83]
	v_mfma_f32_16x16x32_bf16 v[84:87], v[192:195], v[236:239], v[84:87]
	v_mfma_f32_16x16x32_bf16 v[88:91], v[200:203], v[236:239], v[88:91]
	v_mfma_f32_16x16x32_bf16 v[92:95], v[192:195], v[244:247], v[92:95]
	v_mfma_f32_16x16x32_bf16 v[96:99], v[200:203], v[244:247], v[96:99]
	s_setprio 0
	s_setprio 1
	v_mfma_f32_16x16x32_bf16 v[100:103], v[204:207], v[104:107], v[116:119]
	v_mfma_f32_16x16x32_bf16 v[104:107], v[214:217], v[104:107], v[124:127]
	v_mfma_f32_16x16x32_bf16 v[100:103], v[210:213], v[108:111], v[100:103]
	v_mfma_f32_16x16x32_bf16 v[104:107], v[218:221], v[108:111], v[104:107]
	v_mfma_f32_16x16x32_bf16 v[108:111], v[204:207], v[112:115], v[166:169]
	v_mfma_f32_16x16x32_bf16 v[112:115], v[214:217], v[112:115], v[170:173]
	v_mfma_f32_16x16x32_bf16 v[116:119], v[204:207], v[232:235], v[174:177]
	v_mfma_f32_16x16x32_bf16 v[120:123], v[214:217], v[232:235], v[120:123]
	v_mfma_f32_16x16x32_bf16 v[124:127], v[204:207], v[240:243], v[178:181]
	v_mfma_f32_16x16x32_bf16 v[128:131], v[214:217], v[240:243], v[128:131]
	v_mfma_f32_16x16x32_bf16 v[108:111], v[210:213], v[222:225], v[108:111]
	v_mfma_f32_16x16x32_bf16 v[112:115], v[218:221], v[222:225], v[112:115]
	v_mfma_f32_16x16x32_bf16 v[116:119], v[210:213], v[236:239], v[116:119]
	v_mfma_f32_16x16x32_bf16 v[120:123], v[218:221], v[236:239], v[120:123]
	s_setprio 2
	s_barrier
	v_mfma_f32_16x16x32_bf16 v[124:127], v[210:213], v[244:247], v[124:127]
	v_mfma_f32_16x16x32_bf16 v[128:131], v[218:221], v[244:247], v[128:131]
	s_setprio 0
	s_add_i32 s43, s43, 2
	s_cmp_ge_i32 s43, s42
	s_cbranch_scc0 .LBB0_1175
.LBB0_1176:
	s_add_i32 s12, 0, 0x10000
	s_add_i32 s13, 0, 0x14000
	v_mov_b32_e32 v192, v2
	v_mov_b32_e32 v2, v132
	v_add_u32_e32 v144, s12, v209
	v_add_u32_e32 v160, s13, v209
	ds_read_b128 v[132:135], v144
	ds_read_b128 v[136:139], v144 offset:1024
	ds_read_b128 v[140:143], v144 offset:2048
	ds_read_b128 v[144:147], v144 offset:3072
	ds_read_b128 v[148:151], v160
	ds_read_b128 v[152:155], v160 offset:1024
	ds_read_b128 v[156:159], v160 offset:2048
	ds_read_b128 v[160:163], v160 offset:3072
	s_add_u32 s6, s6, 0x80180
	s_mov_b32 m0, s73
	v_add_u32_e32 v212, 0, v208
	s_addc_u32 s7, s7, 0
	ds_read_b128 v[164:167], v212
	ds_read_b128 v[168:171], v212 offset:1024
	ds_read_b128 v[172:175], v212 offset:2048
	ds_read_b128 v[176:179], v212 offset:3072
	ds_read_b128 v[180:183], v212 offset:4096
	ds_read_b128 v[184:187], v212 offset:5120
	ds_read_b128 v[194:197], v212 offset:6144
	ds_read_b128 v[198:201], v212 offset:7168
	global_load_lds_dwordx4 v2, s[6:7]
	s_mov_b32 m0, s76
	v_mov_b32_e32 v189, v3
	global_load_lds_dwordx4 v188, s[6:7]
	s_waitcnt vmcnt(8)
	s_waitcnt lgkmcnt(0)
	s_barrier
	s_setprio 1
	v_mfma_f32_16x16x32_bf16 v[4:7], v[132:135], v[164:167], v[4:7]
	v_mfma_f32_16x16x32_bf16 v[4:7], v[136:139], v[168:171], v[4:7]
	v_mfma_f32_16x16x32_bf16 v[8:11], v[144:147], v[168:171], v[8:11]
	v_mfma_f32_16x16x32_bf16 v[8:11], v[140:143], v[164:167], v[8:11]
	v_mfma_f32_16x16x32_bf16 v[16:19], v[140:143], v[172:175], v[16:19]
	v_mfma_f32_16x16x32_bf16 v[16:19], v[144:147], v[176:179], v[16:19]
	v_mfma_f32_16x16x32_bf16 v[12:15], v[136:139], v[176:179], v[12:15]
	v_mfma_f32_16x16x32_bf16 v[12:15], v[132:135], v[172:175], v[12:15]
	v_mfma_f32_16x16x32_bf16 v[20:23], v[132:135], v[180:183], v[20:23]
	v_mfma_f32_16x16x32_bf16 v[20:23], v[136:139], v[184:187], v[20:23]
	v_mfma_f32_16x16x32_bf16 v[24:27], v[144:147], v[184:187], v[24:27]
	v_mfma_f32_16x16x32_bf16 v[24:27], v[140:143], v[180:183], v[24:27]
	v_mfma_f32_16x16x32_bf16 v[32:35], v[140:143], v[194:197], v[32:35]
	v_mfma_f32_16x16x32_bf16 v[32:35], v[144:147], v[198:201], v[32:35]
	v_mfma_f32_16x16x32_bf16 v[28:31], v[136:139], v[198:201], v[28:31]
	v_mfma_f32_16x16x32_bf16 v[28:31], v[132:135], v[194:197], v[28:31]
	s_setprio 0
	s_setprio 1
	v_mfma_f32_16x16x32_bf16 v[36:39], v[148:151], v[164:167], v[36:39]
	v_mfma_f32_16x16x32_bf16 v[36:39], v[152:155], v[168:171], v[36:39]
	v_mfma_f32_16x16x32_bf16 v[40:43], v[160:163], v[168:171], v[40:43]
	v_mfma_f32_16x16x32_bf16 v[40:43], v[156:159], v[164:167], v[40:43]
	v_mfma_f32_16x16x32_bf16 v[48:51], v[156:159], v[172:175], v[48:51]
	v_mfma_f32_16x16x32_bf16 v[48:51], v[160:163], v[176:179], v[48:51]
	v_mfma_f32_16x16x32_bf16 v[44:47], v[152:155], v[176:179], v[44:47]
	v_mfma_f32_16x16x32_bf16 v[44:47], v[148:151], v[172:175], v[44:47]
	v_mfma_f32_16x16x32_bf16 v[52:55], v[148:151], v[180:183], v[52:55]
	v_mfma_f32_16x16x32_bf16 v[52:55], v[152:155], v[184:187], v[52:55]
	v_mfma_f32_16x16x32_bf16 v[56:59], v[160:163], v[184:187], v[56:59]
	v_mfma_f32_16x16x32_bf16 v[56:59], v[156:159], v[180:183], v[56:59]
	v_mfma_f32_16x16x32_bf16 v[64:67], v[156:159], v[194:197], v[64:67]
	v_mfma_f32_16x16x32_bf16 v[64:67], v[160:163], v[198:201], v[64:67]
	s_setprio 2
	s_barrier
	v_mfma_f32_16x16x32_bf16 v[60:63], v[152:155], v[198:201], v[60:63]
	v_mfma_f32_16x16x32_bf16 v[60:63], v[148:151], v[194:197], v[60:63]
	s_setprio 0
	s_add_i32 s6, s12, s36
	s_mov_b32 m0, s6
	ds_read_b128 v[164:167], v212 offset:16384
	ds_read_b128 v[168:171], v212 offset:17408
	ds_read_b128 v[172:175], v212 offset:18432
	ds_read_b128 v[176:179], v212 offset:19456
	ds_read_b128 v[180:183], v212 offset:20480
	ds_read_b128 v[184:187], v212 offset:21504
	ds_read_b128 v[194:197], v212 offset:22528
	ds_read_b128 v[198:201], v212 offset:23552
	global_load_lds_dwordx4 v192, s[14:15]
	s_add_i32 m0, s6, 0x2000
	s_add_u32 s6, s14, 0x10000
	s_addc_u32 s7, s15, 0
	s_add_i32 s12, s13, s36
	global_load_lds_dwordx4 v190, s[14:15]
	s_mov_b32 m0, s12
	v_mov_b32_e32 v193, v3
	global_load_lds_dwordx4 v192, s[6:7]
	s_add_i32 m0, s12, 0x2000
	v_mov_b32_e32 v191, v3
	global_load_lds_dwordx4 v190, s[6:7]
	s_mov_b32 m0, s37
	v_lshl_add_u64 v[202:203], s[14:15], 0, v[192:193]
	global_load_lds_dwordx4 v2, s[10:11]
	s_mov_b32 m0, s66
	v_lshl_add_u64 v[204:205], s[14:15], 0, v[190:191]
	global_load_lds_dwordx4 v188, s[10:11]
	s_waitcnt vmcnt(8)
	s_waitcnt lgkmcnt(0)
	v_lshl_add_u64 v[206:207], s[10:11], 0, v[2:3]
	v_lshl_add_u64 v[210:211], s[10:11], 0, v[188:189]
	s_barrier
	s_setprio 1
	v_mfma_f32_16x16x32_bf16 v[68:71], v[132:135], v[164:167], v[68:71]
	v_mfma_f32_16x16x32_bf16 v[68:71], v[136:139], v[168:171], v[68:71]
	v_mfma_f32_16x16x32_bf16 v[72:75], v[144:147], v[168:171], v[72:75]
	v_mfma_f32_16x16x32_bf16 v[72:75], v[140:143], v[164:167], v[72:75]
	v_mfma_f32_16x16x32_bf16 v[80:83], v[140:143], v[172:175], v[80:83]
	v_mfma_f32_16x16x32_bf16 v[80:83], v[144:147], v[176:179], v[80:83]
	v_mfma_f32_16x16x32_bf16 v[76:79], v[136:139], v[176:179], v[76:79]
	v_mfma_f32_16x16x32_bf16 v[76:79], v[132:135], v[172:175], v[76:79]
	v_mfma_f32_16x16x32_bf16 v[84:87], v[132:135], v[180:183], v[84:87]
	v_mfma_f32_16x16x32_bf16 v[84:87], v[136:139], v[184:187], v[84:87]
	v_mfma_f32_16x16x32_bf16 v[88:91], v[144:147], v[184:187], v[88:91]
	v_mfma_f32_16x16x32_bf16 v[88:91], v[140:143], v[180:183], v[88:91]
	v_mfma_f32_16x16x32_bf16 v[96:99], v[140:143], v[194:197], v[96:99]
	v_mfma_f32_16x16x32_bf16 v[96:99], v[144:147], v[198:201], v[96:99]
	v_mfma_f32_16x16x32_bf16 v[92:95], v[136:139], v[198:201], v[92:95]
	v_mfma_f32_16x16x32_bf16 v[92:95], v[132:135], v[194:197], v[92:95]
	s_setprio 0
	s_setprio 1
	v_mfma_f32_16x16x32_bf16 v[100:103], v[148:151], v[164:167], v[100:103]
	v_mfma_f32_16x16x32_bf16 v[100:103], v[152:155], v[168:171], v[100:103]
	v_mfma_f32_16x16x32_bf16 v[104:107], v[160:163], v[168:171], v[104:107]
	v_mfma_f32_16x16x32_bf16 v[104:107], v[156:159], v[164:167], v[104:107]
	v_mfma_f32_16x16x32_bf16 v[112:115], v[156:159], v[172:175], v[112:115]
	v_mfma_f32_16x16x32_bf16 v[112:115], v[160:163], v[176:179], v[112:115]
	v_mfma_f32_16x16x32_bf16 v[108:111], v[152:155], v[176:179], v[108:111]
	v_mfma_f32_16x16x32_bf16 v[108:111], v[148:151], v[172:175], v[108:111]
	v_mfma_f32_16x16x32_bf16 v[116:119], v[148:151], v[180:183], v[116:119]
	v_mfma_f32_16x16x32_bf16 v[116:119], v[152:155], v[184:187], v[116:119]
	v_mfma_f32_16x16x32_bf16 v[120:123], v[160:163], v[184:187], v[120:123]
	v_mfma_f32_16x16x32_bf16 v[120:123], v[156:159], v[180:183], v[120:123]
	v_mfma_f32_16x16x32_bf16 v[128:131], v[156:159], v[194:197], v[128:131]
	v_mfma_f32_16x16x32_bf16 v[128:131], v[160:163], v[198:201], v[128:131]
	s_setprio 2
	s_barrier
	v_mfma_f32_16x16x32_bf16 v[124:127], v[152:155], v[198:201], v[124:127]
	v_mfma_f32_16x16x32_bf16 v[124:127], v[148:151], v[194:197], v[124:127]
	s_setprio 0
	s_add_i32 s12, 0, 0x18000
	s_add_i32 s13, 0, 0x1c000
	v_add_u32_e32 v144, s12, v209
	v_add_u32_e32 v160, s13, v209
	ds_read_b128 v[132:135], v144
	ds_read_b128 v[136:139], v144 offset:1024
	ds_read_b128 v[140:143], v144 offset:2048
	ds_read_b128 v[144:147], v144 offset:3072
	ds_read_b128 v[148:151], v160
	ds_read_b128 v[152:155], v160 offset:1024
	ds_read_b128 v[156:159], v160 offset:2048
	ds_read_b128 v[160:163], v160 offset:3072
	s_add_u32 s6, s10, 0x80000
	s_addc_u32 s7, s11, 0
	s_mov_b32 m0, s67
	ds_read_b128 v[164:167], v212 offset:32768
	ds_read_b128 v[168:171], v212 offset:33792
	ds_read_b128 v[172:175], v212 offset:34816
	ds_read_b128 v[176:179], v212 offset:35840
	ds_read_b128 v[180:183], v212 offset:36864
	ds_read_b128 v[184:187], v212 offset:37888
	ds_read_b128 v[194:197], v212 offset:38912
	ds_read_b128 v[198:201], v212 offset:39936
	global_load_lds_dwordx4 v2, s[6:7]
	s_mov_b32 m0, s68
	s_nop 0
	global_load_lds_dwordx4 v188, s[6:7]
	s_waitcnt vmcnt(8)
	s_waitcnt lgkmcnt(0)
	s_barrier
	s_setprio 1
	v_mfma_f32_16x16x32_bf16 v[4:7], v[132:135], v[164:167], v[4:7]
	v_mfma_f32_16x16x32_bf16 v[4:7], v[136:139], v[168:171], v[4:7]
	v_mfma_f32_16x16x32_bf16 v[8:11], v[144:147], v[168:171], v[8:11]
	v_mfma_f32_16x16x32_bf16 v[8:11], v[140:143], v[164:167], v[8:11]
	v_mfma_f32_16x16x32_bf16 v[16:19], v[140:143], v[172:175], v[16:19]
	v_mfma_f32_16x16x32_bf16 v[16:19], v[144:147], v[176:179], v[16:19]
	v_mfma_f32_16x16x32_bf16 v[12:15], v[136:139], v[176:179], v[12:15]
	v_mfma_f32_16x16x32_bf16 v[12:15], v[132:135], v[172:175], v[12:15]
	v_mfma_f32_16x16x32_bf16 v[20:23], v[132:135], v[180:183], v[20:23]
	v_mfma_f32_16x16x32_bf16 v[20:23], v[136:139], v[184:187], v[20:23]
	v_mfma_f32_16x16x32_bf16 v[24:27], v[144:147], v[184:187], v[24:27]
	v_mfma_f32_16x16x32_bf16 v[24:27], v[140:143], v[180:183], v[24:27]
	v_mfma_f32_16x16x32_bf16 v[32:35], v[140:143], v[194:197], v[32:35]
	v_mfma_f32_16x16x32_bf16 v[32:35], v[144:147], v[198:201], v[32:35]
	v_mfma_f32_16x16x32_bf16 v[28:31], v[136:139], v[198:201], v[28:31]
	v_mfma_f32_16x16x32_bf16 v[28:31], v[132:135], v[194:197], v[28:31]
	s_setprio 0
	s_setprio 1
	v_mfma_f32_16x16x32_bf16 v[36:39], v[148:151], v[164:167], v[36:39]
	v_mfma_f32_16x16x32_bf16 v[36:39], v[152:155], v[168:171], v[36:39]
	v_mfma_f32_16x16x32_bf16 v[40:43], v[160:163], v[168:171], v[40:43]
	v_mfma_f32_16x16x32_bf16 v[40:43], v[156:159], v[164:167], v[40:43]
	v_mfma_f32_16x16x32_bf16 v[48:51], v[156:159], v[172:175], v[48:51]
	v_mfma_f32_16x16x32_bf16 v[48:51], v[160:163], v[176:179], v[48:51]
	v_mfma_f32_16x16x32_bf16 v[44:47], v[152:155], v[176:179], v[44:47]
	v_mfma_f32_16x16x32_bf16 v[44:47], v[148:151], v[172:175], v[44:47]
	v_mfma_f32_16x16x32_bf16 v[52:55], v[148:151], v[180:183], v[52:55]
	v_mfma_f32_16x16x32_bf16 v[52:55], v[152:155], v[184:187], v[52:55]
	v_mfma_f32_16x16x32_bf16 v[56:59], v[160:163], v[184:187], v[56:59]
	v_mfma_f32_16x16x32_bf16 v[56:59], v[156:159], v[180:183], v[56:59]
	v_mfma_f32_16x16x32_bf16 v[64:67], v[156:159], v[194:197], v[64:67]
	v_mfma_f32_16x16x32_bf16 v[64:67], v[160:163], v[198:201], v[64:67]
	s_setprio 2
	s_barrier
	v_mfma_f32_16x16x32_bf16 v[60:63], v[152:155], v[198:201], v[60:63]
	v_mfma_f32_16x16x32_bf16 v[60:63], v[148:151], v[194:197], v[60:63]
	s_setprio 0
	s_add_i32 s6, s12, s36
	v_lshl_add_u64 v[202:203], v[202:203], 0, s[86:87]
	s_mov_b32 m0, s6
	ds_read_b128 v[164:167], v212 offset:49152
	ds_read_b128 v[168:171], v212 offset:50176
	ds_read_b128 v[172:175], v212 offset:51200
	ds_read_b128 v[176:179], v212 offset:52224
	ds_read_b128 v[180:183], v212 offset:53248
	ds_read_b128 v[184:187], v212 offset:54272
	ds_read_b128 v[194:197], v212 offset:55296
	ds_read_b128 v[198:201], v212 offset:56320
	global_load_lds_dwordx4 v[202:203], off
	s_add_i32 m0, s6, 0x2000
	s_add_u32 s6, s14, 0x10080
	v_lshl_add_u64 v[202:203], v[204:205], 0, s[86:87]
	s_addc_u32 s7, s15, 0
	s_add_i32 s12, s13, s36
	global_load_lds_dwordx4 v[202:203], off
	s_mov_b32 m0, s12
	v_lshl_add_u64 v[202:203], v[206:207], 0, s[86:87]
	global_load_lds_dwordx4 v192, s[6:7]
	s_add_i32 m0, s12, 0x2000
	s_nop 0
	global_load_lds_dwordx4 v190, s[6:7]
	s_mov_b32 m0, s71
	s_nop 0
	global_load_lds_dwordx4 v[202:203], off
	v_lshl_add_u64 v[202:203], v[210:211], 0, s[86:87]
	s_mov_b32 m0, s72
	s_nop 0
	global_load_lds_dwordx4 v[202:203], off
	s_waitcnt vmcnt(8)
	s_waitcnt lgkmcnt(0)
	s_barrier
	s_setprio 1
	v_mfma_f32_16x16x32_bf16 v[68:71], v[132:135], v[164:167], v[68:71]
	v_mfma_f32_16x16x32_bf16 v[68:71], v[136:139], v[168:171], v[68:71]
	v_mfma_f32_16x16x32_bf16 v[72:75], v[144:147], v[168:171], v[72:75]
	v_mfma_f32_16x16x32_bf16 v[72:75], v[140:143], v[164:167], v[72:75]
	v_mfma_f32_16x16x32_bf16 v[80:83], v[140:143], v[172:175], v[80:83]
	v_mfma_f32_16x16x32_bf16 v[80:83], v[144:147], v[176:179], v[80:83]
	v_mfma_f32_16x16x32_bf16 v[76:79], v[136:139], v[176:179], v[76:79]
	v_mfma_f32_16x16x32_bf16 v[76:79], v[132:135], v[172:175], v[76:79]
	v_mfma_f32_16x16x32_bf16 v[84:87], v[132:135], v[180:183], v[84:87]
	v_mfma_f32_16x16x32_bf16 v[84:87], v[136:139], v[184:187], v[84:87]
	v_mfma_f32_16x16x32_bf16 v[88:91], v[144:147], v[184:187], v[88:91]
	v_mfma_f32_16x16x32_bf16 v[88:91], v[140:143], v[180:183], v[88:91]
	v_mfma_f32_16x16x32_bf16 v[96:99], v[140:143], v[194:197], v[96:99]
	v_mfma_f32_16x16x32_bf16 v[96:99], v[144:147], v[198:201], v[96:99]
	v_mfma_f32_16x16x32_bf16 v[92:95], v[136:139], v[198:201], v[92:95]
	v_mfma_f32_16x16x32_bf16 v[92:95], v[132:135], v[194:197], v[92:95]
	s_setprio 0
	s_setprio 1
	v_mfma_f32_16x16x32_bf16 v[100:103], v[148:151], v[164:167], v[100:103]
	v_mfma_f32_16x16x32_bf16 v[100:103], v[152:155], v[168:171], v[100:103]
	v_mfma_f32_16x16x32_bf16 v[104:107], v[160:163], v[168:171], v[104:107]
	v_mfma_f32_16x16x32_bf16 v[104:107], v[156:159], v[164:167], v[104:107]
	v_mfma_f32_16x16x32_bf16 v[112:115], v[156:159], v[172:175], v[112:115]
	v_mfma_f32_16x16x32_bf16 v[112:115], v[160:163], v[176:179], v[112:115]
	v_mfma_f32_16x16x32_bf16 v[108:111], v[152:155], v[176:179], v[108:111]
	v_mfma_f32_16x16x32_bf16 v[108:111], v[148:151], v[172:175], v[108:111]
	v_mfma_f32_16x16x32_bf16 v[116:119], v[148:151], v[180:183], v[116:119]
	v_mfma_f32_16x16x32_bf16 v[116:119], v[152:155], v[184:187], v[116:119]
	v_mfma_f32_16x16x32_bf16 v[120:123], v[160:163], v[184:187], v[120:123]
	v_mfma_f32_16x16x32_bf16 v[120:123], v[156:159], v[180:183], v[120:123]
	v_mfma_f32_16x16x32_bf16 v[128:131], v[156:159], v[194:197], v[128:131]
	v_mfma_f32_16x16x32_bf16 v[128:131], v[160:163], v[198:201], v[128:131]
	s_setprio 2
	s_barrier
	v_mfma_f32_16x16x32_bf16 v[124:127], v[152:155], v[198:201], v[124:127]
	v_mfma_f32_16x16x32_bf16 v[124:127], v[148:151], v[194:197], v[124:127]
	s_setprio 0
	s_and_b64 vcc, exec, s[58:59]
	s_cbranch_vccz .LBB0_1178
	s_barrier

.LBB0_1625:
	s_add_i32 s51, 0, 0x10000
	s_add_i32 s72, 0, 0x14000
	v_add_u32_e32 v16, s51, v232
	v_add_u32_e32 v32, s72, v232
	ds_read_b128 v[4:7], v16
	ds_read_b128 v[8:11], v16 offset:1024
	ds_read_b128 v[12:15], v16 offset:2048
	ds_read_b128 v[16:19], v16 offset:3072
	ds_read_b128 v[20:23], v32
	ds_read_b128 v[24:27], v32 offset:1024
	ds_read_b128 v[28:31], v32 offset:2048
	ds_read_b128 v[32:35], v32 offset:3072
	v_add_u32_e32 v233, 0, v231
	ds_read_b128 v[36:39], v233
	ds_read_b128 v[40:43], v233 offset:1024
	ds_read_b128 v[44:47], v233 offset:2048
	ds_read_b128 v[48:51], v233 offset:3072
	ds_read_b128 v[52:55], v233 offset:4096
	ds_read_b128 v[56:59], v233 offset:5120
	ds_read_b128 v[60:63], v233 offset:6144
	ds_read_b128 v[64:67], v233 offset:7168
	s_waitcnt vmcnt(8)
	s_waitcnt lgkmcnt(0)
	s_barrier
	s_setprio 1
	v_mfma_f32_16x16x32_bf16 v[68:71], v[4:7], v[36:39], 0
	v_mfma_f32_16x16x32_bf16 v[68:71], v[8:11], v[40:43], v[68:71]
	v_mfma_f32_16x16x32_bf16 v[72:75], v[12:15], v[36:39], 0
	v_mfma_f32_16x16x32_bf16 v[72:75], v[16:19], v[40:43], v[72:75]
	v_mfma_f32_16x16x32_bf16 v[80:83], v[12:15], v[44:47], 0
	v_mfma_f32_16x16x32_bf16 v[80:83], v[16:19], v[48:51], v[80:83]
	v_mfma_f32_16x16x32_bf16 v[76:79], v[4:7], v[44:47], 0
	v_mfma_f32_16x16x32_bf16 v[76:79], v[8:11], v[48:51], v[76:79]
	v_mfma_f32_16x16x32_bf16 v[84:87], v[4:7], v[52:55], 0
	v_mfma_f32_16x16x32_bf16 v[84:87], v[8:11], v[56:59], v[84:87]
	v_mfma_f32_16x16x32_bf16 v[88:91], v[12:15], v[52:55], 0
	v_mfma_f32_16x16x32_bf16 v[88:91], v[16:19], v[56:59], v[88:91]
	v_mfma_f32_16x16x32_bf16 v[96:99], v[12:15], v[60:63], 0
	v_mfma_f32_16x16x32_bf16 v[96:99], v[16:19], v[64:67], v[96:99]
	v_mfma_f32_16x16x32_bf16 v[92:95], v[4:7], v[60:63], 0
	v_mfma_f32_16x16x32_bf16 v[92:95], v[8:11], v[64:67], v[92:95]
	s_setprio 0
	s_setprio 1
	v_mfma_f32_16x16x32_bf16 v[100:103], v[20:23], v[36:39], 0
	v_mfma_f32_16x16x32_bf16 v[36:39], v[28:31], v[36:39], 0
	v_mfma_f32_16x16x32_bf16 v[104:107], v[20:23], v[44:47], 0
	v_mfma_f32_16x16x32_bf16 v[44:47], v[28:31], v[44:47], 0
	v_mfma_f32_16x16x32_bf16 v[108:111], v[20:23], v[52:55], 0
	v_mfma_f32_16x16x32_bf16 v[52:55], v[28:31], v[52:55], 0
	v_mfma_f32_16x16x32_bf16 v[112:115], v[20:23], v[60:63], 0
	v_mfma_f32_16x16x32_bf16 v[60:63], v[28:31], v[60:63], 0
	v_mfma_f32_16x16x32_bf16 v[100:103], v[24:27], v[40:43], v[100:103]
	v_mfma_f32_16x16x32_bf16 v[40:43], v[32:35], v[40:43], v[36:39]
	v_mfma_f32_16x16x32_bf16 v[104:107], v[24:27], v[48:51], v[104:107]
	v_mfma_f32_16x16x32_bf16 v[48:51], v[32:35], v[48:51], v[44:47]
	v_mfma_f32_16x16x32_bf16 v[108:111], v[24:27], v[56:59], v[108:111]
	v_mfma_f32_16x16x32_bf16 v[56:59], v[32:35], v[56:59], v[52:55]
	s_setprio 2
	s_barrier
	v_mfma_f32_16x16x32_bf16 v[112:115], v[24:27], v[64:67], v[112:115]
	v_mfma_f32_16x16x32_bf16 v[64:67], v[32:35], v[64:67], v[60:63]
	s_setprio 0
	v_lshl_add_u64 v[186:187], s[12:13], 0, v[2:3]
	s_add_i32 s51, s51, s56
	v_mov_b32_e32 v191, v3
	v_lshl_add_u64 v[134:135], v[186:187], 0, s[74:75]
	s_mov_b32 m0, s51
	v_lshl_add_u64 v[246:247], s[12:13], 0, v[190:191]
	ds_read_b128 v[36:39], v233 offset:16384
	ds_read_b128 v[44:47], v233 offset:17408
	ds_read_b128 v[52:55], v233 offset:18432
	ds_read_b128 v[60:63], v233 offset:19456
	ds_read_b128 v[116:119], v233 offset:20480
	ds_read_b128 v[120:123], v233 offset:21504
	ds_read_b128 v[124:127], v233 offset:22528
	ds_read_b128 v[128:131], v233 offset:23552
	global_load_lds_dwordx4 v[134:135], off
	v_lshl_add_u64 v[134:135], v[246:247], 0, s[74:75]
	s_add_i32 m0, s51, 0x2000
	s_add_i32 s51, s72, s56
	global_load_lds_dwordx4 v[134:135], off
	s_mov_b32 m0, s51
	v_mov_b32_e32 v133, v3
	global_load_lds_dwordx4 v2, s[16:17]
	s_add_i32 m0, s51, 0x2000
	v_lshl_add_u64 v[248:249], s[14:15], 0, v[132:133]
	v_mov_b32_e32 v189, v3
	global_load_lds_dwordx4 v190, s[16:17]
	v_lshl_add_u64 v[134:135], v[248:249], 0, s[74:75]
	s_mov_b32 m0, s57
	v_lshl_add_u64 v[250:251], s[14:15], 0, v[188:189]
	global_load_lds_dwordx4 v[134:135], off
	v_lshl_add_u64 v[134:135], v[250:251], 0, s[74:75]
	s_mov_b32 m0, s58
	s_nop 0
	global_load_lds_dwordx4 v[134:135], off
	s_waitcnt vmcnt(8)
	s_waitcnt lgkmcnt(0)
	s_barrier
	s_setprio 1
	v_mfma_f32_16x16x32_bf16 v[134:137], v[4:7], v[36:39], 0
	v_mfma_f32_16x16x32_bf16 v[138:141], v[12:15], v[36:39], 0
	v_mfma_f32_16x16x32_bf16 v[142:145], v[4:7], v[52:55], 0
	v_mfma_f32_16x16x32_bf16 v[146:149], v[12:15], v[52:55], 0
	v_mfma_f32_16x16x32_bf16 v[150:153], v[4:7], v[116:119], 0
	v_mfma_f32_16x16x32_bf16 v[154:157], v[12:15], v[116:119], 0
	v_mfma_f32_16x16x32_bf16 v[4:7], v[4:7], v[124:127], 0
	v_mfma_f32_16x16x32_bf16 v[12:15], v[12:15], v[124:127], 0
	v_mfma_f32_16x16x32_bf16 v[134:137], v[8:11], v[44:47], v[134:137]
	v_mfma_f32_16x16x32_bf16 v[138:141], v[16:19], v[44:47], v[138:141]
	v_mfma_f32_16x16x32_bf16 v[142:145], v[8:11], v[60:63], v[142:145]
	v_mfma_f32_16x16x32_bf16 v[146:149], v[16:19], v[60:63], v[146:149]
	v_mfma_f32_16x16x32_bf16 v[150:153], v[8:11], v[120:123], v[150:153]
	v_mfma_f32_16x16x32_bf16 v[154:157], v[16:19], v[120:123], v[154:157]
	v_mfma_f32_16x16x32_bf16 v[158:161], v[8:11], v[128:131], v[4:7]
	v_mfma_f32_16x16x32_bf16 v[162:165], v[16:19], v[128:131], v[12:15]
	s_setprio 0
	s_setprio 1
	v_mfma_f32_16x16x32_bf16 v[4:7], v[20:23], v[36:39], 0
	v_mfma_f32_16x16x32_bf16 v[8:11], v[28:31], v[36:39], 0
	v_mfma_f32_16x16x32_bf16 v[12:15], v[20:23], v[52:55], 0
	v_mfma_f32_16x16x32_bf16 v[16:19], v[28:31], v[52:55], 0
	v_mfma_f32_16x16x32_bf16 v[36:39], v[20:23], v[116:119], 0
	v_mfma_f32_16x16x32_bf16 v[52:55], v[28:31], v[116:119], 0
	v_mfma_f32_16x16x32_bf16 v[20:23], v[20:23], v[124:127], 0
	v_mfma_f32_16x16x32_bf16 v[28:31], v[28:31], v[124:127], 0
	v_mfma_f32_16x16x32_bf16 v[116:119], v[24:27], v[44:47], v[4:7]
	v_mfma_f32_16x16x32_bf16 v[124:127], v[32:35], v[44:47], v[8:11]
	v_mfma_f32_16x16x32_bf16 v[174:177], v[24:27], v[120:123], v[36:39]
	v_mfma_f32_16x16x32_bf16 v[120:123], v[32:35], v[120:123], v[52:55]
	v_mfma_f32_16x16x32_bf16 v[178:181], v[24:27], v[128:131], v[20:23]
	v_mfma_f32_16x16x32_bf16 v[128:131], v[32:35], v[128:131], v[28:31]
	s_setprio 2
	s_barrier
	v_mfma_f32_16x16x32_bf16 v[166:169], v[24:27], v[60:63], v[12:15]
	v_mfma_f32_16x16x32_bf16 v[170:173], v[32:35], v[60:63], v[16:19]
	s_setprio 0
	s_add_i32 s51, 0, 0x18000
	v_add_u32_e32 v4, s51, v232
	s_add_i32 s72, 0, 0x1c000
	ds_read_b128 v[182:185], v4
	ds_read_b128 v[192:195], v4 offset:1024
	ds_read_b128 v[196:199], v4 offset:2048
	ds_read_b128 v[200:203], v4 offset:3072
	v_add_u32_e32 v4, s72, v232
	ds_read_b128 v[204:207], v4
	ds_read_b128 v[208:211], v4 offset:1024
	ds_read_b128 v[212:215], v4 offset:2048
	ds_read_b128 v[216:219], v4 offset:3072
	s_mov_b32 m0, s59
	ds_read_b128 v[44:47], v233 offset:32768
	ds_read_b128 v[52:55], v233 offset:33792
	ds_read_b128 v[60:63], v233 offset:34816
	ds_read_b128 v[220:223], v233 offset:35840
	ds_read_b128 v[224:227], v233 offset:36864
	ds_read_b128 v[234:237], v233 offset:37888
	ds_read_b128 v[238:241], v233 offset:38912
	ds_read_b128 v[242:245], v233 offset:39936
	global_load_lds_dwordx4 v132, s[26:27]
	s_mov_b32 m0, s60
	s_nop 0
	global_load_lds_dwordx4 v188, s[26:27]
	s_waitcnt vmcnt(8)
	s_waitcnt lgkmcnt(0)
	s_barrier
	s_setprio 1
	v_mfma_f32_16x16x32_bf16 v[4:7], v[182:185], v[44:47], v[68:71]
	v_mfma_f32_16x16x32_bf16 v[8:11], v[196:199], v[44:47], v[72:75]
	v_mfma_f32_16x16x32_bf16 v[12:15], v[182:185], v[60:63], v[76:79]
	v_mfma_f32_16x16x32_bf16 v[16:19], v[196:199], v[60:63], v[80:83]
	v_mfma_f32_16x16x32_bf16 v[20:23], v[182:185], v[224:227], v[84:87]
	v_mfma_f32_16x16x32_bf16 v[24:27], v[196:199], v[224:227], v[88:91]
	v_mfma_f32_16x16x32_bf16 v[28:31], v[182:185], v[238:241], v[92:95]
	v_mfma_f32_16x16x32_bf16 v[32:35], v[196:199], v[238:241], v[96:99]
	v_mfma_f32_16x16x32_bf16 v[4:7], v[192:195], v[52:55], v[4:7]
	v_mfma_f32_16x16x32_bf16 v[8:11], v[200:203], v[52:55], v[8:11]
	v_mfma_f32_16x16x32_bf16 v[12:15], v[192:195], v[220:223], v[12:15]
	v_mfma_f32_16x16x32_bf16 v[16:19], v[200:203], v[220:223], v[16:19]
	v_mfma_f32_16x16x32_bf16 v[20:23], v[192:195], v[234:237], v[20:23]
	v_mfma_f32_16x16x32_bf16 v[24:27], v[200:203], v[234:237], v[24:27]
	v_mfma_f32_16x16x32_bf16 v[28:31], v[192:195], v[242:245], v[28:31]
	v_mfma_f32_16x16x32_bf16 v[32:35], v[200:203], v[242:245], v[32:35]
	s_setprio 0
	s_setprio 1
	v_mfma_f32_16x16x32_bf16 v[36:39], v[204:207], v[44:47], v[100:103]
	v_mfma_f32_16x16x32_bf16 v[40:43], v[212:215], v[44:47], v[40:43]
	v_mfma_f32_16x16x32_bf16 v[36:39], v[208:211], v[52:55], v[36:39]
	v_mfma_f32_16x16x32_bf16 v[40:43], v[216:219], v[52:55], v[40:43]
	v_mfma_f32_16x16x32_bf16 v[44:47], v[204:207], v[60:63], v[104:107]
	v_mfma_f32_16x16x32_bf16 v[48:51], v[212:215], v[60:63], v[48:51]
	v_mfma_f32_16x16x32_bf16 v[52:55], v[204:207], v[224:227], v[108:111]
	v_mfma_f32_16x16x32_bf16 v[56:59], v[212:215], v[224:227], v[56:59]
	v_mfma_f32_16x16x32_bf16 v[60:63], v[204:207], v[238:241], v[112:115]
	v_mfma_f32_16x16x32_bf16 v[64:67], v[212:215], v[238:241], v[64:67]
	v_mfma_f32_16x16x32_bf16 v[44:47], v[208:211], v[220:223], v[44:47]
	v_mfma_f32_16x16x32_bf16 v[48:51], v[216:219], v[220:223], v[48:51]
	v_mfma_f32_16x16x32_bf16 v[52:55], v[208:211], v[234:237], v[52:55]
	v_mfma_f32_16x16x32_bf16 v[56:59], v[216:219], v[234:237], v[56:59]
	s_setprio 2
	s_barrier
	v_mfma_f32_16x16x32_bf16 v[60:63], v[208:211], v[242:245], v[60:63]
	v_mfma_f32_16x16x32_bf16 v[64:67], v[216:219], v[242:245], v[64:67]
	s_setprio 0
	s_add_i32 s51, s51, s56
	v_lshl_add_u64 v[68:69], v[186:187], 0, s[24:25]
	s_mov_b32 m0, s51
	ds_read_b128 v[104:107], v233 offset:49152
	ds_read_b128 v[108:111], v233 offset:50176
	ds_read_b128 v[112:115], v233 offset:51200
	ds_read_b128 v[220:223], v233 offset:52224
	ds_read_b128 v[224:227], v233 offset:53248
	ds_read_b128 v[234:237], v233 offset:54272
	ds_read_b128 v[238:241], v233 offset:55296
	ds_read_b128 v[242:245], v233 offset:56320
	global_load_lds_dwordx4 v[68:69], off
	v_lshl_add_u64 v[68:69], v[246:247], 0, s[24:25]
	s_add_i32 m0, s51, 0x2000
	s_add_i32 s51, s72, s56
	global_load_lds_dwordx4 v[68:69], off
	s_mov_b32 m0, s51
	v_lshl_add_u64 v[68:69], v[248:249], 0, s[24:25]
	global_load_lds_dwordx4 v2, s[28:29]
	s_add_i32 m0, s51, 0x2000
	s_nop 0
	global_load_lds_dwordx4 v190, s[28:29]
	s_mov_b32 m0, s64
	s_nop 0
	global_load_lds_dwordx4 v[68:69], off
	v_lshl_add_u64 v[68:69], v[250:251], 0, s[24:25]
	s_mov_b32 m0, s65
	s_nop 0
	global_load_lds_dwordx4 v[68:69], off
	s_waitcnt vmcnt(8)
	s_waitcnt lgkmcnt(0)
	s_barrier
	s_setprio 1
	v_mfma_f32_16x16x32_bf16 v[68:71], v[182:185], v[104:107], v[134:137]
	v_mfma_f32_16x16x32_bf16 v[72:75], v[196:199], v[104:107], v[138:141]
	v_mfma_f32_16x16x32_bf16 v[76:79], v[182:185], v[112:115], v[142:145]
	v_mfma_f32_16x16x32_bf16 v[80:83], v[196:199], v[112:115], v[146:149]
	v_mfma_f32_16x16x32_bf16 v[84:87], v[182:185], v[224:227], v[150:153]
	v_mfma_f32_16x16x32_bf16 v[88:91], v[196:199], v[224:227], v[154:157]
	v_mfma_f32_16x16x32_bf16 v[92:95], v[182:185], v[238:241], v[158:161]
	v_mfma_f32_16x16x32_bf16 v[96:99], v[196:199], v[238:241], v[162:165]
	v_mfma_f32_16x16x32_bf16 v[68:71], v[192:195], v[108:111], v[68:71]
	v_mfma_f32_16x16x32_bf16 v[72:75], v[200:203], v[108:111], v[72:75]
	v_mfma_f32_16x16x32_bf16 v[76:79], v[192:195], v[220:223], v[76:79]
	v_mfma_f32_16x16x32_bf16 v[80:83], v[200:203], v[220:223], v[80:83]
	v_mfma_f32_16x16x32_bf16 v[84:87], v[192:195], v[234:237], v[84:87]
	v_mfma_f32_16x16x32_bf16 v[88:91], v[200:203], v[234:237], v[88:91]
	v_mfma_f32_16x16x32_bf16 v[92:95], v[192:195], v[242:245], v[92:95]
	v_mfma_f32_16x16x32_bf16 v[96:99], v[200:203], v[242:245], v[96:99]
	s_setprio 0
	s_setprio 1
	v_mfma_f32_16x16x32_bf16 v[100:103], v[204:207], v[104:107], v[116:119]
	v_mfma_f32_16x16x32_bf16 v[104:107], v[212:215], v[104:107], v[124:127]
	v_mfma_f32_16x16x32_bf16 v[100:103], v[208:211], v[108:111], v[100:103]
	v_mfma_f32_16x16x32_bf16 v[104:107], v[216:219], v[108:111], v[104:107]
	v_mfma_f32_16x16x32_bf16 v[108:111], v[204:207], v[112:115], v[166:169]
	v_mfma_f32_16x16x32_bf16 v[112:115], v[212:215], v[112:115], v[170:173]
	v_mfma_f32_16x16x32_bf16 v[116:119], v[204:207], v[224:227], v[174:177]
	v_mfma_f32_16x16x32_bf16 v[120:123], v[212:215], v[224:227], v[120:123]
	v_mfma_f32_16x16x32_bf16 v[124:127], v[204:207], v[238:241], v[178:181]
	v_mfma_f32_16x16x32_bf16 v[128:131], v[212:215], v[238:241], v[128:131]
	v_mfma_f32_16x16x32_bf16 v[108:111], v[208:211], v[220:223], v[108:111]
	v_mfma_f32_16x16x32_bf16 v[112:115], v[216:219], v[220:223], v[112:115]
	v_mfma_f32_16x16x32_bf16 v[116:119], v[208:211], v[234:237], v[116:119]
	v_mfma_f32_16x16x32_bf16 v[120:123], v[216:219], v[234:237], v[120:123]
	s_setprio 2
	s_barrier
	v_mfma_f32_16x16x32_bf16 v[124:127], v[208:211], v[242:245], v[124:127]
	v_mfma_f32_16x16x32_bf16 v[128:131], v[216:219], v[242:245], v[128:131]
	s_setprio 0
	s_add_i32 s43, s43, 2
	s_cmp_ge_i32 s43, s42
	s_cbranch_scc0 .LBB0_1625
	v_mov_b32_e32 v192, v2
	s_branch .LBB0_1628

.LBB0_1629:
	s_add_u32 s12, s14, 0xfff80080
	s_addc_u32 s13, s15, -1
	s_add_i32 s29, 0, 0x10000
	s_cmp_eq_u32 s28, 28
	s_cselect_b32 s17, s9, s13
	s_cselect_b32 s16, s8, s12
	s_cselect_b32 s13, s11, s27
	s_cselect_b32 s12, s10, s26
	s_add_i32 s51, 0, 0x14000
	v_add_u32_e32 v144, s29, v232
	v_add_u32_e32 v160, s51, v232
	s_waitcnt lgkmcnt(0)
	ds_read_b128 v[132:135], v144
	ds_read_b128 v[136:139], v144 offset:1024
	ds_read_b128 v[140:143], v144 offset:2048
	ds_read_b128 v[144:147], v144 offset:3072
	ds_read_b128 v[148:151], v160
	ds_read_b128 v[152:155], v160 offset:1024
	ds_read_b128 v[156:159], v160 offset:2048
	ds_read_b128 v[160:163], v160 offset:3072
	s_mov_b32 m0, s66
	v_add_u32_e32 v210, 0, v231
	ds_read_b128 v[164:167], v210
	ds_read_b128 v[168:171], v210 offset:1024
	ds_read_b128 v[172:175], v210 offset:2048
	ds_read_b128 v[176:179], v210 offset:3072
	ds_read_b128 v[180:183], v210 offset:4096
	ds_read_b128 v[184:187], v210 offset:5120
	ds_read_b128 v[194:197], v210 offset:6144
	ds_read_b128 v[198:201], v210 offset:7168
	global_load_lds_dwordx4 v2, s[14:15]
	s_mov_b32 m0, s67
	v_mov_b32_e32 v189, v3
	global_load_lds_dwordx4 v188, s[14:15]
	s_waitcnt vmcnt(8)
	s_waitcnt lgkmcnt(0)
	s_barrier
	s_setprio 1
	v_mfma_f32_16x16x32_bf16 v[4:7], v[132:135], v[164:167], v[4:7]
	v_mfma_f32_16x16x32_bf16 v[4:7], v[136:139], v[168:171], v[4:7]
	v_mfma_f32_16x16x32_bf16 v[8:11], v[144:147], v[168:171], v[8:11]
	v_mfma_f32_16x16x32_bf16 v[8:11], v[140:143], v[164:167], v[8:11]
	v_mfma_f32_16x16x32_bf16 v[16:19], v[140:143], v[172:175], v[16:19]
	v_mfma_f32_16x16x32_bf16 v[16:19], v[144:147], v[176:179], v[16:19]
	v_mfma_f32_16x16x32_bf16 v[12:15], v[136:139], v[176:179], v[12:15]
	v_mfma_f32_16x16x32_bf16 v[12:15], v[132:135], v[172:175], v[12:15]
	v_mfma_f32_16x16x32_bf16 v[20:23], v[132:135], v[180:183], v[20:23]
	v_mfma_f32_16x16x32_bf16 v[20:23], v[136:139], v[184:187], v[20:23]
	v_mfma_f32_16x16x32_bf16 v[24:27], v[144:147], v[184:187], v[24:27]
	v_mfma_f32_16x16x32_bf16 v[24:27], v[140:143], v[180:183], v[24:27]
	v_mfma_f32_16x16x32_bf16 v[32:35], v[140:143], v[194:197], v[32:35]
	v_mfma_f32_16x16x32_bf16 v[32:35], v[144:147], v[198:201], v[32:35]
	v_mfma_f32_16x16x32_bf16 v[28:31], v[136:139], v[198:201], v[28:31]
	v_mfma_f32_16x16x32_bf16 v[28:31], v[132:135], v[194:197], v[28:31]
	s_setprio 0
	s_setprio 1
	v_mfma_f32_16x16x32_bf16 v[36:39], v[148:151], v[164:167], v[36:39]
	v_mfma_f32_16x16x32_bf16 v[36:39], v[152:155], v[168:171], v[36:39]
	v_mfma_f32_16x16x32_bf16 v[40:43], v[160:163], v[168:171], v[40:43]
	v_mfma_f32_16x16x32_bf16 v[40:43], v[156:159], v[164:167], v[40:43]
	v_mfma_f32_16x16x32_bf16 v[48:51], v[156:159], v[172:175], v[48:51]
	v_mfma_f32_16x16x32_bf16 v[48:51], v[160:163], v[176:179], v[48:51]
	v_mfma_f32_16x16x32_bf16 v[44:47], v[152:155], v[176:179], v[44:47]
	v_mfma_f32_16x16x32_bf16 v[44:47], v[148:151], v[172:175], v[44:47]
	v_mfma_f32_16x16x32_bf16 v[52:55], v[148:151], v[180:183], v[52:55]
	v_mfma_f32_16x16x32_bf16 v[52:55], v[152:155], v[184:187], v[52:55]
	v_mfma_f32_16x16x32_bf16 v[56:59], v[160:163], v[184:187], v[56:59]
	v_mfma_f32_16x16x32_bf16 v[56:59], v[156:159], v[180:183], v[56:59]
	v_mfma_f32_16x16x32_bf16 v[64:67], v[156:159], v[194:197], v[64:67]
	v_mfma_f32_16x16x32_bf16 v[64:67], v[160:163], v[198:201], v[64:67]
	s_setprio 2
	s_barrier
	v_mfma_f32_16x16x32_bf16 v[60:63], v[152:155], v[198:201], v[60:63]
	v_mfma_f32_16x16x32_bf16 v[60:63], v[148:151], v[194:197], v[60:63]
	s_setprio 0
	s_add_i32 s29, s29, s56
	s_mov_b32 m0, s29
	ds_read_b128 v[164:167], v210 offset:16384
	ds_read_b128 v[168:171], v210 offset:17408
	ds_read_b128 v[172:175], v210 offset:18432
	ds_read_b128 v[176:179], v210 offset:19456
	ds_read_b128 v[180:183], v210 offset:20480
	ds_read_b128 v[184:187], v210 offset:21504
	ds_read_b128 v[194:197], v210 offset:22528
	ds_read_b128 v[198:201], v210 offset:23552
	global_load_lds_dwordx4 v192, s[12:13]
	s_add_i32 m0, s29, 0x2000
	s_add_u32 s42, s12, 0x80000
	s_addc_u32 s43, s13, 0
	s_add_i32 s29, s51, s56
	global_load_lds_dwordx4 v190, s[12:13]
	s_mov_b32 m0, s29
	v_mov_b32_e32 v193, v3
	global_load_lds_dwordx4 v192, s[42:43]
	s_add_i32 m0, s29, 0x2000
	v_mov_b32_e32 v191, v3
	global_load_lds_dwordx4 v190, s[42:43]
	s_mov_b32 m0, s57
	v_lshl_add_u64 v[202:203], s[12:13], 0, v[192:193]
	global_load_lds_dwordx4 v2, s[16:17]
	s_mov_b32 m0, s58
	v_lshl_add_u64 v[204:205], s[12:13], 0, v[190:191]
	global_load_lds_dwordx4 v188, s[16:17]
	s_waitcnt vmcnt(8)
	s_waitcnt lgkmcnt(0)
	v_lshl_add_u64 v[206:207], s[16:17], 0, v[2:3]
	v_lshl_add_u64 v[208:209], s[16:17], 0, v[188:189]
	s_barrier
	s_setprio 1
	v_mfma_f32_16x16x32_bf16 v[68:71], v[132:135], v[164:167], v[68:71]
	v_mfma_f32_16x16x32_bf16 v[68:71], v[136:139], v[168:171], v[68:71]
	v_mfma_f32_16x16x32_bf16 v[72:75], v[144:147], v[168:171], v[72:75]
	v_mfma_f32_16x16x32_bf16 v[72:75], v[140:143], v[164:167], v[72:75]
	v_mfma_f32_16x16x32_bf16 v[80:83], v[140:143], v[172:175], v[80:83]
	v_mfma_f32_16x16x32_bf16 v[80:83], v[144:147], v[176:179], v[80:83]
	v_mfma_f32_16x16x32_bf16 v[76:79], v[136:139], v[176:179], v[76:79]
	v_mfma_f32_16x16x32_bf16 v[76:79], v[132:135], v[172:175], v[76:79]
	v_mfma_f32_16x16x32_bf16 v[84:87], v[132:135], v[180:183], v[84:87]
	v_mfma_f32_16x16x32_bf16 v[84:87], v[136:139], v[184:187], v[84:87]
	v_mfma_f32_16x16x32_bf16 v[88:91], v[144:147], v[184:187], v[88:91]
	v_mfma_f32_16x16x32_bf16 v[88:91], v[140:143], v[180:183], v[88:91]
	v_mfma_f32_16x16x32_bf16 v[96:99], v[140:143], v[194:197], v[96:99]
	v_mfma_f32_16x16x32_bf16 v[96:99], v[144:147], v[198:201], v[96:99]
	v_mfma_f32_16x16x32_bf16 v[92:95], v[136:139], v[198:201], v[92:95]
	v_mfma_f32_16x16x32_bf16 v[92:95], v[132:135], v[194:197], v[92:95]
	s_setprio 0
	s_setprio 1
	v_mfma_f32_16x16x32_bf16 v[100:103], v[148:151], v[164:167], v[100:103]
	v_mfma_f32_16x16x32_bf16 v[100:103], v[152:155], v[168:171], v[100:103]
	v_mfma_f32_16x16x32_bf16 v[104:107], v[160:163], v[168:171], v[104:107]
	v_mfma_f32_16x16x32_bf16 v[104:107], v[156:159], v[164:167], v[104:107]
	v_mfma_f32_16x16x32_bf16 v[112:115], v[156:159], v[172:175], v[112:115]
	v_mfma_f32_16x16x32_bf16 v[112:115], v[160:163], v[176:179], v[112:115]
	v_mfma_f32_16x16x32_bf16 v[108:111], v[152:155], v[176:179], v[108:111]
	v_mfma_f32_16x16x32_bf16 v[108:111], v[148:151], v[172:175], v[108:111]
	v_mfma_f32_16x16x32_bf16 v[116:119], v[148:151], v[180:183], v[116:119]
	v_mfma_f32_16x16x32_bf16 v[116:119], v[152:155], v[184:187], v[116:119]
	v_mfma_f32_16x16x32_bf16 v[120:123], v[160:163], v[184:187], v[120:123]
	v_mfma_f32_16x16x32_bf16 v[120:123], v[156:159], v[180:183], v[120:123]
	v_mfma_f32_16x16x32_bf16 v[128:131], v[156:159], v[194:197], v[128:131]
	v_mfma_f32_16x16x32_bf16 v[128:131], v[160:163], v[198:201], v[128:131]
	s_setprio 2
	s_barrier
	v_mfma_f32_16x16x32_bf16 v[124:127], v[152:155], v[198:201], v[124:127]
	v_mfma_f32_16x16x32_bf16 v[124:127], v[148:151], v[194:197], v[124:127]
	s_setprio 0
	s_add_i32 s29, 0, 0x18000
	s_add_i32 s42, 0, 0x1c000
	v_add_u32_e32 v144, s29, v232
	v_add_u32_e32 v160, s42, v232
	ds_read_b128 v[132:135], v144
	ds_read_b128 v[136:139], v144 offset:1024
	ds_read_b128 v[140:143], v144 offset:2048
	ds_read_b128 v[144:147], v144 offset:3072
	ds_read_b128 v[148:151], v160
	ds_read_b128 v[152:155], v160 offset:1024
	ds_read_b128 v[156:159], v160 offset:2048
	ds_read_b128 v[160:163], v160 offset:3072
	s_add_u32 s16, s16, 0x80000
	s_addc_u32 s17, s17, 0
	s_mov_b32 m0, s59
	ds_read_b128 v[164:167], v210 offset:32768
	ds_read_b128 v[168:171], v210 offset:33792
	ds_read_b128 v[172:175], v210 offset:34816
	ds_read_b128 v[176:179], v210 offset:35840
	ds_read_b128 v[180:183], v210 offset:36864
	ds_read_b128 v[184:187], v210 offset:37888
	ds_read_b128 v[194:197], v210 offset:38912
	ds_read_b128 v[198:201], v210 offset:39936
	global_load_lds_dwordx4 v2, s[16:17]
	s_mov_b32 m0, s60
	s_nop 0
	global_load_lds_dwordx4 v188, s[16:17]
	s_waitcnt vmcnt(8)
	s_waitcnt lgkmcnt(0)
	s_barrier
	s_setprio 1
	v_mfma_f32_16x16x32_bf16 v[4:7], v[132:135], v[164:167], v[4:7]
	v_mfma_f32_16x16x32_bf16 v[4:7], v[136:139], v[168:171], v[4:7]
	v_mfma_f32_16x16x32_bf16 v[8:11], v[144:147], v[168:171], v[8:11]
	v_mfma_f32_16x16x32_bf16 v[8:11], v[140:143], v[164:167], v[8:11]
	v_mfma_f32_16x16x32_bf16 v[16:19], v[140:143], v[172:175], v[16:19]
	v_mfma_f32_16x16x32_bf16 v[16:19], v[144:147], v[176:179], v[16:19]
	v_mfma_f32_16x16x32_bf16 v[12:15], v[136:139], v[176:179], v[12:15]
	v_mfma_f32_16x16x32_bf16 v[12:15], v[132:135], v[172:175], v[12:15]
	v_mfma_f32_16x16x32_bf16 v[20:23], v[132:135], v[180:183], v[20:23]
	v_mfma_f32_16x16x32_bf16 v[20:23], v[136:139], v[184:187], v[20:23]
	v_mfma_f32_16x16x32_bf16 v[24:27], v[144:147], v[184:187], v[24:27]
	v_mfma_f32_16x16x32_bf16 v[24:27], v[140:143], v[180:183], v[24:27]
	v_mfma_f32_16x16x32_bf16 v[32:35], v[140:143], v[194:197], v[32:35]
	v_mfma_f32_16x16x32_bf16 v[32:35], v[144:147], v[198:201], v[32:35]
	v_mfma_f32_16x16x32_bf16 v[28:31], v[136:139], v[198:201], v[28:31]
	v_mfma_f32_16x16x32_bf16 v[28:31], v[132:135], v[194:197], v[28:31]
	s_setprio 0
	s_setprio 1
	v_mfma_f32_16x16x32_bf16 v[36:39], v[148:151], v[164:167], v[36:39]
	v_mfma_f32_16x16x32_bf16 v[36:39], v[152:155], v[168:171], v[36:39]
	v_mfma_f32_16x16x32_bf16 v[40:43], v[160:163], v[168:171], v[40:43]
	v_mfma_f32_16x16x32_bf16 v[40:43], v[156:159], v[164:167], v[40:43]
	v_mfma_f32_16x16x32_bf16 v[48:51], v[156:159], v[172:175], v[48:51]
	v_mfma_f32_16x16x32_bf16 v[48:51], v[160:163], v[176:179], v[48:51]
	v_mfma_f32_16x16x32_bf16 v[44:47], v[152:155], v[176:179], v[44:47]
	v_mfma_f32_16x16x32_bf16 v[44:47], v[148:151], v[172:175], v[44:47]
	v_mfma_f32_16x16x32_bf16 v[52:55], v[148:151], v[180:183], v[52:55]
	v_mfma_f32_16x16x32_bf16 v[52:55], v[152:155], v[184:187], v[52:55]
	v_mfma_f32_16x16x32_bf16 v[56:59], v[160:163], v[184:187], v[56:59]
	v_mfma_f32_16x16x32_bf16 v[56:59], v[156:159], v[180:183], v[56:59]
	v_mfma_f32_16x16x32_bf16 v[64:67], v[156:159], v[194:197], v[64:67]
	v_mfma_f32_16x16x32_bf16 v[64:67], v[160:163], v[198:201], v[64:67]
	s_setprio 2
	s_barrier
	v_mfma_f32_16x16x32_bf16 v[60:63], v[152:155], v[198:201], v[60:63]
	v_mfma_f32_16x16x32_bf16 v[60:63], v[148:151], v[194:197], v[60:63]
	s_setprio 0
	s_add_i32 s16, s29, s56
	v_lshl_add_u64 v[202:203], v[202:203], 0, s[86:87]
	s_mov_b32 m0, s16
	ds_read_b128 v[164:167], v210 offset:49152
	ds_read_b128 v[168:171], v210 offset:50176
	ds_read_b128 v[172:175], v210 offset:51200
	ds_read_b128 v[176:179], v210 offset:52224
	ds_read_b128 v[180:183], v210 offset:53248
	ds_read_b128 v[184:187], v210 offset:54272
	ds_read_b128 v[194:197], v210 offset:55296
	ds_read_b128 v[198:201], v210 offset:56320
	global_load_lds_dwordx4 v[202:203], off
	s_add_i32 m0, s16, 0x2000
	s_add_u32 s12, s12, 0x80080
	v_lshl_add_u64 v[202:203], v[204:205], 0, s[86:87]
	s_addc_u32 s13, s13, 0
	s_add_i32 s16, s42, s56
	global_load_lds_dwordx4 v[202:203], off
	s_mov_b32 m0, s16
	v_lshl_add_u64 v[202:203], v[206:207], 0, s[86:87]
	global_load_lds_dwordx4 v192, s[12:13]
	s_add_i32 m0, s16, 0x2000
	s_nop 0
	global_load_lds_dwordx4 v190, s[12:13]
	s_mov_b32 m0, s64
	s_nop 0
	global_load_lds_dwordx4 v[202:203], off
	v_lshl_add_u64 v[202:203], v[208:209], 0, s[86:87]
	s_mov_b32 m0, s65
	s_nop 0
	global_load_lds_dwordx4 v[202:203], off
	s_waitcnt vmcnt(8)
	s_waitcnt lgkmcnt(0)
	s_barrier
	s_setprio 1
	v_mfma_f32_16x16x32_bf16 v[68:71], v[132:135], v[164:167], v[68:71]
	v_mfma_f32_16x16x32_bf16 v[68:71], v[136:139], v[168:171], v[68:71]
	v_mfma_f32_16x16x32_bf16 v[72:75], v[144:147], v[168:171], v[72:75]
	v_mfma_f32_16x16x32_bf16 v[72:75], v[140:143], v[164:167], v[72:75]
	v_mfma_f32_16x16x32_bf16 v[80:83], v[140:143], v[172:175], v[80:83]
	v_mfma_f32_16x16x32_bf16 v[80:83], v[144:147], v[176:179], v[80:83]
	v_mfma_f32_16x16x32_bf16 v[76:79], v[136:139], v[176:179], v[76:79]
	v_mfma_f32_16x16x32_bf16 v[76:79], v[132:135], v[172:175], v[76:79]
	v_mfma_f32_16x16x32_bf16 v[84:87], v[132:135], v[180:183], v[84:87]
	v_mfma_f32_16x16x32_bf16 v[84:87], v[136:139], v[184:187], v[84:87]
	v_mfma_f32_16x16x32_bf16 v[88:91], v[144:147], v[184:187], v[88:91]
	v_mfma_f32_16x16x32_bf16 v[88:91], v[140:143], v[180:183], v[88:91]
	v_mfma_f32_16x16x32_bf16 v[96:99], v[140:143], v[194:197], v[96:99]
	v_mfma_f32_16x16x32_bf16 v[96:99], v[144:147], v[198:201], v[96:99]
	v_mfma_f32_16x16x32_bf16 v[92:95], v[136:139], v[198:201], v[92:95]
	v_mfma_f32_16x16x32_bf16 v[92:95], v[132:135], v[194:197], v[92:95]
	s_setprio 0
	s_setprio 1
	v_mfma_f32_16x16x32_bf16 v[100:103], v[148:151], v[164:167], v[100:103]
	v_mfma_f32_16x16x32_bf16 v[100:103], v[152:155], v[168:171], v[100:103]
	v_mfma_f32_16x16x32_bf16 v[104:107], v[160:163], v[168:171], v[104:107]
	v_mfma_f32_16x16x32_bf16 v[104:107], v[156:159], v[164:167], v[104:107]
	v_mfma_f32_16x16x32_bf16 v[112:115], v[156:159], v[172:175], v[112:115]
	v_mfma_f32_16x16x32_bf16 v[112:115], v[160:163], v[176:179], v[112:115]
	v_mfma_f32_16x16x32_bf16 v[108:111], v[152:155], v[176:179], v[108:111]
	v_mfma_f32_16x16x32_bf16 v[108:111], v[148:151], v[172:175], v[108:111]
	v_mfma_f32_16x16x32_bf16 v[116:119], v[148:151], v[180:183], v[116:119]
	v_mfma_f32_16x16x32_bf16 v[116:119], v[152:155], v[184:187], v[116:119]
	v_mfma_f32_16x16x32_bf16 v[120:123], v[160:163], v[184:187], v[120:123]
	v_mfma_f32_16x16x32_bf16 v[120:123], v[156:159], v[180:183], v[120:123]
	v_mfma_f32_16x16x32_bf16 v[128:131], v[156:159], v[194:197], v[128:131]
	v_mfma_f32_16x16x32_bf16 v[128:131], v[160:163], v[198:201], v[128:131]
	s_setprio 2
	s_barrier
	v_mfma_f32_16x16x32_bf16 v[124:127], v[152:155], v[198:201], v[124:127]
	v_mfma_f32_16x16x32_bf16 v[124:127], v[148:151], v[194:197], v[124:127]
	s_setprio 0
	s_add_i32 s28, s28, 2
	s_add_u32 s14, s14, 0x100
	s_addc_u32 s15, s15, 0
	s_add_u32 s26, s26, 0x100
	s_addc_u32 s27, s27, 0
	s_cmp_gt_u32 s28, 29
	s_cbranch_scc0 .LBB0_1629
	s_and_b64 vcc, exec, s[48:49]
	s_cbranch_vccz .LBB0_1632
	s_barrier

.LBB0_2065:
	s_add_i32 s51, 0, 0x10000
	s_add_i32 s71, 0, 0x14000
	v_add_u32_e32 v16, s51, v232
	v_add_u32_e32 v32, s71, v232
	ds_read_b128 v[4:7], v16
	ds_read_b128 v[8:11], v16 offset:1024
	ds_read_b128 v[12:15], v16 offset:2048
	ds_read_b128 v[16:19], v16 offset:3072
	ds_read_b128 v[20:23], v32
	ds_read_b128 v[24:27], v32 offset:1024
	ds_read_b128 v[28:31], v32 offset:2048
	ds_read_b128 v[32:35], v32 offset:3072
	v_add_u32_e32 v233, 0, v231
	ds_read_b128 v[36:39], v233
	ds_read_b128 v[40:43], v233 offset:1024
	ds_read_b128 v[44:47], v233 offset:2048
	ds_read_b128 v[48:51], v233 offset:3072
	ds_read_b128 v[52:55], v233 offset:4096
	ds_read_b128 v[56:59], v233 offset:5120
	ds_read_b128 v[60:63], v233 offset:6144
	ds_read_b128 v[64:67], v233 offset:7168
	s_waitcnt vmcnt(8)
	s_waitcnt lgkmcnt(0)
	s_barrier
	s_setprio 1
	v_mfma_f32_16x16x32_bf16 v[68:71], v[4:7], v[36:39], 0
	v_mfma_f32_16x16x32_bf16 v[68:71], v[8:11], v[40:43], v[68:71]
	v_mfma_f32_16x16x32_bf16 v[72:75], v[12:15], v[36:39], 0
	v_mfma_f32_16x16x32_bf16 v[72:75], v[16:19], v[40:43], v[72:75]
	v_mfma_f32_16x16x32_bf16 v[80:83], v[12:15], v[44:47], 0
	v_mfma_f32_16x16x32_bf16 v[80:83], v[16:19], v[48:51], v[80:83]
	v_mfma_f32_16x16x32_bf16 v[76:79], v[4:7], v[44:47], 0
	v_mfma_f32_16x16x32_bf16 v[76:79], v[8:11], v[48:51], v[76:79]
	v_mfma_f32_16x16x32_bf16 v[84:87], v[4:7], v[52:55], 0
	v_mfma_f32_16x16x32_bf16 v[84:87], v[8:11], v[56:59], v[84:87]
	v_mfma_f32_16x16x32_bf16 v[88:91], v[12:15], v[52:55], 0
	v_mfma_f32_16x16x32_bf16 v[88:91], v[16:19], v[56:59], v[88:91]
	v_mfma_f32_16x16x32_bf16 v[96:99], v[12:15], v[60:63], 0
	v_mfma_f32_16x16x32_bf16 v[96:99], v[16:19], v[64:67], v[96:99]
	v_mfma_f32_16x16x32_bf16 v[92:95], v[4:7], v[60:63], 0
	v_mfma_f32_16x16x32_bf16 v[92:95], v[8:11], v[64:67], v[92:95]
	s_setprio 0
	s_setprio 1
	v_mfma_f32_16x16x32_bf16 v[100:103], v[20:23], v[36:39], 0
	v_mfma_f32_16x16x32_bf16 v[36:39], v[28:31], v[36:39], 0
	v_mfma_f32_16x16x32_bf16 v[104:107], v[20:23], v[44:47], 0
	v_mfma_f32_16x16x32_bf16 v[44:47], v[28:31], v[44:47], 0
	v_mfma_f32_16x16x32_bf16 v[108:111], v[20:23], v[52:55], 0
	v_mfma_f32_16x16x32_bf16 v[52:55], v[28:31], v[52:55], 0
	v_mfma_f32_16x16x32_bf16 v[112:115], v[20:23], v[60:63], 0
	v_mfma_f32_16x16x32_bf16 v[60:63], v[28:31], v[60:63], 0
	v_mfma_f32_16x16x32_bf16 v[100:103], v[24:27], v[40:43], v[100:103]
	v_mfma_f32_16x16x32_bf16 v[40:43], v[32:35], v[40:43], v[36:39]
	v_mfma_f32_16x16x32_bf16 v[104:107], v[24:27], v[48:51], v[104:107]
	v_mfma_f32_16x16x32_bf16 v[48:51], v[32:35], v[48:51], v[44:47]
	v_mfma_f32_16x16x32_bf16 v[108:111], v[24:27], v[56:59], v[108:111]
	v_mfma_f32_16x16x32_bf16 v[56:59], v[32:35], v[56:59], v[52:55]
	s_setprio 2
	s_barrier
	v_mfma_f32_16x16x32_bf16 v[112:115], v[24:27], v[64:67], v[112:115]
	v_mfma_f32_16x16x32_bf16 v[64:67], v[32:35], v[64:67], v[60:63]
	s_setprio 0
	v_lshl_add_u64 v[186:187], s[12:13], 0, v[2:3]
	s_add_i32 s51, s51, s38
	v_mov_b32_e32 v191, v3
	v_lshl_add_u64 v[134:135], v[186:187], 0, s[74:75]
	s_mov_b32 m0, s51
	v_lshl_add_u64 v[246:247], s[12:13], 0, v[190:191]
	ds_read_b128 v[36:39], v233 offset:16384
	ds_read_b128 v[44:47], v233 offset:17408
	ds_read_b128 v[52:55], v233 offset:18432
	ds_read_b128 v[60:63], v233 offset:19456
	ds_read_b128 v[116:119], v233 offset:20480
	ds_read_b128 v[120:123], v233 offset:21504
	ds_read_b128 v[124:127], v233 offset:22528
	ds_read_b128 v[128:131], v233 offset:23552
	global_load_lds_dwordx4 v[134:135], off
	v_lshl_add_u64 v[134:135], v[246:247], 0, s[74:75]
	s_add_i32 m0, s51, 0x2000
	s_add_i32 s51, s71, s38
	global_load_lds_dwordx4 v[134:135], off
	s_mov_b32 m0, s51
	v_mov_b32_e32 v133, v3
	global_load_lds_dwordx4 v2, s[16:17]
	s_add_i32 m0, s51, 0x2000
	v_lshl_add_u64 v[248:249], s[14:15], 0, v[132:133]
	v_mov_b32_e32 v189, v3
	global_load_lds_dwordx4 v190, s[16:17]
	v_lshl_add_u64 v[134:135], v[248:249], 0, s[74:75]
	s_mov_b32 m0, s56
	v_lshl_add_u64 v[250:251], s[14:15], 0, v[188:189]
	global_load_lds_dwordx4 v[134:135], off
	v_lshl_add_u64 v[134:135], v[250:251], 0, s[74:75]
	s_mov_b32 m0, s57
	s_nop 0
	global_load_lds_dwordx4 v[134:135], off
	s_waitcnt vmcnt(8)
	s_waitcnt lgkmcnt(0)
	s_barrier
	s_setprio 1
	v_mfma_f32_16x16x32_bf16 v[134:137], v[4:7], v[36:39], 0
	v_mfma_f32_16x16x32_bf16 v[138:141], v[12:15], v[36:39], 0
	v_mfma_f32_16x16x32_bf16 v[142:145], v[4:7], v[52:55], 0
	v_mfma_f32_16x16x32_bf16 v[146:149], v[12:15], v[52:55], 0
	v_mfma_f32_16x16x32_bf16 v[150:153], v[4:7], v[116:119], 0
	v_mfma_f32_16x16x32_bf16 v[154:157], v[12:15], v[116:119], 0
	v_mfma_f32_16x16x32_bf16 v[4:7], v[4:7], v[124:127], 0
	v_mfma_f32_16x16x32_bf16 v[12:15], v[12:15], v[124:127], 0
	v_mfma_f32_16x16x32_bf16 v[134:137], v[8:11], v[44:47], v[134:137]
	v_mfma_f32_16x16x32_bf16 v[138:141], v[16:19], v[44:47], v[138:141]
	v_mfma_f32_16x16x32_bf16 v[142:145], v[8:11], v[60:63], v[142:145]
	v_mfma_f32_16x16x32_bf16 v[146:149], v[16:19], v[60:63], v[146:149]
	v_mfma_f32_16x16x32_bf16 v[150:153], v[8:11], v[120:123], v[150:153]
	v_mfma_f32_16x16x32_bf16 v[154:157], v[16:19], v[120:123], v[154:157]
	v_mfma_f32_16x16x32_bf16 v[158:161], v[8:11], v[128:131], v[4:7]
	v_mfma_f32_16x16x32_bf16 v[162:165], v[16:19], v[128:131], v[12:15]
	s_setprio 0
	s_setprio 1
	v_mfma_f32_16x16x32_bf16 v[4:7], v[20:23], v[36:39], 0
	v_mfma_f32_16x16x32_bf16 v[8:11], v[28:31], v[36:39], 0
	v_mfma_f32_16x16x32_bf16 v[12:15], v[20:23], v[52:55], 0
	v_mfma_f32_16x16x32_bf16 v[16:19], v[28:31], v[52:55], 0
	v_mfma_f32_16x16x32_bf16 v[36:39], v[20:23], v[116:119], 0
	v_mfma_f32_16x16x32_bf16 v[52:55], v[28:31], v[116:119], 0
	v_mfma_f32_16x16x32_bf16 v[20:23], v[20:23], v[124:127], 0
	v_mfma_f32_16x16x32_bf16 v[28:31], v[28:31], v[124:127], 0
	v_mfma_f32_16x16x32_bf16 v[116:119], v[24:27], v[44:47], v[4:7]
	v_mfma_f32_16x16x32_bf16 v[124:127], v[32:35], v[44:47], v[8:11]
	v_mfma_f32_16x16x32_bf16 v[174:177], v[24:27], v[120:123], v[36:39]
	v_mfma_f32_16x16x32_bf16 v[120:123], v[32:35], v[120:123], v[52:55]
	v_mfma_f32_16x16x32_bf16 v[178:181], v[24:27], v[128:131], v[20:23]
	v_mfma_f32_16x16x32_bf16 v[128:131], v[32:35], v[128:131], v[28:31]
	s_setprio 2
	s_barrier
	v_mfma_f32_16x16x32_bf16 v[166:169], v[24:27], v[60:63], v[12:15]
	v_mfma_f32_16x16x32_bf16 v[170:173], v[32:35], v[60:63], v[16:19]
	s_setprio 0
	s_add_i32 s51, 0, 0x18000
	v_add_u32_e32 v4, s51, v232
	s_add_i32 s71, 0, 0x1c000
	ds_read_b128 v[182:185], v4
	ds_read_b128 v[192:195], v4 offset:1024
	ds_read_b128 v[196:199], v4 offset:2048
	ds_read_b128 v[200:203], v4 offset:3072
	v_add_u32_e32 v4, s71, v232
	ds_read_b128 v[204:207], v4
	ds_read_b128 v[208:211], v4 offset:1024
	ds_read_b128 v[212:215], v4 offset:2048
	ds_read_b128 v[216:219], v4 offset:3072
	s_mov_b32 m0, s58
	ds_read_b128 v[44:47], v233 offset:32768
	ds_read_b128 v[52:55], v233 offset:33792
	ds_read_b128 v[60:63], v233 offset:34816
	ds_read_b128 v[220:223], v233 offset:35840
	ds_read_b128 v[224:227], v233 offset:36864
	ds_read_b128 v[234:237], v233 offset:37888
	ds_read_b128 v[238:241], v233 offset:38912
	ds_read_b128 v[242:245], v233 offset:39936
	global_load_lds_dwordx4 v132, s[26:27]
	s_mov_b32 m0, s59
	s_nop 0
	global_load_lds_dwordx4 v188, s[26:27]
	s_waitcnt vmcnt(8)
	s_waitcnt lgkmcnt(0)
	s_barrier
	s_setprio 1
	v_mfma_f32_16x16x32_bf16 v[4:7], v[182:185], v[44:47], v[68:71]
	v_mfma_f32_16x16x32_bf16 v[8:11], v[196:199], v[44:47], v[72:75]
	v_mfma_f32_16x16x32_bf16 v[12:15], v[182:185], v[60:63], v[76:79]
	v_mfma_f32_16x16x32_bf16 v[16:19], v[196:199], v[60:63], v[80:83]
	v_mfma_f32_16x16x32_bf16 v[20:23], v[182:185], v[224:227], v[84:87]
	v_mfma_f32_16x16x32_bf16 v[24:27], v[196:199], v[224:227], v[88:91]
	v_mfma_f32_16x16x32_bf16 v[28:31], v[182:185], v[238:241], v[92:95]
	v_mfma_f32_16x16x32_bf16 v[32:35], v[196:199], v[238:241], v[96:99]
	v_mfma_f32_16x16x32_bf16 v[4:7], v[192:195], v[52:55], v[4:7]
	v_mfma_f32_16x16x32_bf16 v[8:11], v[200:203], v[52:55], v[8:11]
	v_mfma_f32_16x16x32_bf16 v[12:15], v[192:195], v[220:223], v[12:15]
	v_mfma_f32_16x16x32_bf16 v[16:19], v[200:203], v[220:223], v[16:19]
	v_mfma_f32_16x16x32_bf16 v[20:23], v[192:195], v[234:237], v[20:23]
	v_mfma_f32_16x16x32_bf16 v[24:27], v[200:203], v[234:237], v[24:27]
	v_mfma_f32_16x16x32_bf16 v[28:31], v[192:195], v[242:245], v[28:31]
	v_mfma_f32_16x16x32_bf16 v[32:35], v[200:203], v[242:245], v[32:35]
	s_setprio 0
	s_setprio 1
	v_mfma_f32_16x16x32_bf16 v[36:39], v[204:207], v[44:47], v[100:103]
	v_mfma_f32_16x16x32_bf16 v[40:43], v[212:215], v[44:47], v[40:43]
	v_mfma_f32_16x16x32_bf16 v[36:39], v[208:211], v[52:55], v[36:39]
	v_mfma_f32_16x16x32_bf16 v[40:43], v[216:219], v[52:55], v[40:43]
	v_mfma_f32_16x16x32_bf16 v[44:47], v[204:207], v[60:63], v[104:107]
	v_mfma_f32_16x16x32_bf16 v[48:51], v[212:215], v[60:63], v[48:51]
	v_mfma_f32_16x16x32_bf16 v[52:55], v[204:207], v[224:227], v[108:111]
	v_mfma_f32_16x16x32_bf16 v[56:59], v[212:215], v[224:227], v[56:59]
	v_mfma_f32_16x16x32_bf16 v[60:63], v[204:207], v[238:241], v[112:115]
	v_mfma_f32_16x16x32_bf16 v[64:67], v[212:215], v[238:241], v[64:67]
	v_mfma_f32_16x16x32_bf16 v[44:47], v[208:211], v[220:223], v[44:47]
	v_mfma_f32_16x16x32_bf16 v[48:51], v[216:219], v[220:223], v[48:51]
	v_mfma_f32_16x16x32_bf16 v[52:55], v[208:211], v[234:237], v[52:55]
	v_mfma_f32_16x16x32_bf16 v[56:59], v[216:219], v[234:237], v[56:59]
	s_setprio 2
	s_barrier
	v_mfma_f32_16x16x32_bf16 v[60:63], v[208:211], v[242:245], v[60:63]
	v_mfma_f32_16x16x32_bf16 v[64:67], v[216:219], v[242:245], v[64:67]
	s_setprio 0
	s_add_i32 s51, s51, s38
	v_lshl_add_u64 v[68:69], v[186:187], 0, s[24:25]
	s_mov_b32 m0, s51
	ds_read_b128 v[104:107], v233 offset:49152
	ds_read_b128 v[108:111], v233 offset:50176
	ds_read_b128 v[112:115], v233 offset:51200
	ds_read_b128 v[220:223], v233 offset:52224
	ds_read_b128 v[224:227], v233 offset:53248
	ds_read_b128 v[234:237], v233 offset:54272
	ds_read_b128 v[238:241], v233 offset:55296
	ds_read_b128 v[242:245], v233 offset:56320
	global_load_lds_dwordx4 v[68:69], off
	v_lshl_add_u64 v[68:69], v[246:247], 0, s[24:25]
	s_add_i32 m0, s51, 0x2000
	s_add_i32 s51, s71, s38
	global_load_lds_dwordx4 v[68:69], off
	s_mov_b32 m0, s51
	v_lshl_add_u64 v[68:69], v[248:249], 0, s[24:25]
	global_load_lds_dwordx4 v2, s[28:29]
	s_add_i32 m0, s51, 0x2000
	s_nop 0
	global_load_lds_dwordx4 v190, s[28:29]
	s_mov_b32 m0, s63
	s_nop 0
	global_load_lds_dwordx4 v[68:69], off
	v_lshl_add_u64 v[68:69], v[250:251], 0, s[24:25]
	s_mov_b32 m0, s64
	s_nop 0
	global_load_lds_dwordx4 v[68:69], off
	s_waitcnt vmcnt(8)
	s_waitcnt lgkmcnt(0)
	s_barrier
	s_setprio 1
	v_mfma_f32_16x16x32_bf16 v[68:71], v[182:185], v[104:107], v[134:137]
	v_mfma_f32_16x16x32_bf16 v[72:75], v[196:199], v[104:107], v[138:141]
	v_mfma_f32_16x16x32_bf16 v[76:79], v[182:185], v[112:115], v[142:145]
	v_mfma_f32_16x16x32_bf16 v[80:83], v[196:199], v[112:115], v[146:149]
	v_mfma_f32_16x16x32_bf16 v[84:87], v[182:185], v[224:227], v[150:153]
	v_mfma_f32_16x16x32_bf16 v[88:91], v[196:199], v[224:227], v[154:157]
	v_mfma_f32_16x16x32_bf16 v[92:95], v[182:185], v[238:241], v[158:161]
	v_mfma_f32_16x16x32_bf16 v[96:99], v[196:199], v[238:241], v[162:165]
	v_mfma_f32_16x16x32_bf16 v[68:71], v[192:195], v[108:111], v[68:71]
	v_mfma_f32_16x16x32_bf16 v[72:75], v[200:203], v[108:111], v[72:75]
	v_mfma_f32_16x16x32_bf16 v[76:79], v[192:195], v[220:223], v[76:79]
	v_mfma_f32_16x16x32_bf16 v[80:83], v[200:203], v[220:223], v[80:83]
	v_mfma_f32_16x16x32_bf16 v[84:87], v[192:195], v[234:237], v[84:87]
	v_mfma_f32_16x16x32_bf16 v[88:91], v[200:203], v[234:237], v[88:91]
	v_mfma_f32_16x16x32_bf16 v[92:95], v[192:195], v[242:245], v[92:95]
	v_mfma_f32_16x16x32_bf16 v[96:99], v[200:203], v[242:245], v[96:99]
	s_setprio 0
	s_setprio 1
	v_mfma_f32_16x16x32_bf16 v[100:103], v[204:207], v[104:107], v[116:119]
	v_mfma_f32_16x16x32_bf16 v[104:107], v[212:215], v[104:107], v[124:127]
	v_mfma_f32_16x16x32_bf16 v[100:103], v[208:211], v[108:111], v[100:103]
	v_mfma_f32_16x16x32_bf16 v[104:107], v[216:219], v[108:111], v[104:107]
	v_mfma_f32_16x16x32_bf16 v[108:111], v[204:207], v[112:115], v[166:169]
	v_mfma_f32_16x16x32_bf16 v[112:115], v[212:215], v[112:115], v[170:173]
	v_mfma_f32_16x16x32_bf16 v[116:119], v[204:207], v[224:227], v[174:177]
	v_mfma_f32_16x16x32_bf16 v[120:123], v[212:215], v[224:227], v[120:123]
	v_mfma_f32_16x16x32_bf16 v[124:127], v[204:207], v[238:241], v[178:181]
	v_mfma_f32_16x16x32_bf16 v[128:131], v[212:215], v[238:241], v[128:131]
	v_mfma_f32_16x16x32_bf16 v[108:111], v[208:211], v[220:223], v[108:111]
	v_mfma_f32_16x16x32_bf16 v[112:115], v[216:219], v[220:223], v[112:115]
	v_mfma_f32_16x16x32_bf16 v[116:119], v[208:211], v[234:237], v[116:119]
	v_mfma_f32_16x16x32_bf16 v[120:123], v[216:219], v[234:237], v[120:123]
	s_setprio 2
	s_barrier
	v_mfma_f32_16x16x32_bf16 v[124:127], v[208:211], v[242:245], v[124:127]
	v_mfma_f32_16x16x32_bf16 v[128:131], v[216:219], v[242:245], v[128:131]
	s_setprio 0
	s_add_i32 s45, s45, 2
	s_cmp_ge_i32 s45, s44
	s_cbranch_scc0 .LBB0_2065
	v_mov_b32_e32 v192, v2
	s_branch .LBB0_2068

.LBB0_2069:
	s_add_u32 s12, s14, 0xfff80080
	s_addc_u32 s13, s15, -1
	s_add_i32 s29, 0, 0x10000
	s_cmp_eq_u32 s28, 4
	s_cselect_b32 s17, s9, s13
	s_cselect_b32 s16, s8, s12
	s_cselect_b32 s13, s11, s27
	s_cselect_b32 s12, s10, s26
	s_add_i32 s51, 0, 0x14000
	v_add_u32_e32 v144, s29, v232
	v_add_u32_e32 v160, s51, v232
	s_waitcnt lgkmcnt(0)
	ds_read_b128 v[132:135], v144
	ds_read_b128 v[136:139], v144 offset:1024
	ds_read_b128 v[140:143], v144 offset:2048
	ds_read_b128 v[144:147], v144 offset:3072
	ds_read_b128 v[148:151], v160
	ds_read_b128 v[152:155], v160 offset:1024
	ds_read_b128 v[156:159], v160 offset:2048
	ds_read_b128 v[160:163], v160 offset:3072
	s_mov_b32 m0, s65
	v_add_u32_e32 v210, 0, v231
	ds_read_b128 v[164:167], v210
	ds_read_b128 v[168:171], v210 offset:1024
	ds_read_b128 v[172:175], v210 offset:2048
	ds_read_b128 v[176:179], v210 offset:3072
	ds_read_b128 v[180:183], v210 offset:4096
	ds_read_b128 v[184:187], v210 offset:5120
	ds_read_b128 v[194:197], v210 offset:6144
	ds_read_b128 v[198:201], v210 offset:7168
	global_load_lds_dwordx4 v2, s[14:15]
	s_mov_b32 m0, s66
	v_mov_b32_e32 v189, v3
	global_load_lds_dwordx4 v188, s[14:15]
	s_waitcnt vmcnt(8)
	s_waitcnt lgkmcnt(0)
	s_barrier
	s_setprio 1
	v_mfma_f32_16x16x32_bf16 v[4:7], v[132:135], v[164:167], v[4:7]
	v_mfma_f32_16x16x32_bf16 v[4:7], v[136:139], v[168:171], v[4:7]
	v_mfma_f32_16x16x32_bf16 v[8:11], v[144:147], v[168:171], v[8:11]
	v_mfma_f32_16x16x32_bf16 v[8:11], v[140:143], v[164:167], v[8:11]
	v_mfma_f32_16x16x32_bf16 v[16:19], v[140:143], v[172:175], v[16:19]
	v_mfma_f32_16x16x32_bf16 v[16:19], v[144:147], v[176:179], v[16:19]
	v_mfma_f32_16x16x32_bf16 v[12:15], v[136:139], v[176:179], v[12:15]
	v_mfma_f32_16x16x32_bf16 v[12:15], v[132:135], v[172:175], v[12:15]
	v_mfma_f32_16x16x32_bf16 v[20:23], v[132:135], v[180:183], v[20:23]
	v_mfma_f32_16x16x32_bf16 v[20:23], v[136:139], v[184:187], v[20:23]
	v_mfma_f32_16x16x32_bf16 v[24:27], v[144:147], v[184:187], v[24:27]
	v_mfma_f32_16x16x32_bf16 v[24:27], v[140:143], v[180:183], v[24:27]
	v_mfma_f32_16x16x32_bf16 v[32:35], v[140:143], v[194:197], v[32:35]
	v_mfma_f32_16x16x32_bf16 v[32:35], v[144:147], v[198:201], v[32:35]
	v_mfma_f32_16x16x32_bf16 v[28:31], v[136:139], v[198:201], v[28:31]
	v_mfma_f32_16x16x32_bf16 v[28:31], v[132:135], v[194:197], v[28:31]
	s_setprio 0
	s_setprio 1
	v_mfma_f32_16x16x32_bf16 v[36:39], v[148:151], v[164:167], v[36:39]
	v_mfma_f32_16x16x32_bf16 v[36:39], v[152:155], v[168:171], v[36:39]
	v_mfma_f32_16x16x32_bf16 v[40:43], v[160:163], v[168:171], v[40:43]
	v_mfma_f32_16x16x32_bf16 v[40:43], v[156:159], v[164:167], v[40:43]
	v_mfma_f32_16x16x32_bf16 v[48:51], v[156:159], v[172:175], v[48:51]
	v_mfma_f32_16x16x32_bf16 v[48:51], v[160:163], v[176:179], v[48:51]
	v_mfma_f32_16x16x32_bf16 v[44:47], v[152:155], v[176:179], v[44:47]
	v_mfma_f32_16x16x32_bf16 v[44:47], v[148:151], v[172:175], v[44:47]
	v_mfma_f32_16x16x32_bf16 v[52:55], v[148:151], v[180:183], v[52:55]
	v_mfma_f32_16x16x32_bf16 v[52:55], v[152:155], v[184:187], v[52:55]
	v_mfma_f32_16x16x32_bf16 v[56:59], v[160:163], v[184:187], v[56:59]
	v_mfma_f32_16x16x32_bf16 v[56:59], v[156:159], v[180:183], v[56:59]
	v_mfma_f32_16x16x32_bf16 v[64:67], v[156:159], v[194:197], v[64:67]
	v_mfma_f32_16x16x32_bf16 v[64:67], v[160:163], v[198:201], v[64:67]
	s_setprio 2
	s_barrier
	v_mfma_f32_16x16x32_bf16 v[60:63], v[152:155], v[198:201], v[60:63]
	v_mfma_f32_16x16x32_bf16 v[60:63], v[148:151], v[194:197], v[60:63]
	s_setprio 0
	s_add_i32 s29, s29, s38
	s_mov_b32 m0, s29
	ds_read_b128 v[164:167], v210 offset:16384
	ds_read_b128 v[168:171], v210 offset:17408
	ds_read_b128 v[172:175], v210 offset:18432
	ds_read_b128 v[176:179], v210 offset:19456
	ds_read_b128 v[180:183], v210 offset:20480
	ds_read_b128 v[184:187], v210 offset:21504
	ds_read_b128 v[194:197], v210 offset:22528
	ds_read_b128 v[198:201], v210 offset:23552
	global_load_lds_dwordx4 v192, s[12:13]
	s_add_i32 m0, s29, 0x2000
	s_add_u32 s44, s12, 0x20000
	s_addc_u32 s45, s13, 0
	s_add_i32 s29, s51, s38
	global_load_lds_dwordx4 v190, s[12:13]
	s_mov_b32 m0, s29
	v_mov_b32_e32 v193, v3
	global_load_lds_dwordx4 v192, s[44:45]
	s_add_i32 m0, s29, 0x2000
	v_mov_b32_e32 v191, v3
	global_load_lds_dwordx4 v190, s[44:45]
	s_mov_b32 m0, s56
	v_lshl_add_u64 v[202:203], s[12:13], 0, v[192:193]
	global_load_lds_dwordx4 v2, s[16:17]
	s_mov_b32 m0, s57
	v_lshl_add_u64 v[204:205], s[12:13], 0, v[190:191]
	global_load_lds_dwordx4 v188, s[16:17]
	s_waitcnt vmcnt(8)
	s_waitcnt lgkmcnt(0)
	v_lshl_add_u64 v[206:207], s[16:17], 0, v[2:3]
	v_lshl_add_u64 v[208:209], s[16:17], 0, v[188:189]
	s_barrier
	s_setprio 1
	v_mfma_f32_16x16x32_bf16 v[68:71], v[132:135], v[164:167], v[68:71]
	v_mfma_f32_16x16x32_bf16 v[68:71], v[136:139], v[168:171], v[68:71]
	v_mfma_f32_16x16x32_bf16 v[72:75], v[144:147], v[168:171], v[72:75]
	v_mfma_f32_16x16x32_bf16 v[72:75], v[140:143], v[164:167], v[72:75]
	v_mfma_f32_16x16x32_bf16 v[80:83], v[140:143], v[172:175], v[80:83]
	v_mfma_f32_16x16x32_bf16 v[80:83], v[144:147], v[176:179], v[80:83]
	v_mfma_f32_16x16x32_bf16 v[76:79], v[136:139], v[176:179], v[76:79]
	v_mfma_f32_16x16x32_bf16 v[76:79], v[132:135], v[172:175], v[76:79]
	v_mfma_f32_16x16x32_bf16 v[84:87], v[132:135], v[180:183], v[84:87]
	v_mfma_f32_16x16x32_bf16 v[84:87], v[136:139], v[184:187], v[84:87]
	v_mfma_f32_16x16x32_bf16 v[88:91], v[144:147], v[184:187], v[88:91]
	v_mfma_f32_16x16x32_bf16 v[88:91], v[140:143], v[180:183], v[88:91]
	v_mfma_f32_16x16x32_bf16 v[96:99], v[140:143], v[194:197], v[96:99]
	v_mfma_f32_16x16x32_bf16 v[96:99], v[144:147], v[198:201], v[96:99]
	v_mfma_f32_16x16x32_bf16 v[92:95], v[136:139], v[198:201], v[92:95]
	v_mfma_f32_16x16x32_bf16 v[92:95], v[132:135], v[194:197], v[92:95]
	s_setprio 0
	s_setprio 1
	v_mfma_f32_16x16x32_bf16 v[100:103], v[148:151], v[164:167], v[100:103]
	v_mfma_f32_16x16x32_bf16 v[100:103], v[152:155], v[168:171], v[100:103]
	v_mfma_f32_16x16x32_bf16 v[104:107], v[160:163], v[168:171], v[104:107]
	v_mfma_f32_16x16x32_bf16 v[104:107], v[156:159], v[164:167], v[104:107]
	v_mfma_f32_16x16x32_bf16 v[112:115], v[156:159], v[172:175], v[112:115]
	v_mfma_f32_16x16x32_bf16 v[112:115], v[160:163], v[176:179], v[112:115]
	v_mfma_f32_16x16x32_bf16 v[108:111], v[152:155], v[176:179], v[108:111]
	v_mfma_f32_16x16x32_bf16 v[108:111], v[148:151], v[172:175], v[108:111]
	v_mfma_f32_16x16x32_bf16 v[116:119], v[148:151], v[180:183], v[116:119]
	v_mfma_f32_16x16x32_bf16 v[116:119], v[152:155], v[184:187], v[116:119]
	v_mfma_f32_16x16x32_bf16 v[120:123], v[160:163], v[184:187], v[120:123]
	v_mfma_f32_16x16x32_bf16 v[120:123], v[156:159], v[180:183], v[120:123]
	v_mfma_f32_16x16x32_bf16 v[128:131], v[156:159], v[194:197], v[128:131]
	v_mfma_f32_16x16x32_bf16 v[128:131], v[160:163], v[198:201], v[128:131]
	s_setprio 2
	s_barrier
	v_mfma_f32_16x16x32_bf16 v[124:127], v[152:155], v[198:201], v[124:127]
	v_mfma_f32_16x16x32_bf16 v[124:127], v[148:151], v[194:197], v[124:127]
	s_setprio 0
	s_add_i32 s29, 0, 0x18000
	s_add_i32 s44, 0, 0x1c000
	v_add_u32_e32 v144, s29, v232
	v_add_u32_e32 v160, s44, v232
	ds_read_b128 v[132:135], v144
	ds_read_b128 v[136:139], v144 offset:1024
	ds_read_b128 v[140:143], v144 offset:2048
	ds_read_b128 v[144:147], v144 offset:3072
	ds_read_b128 v[148:151], v160
	ds_read_b128 v[152:155], v160 offset:1024
	ds_read_b128 v[156:159], v160 offset:2048
	ds_read_b128 v[160:163], v160 offset:3072
	s_add_u32 s16, s16, 0x80000
	s_addc_u32 s17, s17, 0
	s_mov_b32 m0, s58
	ds_read_b128 v[164:167], v210 offset:32768
	ds_read_b128 v[168:171], v210 offset:33792
	ds_read_b128 v[172:175], v210 offset:34816
	ds_read_b128 v[176:179], v210 offset:35840
	ds_read_b128 v[180:183], v210 offset:36864
	ds_read_b128 v[184:187], v210 offset:37888
	ds_read_b128 v[194:197], v210 offset:38912
	ds_read_b128 v[198:201], v210 offset:39936
	global_load_lds_dwordx4 v2, s[16:17]
	s_mov_b32 m0, s59
	s_nop 0
	global_load_lds_dwordx4 v188, s[16:17]
	s_waitcnt vmcnt(8)
	s_waitcnt lgkmcnt(0)
	s_barrier
	s_setprio 1
	v_mfma_f32_16x16x32_bf16 v[4:7], v[132:135], v[164:167], v[4:7]
	v_mfma_f32_16x16x32_bf16 v[4:7], v[136:139], v[168:171], v[4:7]
	v_mfma_f32_16x16x32_bf16 v[8:11], v[144:147], v[168:171], v[8:11]
	v_mfma_f32_16x16x32_bf16 v[8:11], v[140:143], v[164:167], v[8:11]
	v_mfma_f32_16x16x32_bf16 v[16:19], v[140:143], v[172:175], v[16:19]
	v_mfma_f32_16x16x32_bf16 v[16:19], v[144:147], v[176:179], v[16:19]
	v_mfma_f32_16x16x32_bf16 v[12:15], v[136:139], v[176:179], v[12:15]
	v_mfma_f32_16x16x32_bf16 v[12:15], v[132:135], v[172:175], v[12:15]
	v_mfma_f32_16x16x32_bf16 v[20:23], v[132:135], v[180:183], v[20:23]
	v_mfma_f32_16x16x32_bf16 v[20:23], v[136:139], v[184:187], v[20:23]
	v_mfma_f32_16x16x32_bf16 v[24:27], v[144:147], v[184:187], v[24:27]
	v_mfma_f32_16x16x32_bf16 v[24:27], v[140:143], v[180:183], v[24:27]
	v_mfma_f32_16x16x32_bf16 v[32:35], v[140:143], v[194:197], v[32:35]
	v_mfma_f32_16x16x32_bf16 v[32:35], v[144:147], v[198:201], v[32:35]
	v_mfma_f32_16x16x32_bf16 v[28:31], v[136:139], v[198:201], v[28:31]
	v_mfma_f32_16x16x32_bf16 v[28:31], v[132:135], v[194:197], v[28:31]
	s_setprio 0
	s_setprio 1
	v_mfma_f32_16x16x32_bf16 v[36:39], v[148:151], v[164:167], v[36:39]
	v_mfma_f32_16x16x32_bf16 v[36:39], v[152:155], v[168:171], v[36:39]
	v_mfma_f32_16x16x32_bf16 v[40:43], v[160:163], v[168:171], v[40:43]
	v_mfma_f32_16x16x32_bf16 v[40:43], v[156:159], v[164:167], v[40:43]
	v_mfma_f32_16x16x32_bf16 v[48:51], v[156:159], v[172:175], v[48:51]
	v_mfma_f32_16x16x32_bf16 v[48:51], v[160:163], v[176:179], v[48:51]
	v_mfma_f32_16x16x32_bf16 v[44:47], v[152:155], v[176:179], v[44:47]
	v_mfma_f32_16x16x32_bf16 v[44:47], v[148:151], v[172:175], v[44:47]
	v_mfma_f32_16x16x32_bf16 v[52:55], v[148:151], v[180:183], v[52:55]
	v_mfma_f32_16x16x32_bf16 v[52:55], v[152:155], v[184:187], v[52:55]
	v_mfma_f32_16x16x32_bf16 v[56:59], v[160:163], v[184:187], v[56:59]
	v_mfma_f32_16x16x32_bf16 v[56:59], v[156:159], v[180:183], v[56:59]
	v_mfma_f32_16x16x32_bf16 v[64:67], v[156:159], v[194:197], v[64:67]
	v_mfma_f32_16x16x32_bf16 v[64:67], v[160:163], v[198:201], v[64:67]
	s_setprio 2
	s_barrier
	v_mfma_f32_16x16x32_bf16 v[60:63], v[152:155], v[198:201], v[60:63]
	v_mfma_f32_16x16x32_bf16 v[60:63], v[148:151], v[194:197], v[60:63]
	s_setprio 0
	s_add_i32 s16, s29, s38
	v_lshl_add_u64 v[202:203], v[202:203], 0, s[86:87]
	s_mov_b32 m0, s16
	ds_read_b128 v[164:167], v210 offset:49152
	ds_read_b128 v[168:171], v210 offset:50176
	ds_read_b128 v[172:175], v210 offset:51200
	ds_read_b128 v[176:179], v210 offset:52224
	ds_read_b128 v[180:183], v210 offset:53248
	ds_read_b128 v[184:187], v210 offset:54272
	ds_read_b128 v[194:197], v210 offset:55296
	ds_read_b128 v[198:201], v210 offset:56320
	global_load_lds_dwordx4 v[202:203], off
	s_add_i32 m0, s16, 0x2000
	s_add_u32 s12, s12, 0x20080
	v_lshl_add_u64 v[202:203], v[204:205], 0, s[86:87]
	s_addc_u32 s13, s13, 0
	s_add_i32 s16, s44, s38
	global_load_lds_dwordx4 v[202:203], off
	s_mov_b32 m0, s16
	v_lshl_add_u64 v[202:203], v[206:207], 0, s[86:87]
	global_load_lds_dwordx4 v192, s[12:13]
	s_add_i32 m0, s16, 0x2000
	s_nop 0
	global_load_lds_dwordx4 v190, s[12:13]
	s_mov_b32 m0, s63
	s_nop 0
	global_load_lds_dwordx4 v[202:203], off
	v_lshl_add_u64 v[202:203], v[208:209], 0, s[86:87]
	s_mov_b32 m0, s64
	s_nop 0
	global_load_lds_dwordx4 v[202:203], off
	s_waitcnt vmcnt(8)
	s_waitcnt lgkmcnt(0)
	s_barrier
	s_setprio 1
	v_mfma_f32_16x16x32_bf16 v[68:71], v[132:135], v[164:167], v[68:71]
	v_mfma_f32_16x16x32_bf16 v[68:71], v[136:139], v[168:171], v[68:71]
	v_mfma_f32_16x16x32_bf16 v[72:75], v[144:147], v[168:171], v[72:75]
	v_mfma_f32_16x16x32_bf16 v[72:75], v[140:143], v[164:167], v[72:75]
	v_mfma_f32_16x16x32_bf16 v[80:83], v[140:143], v[172:175], v[80:83]
	v_mfma_f32_16x16x32_bf16 v[80:83], v[144:147], v[176:179], v[80:83]
	v_mfma_f32_16x16x32_bf16 v[76:79], v[136:139], v[176:179], v[76:79]
	v_mfma_f32_16x16x32_bf16 v[76:79], v[132:135], v[172:175], v[76:79]
	v_mfma_f32_16x16x32_bf16 v[84:87], v[132:135], v[180:183], v[84:87]
	v_mfma_f32_16x16x32_bf16 v[84:87], v[136:139], v[184:187], v[84:87]
	v_mfma_f32_16x16x32_bf16 v[88:91], v[144:147], v[184:187], v[88:91]
	v_mfma_f32_16x16x32_bf16 v[88:91], v[140:143], v[180:183], v[88:91]
	v_mfma_f32_16x16x32_bf16 v[96:99], v[140:143], v[194:197], v[96:99]
	v_mfma_f32_16x16x32_bf16 v[96:99], v[144:147], v[198:201], v[96:99]
	v_mfma_f32_16x16x32_bf16 v[92:95], v[136:139], v[198:201], v[92:95]
	v_mfma_f32_16x16x32_bf16 v[92:95], v[132:135], v[194:197], v[92:95]
	s_setprio 0
	s_setprio 1
	v_mfma_f32_16x16x32_bf16 v[100:103], v[148:151], v[164:167], v[100:103]
	v_mfma_f32_16x16x32_bf16 v[100:103], v[152:155], v[168:171], v[100:103]
	v_mfma_f32_16x16x32_bf16 v[104:107], v[160:163], v[168:171], v[104:107]
	v_mfma_f32_16x16x32_bf16 v[104:107], v[156:159], v[164:167], v[104:107]
	v_mfma_f32_16x16x32_bf16 v[112:115], v[156:159], v[172:175], v[112:115]
	v_mfma_f32_16x16x32_bf16 v[112:115], v[160:163], v[176:179], v[112:115]
	v_mfma_f32_16x16x32_bf16 v[108:111], v[152:155], v[176:179], v[108:111]
	v_mfma_f32_16x16x32_bf16 v[108:111], v[148:151], v[172:175], v[108:111]
	v_mfma_f32_16x16x32_bf16 v[116:119], v[148:151], v[180:183], v[116:119]
	v_mfma_f32_16x16x32_bf16 v[116:119], v[152:155], v[184:187], v[116:119]
	v_mfma_f32_16x16x32_bf16 v[120:123], v[160:163], v[184:187], v[120:123]
	v_mfma_f32_16x16x32_bf16 v[120:123], v[156:159], v[180:183], v[120:123]
	v_mfma_f32_16x16x32_bf16 v[128:131], v[156:159], v[194:197], v[128:131]
	v_mfma_f32_16x16x32_bf16 v[128:131], v[160:163], v[198:201], v[128:131]
	s_setprio 2
	s_barrier
	v_mfma_f32_16x16x32_bf16 v[124:127], v[152:155], v[198:201], v[124:127]
	v_mfma_f32_16x16x32_bf16 v[124:127], v[148:151], v[194:197], v[124:127]
	s_setprio 0
	s_add_i32 s28, s28, 2
	s_add_u32 s14, s14, 0x100
	s_addc_u32 s15, s15, 0
	s_add_u32 s26, s26, 0x100
	s_addc_u32 s27, s27, 0
	s_cmp_gt_u32 s28, 5
	s_cbranch_scc0 .LBB0_2069
	s_and_b64 vcc, exec, s[48:49]
	s_cbranch_vccz .LBB0_2072
	s_barrier

.LBB0_2159:
	s_add_i32 s68, 0, 0x10000
	s_add_i32 s69, 0, 0x14000
	v_add_u32_e32 v16, s68, v143
	v_add_u32_e32 v32, s69, v143
	ds_read_b128 v[4:7], v16
	ds_read_b128 v[8:11], v16 offset:1024
	ds_read_b128 v[12:15], v16 offset:2048
	ds_read_b128 v[16:19], v16 offset:3072
	ds_read_b128 v[20:23], v32
	ds_read_b128 v[24:27], v32 offset:1024
	ds_read_b128 v[28:31], v32 offset:2048
	ds_read_b128 v[32:35], v32 offset:3072
	v_add_u32_e32 v231, 0, v142
	ds_read_b128 v[36:39], v231
	ds_read_b128 v[40:43], v231 offset:1024
	ds_read_b128 v[44:47], v231 offset:2048
	ds_read_b128 v[48:51], v231 offset:3072
	ds_read_b128 v[52:55], v231 offset:4096
	ds_read_b128 v[56:59], v231 offset:5120
	ds_read_b128 v[60:63], v231 offset:6144
	ds_read_b128 v[64:67], v231 offset:7168
	s_waitcnt vmcnt(8)
	s_waitcnt lgkmcnt(0)
	s_barrier
	s_setprio 1
	v_mfma_f32_16x16x32_f16 v[68:71], v[4:7], v[36:39], 0
	v_mfma_f32_16x16x32_f16 v[72:75], v[12:15], v[36:39], 0
	v_mfma_f32_16x16x32_f16 v[76:79], v[4:7], v[44:47], 0
	v_mfma_f32_16x16x32_f16 v[80:83], v[12:15], v[44:47], 0
	v_mfma_f32_16x16x32_f16 v[84:87], v[4:7], v[52:55], 0
	v_mfma_f32_16x16x32_f16 v[88:91], v[12:15], v[52:55], 0
	v_mfma_f32_16x16x32_f16 v[92:95], v[4:7], v[60:63], 0
	v_mfma_f32_16x16x32_f16 v[96:99], v[12:15], v[60:63], 0
	v_mfma_f32_16x16x32_f16 v[68:71], v[8:11], v[40:43], v[68:71]
	v_mfma_f32_16x16x32_f16 v[72:75], v[16:19], v[40:43], v[72:75]
	v_mfma_f32_16x16x32_f16 v[76:79], v[8:11], v[48:51], v[76:79]
	v_mfma_f32_16x16x32_f16 v[80:83], v[16:19], v[48:51], v[80:83]
	v_mfma_f32_16x16x32_f16 v[84:87], v[8:11], v[56:59], v[84:87]
	v_mfma_f32_16x16x32_f16 v[88:91], v[16:19], v[56:59], v[88:91]
	v_mfma_f32_16x16x32_f16 v[92:95], v[8:11], v[64:67], v[92:95]
	v_mfma_f32_16x16x32_f16 v[100:103], v[16:19], v[64:67], v[96:99]
	s_setprio 0
	s_setprio 1
	v_mfma_f32_16x16x32_f16 v[96:99], v[20:23], v[36:39], 0
	v_mfma_f32_16x16x32_f16 v[36:39], v[28:31], v[36:39], 0
	v_mfma_f32_16x16x32_f16 v[104:107], v[20:23], v[44:47], 0
	v_mfma_f32_16x16x32_f16 v[44:47], v[28:31], v[44:47], 0
	v_mfma_f32_16x16x32_f16 v[108:111], v[20:23], v[52:55], 0
	v_mfma_f32_16x16x32_f16 v[52:55], v[28:31], v[52:55], 0
	v_mfma_f32_16x16x32_f16 v[112:115], v[20:23], v[60:63], 0
	v_mfma_f32_16x16x32_f16 v[60:63], v[28:31], v[60:63], 0
	v_mfma_f32_16x16x32_f16 v[116:119], v[24:27], v[40:43], v[96:99]
	v_mfma_f32_16x16x32_f16 v[36:39], v[32:35], v[40:43], v[36:39]
	v_mfma_f32_16x16x32_f16 v[40:43], v[24:27], v[48:51], v[104:107]
	v_mfma_f32_16x16x32_f16 v[44:47], v[32:35], v[48:51], v[44:47]
	v_mfma_f32_16x16x32_f16 v[48:51], v[24:27], v[56:59], v[108:111]
	v_mfma_f32_16x16x32_f16 v[52:55], v[32:35], v[56:59], v[52:55]
	s_setprio 2
	s_barrier
	v_mfma_f32_16x16x32_f16 v[56:59], v[24:27], v[64:67], v[112:115]
	v_mfma_f32_16x16x32_f16 v[60:63], v[32:35], v[64:67], v[60:63]
	s_setprio 0
	v_lshl_add_u64 v[138:139], s[8:9], 0, v[2:3]
	s_add_i32 s68, s68, s53
	v_mov_b32_e32 v135, v3
	v_lshl_add_u64 v[144:145], v[138:139], 0, s[74:75]
	s_mov_b32 m0, s68
	v_lshl_add_u64 v[192:193], s[8:9], 0, v[134:135]
	ds_read_b128 v[64:67], v231 offset:16384
	ds_read_b128 v[96:99], v231 offset:17408
	ds_read_b128 v[104:107], v231 offset:18432
	ds_read_b128 v[108:111], v231 offset:19456
	ds_read_b128 v[112:115], v231 offset:20480
	ds_read_b128 v[120:123], v231 offset:21504
	ds_read_b128 v[124:127], v231 offset:22528
	ds_read_b128 v[128:131], v231 offset:23552
	global_load_lds_dwordx4 v[144:145], off
	v_lshl_add_u64 v[144:145], v[192:193], 0, s[74:75]
	s_add_i32 m0, s68, 0x2000
	s_add_i32 s68, s69, s53
	global_load_lds_dwordx4 v[144:145], off
	s_mov_b32 m0, s68
	v_mov_b32_e32 v137, v3
	global_load_lds_dwordx4 v2, s[40:41]
	s_add_i32 m0, s68, 0x2000
	v_lshl_add_u64 v[248:249], s[6:7], 0, v[136:137]
	v_mov_b32_e32 v133, v3
	global_load_lds_dwordx4 v134, s[40:41]
	v_lshl_add_u64 v[144:145], v[248:249], 0, s[74:75]
	s_mov_b32 m0, s54
	v_lshl_add_u64 v[250:251], s[6:7], 0, v[132:133]
	global_load_lds_dwordx4 v[144:145], off
	v_lshl_add_u64 v[144:145], v[250:251], 0, s[74:75]
	s_mov_b32 m0, s55
	s_nop 0
	global_load_lds_dwordx4 v[144:145], off
	s_waitcnt vmcnt(8)
	s_waitcnt lgkmcnt(0)
	s_barrier
	s_setprio 1
	v_mfma_f32_16x16x32_f16 v[144:147], v[4:7], v[64:67], 0
	v_mfma_f32_16x16x32_f16 v[148:151], v[12:15], v[64:67], 0
	v_mfma_f32_16x16x32_f16 v[152:155], v[4:7], v[104:107], 0
	v_mfma_f32_16x16x32_f16 v[156:159], v[12:15], v[104:107], 0
	v_mfma_f32_16x16x32_f16 v[160:163], v[4:7], v[112:115], 0
	v_mfma_f32_16x16x32_f16 v[164:167], v[12:15], v[112:115], 0
	v_mfma_f32_16x16x32_f16 v[4:7], v[4:7], v[124:127], 0
	v_mfma_f32_16x16x32_f16 v[12:15], v[12:15], v[124:127], 0
	v_mfma_f32_16x16x32_f16 v[144:147], v[8:11], v[96:99], v[144:147]
	v_mfma_f32_16x16x32_f16 v[152:155], v[8:11], v[108:111], v[152:155]
	v_mfma_f32_16x16x32_f16 v[160:163], v[8:11], v[120:123], v[160:163]
	v_mfma_f32_16x16x32_f16 v[4:7], v[8:11], v[128:131], v[4:7]
	v_mfma_f32_16x16x32_f16 v[8:11], v[16:19], v[128:131], v[12:15]
	v_mfma_f32_16x16x32_f16 v[148:151], v[16:19], v[96:99], v[148:151]
	v_mfma_f32_16x16x32_f16 v[156:159], v[16:19], v[108:111], v[156:159]
	v_mfma_f32_16x16x32_f16 v[164:167], v[16:19], v[120:123], v[164:167]
	s_setprio 0
	s_setprio 1
	v_mfma_f32_16x16x32_f16 v[12:15], v[20:23], v[64:67], 0
	v_mfma_f32_16x16x32_f16 v[16:19], v[28:31], v[64:67], 0
	v_mfma_f32_16x16x32_f16 v[64:67], v[20:23], v[104:107], 0
	v_mfma_f32_16x16x32_f16 v[104:107], v[28:31], v[104:107], 0
	v_mfma_f32_16x16x32_f16 v[168:171], v[20:23], v[112:115], 0
	v_mfma_f32_16x16x32_f16 v[112:115], v[28:31], v[112:115], 0
	v_mfma_f32_16x16x32_f16 v[20:23], v[20:23], v[124:127], 0
	v_mfma_f32_16x16x32_f16 v[28:31], v[28:31], v[124:127], 0
	v_mfma_f32_16x16x32_f16 v[12:15], v[24:27], v[96:99], v[12:15]
	v_mfma_f32_16x16x32_f16 v[172:175], v[32:35], v[96:99], v[16:19]
	v_mfma_f32_16x16x32_f16 v[176:179], v[24:27], v[108:111], v[64:67]
	v_mfma_f32_16x16x32_f16 v[180:183], v[32:35], v[108:111], v[104:107]
	v_mfma_f32_16x16x32_f16 v[168:171], v[24:27], v[120:123], v[168:171]
	v_mfma_f32_16x16x32_f16 v[184:187], v[32:35], v[120:123], v[112:115]
	s_setprio 2
	s_barrier
	v_mfma_f32_16x16x32_f16 v[188:191], v[24:27], v[128:131], v[20:23]
	v_mfma_f32_16x16x32_f16 v[196:199], v[32:35], v[128:131], v[28:31]
	s_setprio 0
	s_add_i32 s68, 0, 0x18000
	v_add_u32_e32 v24, s68, v143
	s_add_i32 s69, 0, 0x1c000
	ds_read_b128 v[16:19], v24
	ds_read_b128 v[20:23], v24 offset:1024
	ds_read_b128 v[28:31], v24 offset:2048
	ds_read_b128 v[200:203], v24 offset:3072
	v_add_u32_e32 v24, s69, v143
	ds_read_b128 v[204:207], v24
	ds_read_b128 v[208:211], v24 offset:1024
	ds_read_b128 v[212:215], v24 offset:2048
	ds_read_b128 v[216:219], v24 offset:3072
	s_mov_b32 m0, s56
	ds_read_b128 v[24:27], v231 offset:32768
	ds_read_b128 v[32:35], v231 offset:33792
	ds_read_b128 v[64:67], v231 offset:34816
	ds_read_b128 v[220:223], v231 offset:35840
	ds_read_b128 v[224:227], v231 offset:36864
	ds_read_b128 v[232:235], v231 offset:37888
	ds_read_b128 v[236:239], v231 offset:38912
	ds_read_b128 v[240:243], v231 offset:39936
	global_load_lds_dwordx4 v136, s[42:43]
	s_mov_b32 m0, s57
	s_nop 0
	global_load_lds_dwordx4 v132, s[42:43]
	s_waitcnt vmcnt(8)
	s_waitcnt lgkmcnt(0)
	s_barrier
	s_setprio 1
	v_mfma_f32_16x16x32_f16 v[68:71], v[16:19], v[24:27], v[68:71]
	v_mfma_f32_16x16x32_f16 v[128:131], v[20:23], v[32:35], v[68:71]
	v_mfma_f32_16x16x32_f16 v[68:71], v[28:31], v[24:27], v[72:75]
	v_mfma_f32_16x16x32_f16 v[120:123], v[200:203], v[32:35], v[68:71]
	v_mfma_f32_16x16x32_f16 v[68:71], v[16:19], v[64:67], v[76:79]
	v_mfma_f32_16x16x32_f16 v[112:115], v[20:23], v[220:223], v[68:71]
	v_mfma_f32_16x16x32_f16 v[68:71], v[28:31], v[64:67], v[80:83]
	v_mfma_f32_16x16x32_f16 v[104:107], v[200:203], v[220:223], v[68:71]
	v_mfma_f32_16x16x32_f16 v[68:71], v[16:19], v[224:227], v[84:87]
	v_mfma_f32_16x16x32_f16 v[96:99], v[20:23], v[232:235], v[68:71]
	v_mfma_f32_16x16x32_f16 v[68:71], v[28:31], v[224:227], v[88:91]
	v_mfma_f32_16x16x32_f16 v[88:91], v[200:203], v[232:235], v[68:71]
	v_mfma_f32_16x16x32_f16 v[68:71], v[16:19], v[236:239], v[92:95]
	v_mfma_f32_16x16x32_f16 v[80:83], v[20:23], v[240:243], v[68:71]
	v_mfma_f32_16x16x32_f16 v[68:71], v[28:31], v[236:239], v[100:103]
	v_mfma_f32_16x16x32_f16 v[72:75], v[200:203], v[240:243], v[68:71]
	s_setprio 0
	s_setprio 1
	v_mfma_f32_16x16x32_f16 v[68:71], v[204:207], v[24:27], v[116:119]
	v_mfma_f32_16x16x32_f16 v[24:27], v[212:215], v[24:27], v[36:39]
	v_mfma_f32_16x16x32_f16 v[116:119], v[216:219], v[32:35], v[24:27]
	v_mfma_f32_16x16x32_f16 v[24:27], v[204:207], v[64:67], v[40:43]
	v_mfma_f32_16x16x32_f16 v[108:111], v[208:211], v[220:223], v[24:27]
	v_mfma_f32_16x16x32_f16 v[24:27], v[212:215], v[64:67], v[44:47]
	v_mfma_f32_16x16x32_f16 v[100:103], v[216:219], v[220:223], v[24:27]
	v_mfma_f32_16x16x32_f16 v[24:27], v[204:207], v[224:227], v[48:51]
	v_mfma_f32_16x16x32_f16 v[92:95], v[208:211], v[232:235], v[24:27]
	v_mfma_f32_16x16x32_f16 v[24:27], v[212:215], v[224:227], v[52:55]
	v_mfma_f32_16x16x32_f16 v[84:87], v[216:219], v[232:235], v[24:27]
	v_mfma_f32_16x16x32_f16 v[24:27], v[204:207], v[236:239], v[56:59]
	v_mfma_f32_16x16x32_f16 v[76:79], v[208:211], v[240:243], v[24:27]
	v_mfma_f32_16x16x32_f16 v[24:27], v[212:215], v[236:239], v[60:63]
	s_setprio 2
	s_barrier
	v_mfma_f32_16x16x32_f16 v[124:127], v[208:211], v[32:35], v[68:71]
	v_mfma_f32_16x16x32_f16 v[68:71], v[216:219], v[240:243], v[24:27]
	s_setprio 0
	s_add_i32 s68, s68, s53
	s_nop 2
	v_lshl_add_u64 v[24:25], v[138:139], 0, s[24:25]
	s_mov_b32 m0, s68
	ds_read_b128 v[36:39], v231 offset:49152
	ds_read_b128 v[44:47], v231 offset:50176
	ds_read_b128 v[220:223], v231 offset:51200
	ds_read_b128 v[224:227], v231 offset:52224
	ds_read_b128 v[232:235], v231 offset:53248
	ds_read_b128 v[236:239], v231 offset:54272
	ds_read_b128 v[240:243], v231 offset:55296
	ds_read_b128 v[244:247], v231 offset:56320
	global_load_lds_dwordx4 v[24:25], off
	v_lshl_add_u64 v[24:25], v[192:193], 0, s[24:25]
	s_add_i32 m0, s68, 0x2000
	s_add_i32 s68, s69, s53
	global_load_lds_dwordx4 v[24:25], off
	s_mov_b32 m0, s68
	v_lshl_add_u64 v[24:25], v[248:249], 0, s[24:25]
	global_load_lds_dwordx4 v2, s[44:45]
	s_add_i32 m0, s68, 0x2000
	s_nop 0
	global_load_lds_dwordx4 v134, s[44:45]
	s_mov_b32 m0, s59
	s_nop 0
	global_load_lds_dwordx4 v[24:25], off
	v_lshl_add_u64 v[24:25], v[250:251], 0, s[24:25]
	s_mov_b32 m0, s60
	s_nop 0
	global_load_lds_dwordx4 v[24:25], off
	s_waitcnt vmcnt(8)
	s_waitcnt lgkmcnt(0)
	s_barrier
	s_setprio 1
	v_mfma_f32_16x16x32_f16 v[24:27], v[16:19], v[36:39], v[144:147]
	v_mfma_f32_16x16x32_f16 v[64:67], v[20:23], v[44:47], v[24:27]
	v_mfma_f32_16x16x32_f16 v[24:27], v[28:31], v[36:39], v[148:151]
	v_mfma_f32_16x16x32_f16 v[56:59], v[200:203], v[44:47], v[24:27]
	v_mfma_f32_16x16x32_f16 v[24:27], v[16:19], v[220:223], v[152:155]
	v_mfma_f32_16x16x32_f16 v[48:51], v[20:23], v[224:227], v[24:27]
	v_mfma_f32_16x16x32_f16 v[24:27], v[28:31], v[220:223], v[156:159]
	v_mfma_f32_16x16x32_f16 v[40:43], v[200:203], v[224:227], v[24:27]
	v_mfma_f32_16x16x32_f16 v[24:27], v[16:19], v[232:235], v[160:163]
	v_mfma_f32_16x16x32_f16 v[4:7], v[16:19], v[240:243], v[4:7]
	v_mfma_f32_16x16x32_f16 v[32:35], v[20:23], v[236:239], v[24:27]
	v_mfma_f32_16x16x32_f16 v[24:27], v[28:31], v[232:235], v[164:167]
	v_mfma_f32_16x16x32_f16 v[16:19], v[20:23], v[244:247], v[4:7]
	v_mfma_f32_16x16x32_f16 v[4:7], v[28:31], v[240:243], v[8:11]
	v_mfma_f32_16x16x32_f16 v[24:27], v[200:203], v[236:239], v[24:27]
	v_mfma_f32_16x16x32_f16 v[8:11], v[200:203], v[244:247], v[4:7]
	s_setprio 0
	s_setprio 1
	v_mfma_f32_16x16x32_f16 v[4:7], v[204:207], v[36:39], v[12:15]
	v_mfma_f32_16x16x32_f16 v[60:63], v[208:211], v[44:47], v[4:7]
	v_mfma_f32_16x16x32_f16 v[4:7], v[212:215], v[36:39], v[172:175]
	v_mfma_f32_16x16x32_f16 v[52:55], v[216:219], v[44:47], v[4:7]
	v_mfma_f32_16x16x32_f16 v[4:7], v[204:207], v[220:223], v[176:179]
	v_mfma_f32_16x16x32_f16 v[44:47], v[208:211], v[224:227], v[4:7]
	v_mfma_f32_16x16x32_f16 v[4:7], v[212:215], v[220:223], v[180:183]
	v_mfma_f32_16x16x32_f16 v[36:39], v[216:219], v[224:227], v[4:7]
	v_mfma_f32_16x16x32_f16 v[4:7], v[204:207], v[232:235], v[168:171]
	v_mfma_f32_16x16x32_f16 v[28:31], v[208:211], v[236:239], v[4:7]
	v_mfma_f32_16x16x32_f16 v[4:7], v[212:215], v[232:235], v[184:187]
	v_mfma_f32_16x16x32_f16 v[20:23], v[216:219], v[236:239], v[4:7]
	v_mfma_f32_16x16x32_f16 v[4:7], v[204:207], v[240:243], v[188:191]
	v_mfma_f32_16x16x32_f16 v[12:15], v[208:211], v[244:247], v[4:7]
	s_setprio 2
	s_barrier
	v_mfma_f32_16x16x32_f16 v[4:7], v[212:215], v[240:243], v[196:199]
	v_mfma_f32_16x16x32_f16 v[4:7], v[216:219], v[244:247], v[4:7]
	s_setprio 0
	s_add_i32 s67, s67, 2
	s_cmp_ge_i32 s67, s11
	s_cbranch_scc0 .LBB0_2159

.LBB0_2161:
	s_add_u32 s68, s6, s40
	s_addc_u32 s69, s7, s41
	s_add_u32 s42, s68, 0x200
	s_addc_u32 s43, s69, 0
	s_add_u32 s44, s8, s40
	s_addc_u32 s45, s9, s41
	s_add_u32 s67, s44, 0x200
	s_addc_u32 s70, s45, 0
	s_add_i32 s71, 0, 0x10000
	s_cmp_eq_u32 s11, 28
	s_cselect_b32 s45, s29, s43
	s_cselect_b32 s44, s28, s42
	v_add_u32_e32 v133, s71, v143
	s_cselect_b32 s43, s37, s70
	s_cselect_b32 s42, s36, s67
	s_add_i32 s67, 0, 0x14000
	ds_read_b128 v[144:147], v133
	ds_read_b128 v[148:151], v133 offset:1024
	ds_read_b128 v[152:155], v133 offset:2048
	ds_read_b128 v[156:159], v133 offset:3072
	v_add_u32_e32 v133, s67, v143
	ds_read_b128 v[160:163], v133
	ds_read_b128 v[164:167], v133 offset:1024
	ds_read_b128 v[168:171], v133 offset:2048
	ds_read_b128 v[172:175], v133 offset:3072
	v_lshl_add_u64 v[136:137], s[68:69], 0, v[2:3]
	s_mov_b32 m0, s61
	v_add_u32_e32 v216, 0, v142
	v_lshl_add_u64 v[136:137], v[136:137], 0, s[34:35]
	v_mov_b32_e32 v133, v3
	ds_read_b128 v[176:179], v216
	ds_read_b128 v[180:183], v216 offset:1024
	ds_read_b128 v[184:187], v216 offset:2048
	ds_read_b128 v[188:191], v216 offset:3072
	ds_read_b128 v[196:199], v216 offset:4096
	ds_read_b128 v[200:203], v216 offset:5120
	ds_read_b128 v[204:207], v216 offset:6144
	ds_read_b128 v[208:211], v216 offset:7168
	global_load_lds_dwordx4 v[136:137], off
	v_lshl_add_u64 v[136:137], s[68:69], 0, v[132:133]
	v_lshl_add_u64 v[136:137], v[136:137], 0, s[34:35]
	s_mov_b32 m0, s62
	s_nop 0
	global_load_lds_dwordx4 v[136:137], off
	s_waitcnt vmcnt(8)
	s_waitcnt lgkmcnt(0)
	s_barrier
	s_setprio 1
	v_mfma_f32_16x16x32_f16 v[128:131], v[144:147], v[176:179], v[128:131]
	v_mfma_f32_16x16x32_f16 v[128:131], v[148:151], v[180:183], v[128:131]
	v_mfma_f32_16x16x32_f16 v[120:123], v[156:159], v[180:183], v[120:123]
	v_mfma_f32_16x16x32_f16 v[120:123], v[152:155], v[176:179], v[120:123]
	v_mfma_f32_16x16x32_f16 v[104:107], v[152:155], v[184:187], v[104:107]
	v_mfma_f32_16x16x32_f16 v[104:107], v[156:159], v[188:191], v[104:107]
	v_mfma_f32_16x16x32_f16 v[112:115], v[148:151], v[188:191], v[112:115]
	v_mfma_f32_16x16x32_f16 v[112:115], v[144:147], v[184:187], v[112:115]
	v_mfma_f32_16x16x32_f16 v[96:99], v[144:147], v[196:199], v[96:99]
	v_mfma_f32_16x16x32_f16 v[96:99], v[148:151], v[200:203], v[96:99]
	v_mfma_f32_16x16x32_f16 v[88:91], v[156:159], v[200:203], v[88:91]
	v_mfma_f32_16x16x32_f16 v[88:91], v[152:155], v[196:199], v[88:91]
	v_mfma_f32_16x16x32_f16 v[72:75], v[152:155], v[204:207], v[72:75]
	v_mfma_f32_16x16x32_f16 v[72:75], v[156:159], v[208:211], v[72:75]
	v_mfma_f32_16x16x32_f16 v[80:83], v[148:151], v[208:211], v[80:83]
	v_mfma_f32_16x16x32_f16 v[80:83], v[144:147], v[204:207], v[80:83]
	s_setprio 0
	s_setprio 1
	v_mfma_f32_16x16x32_f16 v[124:127], v[160:163], v[176:179], v[124:127]
	v_mfma_f32_16x16x32_f16 v[124:127], v[164:167], v[180:183], v[124:127]
	v_mfma_f32_16x16x32_f16 v[116:119], v[172:175], v[180:183], v[116:119]
	v_mfma_f32_16x16x32_f16 v[116:119], v[168:171], v[176:179], v[116:119]
	v_mfma_f32_16x16x32_f16 v[100:103], v[168:171], v[184:187], v[100:103]
	v_mfma_f32_16x16x32_f16 v[100:103], v[172:175], v[188:191], v[100:103]
	v_mfma_f32_16x16x32_f16 v[108:111], v[164:167], v[188:191], v[108:111]
	v_mfma_f32_16x16x32_f16 v[108:111], v[160:163], v[184:187], v[108:111]
	v_mfma_f32_16x16x32_f16 v[92:95], v[160:163], v[196:199], v[92:95]
	v_mfma_f32_16x16x32_f16 v[92:95], v[164:167], v[200:203], v[92:95]
	v_mfma_f32_16x16x32_f16 v[84:87], v[172:175], v[200:203], v[84:87]
	v_mfma_f32_16x16x32_f16 v[84:87], v[168:171], v[196:199], v[84:87]
	v_mfma_f32_16x16x32_f16 v[68:71], v[168:171], v[204:207], v[68:71]
	v_mfma_f32_16x16x32_f16 v[68:71], v[172:175], v[208:211], v[68:71]
	s_setprio 2
	s_barrier
	v_mfma_f32_16x16x32_f16 v[76:79], v[164:167], v[208:211], v[76:79]
	v_mfma_f32_16x16x32_f16 v[76:79], v[160:163], v[204:207], v[76:79]
	s_setprio 0
	s_add_i32 s68, s71, s53
	s_mov_b32 m0, s68
	ds_read_b128 v[176:179], v216 offset:16384
	ds_read_b128 v[180:183], v216 offset:17408
	ds_read_b128 v[184:187], v216 offset:18432
	ds_read_b128 v[188:191], v216 offset:19456
	ds_read_b128 v[196:199], v216 offset:20480
	ds_read_b128 v[200:203], v216 offset:21504
	ds_read_b128 v[204:207], v216 offset:22528
	ds_read_b128 v[208:211], v216 offset:23552
	global_load_lds_dwordx4 v138, s[42:43]
	s_add_i32 m0, s68, 0x2000
	s_add_u32 s68, s42, 0x80000
	s_addc_u32 s69, s43, 0
	s_add_i32 s67, s67, s53
	global_load_lds_dwordx4 v134, s[42:43]
	s_mov_b32 m0, s67
	v_mov_b32_e32 v139, v3
	global_load_lds_dwordx4 v138, s[68:69]
	s_add_i32 m0, s67, 0x2000
	v_mov_b32_e32 v135, v3
	global_load_lds_dwordx4 v134, s[68:69]
	s_mov_b32 m0, s54
	v_lshl_add_u64 v[136:137], s[42:43], 0, v[138:139]
	global_load_lds_dwordx4 v2, s[44:45]
	s_mov_b32 m0, s55
	v_lshl_add_u64 v[192:193], s[42:43], 0, v[134:135]
	global_load_lds_dwordx4 v132, s[44:45]
	s_waitcnt vmcnt(8)
	s_waitcnt lgkmcnt(0)
	v_lshl_add_u64 v[212:213], s[44:45], 0, v[2:3]
	v_lshl_add_u64 v[214:215], s[44:45], 0, v[132:133]
	s_barrier
	s_setprio 1
	v_mfma_f32_16x16x32_f16 v[64:67], v[144:147], v[176:179], v[64:67]
	v_mfma_f32_16x16x32_f16 v[64:67], v[148:151], v[180:183], v[64:67]
	v_mfma_f32_16x16x32_f16 v[56:59], v[156:159], v[180:183], v[56:59]
	v_mfma_f32_16x16x32_f16 v[56:59], v[152:155], v[176:179], v[56:59]
	v_mfma_f32_16x16x32_f16 v[40:43], v[152:155], v[184:187], v[40:43]
	v_mfma_f32_16x16x32_f16 v[40:43], v[156:159], v[188:191], v[40:43]
	v_mfma_f32_16x16x32_f16 v[48:51], v[148:151], v[188:191], v[48:51]
	v_mfma_f32_16x16x32_f16 v[48:51], v[144:147], v[184:187], v[48:51]
	v_mfma_f32_16x16x32_f16 v[32:35], v[144:147], v[196:199], v[32:35]
	v_mfma_f32_16x16x32_f16 v[32:35], v[148:151], v[200:203], v[32:35]
	v_mfma_f32_16x16x32_f16 v[24:27], v[156:159], v[200:203], v[24:27]
	v_mfma_f32_16x16x32_f16 v[24:27], v[152:155], v[196:199], v[24:27]
	v_mfma_f32_16x16x32_f16 v[8:11], v[152:155], v[204:207], v[8:11]
	v_mfma_f32_16x16x32_f16 v[8:11], v[156:159], v[208:211], v[8:11]
	v_mfma_f32_16x16x32_f16 v[16:19], v[148:151], v[208:211], v[16:19]
	v_mfma_f32_16x16x32_f16 v[16:19], v[144:147], v[204:207], v[16:19]
	s_setprio 0
	s_setprio 1
	v_mfma_f32_16x16x32_f16 v[60:63], v[160:163], v[176:179], v[60:63]
	v_mfma_f32_16x16x32_f16 v[60:63], v[164:167], v[180:183], v[60:63]
	v_mfma_f32_16x16x32_f16 v[52:55], v[172:175], v[180:183], v[52:55]
	v_mfma_f32_16x16x32_f16 v[52:55], v[168:171], v[176:179], v[52:55]
	v_mfma_f32_16x16x32_f16 v[36:39], v[168:171], v[184:187], v[36:39]
	v_mfma_f32_16x16x32_f16 v[36:39], v[172:175], v[188:191], v[36:39]
	v_mfma_f32_16x16x32_f16 v[44:47], v[164:167], v[188:191], v[44:47]
	v_mfma_f32_16x16x32_f16 v[44:47], v[160:163], v[184:187], v[44:47]
	v_mfma_f32_16x16x32_f16 v[28:31], v[160:163], v[196:199], v[28:31]
	v_mfma_f32_16x16x32_f16 v[28:31], v[164:167], v[200:203], v[28:31]
	v_mfma_f32_16x16x32_f16 v[20:23], v[172:175], v[200:203], v[20:23]
	v_mfma_f32_16x16x32_f16 v[20:23], v[168:171], v[196:199], v[20:23]
	v_mfma_f32_16x16x32_f16 v[4:7], v[168:171], v[204:207], v[4:7]
	v_mfma_f32_16x16x32_f16 v[4:7], v[172:175], v[208:211], v[4:7]
	s_setprio 2
	s_barrier
	v_mfma_f32_16x16x32_f16 v[12:15], v[164:167], v[208:211], v[12:15]
	v_mfma_f32_16x16x32_f16 v[12:15], v[160:163], v[204:207], v[12:15]
	s_setprio 0
	s_add_i32 s67, 0, 0x18000
	v_add_u32_e32 v135, s67, v143
	s_add_i32 s68, 0, 0x1c000
	ds_read_b128 v[144:147], v135
	ds_read_b128 v[148:151], v135 offset:1024
	ds_read_b128 v[152:155], v135 offset:2048
	ds_read_b128 v[156:159], v135 offset:3072
	v_add_u32_e32 v135, s68, v143
	ds_read_b128 v[160:163], v135
	ds_read_b128 v[164:167], v135 offset:1024
	ds_read_b128 v[168:171], v135 offset:2048
	ds_read_b128 v[172:175], v135 offset:3072
	s_add_u32 s44, s44, 0x80000
	s_addc_u32 s45, s45, 0
	s_mov_b32 m0, s56
	ds_read_b128 v[176:179], v216 offset:32768
	ds_read_b128 v[180:183], v216 offset:33792
	ds_read_b128 v[184:187], v216 offset:34816
	ds_read_b128 v[188:191], v216 offset:35840
	ds_read_b128 v[196:199], v216 offset:36864
	ds_read_b128 v[200:203], v216 offset:37888
	ds_read_b128 v[204:207], v216 offset:38912
	ds_read_b128 v[208:211], v216 offset:39936
	global_load_lds_dwordx4 v2, s[44:45]
	s_mov_b32 m0, s57
	s_nop 0
	global_load_lds_dwordx4 v132, s[44:45]
	s_waitcnt vmcnt(8)
	s_waitcnt lgkmcnt(0)
	s_barrier
	s_setprio 1
	v_mfma_f32_16x16x32_f16 v[128:131], v[144:147], v[176:179], v[128:131]
	v_mfma_f32_16x16x32_f16 v[128:131], v[148:151], v[180:183], v[128:131]
	v_mfma_f32_16x16x32_f16 v[120:123], v[156:159], v[180:183], v[120:123]
	v_mfma_f32_16x16x32_f16 v[120:123], v[152:155], v[176:179], v[120:123]
	v_mfma_f32_16x16x32_f16 v[104:107], v[152:155], v[184:187], v[104:107]
	v_mfma_f32_16x16x32_f16 v[104:107], v[156:159], v[188:191], v[104:107]
	v_mfma_f32_16x16x32_f16 v[112:115], v[148:151], v[188:191], v[112:115]
	v_mfma_f32_16x16x32_f16 v[112:115], v[144:147], v[184:187], v[112:115]
	v_mfma_f32_16x16x32_f16 v[96:99], v[144:147], v[196:199], v[96:99]
	v_mfma_f32_16x16x32_f16 v[96:99], v[148:151], v[200:203], v[96:99]
	v_mfma_f32_16x16x32_f16 v[88:91], v[156:159], v[200:203], v[88:91]
	v_mfma_f32_16x16x32_f16 v[88:91], v[152:155], v[196:199], v[88:91]
	v_mfma_f32_16x16x32_f16 v[72:75], v[152:155], v[204:207], v[72:75]
	v_mfma_f32_16x16x32_f16 v[72:75], v[156:159], v[208:211], v[72:75]
	v_mfma_f32_16x16x32_f16 v[80:83], v[148:151], v[208:211], v[80:83]
	v_mfma_f32_16x16x32_f16 v[80:83], v[144:147], v[204:207], v[80:83]
	s_setprio 0
	s_setprio 1
	v_mfma_f32_16x16x32_f16 v[124:127], v[160:163], v[176:179], v[124:127]
	v_mfma_f32_16x16x32_f16 v[124:127], v[164:167], v[180:183], v[124:127]
	v_mfma_f32_16x16x32_f16 v[116:119], v[172:175], v[180:183], v[116:119]
	v_mfma_f32_16x16x32_f16 v[116:119], v[168:171], v[176:179], v[116:119]
	v_mfma_f32_16x16x32_f16 v[100:103], v[168:171], v[184:187], v[100:103]
	v_mfma_f32_16x16x32_f16 v[100:103], v[172:175], v[188:191], v[100:103]
	v_mfma_f32_16x16x32_f16 v[108:111], v[164:167], v[188:191], v[108:111]
	v_mfma_f32_16x16x32_f16 v[108:111], v[160:163], v[184:187], v[108:111]
	v_mfma_f32_16x16x32_f16 v[92:95], v[160:163], v[196:199], v[92:95]
	v_mfma_f32_16x16x32_f16 v[92:95], v[164:167], v[200:203], v[92:95]
	v_mfma_f32_16x16x32_f16 v[84:87], v[172:175], v[200:203], v[84:87]
	v_mfma_f32_16x16x32_f16 v[84:87], v[168:171], v[196:199], v[84:87]
	v_mfma_f32_16x16x32_f16 v[68:71], v[168:171], v[204:207], v[68:71]
	v_mfma_f32_16x16x32_f16 v[68:71], v[172:175], v[208:211], v[68:71]
	s_setprio 2
	s_barrier
	v_mfma_f32_16x16x32_f16 v[76:79], v[164:167], v[208:211], v[76:79]
	v_mfma_f32_16x16x32_f16 v[76:79], v[160:163], v[204:207], v[76:79]
	s_setprio 0
	s_add_i32 s44, s67, s53
	v_lshl_add_u64 v[136:137], v[136:137], 0, s[86:87]
	s_mov_b32 m0, s44
	ds_read_b128 v[176:179], v216 offset:49152
	ds_read_b128 v[180:183], v216 offset:50176
	ds_read_b128 v[184:187], v216 offset:51200
	ds_read_b128 v[188:191], v216 offset:52224
	ds_read_b128 v[196:199], v216 offset:53248
	ds_read_b128 v[200:203], v216 offset:54272
	ds_read_b128 v[204:207], v216 offset:55296
	ds_read_b128 v[208:211], v216 offset:56320
	global_load_lds_dwordx4 v[136:137], off
	s_add_i32 m0, s44, 0x2000
	s_add_u32 s42, s42, 0x80080
	v_lshl_add_u64 v[136:137], v[192:193], 0, s[86:87]
	s_addc_u32 s43, s43, 0
	s_add_i32 s44, s68, s53
	global_load_lds_dwordx4 v[136:137], off
	s_mov_b32 m0, s44
	v_lshl_add_u64 v[136:137], v[212:213], 0, s[86:87]
	global_load_lds_dwordx4 v138, s[42:43]
	s_add_i32 m0, s44, 0x2000
	s_nop 0
	global_load_lds_dwordx4 v134, s[42:43]
	s_mov_b32 m0, s59
	s_nop 0
	global_load_lds_dwordx4 v[136:137], off
	v_lshl_add_u64 v[136:137], v[214:215], 0, s[86:87]
	s_mov_b32 m0, s60
	s_nop 0
	global_load_lds_dwordx4 v[136:137], off
	s_waitcnt vmcnt(8)
	s_waitcnt lgkmcnt(0)
	s_barrier
	s_setprio 1
	v_mfma_f32_16x16x32_f16 v[64:67], v[144:147], v[176:179], v[64:67]
	v_mfma_f32_16x16x32_f16 v[64:67], v[148:151], v[180:183], v[64:67]
	v_mfma_f32_16x16x32_f16 v[56:59], v[156:159], v[180:183], v[56:59]
	v_mfma_f32_16x16x32_f16 v[56:59], v[152:155], v[176:179], v[56:59]
	v_mfma_f32_16x16x32_f16 v[40:43], v[152:155], v[184:187], v[40:43]
	v_mfma_f32_16x16x32_f16 v[40:43], v[156:159], v[188:191], v[40:43]
	v_mfma_f32_16x16x32_f16 v[48:51], v[148:151], v[188:191], v[48:51]
	v_mfma_f32_16x16x32_f16 v[48:51], v[144:147], v[184:187], v[48:51]
	v_mfma_f32_16x16x32_f16 v[32:35], v[144:147], v[196:199], v[32:35]
	v_mfma_f32_16x16x32_f16 v[32:35], v[148:151], v[200:203], v[32:35]
	v_mfma_f32_16x16x32_f16 v[24:27], v[156:159], v[200:203], v[24:27]
	v_mfma_f32_16x16x32_f16 v[24:27], v[152:155], v[196:199], v[24:27]
	v_mfma_f32_16x16x32_f16 v[8:11], v[152:155], v[204:207], v[8:11]
	v_mfma_f32_16x16x32_f16 v[8:11], v[156:159], v[208:211], v[8:11]
	v_mfma_f32_16x16x32_f16 v[16:19], v[148:151], v[208:211], v[16:19]
	v_mfma_f32_16x16x32_f16 v[16:19], v[144:147], v[204:207], v[16:19]
	s_setprio 0
	s_setprio 1
	v_mfma_f32_16x16x32_f16 v[60:63], v[160:163], v[176:179], v[60:63]
	v_mfma_f32_16x16x32_f16 v[60:63], v[164:167], v[180:183], v[60:63]
	v_mfma_f32_16x16x32_f16 v[52:55], v[172:175], v[180:183], v[52:55]
	v_mfma_f32_16x16x32_f16 v[52:55], v[168:171], v[176:179], v[52:55]
	v_mfma_f32_16x16x32_f16 v[36:39], v[168:171], v[184:187], v[36:39]
	v_mfma_f32_16x16x32_f16 v[36:39], v[172:175], v[188:191], v[36:39]
	v_mfma_f32_16x16x32_f16 v[44:47], v[164:167], v[188:191], v[44:47]
	v_mfma_f32_16x16x32_f16 v[44:47], v[160:163], v[184:187], v[44:47]
	v_mfma_f32_16x16x32_f16 v[28:31], v[160:163], v[196:199], v[28:31]
	v_mfma_f32_16x16x32_f16 v[28:31], v[164:167], v[200:203], v[28:31]
	v_mfma_f32_16x16x32_f16 v[20:23], v[172:175], v[200:203], v[20:23]
	v_mfma_f32_16x16x32_f16 v[20:23], v[168:171], v[196:199], v[20:23]
	v_mfma_f32_16x16x32_f16 v[4:7], v[168:171], v[204:207], v[4:7]
	v_mfma_f32_16x16x32_f16 v[4:7], v[172:175], v[208:211], v[4:7]
	s_setprio 2
	s_barrier
	v_mfma_f32_16x16x32_f16 v[12:15], v[164:167], v[208:211], v[12:15]
	v_mfma_f32_16x16x32_f16 v[12:15], v[160:163], v[204:207], v[12:15]
	s_setprio 0
	s_add_i32 s11, s11, 2
	s_add_u32 s40, s40, 0x100
	s_addc_u32 s41, s41, 0
	s_cmp_gt_u32 s11, 29
	s_cbranch_scc0 .LBB0_2161
	s_andn2_b64 vcc, exec, s[26:27]
	s_cbranch_vccnz .LBB0_2164
	s_add_u32 s6, s28, 0x80080
	s_addc_u32 s7, s29, 0
	s_mov_b32 m0, s61
	v_lshl_add_u64 v[144:145], s[6:7], 0, v[2:3]
	v_lshl_add_u64 v[136:137], s[6:7], 0, v[132:133]
	global_load_lds_dwordx4 v[144:145], off
	s_mov_b32 m0, s62
	s_mov_b32 s47, s65
	global_load_lds_dwordx4 v[136:137], off
	s_mov_b32 s64, s10
	s_mov_b64 s[8:9], s[14:15]
	s_mov_b64 s[6:7], s[12:13]
	s_mov_b32 s63, s66

.LBB0_2269:
	s_add_i32 s51, 0, 0x10000
	s_add_i32 s71, 0, 0x14000
	v_add_u32_e32 v16, s51, v232
	v_add_u32_e32 v32, s71, v232
	ds_read_b128 v[4:7], v16
	ds_read_b128 v[8:11], v16 offset:1024
	ds_read_b128 v[12:15], v16 offset:2048
	ds_read_b128 v[16:19], v16 offset:3072
	ds_read_b128 v[20:23], v32
	ds_read_b128 v[24:27], v32 offset:1024
	ds_read_b128 v[28:31], v32 offset:2048
	ds_read_b128 v[32:35], v32 offset:3072
	v_add_u32_e32 v233, 0, v231
	ds_read_b128 v[36:39], v233
	ds_read_b128 v[40:43], v233 offset:1024
	ds_read_b128 v[44:47], v233 offset:2048
	ds_read_b128 v[48:51], v233 offset:3072
	ds_read_b128 v[52:55], v233 offset:4096
	ds_read_b128 v[56:59], v233 offset:5120
	ds_read_b128 v[60:63], v233 offset:6144
	ds_read_b128 v[64:67], v233 offset:7168
	s_waitcnt vmcnt(8)
	s_waitcnt lgkmcnt(0)
	s_barrier
	s_setprio 1
	v_mfma_f32_16x16x32_bf16 v[68:71], v[4:7], v[36:39], 0
	v_mfma_f32_16x16x32_bf16 v[68:71], v[8:11], v[40:43], v[68:71]
	v_mfma_f32_16x16x32_bf16 v[72:75], v[12:15], v[36:39], 0
	v_mfma_f32_16x16x32_bf16 v[72:75], v[16:19], v[40:43], v[72:75]
	v_mfma_f32_16x16x32_bf16 v[80:83], v[12:15], v[44:47], 0
	v_mfma_f32_16x16x32_bf16 v[80:83], v[16:19], v[48:51], v[80:83]
	v_mfma_f32_16x16x32_bf16 v[76:79], v[4:7], v[44:47], 0
	v_mfma_f32_16x16x32_bf16 v[76:79], v[8:11], v[48:51], v[76:79]
	v_mfma_f32_16x16x32_bf16 v[84:87], v[4:7], v[52:55], 0
	v_mfma_f32_16x16x32_bf16 v[84:87], v[8:11], v[56:59], v[84:87]
	v_mfma_f32_16x16x32_bf16 v[88:91], v[12:15], v[52:55], 0
	v_mfma_f32_16x16x32_bf16 v[88:91], v[16:19], v[56:59], v[88:91]
	v_mfma_f32_16x16x32_bf16 v[96:99], v[12:15], v[60:63], 0
	v_mfma_f32_16x16x32_bf16 v[96:99], v[16:19], v[64:67], v[96:99]
	v_mfma_f32_16x16x32_bf16 v[92:95], v[4:7], v[60:63], 0
	v_mfma_f32_16x16x32_bf16 v[92:95], v[8:11], v[64:67], v[92:95]
	s_setprio 0
	s_setprio 1
	v_mfma_f32_16x16x32_bf16 v[100:103], v[20:23], v[36:39], 0
	v_mfma_f32_16x16x32_bf16 v[36:39], v[28:31], v[36:39], 0
	v_mfma_f32_16x16x32_bf16 v[104:107], v[20:23], v[44:47], 0
	v_mfma_f32_16x16x32_bf16 v[44:47], v[28:31], v[44:47], 0
	v_mfma_f32_16x16x32_bf16 v[108:111], v[20:23], v[52:55], 0
	v_mfma_f32_16x16x32_bf16 v[52:55], v[28:31], v[52:55], 0
	v_mfma_f32_16x16x32_bf16 v[112:115], v[20:23], v[60:63], 0
	v_mfma_f32_16x16x32_bf16 v[60:63], v[28:31], v[60:63], 0
	v_mfma_f32_16x16x32_bf16 v[100:103], v[24:27], v[40:43], v[100:103]
	v_mfma_f32_16x16x32_bf16 v[40:43], v[32:35], v[40:43], v[36:39]
	v_mfma_f32_16x16x32_bf16 v[104:107], v[24:27], v[48:51], v[104:107]
	v_mfma_f32_16x16x32_bf16 v[48:51], v[32:35], v[48:51], v[44:47]
	v_mfma_f32_16x16x32_bf16 v[108:111], v[24:27], v[56:59], v[108:111]
	v_mfma_f32_16x16x32_bf16 v[56:59], v[32:35], v[56:59], v[52:55]
	s_setprio 2
	s_barrier
	v_mfma_f32_16x16x32_bf16 v[112:115], v[24:27], v[64:67], v[112:115]
	v_mfma_f32_16x16x32_bf16 v[64:67], v[32:35], v[64:67], v[60:63]
	s_setprio 0
	v_lshl_add_u64 v[186:187], s[12:13], 0, v[2:3]
	s_add_i32 s51, s51, s38
	v_mov_b32_e32 v191, v3
	v_lshl_add_u64 v[134:135], v[186:187], 0, s[74:75]
	s_mov_b32 m0, s51
	v_lshl_add_u64 v[246:247], s[12:13], 0, v[190:191]
	ds_read_b128 v[36:39], v233 offset:16384
	ds_read_b128 v[44:47], v233 offset:17408
	ds_read_b128 v[52:55], v233 offset:18432
	ds_read_b128 v[60:63], v233 offset:19456
	ds_read_b128 v[116:119], v233 offset:20480
	ds_read_b128 v[120:123], v233 offset:21504
	ds_read_b128 v[124:127], v233 offset:22528
	ds_read_b128 v[128:131], v233 offset:23552
	global_load_lds_dwordx4 v[134:135], off
	v_lshl_add_u64 v[134:135], v[246:247], 0, s[74:75]
	s_add_i32 m0, s51, 0x2000
	s_add_i32 s51, s71, s38
	global_load_lds_dwordx4 v[134:135], off
	s_mov_b32 m0, s51
	v_mov_b32_e32 v133, v3
	global_load_lds_dwordx4 v2, s[16:17]
	s_add_i32 m0, s51, 0x2000
	v_lshl_add_u64 v[248:249], s[14:15], 0, v[132:133]
	v_mov_b32_e32 v189, v3
	global_load_lds_dwordx4 v190, s[16:17]
	v_lshl_add_u64 v[134:135], v[248:249], 0, s[74:75]
	s_mov_b32 m0, s56
	v_lshl_add_u64 v[250:251], s[14:15], 0, v[188:189]
	global_load_lds_dwordx4 v[134:135], off
	v_lshl_add_u64 v[134:135], v[250:251], 0, s[74:75]
	s_mov_b32 m0, s57
	s_nop 0
	global_load_lds_dwordx4 v[134:135], off
	s_waitcnt vmcnt(8)
	s_waitcnt lgkmcnt(0)
	s_barrier
	s_setprio 1
	v_mfma_f32_16x16x32_bf16 v[134:137], v[4:7], v[36:39], 0
	v_mfma_f32_16x16x32_bf16 v[138:141], v[12:15], v[36:39], 0
	v_mfma_f32_16x16x32_bf16 v[142:145], v[4:7], v[52:55], 0
	v_mfma_f32_16x16x32_bf16 v[146:149], v[12:15], v[52:55], 0
	v_mfma_f32_16x16x32_bf16 v[150:153], v[4:7], v[116:119], 0
	v_mfma_f32_16x16x32_bf16 v[154:157], v[12:15], v[116:119], 0
	v_mfma_f32_16x16x32_bf16 v[4:7], v[4:7], v[124:127], 0
	v_mfma_f32_16x16x32_bf16 v[12:15], v[12:15], v[124:127], 0
	v_mfma_f32_16x16x32_bf16 v[134:137], v[8:11], v[44:47], v[134:137]
	v_mfma_f32_16x16x32_bf16 v[138:141], v[16:19], v[44:47], v[138:141]
	v_mfma_f32_16x16x32_bf16 v[142:145], v[8:11], v[60:63], v[142:145]
	v_mfma_f32_16x16x32_bf16 v[146:149], v[16:19], v[60:63], v[146:149]
	v_mfma_f32_16x16x32_bf16 v[150:153], v[8:11], v[120:123], v[150:153]
	v_mfma_f32_16x16x32_bf16 v[154:157], v[16:19], v[120:123], v[154:157]
	v_mfma_f32_16x16x32_bf16 v[158:161], v[8:11], v[128:131], v[4:7]
	v_mfma_f32_16x16x32_bf16 v[162:165], v[16:19], v[128:131], v[12:15]
	s_setprio 0
	s_setprio 1
	v_mfma_f32_16x16x32_bf16 v[4:7], v[20:23], v[36:39], 0
	v_mfma_f32_16x16x32_bf16 v[8:11], v[28:31], v[36:39], 0
	v_mfma_f32_16x16x32_bf16 v[12:15], v[20:23], v[52:55], 0
	v_mfma_f32_16x16x32_bf16 v[16:19], v[28:31], v[52:55], 0
	v_mfma_f32_16x16x32_bf16 v[36:39], v[20:23], v[116:119], 0
	v_mfma_f32_16x16x32_bf16 v[52:55], v[28:31], v[116:119], 0
	v_mfma_f32_16x16x32_bf16 v[20:23], v[20:23], v[124:127], 0
	v_mfma_f32_16x16x32_bf16 v[28:31], v[28:31], v[124:127], 0
	v_mfma_f32_16x16x32_bf16 v[116:119], v[24:27], v[44:47], v[4:7]
	v_mfma_f32_16x16x32_bf16 v[124:127], v[32:35], v[44:47], v[8:11]
	v_mfma_f32_16x16x32_bf16 v[174:177], v[24:27], v[120:123], v[36:39]
	v_mfma_f32_16x16x32_bf16 v[120:123], v[32:35], v[120:123], v[52:55]
	v_mfma_f32_16x16x32_bf16 v[178:181], v[24:27], v[128:131], v[20:23]
	v_mfma_f32_16x16x32_bf16 v[128:131], v[32:35], v[128:131], v[28:31]
	s_setprio 2
	s_barrier
	v_mfma_f32_16x16x32_bf16 v[166:169], v[24:27], v[60:63], v[12:15]
	v_mfma_f32_16x16x32_bf16 v[170:173], v[32:35], v[60:63], v[16:19]
	s_setprio 0
	s_add_i32 s51, 0, 0x18000
	v_add_u32_e32 v4, s51, v232
	s_add_i32 s71, 0, 0x1c000
	ds_read_b128 v[182:185], v4
	ds_read_b128 v[192:195], v4 offset:1024
	ds_read_b128 v[196:199], v4 offset:2048
	ds_read_b128 v[200:203], v4 offset:3072
	v_add_u32_e32 v4, s71, v232
	ds_read_b128 v[204:207], v4
	ds_read_b128 v[208:211], v4 offset:1024
	ds_read_b128 v[212:215], v4 offset:2048
	ds_read_b128 v[216:219], v4 offset:3072
	s_mov_b32 m0, s58
	ds_read_b128 v[44:47], v233 offset:32768
	ds_read_b128 v[52:55], v233 offset:33792
	ds_read_b128 v[60:63], v233 offset:34816
	ds_read_b128 v[220:223], v233 offset:35840
	ds_read_b128 v[224:227], v233 offset:36864
	ds_read_b128 v[234:237], v233 offset:37888
	ds_read_b128 v[238:241], v233 offset:38912
	ds_read_b128 v[242:245], v233 offset:39936
	global_load_lds_dwordx4 v132, s[26:27]
	s_mov_b32 m0, s59
	s_nop 0
	global_load_lds_dwordx4 v188, s[26:27]
	s_waitcnt vmcnt(8)
	s_waitcnt lgkmcnt(0)
	s_barrier
	s_setprio 1
	v_mfma_f32_16x16x32_bf16 v[4:7], v[182:185], v[44:47], v[68:71]
	v_mfma_f32_16x16x32_bf16 v[8:11], v[196:199], v[44:47], v[72:75]
	v_mfma_f32_16x16x32_bf16 v[12:15], v[182:185], v[60:63], v[76:79]
	v_mfma_f32_16x16x32_bf16 v[16:19], v[196:199], v[60:63], v[80:83]
	v_mfma_f32_16x16x32_bf16 v[20:23], v[182:185], v[224:227], v[84:87]
	v_mfma_f32_16x16x32_bf16 v[24:27], v[196:199], v[224:227], v[88:91]
	v_mfma_f32_16x16x32_bf16 v[28:31], v[182:185], v[238:241], v[92:95]
	v_mfma_f32_16x16x32_bf16 v[32:35], v[196:199], v[238:241], v[96:99]
	v_mfma_f32_16x16x32_bf16 v[4:7], v[192:195], v[52:55], v[4:7]
	v_mfma_f32_16x16x32_bf16 v[8:11], v[200:203], v[52:55], v[8:11]
	v_mfma_f32_16x16x32_bf16 v[12:15], v[192:195], v[220:223], v[12:15]
	v_mfma_f32_16x16x32_bf16 v[16:19], v[200:203], v[220:223], v[16:19]
	v_mfma_f32_16x16x32_bf16 v[20:23], v[192:195], v[234:237], v[20:23]
	v_mfma_f32_16x16x32_bf16 v[24:27], v[200:203], v[234:237], v[24:27]
	v_mfma_f32_16x16x32_bf16 v[28:31], v[192:195], v[242:245], v[28:31]
	v_mfma_f32_16x16x32_bf16 v[32:35], v[200:203], v[242:245], v[32:35]
	s_setprio 0
	s_setprio 1
	v_mfma_f32_16x16x32_bf16 v[36:39], v[204:207], v[44:47], v[100:103]
	v_mfma_f32_16x16x32_bf16 v[40:43], v[212:215], v[44:47], v[40:43]
	v_mfma_f32_16x16x32_bf16 v[36:39], v[208:211], v[52:55], v[36:39]
	v_mfma_f32_16x16x32_bf16 v[40:43], v[216:219], v[52:55], v[40:43]
	v_mfma_f32_16x16x32_bf16 v[44:47], v[204:207], v[60:63], v[104:107]
	v_mfma_f32_16x16x32_bf16 v[48:51], v[212:215], v[60:63], v[48:51]
	v_mfma_f32_16x16x32_bf16 v[52:55], v[204:207], v[224:227], v[108:111]
	v_mfma_f32_16x16x32_bf16 v[56:59], v[212:215], v[224:227], v[56:59]
	v_mfma_f32_16x16x32_bf16 v[60:63], v[204:207], v[238:241], v[112:115]
	v_mfma_f32_16x16x32_bf16 v[64:67], v[212:215], v[238:241], v[64:67]
	v_mfma_f32_16x16x32_bf16 v[44:47], v[208:211], v[220:223], v[44:47]
	v_mfma_f32_16x16x32_bf16 v[48:51], v[216:219], v[220:223], v[48:51]
	v_mfma_f32_16x16x32_bf16 v[52:55], v[208:211], v[234:237], v[52:55]
	v_mfma_f32_16x16x32_bf16 v[56:59], v[216:219], v[234:237], v[56:59]
	s_setprio 2
	s_barrier
	v_mfma_f32_16x16x32_bf16 v[60:63], v[208:211], v[242:245], v[60:63]
	v_mfma_f32_16x16x32_bf16 v[64:67], v[216:219], v[242:245], v[64:67]
	s_setprio 0
	s_add_i32 s51, s51, s38
	v_lshl_add_u64 v[68:69], v[186:187], 0, s[24:25]
	s_mov_b32 m0, s51
	ds_read_b128 v[104:107], v233 offset:49152
	ds_read_b128 v[108:111], v233 offset:50176
	ds_read_b128 v[112:115], v233 offset:51200
	ds_read_b128 v[220:223], v233 offset:52224
	ds_read_b128 v[224:227], v233 offset:53248
	ds_read_b128 v[234:237], v233 offset:54272
	ds_read_b128 v[238:241], v233 offset:55296
	ds_read_b128 v[242:245], v233 offset:56320
	global_load_lds_dwordx4 v[68:69], off
	v_lshl_add_u64 v[68:69], v[246:247], 0, s[24:25]
	s_add_i32 m0, s51, 0x2000
	s_add_i32 s51, s71, s38
	global_load_lds_dwordx4 v[68:69], off
	s_mov_b32 m0, s51
	v_lshl_add_u64 v[68:69], v[248:249], 0, s[24:25]
	global_load_lds_dwordx4 v2, s[28:29]
	s_add_i32 m0, s51, 0x2000
	s_nop 0
	global_load_lds_dwordx4 v190, s[28:29]
	s_mov_b32 m0, s63
	s_nop 0
	global_load_lds_dwordx4 v[68:69], off
	v_lshl_add_u64 v[68:69], v[250:251], 0, s[24:25]
	s_mov_b32 m0, s64
	s_nop 0
	global_load_lds_dwordx4 v[68:69], off
	s_waitcnt vmcnt(8)
	s_waitcnt lgkmcnt(0)
	s_barrier
	s_setprio 1
	v_mfma_f32_16x16x32_bf16 v[68:71], v[182:185], v[104:107], v[134:137]
	v_mfma_f32_16x16x32_bf16 v[72:75], v[196:199], v[104:107], v[138:141]
	v_mfma_f32_16x16x32_bf16 v[76:79], v[182:185], v[112:115], v[142:145]
	v_mfma_f32_16x16x32_bf16 v[80:83], v[196:199], v[112:115], v[146:149]
	v_mfma_f32_16x16x32_bf16 v[84:87], v[182:185], v[224:227], v[150:153]
	v_mfma_f32_16x16x32_bf16 v[88:91], v[196:199], v[224:227], v[154:157]
	v_mfma_f32_16x16x32_bf16 v[92:95], v[182:185], v[238:241], v[158:161]
	v_mfma_f32_16x16x32_bf16 v[96:99], v[196:199], v[238:241], v[162:165]
	v_mfma_f32_16x16x32_bf16 v[68:71], v[192:195], v[108:111], v[68:71]
	v_mfma_f32_16x16x32_bf16 v[72:75], v[200:203], v[108:111], v[72:75]
	v_mfma_f32_16x16x32_bf16 v[76:79], v[192:195], v[220:223], v[76:79]
	v_mfma_f32_16x16x32_bf16 v[80:83], v[200:203], v[220:223], v[80:83]
	v_mfma_f32_16x16x32_bf16 v[84:87], v[192:195], v[234:237], v[84:87]
	v_mfma_f32_16x16x32_bf16 v[88:91], v[200:203], v[234:237], v[88:91]
	v_mfma_f32_16x16x32_bf16 v[92:95], v[192:195], v[242:245], v[92:95]
	v_mfma_f32_16x16x32_bf16 v[96:99], v[200:203], v[242:245], v[96:99]
	s_setprio 0
	s_setprio 1
	v_mfma_f32_16x16x32_bf16 v[100:103], v[204:207], v[104:107], v[116:119]
	v_mfma_f32_16x16x32_bf16 v[104:107], v[212:215], v[104:107], v[124:127]
	v_mfma_f32_16x16x32_bf16 v[100:103], v[208:211], v[108:111], v[100:103]
	v_mfma_f32_16x16x32_bf16 v[104:107], v[216:219], v[108:111], v[104:107]
	v_mfma_f32_16x16x32_bf16 v[108:111], v[204:207], v[112:115], v[166:169]
	v_mfma_f32_16x16x32_bf16 v[112:115], v[212:215], v[112:115], v[170:173]
	v_mfma_f32_16x16x32_bf16 v[116:119], v[204:207], v[224:227], v[174:177]
	v_mfma_f32_16x16x32_bf16 v[120:123], v[212:215], v[224:227], v[120:123]
	v_mfma_f32_16x16x32_bf16 v[124:127], v[204:207], v[238:241], v[178:181]
	v_mfma_f32_16x16x32_bf16 v[128:131], v[212:215], v[238:241], v[128:131]
	v_mfma_f32_16x16x32_bf16 v[108:111], v[208:211], v[220:223], v[108:111]
	v_mfma_f32_16x16x32_bf16 v[112:115], v[216:219], v[220:223], v[112:115]
	v_mfma_f32_16x16x32_bf16 v[116:119], v[208:211], v[234:237], v[116:119]
	v_mfma_f32_16x16x32_bf16 v[120:123], v[216:219], v[234:237], v[120:123]
	s_setprio 2
	s_barrier
	v_mfma_f32_16x16x32_bf16 v[124:127], v[208:211], v[242:245], v[124:127]
	v_mfma_f32_16x16x32_bf16 v[128:131], v[216:219], v[242:245], v[128:131]
	s_setprio 0
	s_add_i32 s41, s41, 2
	s_cmp_ge_i32 s41, s40
	s_cbranch_scc0 .LBB0_2269
	v_mov_b32_e32 v192, v2
	s_branch .LBB0_2272

.LBB0_2273:
	s_add_u32 s12, s14, 0xfffc0080
	s_addc_u32 s13, s15, -1
	s_add_i32 s29, 0, 0x10000
	s_cmp_eq_u32 s28, 12
	s_cselect_b32 s17, s9, s13
	s_cselect_b32 s16, s8, s12
	s_cselect_b32 s13, s11, s27
	s_cselect_b32 s12, s10, s26
	s_add_i32 s51, 0, 0x14000
	v_add_u32_e32 v144, s29, v232
	v_add_u32_e32 v160, s51, v232
	s_waitcnt lgkmcnt(0)
	ds_read_b128 v[132:135], v144
	ds_read_b128 v[136:139], v144 offset:1024
	ds_read_b128 v[140:143], v144 offset:2048
	ds_read_b128 v[144:147], v144 offset:3072
	ds_read_b128 v[148:151], v160
	ds_read_b128 v[152:155], v160 offset:1024
	ds_read_b128 v[156:159], v160 offset:2048
	ds_read_b128 v[160:163], v160 offset:3072
	s_mov_b32 m0, s65
	v_add_u32_e32 v210, 0, v231
	ds_read_b128 v[164:167], v210
	ds_read_b128 v[168:171], v210 offset:1024
	ds_read_b128 v[172:175], v210 offset:2048
	ds_read_b128 v[176:179], v210 offset:3072
	ds_read_b128 v[180:183], v210 offset:4096
	ds_read_b128 v[184:187], v210 offset:5120
	ds_read_b128 v[194:197], v210 offset:6144
	ds_read_b128 v[198:201], v210 offset:7168
	global_load_lds_dwordx4 v2, s[14:15]
	s_mov_b32 m0, s66
	v_mov_b32_e32 v189, v3
	global_load_lds_dwordx4 v188, s[14:15]
	s_waitcnt vmcnt(8)
	s_waitcnt lgkmcnt(0)
	s_barrier
	s_setprio 1
	v_mfma_f32_16x16x32_bf16 v[4:7], v[132:135], v[164:167], v[4:7]
	v_mfma_f32_16x16x32_bf16 v[4:7], v[136:139], v[168:171], v[4:7]
	v_mfma_f32_16x16x32_bf16 v[8:11], v[144:147], v[168:171], v[8:11]
	v_mfma_f32_16x16x32_bf16 v[8:11], v[140:143], v[164:167], v[8:11]
	v_mfma_f32_16x16x32_bf16 v[16:19], v[140:143], v[172:175], v[16:19]
	v_mfma_f32_16x16x32_bf16 v[16:19], v[144:147], v[176:179], v[16:19]
	v_mfma_f32_16x16x32_bf16 v[12:15], v[136:139], v[176:179], v[12:15]
	v_mfma_f32_16x16x32_bf16 v[12:15], v[132:135], v[172:175], v[12:15]
	v_mfma_f32_16x16x32_bf16 v[20:23], v[132:135], v[180:183], v[20:23]
	v_mfma_f32_16x16x32_bf16 v[20:23], v[136:139], v[184:187], v[20:23]
	v_mfma_f32_16x16x32_bf16 v[24:27], v[144:147], v[184:187], v[24:27]
	v_mfma_f32_16x16x32_bf16 v[24:27], v[140:143], v[180:183], v[24:27]
	v_mfma_f32_16x16x32_bf16 v[32:35], v[140:143], v[194:197], v[32:35]
	v_mfma_f32_16x16x32_bf16 v[32:35], v[144:147], v[198:201], v[32:35]
	v_mfma_f32_16x16x32_bf16 v[28:31], v[136:139], v[198:201], v[28:31]
	v_mfma_f32_16x16x32_bf16 v[28:31], v[132:135], v[194:197], v[28:31]
	s_setprio 0
	s_setprio 1
	v_mfma_f32_16x16x32_bf16 v[36:39], v[148:151], v[164:167], v[36:39]
	v_mfma_f32_16x16x32_bf16 v[36:39], v[152:155], v[168:171], v[36:39]
	v_mfma_f32_16x16x32_bf16 v[40:43], v[160:163], v[168:171], v[40:43]
	v_mfma_f32_16x16x32_bf16 v[40:43], v[156:159], v[164:167], v[40:43]
	v_mfma_f32_16x16x32_bf16 v[48:51], v[156:159], v[172:175], v[48:51]
	v_mfma_f32_16x16x32_bf16 v[48:51], v[160:163], v[176:179], v[48:51]
	v_mfma_f32_16x16x32_bf16 v[44:47], v[152:155], v[176:179], v[44:47]
	v_mfma_f32_16x16x32_bf16 v[44:47], v[148:151], v[172:175], v[44:47]
	v_mfma_f32_16x16x32_bf16 v[52:55], v[148:151], v[180:183], v[52:55]
	v_mfma_f32_16x16x32_bf16 v[52:55], v[152:155], v[184:187], v[52:55]
	v_mfma_f32_16x16x32_bf16 v[56:59], v[160:163], v[184:187], v[56:59]
	v_mfma_f32_16x16x32_bf16 v[56:59], v[156:159], v[180:183], v[56:59]
	v_mfma_f32_16x16x32_bf16 v[64:67], v[156:159], v[194:197], v[64:67]
	v_mfma_f32_16x16x32_bf16 v[64:67], v[160:163], v[198:201], v[64:67]
	s_setprio 2
	s_barrier
	v_mfma_f32_16x16x32_bf16 v[60:63], v[152:155], v[198:201], v[60:63]
	v_mfma_f32_16x16x32_bf16 v[60:63], v[148:151], v[194:197], v[60:63]
	s_setprio 0
	s_add_i32 s29, s29, s38
	s_mov_b32 m0, s29
	ds_read_b128 v[164:167], v210 offset:16384
	ds_read_b128 v[168:171], v210 offset:17408
	ds_read_b128 v[172:175], v210 offset:18432
	ds_read_b128 v[176:179], v210 offset:19456
	ds_read_b128 v[180:183], v210 offset:20480
	ds_read_b128 v[184:187], v210 offset:21504
	ds_read_b128 v[194:197], v210 offset:22528
	ds_read_b128 v[198:201], v210 offset:23552
	global_load_lds_dwordx4 v192, s[12:13]
	s_add_i32 m0, s29, 0x2000
	s_add_u32 s40, s12, 0x100000
	s_addc_u32 s41, s13, 0
	s_add_i32 s29, s51, s38
	global_load_lds_dwordx4 v190, s[12:13]
	s_mov_b32 m0, s29
	v_mov_b32_e32 v193, v3
	global_load_lds_dwordx4 v192, s[40:41]
	s_add_i32 m0, s29, 0x2000
	v_mov_b32_e32 v191, v3
	global_load_lds_dwordx4 v190, s[40:41]
	s_mov_b32 m0, s56
	v_lshl_add_u64 v[202:203], s[12:13], 0, v[192:193]
	global_load_lds_dwordx4 v2, s[16:17]
	s_mov_b32 m0, s57
	v_lshl_add_u64 v[204:205], s[12:13], 0, v[190:191]
	global_load_lds_dwordx4 v188, s[16:17]
	s_waitcnt vmcnt(8)
	s_waitcnt lgkmcnt(0)
	v_lshl_add_u64 v[206:207], s[16:17], 0, v[2:3]
	v_lshl_add_u64 v[208:209], s[16:17], 0, v[188:189]
	s_barrier
	s_setprio 1
	v_mfma_f32_16x16x32_bf16 v[68:71], v[132:135], v[164:167], v[68:71]
	v_mfma_f32_16x16x32_bf16 v[68:71], v[136:139], v[168:171], v[68:71]
	v_mfma_f32_16x16x32_bf16 v[72:75], v[144:147], v[168:171], v[72:75]
	v_mfma_f32_16x16x32_bf16 v[72:75], v[140:143], v[164:167], v[72:75]
	v_mfma_f32_16x16x32_bf16 v[80:83], v[140:143], v[172:175], v[80:83]
	v_mfma_f32_16x16x32_bf16 v[80:83], v[144:147], v[176:179], v[80:83]
	v_mfma_f32_16x16x32_bf16 v[76:79], v[136:139], v[176:179], v[76:79]
	v_mfma_f32_16x16x32_bf16 v[76:79], v[132:135], v[172:175], v[76:79]
	v_mfma_f32_16x16x32_bf16 v[84:87], v[132:135], v[180:183], v[84:87]
	v_mfma_f32_16x16x32_bf16 v[84:87], v[136:139], v[184:187], v[84:87]
	v_mfma_f32_16x16x32_bf16 v[88:91], v[144:147], v[184:187], v[88:91]
	v_mfma_f32_16x16x32_bf16 v[88:91], v[140:143], v[180:183], v[88:91]
	v_mfma_f32_16x16x32_bf16 v[96:99], v[140:143], v[194:197], v[96:99]
	v_mfma_f32_16x16x32_bf16 v[96:99], v[144:147], v[198:201], v[96:99]
	v_mfma_f32_16x16x32_bf16 v[92:95], v[136:139], v[198:201], v[92:95]
	v_mfma_f32_16x16x32_bf16 v[92:95], v[132:135], v[194:197], v[92:95]
	s_setprio 0
	s_setprio 1
	v_mfma_f32_16x16x32_bf16 v[100:103], v[148:151], v[164:167], v[100:103]
	v_mfma_f32_16x16x32_bf16 v[100:103], v[152:155], v[168:171], v[100:103]
	v_mfma_f32_16x16x32_bf16 v[104:107], v[160:163], v[168:171], v[104:107]
	v_mfma_f32_16x16x32_bf16 v[104:107], v[156:159], v[164:167], v[104:107]
	v_mfma_f32_16x16x32_bf16 v[112:115], v[156:159], v[172:175], v[112:115]
	v_mfma_f32_16x16x32_bf16 v[112:115], v[160:163], v[176:179], v[112:115]
	v_mfma_f32_16x16x32_bf16 v[108:111], v[152:155], v[176:179], v[108:111]
	v_mfma_f32_16x16x32_bf16 v[108:111], v[148:151], v[172:175], v[108:111]
	v_mfma_f32_16x16x32_bf16 v[116:119], v[148:151], v[180:183], v[116:119]
	v_mfma_f32_16x16x32_bf16 v[116:119], v[152:155], v[184:187], v[116:119]
	v_mfma_f32_16x16x32_bf16 v[120:123], v[160:163], v[184:187], v[120:123]
	v_mfma_f32_16x16x32_bf16 v[120:123], v[156:159], v[180:183], v[120:123]
	v_mfma_f32_16x16x32_bf16 v[128:131], v[156:159], v[194:197], v[128:131]
	v_mfma_f32_16x16x32_bf16 v[128:131], v[160:163], v[198:201], v[128:131]
	s_setprio 2
	s_barrier
	v_mfma_f32_16x16x32_bf16 v[124:127], v[152:155], v[198:201], v[124:127]
	v_mfma_f32_16x16x32_bf16 v[124:127], v[148:151], v[194:197], v[124:127]
	s_setprio 0
	s_add_i32 s29, 0, 0x18000
	s_add_i32 s40, 0, 0x1c000
	v_add_u32_e32 v144, s29, v232
	v_add_u32_e32 v160, s40, v232
	ds_read_b128 v[132:135], v144
	ds_read_b128 v[136:139], v144 offset:1024
	ds_read_b128 v[140:143], v144 offset:2048
	ds_read_b128 v[144:147], v144 offset:3072
	ds_read_b128 v[148:151], v160
	ds_read_b128 v[152:155], v160 offset:1024
	ds_read_b128 v[156:159], v160 offset:2048
	ds_read_b128 v[160:163], v160 offset:3072
	s_add_u32 s16, s16, 0x40000
	s_addc_u32 s17, s17, 0
	s_mov_b32 m0, s58
	ds_read_b128 v[164:167], v210 offset:32768
	ds_read_b128 v[168:171], v210 offset:33792
	ds_read_b128 v[172:175], v210 offset:34816
	ds_read_b128 v[176:179], v210 offset:35840
	ds_read_b128 v[180:183], v210 offset:36864
	ds_read_b128 v[184:187], v210 offset:37888
	ds_read_b128 v[194:197], v210 offset:38912
	ds_read_b128 v[198:201], v210 offset:39936
	global_load_lds_dwordx4 v2, s[16:17]
	s_mov_b32 m0, s59
	s_nop 0
	global_load_lds_dwordx4 v188, s[16:17]
	s_waitcnt vmcnt(8)
	s_waitcnt lgkmcnt(0)
	s_barrier
	s_setprio 1
	v_mfma_f32_16x16x32_bf16 v[4:7], v[132:135], v[164:167], v[4:7]
	v_mfma_f32_16x16x32_bf16 v[4:7], v[136:139], v[168:171], v[4:7]
	v_mfma_f32_16x16x32_bf16 v[8:11], v[144:147], v[168:171], v[8:11]
	v_mfma_f32_16x16x32_bf16 v[8:11], v[140:143], v[164:167], v[8:11]
	v_mfma_f32_16x16x32_bf16 v[16:19], v[140:143], v[172:175], v[16:19]
	v_mfma_f32_16x16x32_bf16 v[16:19], v[144:147], v[176:179], v[16:19]
	v_mfma_f32_16x16x32_bf16 v[12:15], v[136:139], v[176:179], v[12:15]
	v_mfma_f32_16x16x32_bf16 v[12:15], v[132:135], v[172:175], v[12:15]
	v_mfma_f32_16x16x32_bf16 v[20:23], v[132:135], v[180:183], v[20:23]
	v_mfma_f32_16x16x32_bf16 v[20:23], v[136:139], v[184:187], v[20:23]
	v_mfma_f32_16x16x32_bf16 v[24:27], v[144:147], v[184:187], v[24:27]
	v_mfma_f32_16x16x32_bf16 v[24:27], v[140:143], v[180:183], v[24:27]
	v_mfma_f32_16x16x32_bf16 v[32:35], v[140:143], v[194:197], v[32:35]
	v_mfma_f32_16x16x32_bf16 v[32:35], v[144:147], v[198:201], v[32:35]
	v_mfma_f32_16x16x32_bf16 v[28:31], v[136:139], v[198:201], v[28:31]
	v_mfma_f32_16x16x32_bf16 v[28:31], v[132:135], v[194:197], v[28:31]
	s_setprio 0
	s_setprio 1
	v_mfma_f32_16x16x32_bf16 v[36:39], v[148:151], v[164:167], v[36:39]
	v_mfma_f32_16x16x32_bf16 v[36:39], v[152:155], v[168:171], v[36:39]
	v_mfma_f32_16x16x32_bf16 v[40:43], v[160:163], v[168:171], v[40:43]
	v_mfma_f32_16x16x32_bf16 v[40:43], v[156:159], v[164:167], v[40:43]
	v_mfma_f32_16x16x32_bf16 v[48:51], v[156:159], v[172:175], v[48:51]
	v_mfma_f32_16x16x32_bf16 v[48:51], v[160:163], v[176:179], v[48:51]
	v_mfma_f32_16x16x32_bf16 v[44:47], v[152:155], v[176:179], v[44:47]
	v_mfma_f32_16x16x32_bf16 v[44:47], v[148:151], v[172:175], v[44:47]
	v_mfma_f32_16x16x32_bf16 v[52:55], v[148:151], v[180:183], v[52:55]
	v_mfma_f32_16x16x32_bf16 v[52:55], v[152:155], v[184:187], v[52:55]
	v_mfma_f32_16x16x32_bf16 v[56:59], v[160:163], v[184:187], v[56:59]
	v_mfma_f32_16x16x32_bf16 v[56:59], v[156:159], v[180:183], v[56:59]
	v_mfma_f32_16x16x32_bf16 v[64:67], v[156:159], v[194:197], v[64:67]
	v_mfma_f32_16x16x32_bf16 v[64:67], v[160:163], v[198:201], v[64:67]
	s_setprio 2
	s_barrier
	v_mfma_f32_16x16x32_bf16 v[60:63], v[152:155], v[198:201], v[60:63]
	v_mfma_f32_16x16x32_bf16 v[60:63], v[148:151], v[194:197], v[60:63]
	s_setprio 0
	s_add_i32 s16, s29, s38
	v_lshl_add_u64 v[202:203], v[202:203], 0, s[86:87]
	s_mov_b32 m0, s16
	ds_read_b128 v[164:167], v210 offset:49152
	ds_read_b128 v[168:171], v210 offset:50176
	ds_read_b128 v[172:175], v210 offset:51200
	ds_read_b128 v[176:179], v210 offset:52224
	ds_read_b128 v[180:183], v210 offset:53248
	ds_read_b128 v[184:187], v210 offset:54272
	ds_read_b128 v[194:197], v210 offset:55296
	ds_read_b128 v[198:201], v210 offset:56320
	global_load_lds_dwordx4 v[202:203], off
	s_add_i32 m0, s16, 0x2000
	s_add_u32 s12, s12, 0x100080
	v_lshl_add_u64 v[202:203], v[204:205], 0, s[86:87]
	s_addc_u32 s13, s13, 0
	s_add_i32 s16, s40, s38
	global_load_lds_dwordx4 v[202:203], off
	s_mov_b32 m0, s16
	v_lshl_add_u64 v[202:203], v[206:207], 0, s[86:87]
	global_load_lds_dwordx4 v192, s[12:13]
	s_add_i32 m0, s16, 0x2000
	s_nop 0
	global_load_lds_dwordx4 v190, s[12:13]
	s_mov_b32 m0, s63
	s_nop 0
	global_load_lds_dwordx4 v[202:203], off
	v_lshl_add_u64 v[202:203], v[208:209], 0, s[86:87]
	s_mov_b32 m0, s64
	s_nop 0
	global_load_lds_dwordx4 v[202:203], off
	s_waitcnt vmcnt(8)
	s_waitcnt lgkmcnt(0)
	s_barrier
	s_setprio 1
	v_mfma_f32_16x16x32_bf16 v[68:71], v[132:135], v[164:167], v[68:71]
	v_mfma_f32_16x16x32_bf16 v[68:71], v[136:139], v[168:171], v[68:71]
	v_mfma_f32_16x16x32_bf16 v[72:75], v[144:147], v[168:171], v[72:75]
	v_mfma_f32_16x16x32_bf16 v[72:75], v[140:143], v[164:167], v[72:75]
	v_mfma_f32_16x16x32_bf16 v[80:83], v[140:143], v[172:175], v[80:83]
	v_mfma_f32_16x16x32_bf16 v[80:83], v[144:147], v[176:179], v[80:83]
	v_mfma_f32_16x16x32_bf16 v[76:79], v[136:139], v[176:179], v[76:79]
	v_mfma_f32_16x16x32_bf16 v[76:79], v[132:135], v[172:175], v[76:79]
	v_mfma_f32_16x16x32_bf16 v[84:87], v[132:135], v[180:183], v[84:87]
	v_mfma_f32_16x16x32_bf16 v[84:87], v[136:139], v[184:187], v[84:87]
	v_mfma_f32_16x16x32_bf16 v[88:91], v[144:147], v[184:187], v[88:91]
	v_mfma_f32_16x16x32_bf16 v[88:91], v[140:143], v[180:183], v[88:91]
	v_mfma_f32_16x16x32_bf16 v[96:99], v[140:143], v[194:197], v[96:99]
	v_mfma_f32_16x16x32_bf16 v[96:99], v[144:147], v[198:201], v[96:99]
	v_mfma_f32_16x16x32_bf16 v[92:95], v[136:139], v[198:201], v[92:95]
	v_mfma_f32_16x16x32_bf16 v[92:95], v[132:135], v[194:197], v[92:95]
	s_setprio 0
	s_setprio 1
	v_mfma_f32_16x16x32_bf16 v[100:103], v[148:151], v[164:167], v[100:103]
	v_mfma_f32_16x16x32_bf16 v[100:103], v[152:155], v[168:171], v[100:103]
	v_mfma_f32_16x16x32_bf16 v[104:107], v[160:163], v[168:171], v[104:107]
	v_mfma_f32_16x16x32_bf16 v[104:107], v[156:159], v[164:167], v[104:107]
	v_mfma_f32_16x16x32_bf16 v[112:115], v[156:159], v[172:175], v[112:115]
	v_mfma_f32_16x16x32_bf16 v[112:115], v[160:163], v[176:179], v[112:115]
	v_mfma_f32_16x16x32_bf16 v[108:111], v[152:155], v[176:179], v[108:111]
	v_mfma_f32_16x16x32_bf16 v[108:111], v[148:151], v[172:175], v[108:111]
	v_mfma_f32_16x16x32_bf16 v[116:119], v[148:151], v[180:183], v[116:119]
	v_mfma_f32_16x16x32_bf16 v[116:119], v[152:155], v[184:187], v[116:119]
	v_mfma_f32_16x16x32_bf16 v[120:123], v[160:163], v[184:187], v[120:123]
	v_mfma_f32_16x16x32_bf16 v[120:123], v[156:159], v[180:183], v[120:123]
	v_mfma_f32_16x16x32_bf16 v[128:131], v[156:159], v[194:197], v[128:131]
	v_mfma_f32_16x16x32_bf16 v[128:131], v[160:163], v[198:201], v[128:131]
	s_setprio 2
	s_barrier
	v_mfma_f32_16x16x32_bf16 v[124:127], v[152:155], v[198:201], v[124:127]
	v_mfma_f32_16x16x32_bf16 v[124:127], v[148:151], v[194:197], v[124:127]
	s_setprio 0
	s_add_i32 s28, s28, 2
	s_add_u32 s14, s14, 0x100
	s_addc_u32 s15, s15, 0
	s_add_u32 s26, s26, 0x100
	s_addc_u32 s27, s27, 0
	s_cmp_gt_u32 s28, 13
	s_cbranch_scc0 .LBB0_2273
	s_and_b64 vcc, exec, s[48:49]
	s_cbranch_vccz .LBB0_2276
	s_barrier
